# GEMM K-loops: per-phase s_setprio flips removed; one static priority raise for waves 4-7 around each K-loop (reset before the epilogue)
# speedup vs baseline: 1.0126x; 1.0083x over previous
; #define PG8_STAGE(bufoff, gbase, voff) do { _Pragma("unroll") for (int _i = 0; _i < 2; ++_i) \
;     __builtin_amdgcn_global_load_lds((const unsigned*)((const char*)(gbase) + (voff)[_i]), (LAS unsigned*)(lds + (bufoff) + ldsw + _i * 8192), 16, 0, 0); } while (0)
; #define PG8_LDA(dst, b, h) do { _Pragma("unroll") for (int m = 0; m < 4; ++m) _Pragma("unroll") for (int k = 0; k < 2; ++k) dst[m][k] = *(const LAS bf16x8*)(lds + PG8_SA(b, h) + aoff + m * 2048 + k * 1024); } while (0)
; #define PG8_LDB(dst, b, h) do { _Pragma("unroll") for (int n = 0; n < 2; ++n) _Pragma("unroll") for (int k = 0; k < 2; ++k) dst[n][k] = *(const LAS bf16x8*)(lds + PG8_SB(b, h) + boff + n * 2048 + k * 1024); } while (0)
; #define PG8_MMA(ai, bj, At, Bt) do { __builtin_amdgcn_s_setprio(1); _Pragma("unroll") for (int m = 0; m < 4; ++m) _Pragma("unroll") for (int n = 0; n < 2; ++n) _Pragma("unroll") for (int k = 0; k < 2; ++k) \
;     acc[ai][bj][m][n] = __builtin_amdgcn_mfma_f32_16x16x32_bf16(Bt[n][k], At[m][k], acc[ai][bj][m][n], 0, 0, 0); __builtin_amdgcn_s_setprio(0); } while (0)
; #define PG8_WAIT_L(n) asm volatile("s_waitcnt lgkmcnt(" #n ")" ::: "memory")
; #define PG8_BAR __builtin_amdgcn_s_barrier()
; template <class Epi>
; __device__ __forceinline__ void gemm_phase(LAS unsigned char* lds, const Gemm g, const StaticOrder& S, const Epi& E, int wv0) {
;     ...
;   for (;;) {
;     const bool has_next = S.next(ui + 1, nxt);
;     const char* nA = has_next ? (const char*)g.A + (size_t)nxt.pm * tstepA : cA; const char* nB = has_next ? (const char*)g.Bt + (size_t)nxt.pn * tstepB : cB;
;     for (int t = 0; t < nt; t += 2) {
;       const bool last = (t == nt - 2);
;       const char* a1 = cA + (size_t)(t + 1) * kstep;
;       const char* a2 = last ? nA : cA + (size_t)(t + 2) * kstep; const char* b2 = last ? nB : cB + (size_t)(t + 2) * kstep;
;       const char* a3 = a2 + kstep; const char* b3 = b2 + kstep;
;       PG8_LDB(B0, 0, 0); PG8_SCHED; PG8_LDA(At, 0, 0); PG8_STAGE(PG8_SA(1, 1), a1 + hstepA, voffA);
;       PG8_WAIT_L(8); PG8_BAR; PG8_WAIT_L(0); PG8_MMA(0, 0, At, B0); PG8_BAR; PG8_SCHED;
;     ...
; #pragma unroll
;     for (int a = 0; a < 2; ++a)
; #pragma unroll
;       for (int b = 0; b < 2; ++b)
; #pragma unroll
;         for (int m = 0; m < 4; ++m)
; #pragma unroll
;           for (int n = 0; n < 2; ++n) acc[a][b][m][n] = (f32x4){0.f, 0.f, 0.f, 0.f};
.LBB0_152:
	s_ashr_i32 s19, s18, 31
	v_mov_b64_e32 v[0:1], 0x480
	s_lshl_b64 s[0:1], s[18:19], 20
	v_cmp_lt_i64_e32 vcc, s[20:21], v[0:1]
	s_add_u32 s20, s36, s0
	s_addc_u32 s21, s37, s1
	s_and_b64 s[0:1], vcc, exec
	s_cselect_b32 s1, s21, s9
	s_cselect_b32 s5, s20, s8
	s_ashr_i32 s17, s16, 31
	s_lshl_b64 s[22:23], s[16:17], 20
	s_add_u32 s22, s10, s22
	s_addc_u32 s23, s11, s23
	s_and_b64 s[26:27], vcc, exec
	s_cselect_b32 s7, s23, s25
	s_cselect_b32 s17, s22, s24
	s_add_u32 s8, s8, 0x80080
	s_addc_u32 s9, s9, 0
	s_add_u32 s19, s24, 0x100
	v_mov_b32_e32 v4, 0
	s_addc_u32 s28, s25, 0
	s_mov_b32 s29, -2
	v_mov_b32_e32 v5, v4
	v_mov_b32_e32 v6, v4
	v_mov_b32_e32 v7, v4
	v_mov_b32_e32 v0, v4
	v_mov_b32_e32 v1, v4
	v_mov_b32_e32 v2, v4
	v_mov_b32_e32 v3, v4
	v_mov_b32_e32 v12, v4
	v_mov_b32_e32 v13, v4
	v_mov_b32_e32 v14, v4
	v_mov_b32_e32 v15, v4
	v_mov_b32_e32 v8, v4
	v_mov_b32_e32 v9, v4
	v_mov_b32_e32 v10, v4
	v_mov_b32_e32 v11, v4
	v_mov_b32_e32 v20, v4
	v_mov_b32_e32 v21, v4
	v_mov_b32_e32 v22, v4
	v_mov_b32_e32 v23, v4
	v_mov_b32_e32 v16, v4
	v_mov_b32_e32 v17, v4
	v_mov_b32_e32 v18, v4
	v_mov_b32_e32 v19, v4
	v_mov_b32_e32 v28, v4
	v_mov_b32_e32 v29, v4
	v_mov_b32_e32 v30, v4
	v_mov_b32_e32 v31, v4
	v_mov_b32_e32 v24, v4
	v_mov_b32_e32 v25, v4
	v_mov_b32_e32 v26, v4
	v_mov_b32_e32 v27, v4
	v_mov_b32_e32 v72, v4
	v_mov_b32_e32 v73, v4
	v_mov_b32_e32 v74, v4
	v_mov_b32_e32 v75, v4
	v_mov_b32_e32 v76, v4
	v_mov_b32_e32 v77, v4
	v_mov_b32_e32 v78, v4
	v_mov_b32_e32 v79, v4
	v_mov_b32_e32 v80, v4
	v_mov_b32_e32 v81, v4
	v_mov_b32_e32 v82, v4
	v_mov_b32_e32 v83, v4
	v_mov_b32_e32 v84, v4
	v_mov_b32_e32 v85, v4
	v_mov_b32_e32 v86, v4
	v_mov_b32_e32 v87, v4
	v_mov_b32_e32 v98, v4
	v_mov_b32_e32 v99, v4
	v_mov_b32_e32 v100, v4
	v_mov_b32_e32 v101, v4
	v_mov_b32_e32 v102, v4
	v_mov_b32_e32 v103, v4
	v_mov_b32_e32 v104, v4
	v_mov_b32_e32 v105, v4
	v_mov_b32_e32 v114, v4
	v_mov_b32_e32 v115, v4
	v_mov_b32_e32 v116, v4
	v_mov_b32_e32 v117, v4
	v_mov_b32_e32 v118, v4
	v_mov_b32_e32 v119, v4
	v_mov_b32_e32 v120, v4
	v_mov_b32_e32 v121, v4
	v_mov_b32_e32 v36, v4
	v_mov_b32_e32 v37, v4
	v_mov_b32_e32 v38, v4
	v_mov_b32_e32 v39, v4
	v_mov_b32_e32 v32, v4
	v_mov_b32_e32 v33, v4
	v_mov_b32_e32 v34, v4
	v_mov_b32_e32 v35, v4
	v_mov_b32_e32 v44, v4
	v_mov_b32_e32 v45, v4
	v_mov_b32_e32 v46, v4
	v_mov_b32_e32 v47, v4
	v_mov_b32_e32 v40, v4
	v_mov_b32_e32 v41, v4
	v_mov_b32_e32 v42, v4
	v_mov_b32_e32 v43, v4
	v_mov_b32_e32 v52, v4
	v_mov_b32_e32 v53, v4
	v_mov_b32_e32 v54, v4
	v_mov_b32_e32 v55, v4
	v_mov_b32_e32 v48, v4
	v_mov_b32_e32 v49, v4
	v_mov_b32_e32 v50, v4
	v_mov_b32_e32 v51, v4
	v_mov_b32_e32 v60, v4
	v_mov_b32_e32 v61, v4
	v_mov_b32_e32 v62, v4
	v_mov_b32_e32 v63, v4
	v_mov_b32_e32 v56, v4
	v_mov_b32_e32 v57, v4
	v_mov_b32_e32 v58, v4
	v_mov_b32_e32 v59, v4
	v_mov_b32_e32 v130, v4
	v_mov_b32_e32 v131, v4
	v_mov_b32_e32 v132, v4
	v_mov_b32_e32 v133, v4
	v_mov_b32_e32 v134, v4
	v_mov_b32_e32 v135, v4
	v_mov_b32_e32 v136, v4
	v_mov_b32_e32 v137, v4
	v_mov_b32_e32 v146, v4
	v_mov_b32_e32 v147, v4
	v_mov_b32_e32 v148, v4
	v_mov_b32_e32 v149, v4
	v_mov_b32_e32 v150, v4
	v_mov_b32_e32 v151, v4
	v_mov_b32_e32 v152, v4
	v_mov_b32_e32 v153, v4
	v_mov_b32_e32 v154, v4
	v_mov_b32_e32 v155, v4
	v_mov_b32_e32 v156, v4
	v_mov_b32_e32 v157, v4
	v_mov_b32_e32 v158, v4
	v_mov_b32_e32 v159, v4
	v_mov_b32_e32 v160, v4
	v_mov_b32_e32 v161, v4
	v_mov_b32_e32 v64, v4
	v_mov_b32_e32 v65, v4
	v_mov_b32_e32 v66, v4
	v_mov_b32_e32 v67, v4
	v_mov_b32_e32 v68, v4
	v_mov_b32_e32 v69, v4
	v_mov_b32_e32 v70, v4
	v_mov_b32_e32 v71, v4
	s_cmp_lt_u32 s53, 4
	s_cbranch_scc1 .Lgprio0
	s_setprio 1
.Lgprio0:
.LBB0_153:
	s_add_u32 s0, s8, 0xfff80080
	s_addc_u32 s24, s9, -1
	s_add_i32 s49, 0, 0x10000
	v_add_u32_e32 v96, s49, v196
	s_waitcnt vmcnt(6)
	ds_read_b128 v[88:91], v96
	ds_read_b128 v[92:95], v96 offset:1024
	ds_read_b128 v[106:109], v96 offset:2048
	ds_read_b128 v[110:113], v96 offset:3072
	s_cmp_eq_u32 s29, 28
	s_cselect_b32 s27, s1, s24
	s_cselect_b32 s26, s5, s0
	s_cselect_b32 s25, s7, s28
	s_cselect_b32 s24, s17, s19
	v_lshl_add_u64 v[190:191], s[8:9], 0, v[170:171]
	s_add_i32 m0, s39, 0xc000
	ds_read_b128 v[122:125], v197
	ds_read_b128 v[126:129], v197 offset:1024
	ds_read_b128 v[138:141], v197 offset:2048
	ds_read_b128 v[142:145], v197 offset:3072
	ds_read_b128 v[174:177], v197 offset:4096
	ds_read_b128 v[178:181], v197 offset:5120
	ds_read_b128 v[182:185], v197 offset:6144
	ds_read_b128 v[186:189], v197 offset:7168
	global_load_lds_dwordx4 v[190:191], off
	v_lshl_add_u64 v[190:191], s[8:9], 0, v[172:173]
	s_add_i32 m0, s39, 0xe000
	s_nop 0
	global_load_lds_dwordx4 v[190:191], off
	s_waitcnt lgkmcnt(8)
	s_barrier
	s_waitcnt lgkmcnt(0)
	s_waitcnt lgkmcnt(0)
	v_mfma_f32_16x16x32_bf16 v[68:71], v[88:91], v[122:125], v[68:71]
	v_mfma_f32_16x16x32_bf16 v[64:67], v[106:109], v[122:125], v[64:67]
	v_mfma_f32_16x16x32_bf16 v[158:161], v[88:91], v[138:141], v[158:161]
	v_mfma_f32_16x16x32_bf16 v[154:157], v[106:109], v[138:141], v[154:157]
	v_mfma_f32_16x16x32_bf16 v[150:153], v[88:91], v[174:177], v[150:153]
	v_mfma_f32_16x16x32_bf16 v[146:149], v[106:109], v[174:177], v[146:149]
	v_mfma_f32_16x16x32_bf16 v[134:137], v[88:91], v[182:185], v[134:137]
	v_mfma_f32_16x16x32_bf16 v[130:133], v[106:109], v[182:185], v[130:133]
	v_mfma_f32_16x16x32_bf16 v[68:71], v[92:95], v[126:129], v[68:71]
	v_mfma_f32_16x16x32_bf16 v[64:67], v[110:113], v[126:129], v[64:67]
	v_mfma_f32_16x16x32_bf16 v[158:161], v[92:95], v[142:145], v[158:161]
	v_mfma_f32_16x16x32_bf16 v[154:157], v[110:113], v[142:145], v[154:157]
	v_mfma_f32_16x16x32_bf16 v[150:153], v[92:95], v[178:181], v[150:153]
	v_mfma_f32_16x16x32_bf16 v[146:149], v[110:113], v[178:181], v[146:149]
	v_mfma_f32_16x16x32_bf16 v[134:137], v[92:95], v[186:189], v[134:137]
	v_mfma_f32_16x16x32_bf16 v[130:133], v[110:113], v[186:189], v[130:133]
	s_barrier
; #define PG8_STAGE(bufoff, gbase, voff) do { _Pragma("unroll") for (int _i = 0; _i < 2; ++_i) \
;     __builtin_amdgcn_global_load_lds((const unsigned*)((const char*)(gbase) + (voff)[_i]), (LAS unsigned*)(lds + (bufoff) + ldsw + _i * 8192), 16, 0, 0); } while (0)
; #define PG8_LDA(dst, b, h) do { _Pragma("unroll") for (int m = 0; m < 4; ++m) _Pragma("unroll") for (int k = 0; k < 2; ++k) dst[m][k] = *(const LAS bf16x8*)(lds + PG8_SA(b, h) + aoff + m * 2048 + k * 1024); } while (0)
; #define PG8_LDB(dst, b, h) do { _Pragma("unroll") for (int n = 0; n < 2; ++n) _Pragma("unroll") for (int k = 0; k < 2; ++k) dst[n][k] = *(const LAS bf16x8*)(lds + PG8_SB(b, h) + boff + n * 2048 + k * 1024); } while (0)
; #define PG8_MMA(ai, bj, At, Bt) do { __builtin_amdgcn_s_setprio(1); _Pragma("unroll") for (int m = 0; m < 4; ++m) _Pragma("unroll") for (int n = 0; n < 2; ++n) _Pragma("unroll") for (int k = 0; k < 2; ++k) \
;     acc[ai][bj][m][n] = __builtin_amdgcn_mfma_f32_16x16x32_bf16(Bt[n][k], At[m][k], acc[ai][bj][m][n], 0, 0, 0); __builtin_amdgcn_s_setprio(0); } while (0)
; #define PG8_WAIT_V(n) asm volatile("s_waitcnt vmcnt(" #n ")" ::: "memory")
; #define PG8_WAIT_L(n) asm volatile("s_waitcnt lgkmcnt(" #n ")" ::: "memory")
; #define PG8_BAR __builtin_amdgcn_s_barrier()
; #define PG8_SCHED __builtin_amdgcn_sched_barrier(0)
; template <class Epi>
; __device__ __forceinline__ void gemm_phase(LAS unsigned char* lds, const Gemm g, const StaticOrder& S, const Epi& E, int wv0) {
;     ...
;       PG8_LDB(B1, 0, 1); PG8_STAGE(PG8_SB(0, 0), b2, voffB);
;       PG8_BAR; PG8_WAIT_L(0); PG8_MMA(0, 1, At, B1); PG8_BAR;
;       PG8_LDA(At, 0, 1); PG8_STAGE(PG8_SA(0, 0), a2, voffA);
;       PG8_BAR; PG8_WAIT_L(0); PG8_MMA(1, 0, At, B0); PG8_BAR; PG8_SCHED;
;       PG8_STAGE(PG8_SB(0, 1), b2 + hstepB, voffB);
;       PG8_WAIT_V(6); PG8_BAR; PG8_MMA(1, 1, At, B1); PG8_BAR;
;       PG8_LDB(B0, 1, 0); PG8_SCHED; PG8_LDA(At, 1, 0); PG8_STAGE(PG8_SA(0, 1), a2 + hstepA, voffA);
	s_add_i32 s0, 0, 0x14000
	s_add_i32 s49, s49, s38
	v_add_u32_e32 v96, s0, v196
	v_lshl_add_u64 v[210:211], s[24:25], 0, v[164:165]
	s_mov_b32 m0, s49
	ds_read_b128 v[190:193], v96
	ds_read_b128 v[198:201], v96 offset:1024
	ds_read_b128 v[202:205], v96 offset:2048
	ds_read_b128 v[206:209], v96 offset:3072
	global_load_lds_dwordx4 v[210:211], off
	v_lshl_add_u64 v[212:213], s[24:25], 0, v[168:169]
	s_add_i32 m0, s49, 0x2000
	s_nop 0
	global_load_lds_dwordx4 v[212:213], off
	s_barrier
	s_waitcnt lgkmcnt(0)
	s_waitcnt lgkmcnt(0)
	v_mfma_f32_16x16x32_bf16 v[56:59], v[190:193], v[122:125], v[56:59]
	v_mfma_f32_16x16x32_bf16 v[60:63], v[202:205], v[122:125], v[60:63]
	v_mfma_f32_16x16x32_bf16 v[48:51], v[190:193], v[138:141], v[48:51]
	v_mfma_f32_16x16x32_bf16 v[52:55], v[202:205], v[138:141], v[52:55]
	v_mfma_f32_16x16x32_bf16 v[40:43], v[190:193], v[174:177], v[40:43]
	v_mfma_f32_16x16x32_bf16 v[44:47], v[202:205], v[174:177], v[44:47]
	v_mfma_f32_16x16x32_bf16 v[32:35], v[190:193], v[182:185], v[32:35]
	v_mfma_f32_16x16x32_bf16 v[36:39], v[202:205], v[182:185], v[36:39]
	v_mfma_f32_16x16x32_bf16 v[56:59], v[198:201], v[126:129], v[56:59]
	v_mfma_f32_16x16x32_bf16 v[60:63], v[206:209], v[126:129], v[60:63]
	v_mfma_f32_16x16x32_bf16 v[48:51], v[198:201], v[142:145], v[48:51]
	v_mfma_f32_16x16x32_bf16 v[52:55], v[206:209], v[142:145], v[52:55]
	v_mfma_f32_16x16x32_bf16 v[40:43], v[198:201], v[178:181], v[40:43]
	v_mfma_f32_16x16x32_bf16 v[44:47], v[206:209], v[178:181], v[44:47]
	v_mfma_f32_16x16x32_bf16 v[32:35], v[198:201], v[186:189], v[32:35]
	v_mfma_f32_16x16x32_bf16 v[36:39], v[206:209], v[186:189], v[36:39]
	s_mov_b32 m0, s39
	v_lshl_add_u64 v[214:215], s[26:27], 0, v[162:163]
	s_barrier
	ds_read_b128 v[122:125], v197 offset:16384
	ds_read_b128 v[126:129], v197 offset:17408
	ds_read_b128 v[138:141], v197 offset:18432
	ds_read_b128 v[142:145], v197 offset:19456
	ds_read_b128 v[174:177], v197 offset:20480
	ds_read_b128 v[178:181], v197 offset:21504
	ds_read_b128 v[182:185], v197 offset:22528
	ds_read_b128 v[186:189], v197 offset:23552
	global_load_lds_dwordx4 v[214:215], off
	v_lshl_add_u64 v[216:217], s[26:27], 0, v[166:167]
	s_mov_b32 m0, s40
	s_nop 0
	global_load_lds_dwordx4 v[216:217], off
	s_barrier
	s_waitcnt lgkmcnt(0)
	s_waitcnt lgkmcnt(0)
	v_mfma_f32_16x16x32_bf16 v[118:121], v[88:91], v[122:125], v[118:121]
	v_mfma_f32_16x16x32_bf16 v[114:117], v[106:109], v[122:125], v[114:117]
	v_mfma_f32_16x16x32_bf16 v[102:105], v[88:91], v[138:141], v[102:105]
	v_mfma_f32_16x16x32_bf16 v[98:101], v[106:109], v[138:141], v[98:101]
	v_mfma_f32_16x16x32_bf16 v[84:87], v[88:91], v[174:177], v[84:87]
	v_mfma_f32_16x16x32_bf16 v[80:83], v[106:109], v[174:177], v[80:83]
	v_mfma_f32_16x16x32_bf16 v[76:79], v[88:91], v[182:185], v[76:79]
	v_mfma_f32_16x16x32_bf16 v[72:75], v[106:109], v[182:185], v[72:75]
	v_mfma_f32_16x16x32_bf16 v[118:121], v[92:95], v[126:129], v[118:121]
	v_mfma_f32_16x16x32_bf16 v[114:117], v[110:113], v[126:129], v[114:117]
	v_mfma_f32_16x16x32_bf16 v[102:105], v[92:95], v[142:145], v[102:105]
	v_mfma_f32_16x16x32_bf16 v[98:101], v[110:113], v[142:145], v[98:101]
	v_mfma_f32_16x16x32_bf16 v[84:87], v[92:95], v[178:181], v[84:87]
	v_mfma_f32_16x16x32_bf16 v[80:83], v[110:113], v[178:181], v[80:83]
	v_mfma_f32_16x16x32_bf16 v[76:79], v[92:95], v[186:189], v[76:79]
	v_mfma_f32_16x16x32_bf16 v[72:75], v[110:113], v[186:189], v[72:75]
	s_barrier
	s_add_u32 s50, s24, 0x80000
	s_addc_u32 s51, s25, 0
	s_add_i32 s0, s0, s38
	v_lshl_add_u64 v[88:89], s[50:51], 0, v[164:165]
	s_mov_b32 m0, s0
	s_nop 0
	global_load_lds_dwordx4 v[88:89], off
	v_lshl_add_u64 v[88:89], s[50:51], 0, v[168:169]
	s_add_i32 m0, s0, 0x2000
	s_nop 0
	global_load_lds_dwordx4 v[88:89], off
	s_waitcnt vmcnt(6)
	s_barrier
	v_mfma_f32_16x16x32_bf16 v[24:27], v[190:193], v[122:125], v[24:27]
	v_mfma_f32_16x16x32_bf16 v[28:31], v[202:205], v[122:125], v[28:31]
	v_mfma_f32_16x16x32_bf16 v[16:19], v[190:193], v[138:141], v[16:19]
	v_mfma_f32_16x16x32_bf16 v[20:23], v[202:205], v[138:141], v[20:23]
	v_mfma_f32_16x16x32_bf16 v[8:11], v[190:193], v[174:177], v[8:11]
	v_mfma_f32_16x16x32_bf16 v[12:15], v[202:205], v[174:177], v[12:15]
	v_mfma_f32_16x16x32_bf16 v[0:3], v[190:193], v[182:185], v[0:3]
	v_mfma_f32_16x16x32_bf16 v[4:7], v[202:205], v[182:185], v[4:7]
	v_mfma_f32_16x16x32_bf16 v[24:27], v[198:201], v[126:129], v[24:27]
	v_mfma_f32_16x16x32_bf16 v[28:31], v[206:209], v[126:129], v[28:31]
	v_mfma_f32_16x16x32_bf16 v[16:19], v[198:201], v[142:145], v[16:19]
	v_mfma_f32_16x16x32_bf16 v[20:23], v[206:209], v[142:145], v[20:23]
	v_mfma_f32_16x16x32_bf16 v[8:11], v[198:201], v[178:181], v[8:11]
	v_mfma_f32_16x16x32_bf16 v[12:15], v[206:209], v[178:181], v[12:15]
	v_mfma_f32_16x16x32_bf16 v[0:3], v[198:201], v[186:189], v[0:3]
	v_mfma_f32_16x16x32_bf16 v[4:7], v[206:209], v[186:189], v[4:7]
	s_add_i32 s0, 0, 0x18000
	v_add_u32_e32 v96, s0, v196
	s_barrier
	ds_read_b128 v[88:91], v96
	ds_read_b128 v[92:95], v96 offset:1024
	ds_read_b128 v[106:109], v96 offset:2048
	ds_read_b128 v[110:113], v96 offset:3072
	s_add_u32 s26, s26, 0x80000
	s_addc_u32 s27, s27, 0
	s_mov_b32 m0, s41
	v_lshl_add_u64 v[190:191], s[26:27], 0, v[162:163]
	ds_read_b128 v[122:125], v197 offset:32768
	ds_read_b128 v[126:129], v197 offset:33792
	ds_read_b128 v[138:141], v197 offset:34816
	ds_read_b128 v[142:145], v197 offset:35840
	ds_read_b128 v[174:177], v197 offset:36864
	ds_read_b128 v[178:181], v197 offset:37888
	ds_read_b128 v[182:185], v197 offset:38912
	ds_read_b128 v[186:189], v197 offset:39936
	global_load_lds_dwordx4 v[190:191], off
	v_lshl_add_u64 v[190:191], s[26:27], 0, v[166:167]
	s_mov_b32 m0, s42
	s_nop 0
	global_load_lds_dwordx4 v[190:191], off
	s_waitcnt lgkmcnt(8)
	s_barrier
; #define PG8_STAGE(bufoff, gbase, voff) do { _Pragma("unroll") for (int _i = 0; _i < 2; ++_i) \
;     __builtin_amdgcn_global_load_lds((const unsigned*)((const char*)(gbase) + (voff)[_i]), (LAS unsigned*)(lds + (bufoff) + ldsw + _i * 8192), 16, 0, 0); } while (0)
; #define PG8_LDA(dst, b, h) do { _Pragma("unroll") for (int m = 0; m < 4; ++m) _Pragma("unroll") for (int k = 0; k < 2; ++k) dst[m][k] = *(const LAS bf16x8*)(lds + PG8_SA(b, h) + aoff + m * 2048 + k * 1024); } while (0)
; #define PG8_LDB(dst, b, h) do { _Pragma("unroll") for (int n = 0; n < 2; ++n) _Pragma("unroll") for (int k = 0; k < 2; ++k) dst[n][k] = *(const LAS bf16x8*)(lds + PG8_SB(b, h) + boff + n * 2048 + k * 1024); } while (0)
; #define PG8_MMA(ai, bj, At, Bt) do { __builtin_amdgcn_s_setprio(1); _Pragma("unroll") for (int m = 0; m < 4; ++m) _Pragma("unroll") for (int n = 0; n < 2; ++n) _Pragma("unroll") for (int k = 0; k < 2; ++k) \
;     acc[ai][bj][m][n] = __builtin_amdgcn_mfma_f32_16x16x32_bf16(Bt[n][k], At[m][k], acc[ai][bj][m][n], 0, 0, 0); __builtin_amdgcn_s_setprio(0); } while (0)
; #define PG8_WAIT_V(n) asm volatile("s_waitcnt vmcnt(" #n ")" ::: "memory")
; #define PG8_WAIT_L(n) asm volatile("s_waitcnt lgkmcnt(" #n ")" ::: "memory")
; #define PG8_BAR __builtin_amdgcn_s_barrier()
; #define PG8_SCHED __builtin_amdgcn_sched_barrier(0)
; template <class Epi>
; __device__ __forceinline__ void gemm_phase(LAS unsigned char* lds, const Gemm g, const StaticOrder& S, const Epi& E, int wv0) {
;     ...
;       PG8_LDB(B0, 1, 0); PG8_SCHED; PG8_LDA(At, 1, 0); PG8_STAGE(PG8_SA(0, 1), a2 + hstepA, voffA);
;       PG8_WAIT_L(8); PG8_BAR; PG8_WAIT_L(0); PG8_MMA(0, 0, At, B0); PG8_BAR; PG8_SCHED;
;       PG8_LDB(B1, 1, 1); PG8_STAGE(PG8_SB(1, 0), b3, voffB);
;       PG8_BAR; PG8_WAIT_L(0); PG8_MMA(0, 1, At, B1); PG8_BAR;
;       PG8_LDA(At, 1, 1); PG8_STAGE(PG8_SA(1, 0), a3, voffA);
;       PG8_BAR; PG8_WAIT_L(0); PG8_MMA(1, 0, At, B0); PG8_BAR; PG8_SCHED;
;       PG8_STAGE(PG8_SB(1, 1), b3 + hstepB, voffB);
;       PG8_WAIT_V(6); PG8_BAR; PG8_MMA(1, 1, At, B1); PG8_BAR;
;     }
;     E(acc, cur, wr, wc, fr, fq);
	s_waitcnt lgkmcnt(0)
	s_waitcnt lgkmcnt(0)
	v_mfma_f32_16x16x32_bf16 v[68:71], v[88:91], v[122:125], v[68:71]
	v_mfma_f32_16x16x32_bf16 v[64:67], v[106:109], v[122:125], v[64:67]
	v_mfma_f32_16x16x32_bf16 v[158:161], v[88:91], v[138:141], v[158:161]
	v_mfma_f32_16x16x32_bf16 v[154:157], v[106:109], v[138:141], v[154:157]
	v_mfma_f32_16x16x32_bf16 v[150:153], v[88:91], v[174:177], v[150:153]
	v_mfma_f32_16x16x32_bf16 v[146:149], v[106:109], v[174:177], v[146:149]
	v_mfma_f32_16x16x32_bf16 v[134:137], v[88:91], v[182:185], v[134:137]
	v_mfma_f32_16x16x32_bf16 v[130:133], v[106:109], v[182:185], v[130:133]
	v_mfma_f32_16x16x32_bf16 v[68:71], v[92:95], v[126:129], v[68:71]
	v_mfma_f32_16x16x32_bf16 v[64:67], v[110:113], v[126:129], v[64:67]
	v_mfma_f32_16x16x32_bf16 v[158:161], v[92:95], v[142:145], v[158:161]
	v_mfma_f32_16x16x32_bf16 v[154:157], v[110:113], v[142:145], v[154:157]
	v_mfma_f32_16x16x32_bf16 v[150:153], v[92:95], v[178:181], v[150:153]
	v_mfma_f32_16x16x32_bf16 v[146:149], v[110:113], v[178:181], v[146:149]
	v_mfma_f32_16x16x32_bf16 v[134:137], v[92:95], v[186:189], v[134:137]
	v_mfma_f32_16x16x32_bf16 v[130:133], v[110:113], v[186:189], v[130:133]
	s_barrier
	s_add_i32 s26, 0, 0x1c000
	s_add_i32 s0, s0, s38
	v_add_u32_e32 v96, s26, v196
	v_lshl_add_u64 v[210:211], v[210:211], 0, s[72:73]
	s_mov_b32 m0, s0
	ds_read_b128 v[190:193], v96
	ds_read_b128 v[198:201], v96 offset:1024
	ds_read_b128 v[202:205], v96 offset:2048
	ds_read_b128 v[206:209], v96 offset:3072
	global_load_lds_dwordx4 v[210:211], off
	v_lshl_add_u64 v[210:211], v[212:213], 0, s[72:73]
	s_add_i32 m0, s0, 0x2000
	s_nop 0
	global_load_lds_dwordx4 v[210:211], off
	s_barrier
	s_waitcnt lgkmcnt(0)
	s_waitcnt lgkmcnt(0)
	v_mfma_f32_16x16x32_bf16 v[56:59], v[190:193], v[122:125], v[56:59]
	v_mfma_f32_16x16x32_bf16 v[60:63], v[202:205], v[122:125], v[60:63]
	v_mfma_f32_16x16x32_bf16 v[48:51], v[190:193], v[138:141], v[48:51]
	v_mfma_f32_16x16x32_bf16 v[52:55], v[202:205], v[138:141], v[52:55]
	v_mfma_f32_16x16x32_bf16 v[40:43], v[190:193], v[174:177], v[40:43]
	v_mfma_f32_16x16x32_bf16 v[44:47], v[202:205], v[174:177], v[44:47]
	v_mfma_f32_16x16x32_bf16 v[32:35], v[190:193], v[182:185], v[32:35]
	v_mfma_f32_16x16x32_bf16 v[36:39], v[202:205], v[182:185], v[36:39]
	v_mfma_f32_16x16x32_bf16 v[56:59], v[198:201], v[126:129], v[56:59]
	v_mfma_f32_16x16x32_bf16 v[60:63], v[206:209], v[126:129], v[60:63]
	v_mfma_f32_16x16x32_bf16 v[48:51], v[198:201], v[142:145], v[48:51]
	v_mfma_f32_16x16x32_bf16 v[52:55], v[206:209], v[142:145], v[52:55]
	v_mfma_f32_16x16x32_bf16 v[40:43], v[198:201], v[178:181], v[40:43]
	v_mfma_f32_16x16x32_bf16 v[44:47], v[206:209], v[178:181], v[44:47]
	v_mfma_f32_16x16x32_bf16 v[32:35], v[198:201], v[186:189], v[32:35]
	v_mfma_f32_16x16x32_bf16 v[36:39], v[206:209], v[186:189], v[36:39]
	s_mov_b32 m0, s44
	v_lshl_add_u64 v[210:211], v[214:215], 0, s[72:73]
	s_barrier
	ds_read_b128 v[122:125], v197 offset:49152
	ds_read_b128 v[126:129], v197 offset:50176
	ds_read_b128 v[138:141], v197 offset:51200
	ds_read_b128 v[142:145], v197 offset:52224
	ds_read_b128 v[174:177], v197 offset:53248
	ds_read_b128 v[178:181], v197 offset:54272
	ds_read_b128 v[182:185], v197 offset:55296
	ds_read_b128 v[186:189], v197 offset:56320
	global_load_lds_dwordx4 v[210:211], off
	v_lshl_add_u64 v[210:211], v[216:217], 0, s[72:73]
	s_mov_b32 m0, s45
	s_nop 0
	global_load_lds_dwordx4 v[210:211], off
	s_barrier
	s_waitcnt lgkmcnt(0)
	s_waitcnt lgkmcnt(0)
	v_mfma_f32_16x16x32_bf16 v[118:121], v[88:91], v[122:125], v[118:121]
	v_mfma_f32_16x16x32_bf16 v[114:117], v[106:109], v[122:125], v[114:117]
	v_mfma_f32_16x16x32_bf16 v[102:105], v[88:91], v[138:141], v[102:105]
	v_mfma_f32_16x16x32_bf16 v[98:101], v[106:109], v[138:141], v[98:101]
	v_mfma_f32_16x16x32_bf16 v[84:87], v[88:91], v[174:177], v[84:87]
	v_mfma_f32_16x16x32_bf16 v[80:83], v[106:109], v[174:177], v[80:83]
	v_mfma_f32_16x16x32_bf16 v[76:79], v[88:91], v[182:185], v[76:79]
	v_mfma_f32_16x16x32_bf16 v[72:75], v[106:109], v[182:185], v[72:75]
	v_mfma_f32_16x16x32_bf16 v[118:121], v[92:95], v[126:129], v[118:121]
	v_mfma_f32_16x16x32_bf16 v[114:117], v[110:113], v[126:129], v[114:117]
	v_mfma_f32_16x16x32_bf16 v[102:105], v[92:95], v[142:145], v[102:105]
	v_mfma_f32_16x16x32_bf16 v[98:101], v[110:113], v[142:145], v[98:101]
	v_mfma_f32_16x16x32_bf16 v[84:87], v[92:95], v[178:181], v[84:87]
	v_mfma_f32_16x16x32_bf16 v[80:83], v[110:113], v[178:181], v[80:83]
	v_mfma_f32_16x16x32_bf16 v[76:79], v[92:95], v[186:189], v[76:79]
	v_mfma_f32_16x16x32_bf16 v[72:75], v[110:113], v[186:189], v[72:75]
	s_barrier
	s_add_u32 s24, s24, 0x80080
	s_addc_u32 s25, s25, 0
	s_add_i32 s0, s26, s38
	v_lshl_add_u64 v[88:89], s[24:25], 0, v[164:165]
	s_mov_b32 m0, s0
	s_nop 0
	global_load_lds_dwordx4 v[88:89], off
	v_lshl_add_u64 v[88:89], s[24:25], 0, v[168:169]
	s_add_i32 m0, s0, 0x2000
	s_nop 0
	global_load_lds_dwordx4 v[88:89], off
	s_waitcnt vmcnt(6)
	s_barrier
	v_mfma_f32_16x16x32_bf16 v[24:27], v[190:193], v[122:125], v[24:27]
	v_mfma_f32_16x16x32_bf16 v[28:31], v[202:205], v[122:125], v[28:31]
	v_mfma_f32_16x16x32_bf16 v[16:19], v[190:193], v[138:141], v[16:19]
	v_mfma_f32_16x16x32_bf16 v[20:23], v[202:205], v[138:141], v[20:23]
	v_mfma_f32_16x16x32_bf16 v[8:11], v[190:193], v[174:177], v[8:11]
	v_mfma_f32_16x16x32_bf16 v[12:15], v[202:205], v[174:177], v[12:15]
	v_mfma_f32_16x16x32_bf16 v[0:3], v[190:193], v[182:185], v[0:3]
	v_mfma_f32_16x16x32_bf16 v[4:7], v[202:205], v[182:185], v[4:7]
	v_mfma_f32_16x16x32_bf16 v[24:27], v[198:201], v[126:129], v[24:27]
	v_mfma_f32_16x16x32_bf16 v[28:31], v[206:209], v[126:129], v[28:31]
	v_mfma_f32_16x16x32_bf16 v[16:19], v[198:201], v[142:145], v[16:19]
	v_mfma_f32_16x16x32_bf16 v[20:23], v[206:209], v[142:145], v[20:23]
	v_mfma_f32_16x16x32_bf16 v[8:11], v[198:201], v[178:181], v[8:11]
	v_mfma_f32_16x16x32_bf16 v[12:15], v[206:209], v[178:181], v[12:15]
	v_mfma_f32_16x16x32_bf16 v[0:3], v[198:201], v[186:189], v[0:3]
	v_mfma_f32_16x16x32_bf16 v[4:7], v[206:209], v[186:189], v[4:7]
	s_add_i32 s29, s29, 2
	s_add_u32 s8, s8, 0x100
	s_addc_u32 s9, s9, 0
	s_add_u32 s19, s19, 0x100
	s_addc_u32 s28, s28, 0
	s_cmp_gt_u32 s29, 29
	s_barrier
	s_cbranch_scc0 .LBB0_153
	s_setprio 0
	s_lshl_b32 s0, s4, 8
	s_or_b32 s17, s0, s43
	s_and_b32 s0, s17, 0xffffff40
	v_bitop3_b32 v88, s17, 56, v195 bitop3:0xc8
	v_lshlrev_b32_e32 v96, 2, v88
	s_cmpk_eq_i32 s0, 0x500
	v_lshl_add_u32 v176, s6, 8, v194
	s_cselect_b64 s[4:5], -1, 0
	s_cmpk_lg_i32 s0, 0x500
	v_lshl_add_u64 v[178:179], s[14:15], 0, v[96:97]
	s_cbranch_scc1 .LBB0_156
	v_ashrrev_i32_e32 v177, 31, v176
	v_lshlrev_b64 v[88:89], 8, v[176:177]
	v_lshl_add_u64 v[88:89], v[178:179], 0, v[88:89]
	global_load_dwordx4 v[138:141], v[88:89], off offset:16
	global_load_dwordx4 v[142:145], v[88:89], off

; #define PG8_STAGE(bufoff, gbase, voff) do { _Pragma("unroll") for (int _i = 0; _i < 2; ++_i) \
;     __builtin_amdgcn_global_load_lds((const unsigned*)((const char*)(gbase) + (voff)[_i]), (LAS unsigned*)(lds + (bufoff) + ldsw + _i * 8192), 16, 0, 0); } while (0)
; #define PG8_LDA(dst, b, h) do { _Pragma("unroll") for (int m = 0; m < 4; ++m) _Pragma("unroll") for (int k = 0; k < 2; ++k) dst[m][k] = *(const LAS bf16x8*)(lds + PG8_SA(b, h) + aoff + m * 2048 + k * 1024); } while (0)
; #define PG8_LDB(dst, b, h) do { _Pragma("unroll") for (int n = 0; n < 2; ++n) _Pragma("unroll") for (int k = 0; k < 2; ++k) dst[n][k] = *(const LAS bf16x8*)(lds + PG8_SB(b, h) + boff + n * 2048 + k * 1024); } while (0)
; #define PG8_MMA(ai, bj, At, Bt) do { __builtin_amdgcn_s_setprio(1); _Pragma("unroll") for (int m = 0; m < 4; ++m) _Pragma("unroll") for (int n = 0; n < 2; ++n) _Pragma("unroll") for (int k = 0; k < 2; ++k) \
;     acc[ai][bj][m][n] = __builtin_amdgcn_mfma_f32_16x16x32_bf16(Bt[n][k], At[m][k], acc[ai][bj][m][n], 0, 0, 0); __builtin_amdgcn_s_setprio(0); } while (0)
; #define PG8_WAIT_L(n) asm volatile("s_waitcnt lgkmcnt(" #n ")" ::: "memory")
; #define PG8_BAR __builtin_amdgcn_s_barrier()
; template <class Epi>
; __device__ __forceinline__ void gemm_phase(LAS unsigned char* lds, const Gemm g, const StaticOrder& S, const Epi& E, int wv0) {
;     ...
;     const bool has_next = S.next(ui + 1, nxt);
;     const char* nA = has_next ? (const char*)g.A + (size_t)nxt.pm * tstepA : cA; const char* nB = has_next ? (const char*)g.Bt + (size_t)nxt.pn * tstepB : cB;
;     for (int t = 0; t < nt; t += 2) {
;       const bool last = (t == nt - 2);
;       const char* a1 = cA + (size_t)(t + 1) * kstep;
;       const char* a2 = last ? nA : cA + (size_t)(t + 2) * kstep; const char* b2 = last ? nB : cB + (size_t)(t + 2) * kstep;
;       const char* a3 = a2 + kstep; const char* b3 = b2 + kstep;
;       PG8_LDB(B0, 0, 0); PG8_SCHED; PG8_LDA(At, 0, 0); PG8_STAGE(PG8_SA(1, 1), a1 + hstepA, voffA);
;       PG8_WAIT_L(8); PG8_BAR; PG8_WAIT_L(0); PG8_MMA(0, 0, At, B0); PG8_BAR; PG8_SCHED;
;     ...
; #pragma unroll
;     for (int a = 0; a < 2; ++a)
; #pragma unroll
;       for (int b = 0; b < 2; ++b)
; #pragma unroll
;         for (int m = 0; m < 4; ++m)
; #pragma unroll
;           for (int n = 0; n < 2; ++n) acc[a][b][m][n] = (f32x4){0.f, 0.f, 0.f, 0.f};
.LBB0_670:
	s_ashr_i32 s11, s10, 31
	s_lshl_b64 s[14:15], s[10:11], 18
	s_add_u32 s14, s29, s14
	s_addc_u32 s15, s30, s15
	s_and_b64 s[4:5], s[4:5], exec
	s_cselect_b32 s11, s15, s21
	s_cselect_b32 s17, s14, s20
	s_add_u32 s44, s20, 0x100
	v_mov_b32_e32 v0, 0
	s_addc_u32 s45, s21, 0
	s_mov_b32 s46, -2
	v_mov_b32_e32 v1, v0
	v_mov_b32_e32 v2, v0
	v_mov_b32_e32 v3, v0
	v_mov_b32_e32 v4, v0
	v_mov_b32_e32 v5, v0
	v_mov_b32_e32 v6, v0
	v_mov_b32_e32 v7, v0
	v_mov_b32_e32 v16, v0
	v_mov_b32_e32 v17, v0
	v_mov_b32_e32 v18, v0
	v_mov_b32_e32 v19, v0
	v_mov_b32_e32 v20, v0
	v_mov_b32_e32 v21, v0
	v_mov_b32_e32 v22, v0
	v_mov_b32_e32 v23, v0
	v_mov_b32_e32 v32, v0
	v_mov_b32_e32 v33, v0
	v_mov_b32_e32 v34, v0
	v_mov_b32_e32 v35, v0
	v_mov_b32_e32 v36, v0
	v_mov_b32_e32 v37, v0
	v_mov_b32_e32 v38, v0
	v_mov_b32_e32 v39, v0
	v_mov_b32_e32 v48, v0
	v_mov_b32_e32 v49, v0
	v_mov_b32_e32 v50, v0
	v_mov_b32_e32 v51, v0
	v_mov_b32_e32 v52, v0
	v_mov_b32_e32 v53, v0
	v_mov_b32_e32 v54, v0
	v_mov_b32_e32 v55, v0
	v_mov_b32_e32 v8, v0
	v_mov_b32_e32 v9, v0
	v_mov_b32_e32 v10, v0
	v_mov_b32_e32 v11, v0
	v_mov_b32_e32 v12, v0
	v_mov_b32_e32 v13, v0
	v_mov_b32_e32 v14, v0
	v_mov_b32_e32 v15, v0
	v_mov_b32_e32 v24, v0
	v_mov_b32_e32 v25, v0
	v_mov_b32_e32 v26, v0
	v_mov_b32_e32 v27, v0
	v_mov_b32_e32 v28, v0
	v_mov_b32_e32 v29, v0
	v_mov_b32_e32 v30, v0
	v_mov_b32_e32 v31, v0
	v_mov_b32_e32 v40, v0
	v_mov_b32_e32 v41, v0
	v_mov_b32_e32 v42, v0
	v_mov_b32_e32 v43, v0
	v_mov_b32_e32 v44, v0
	v_mov_b32_e32 v45, v0
	v_mov_b32_e32 v46, v0
	v_mov_b32_e32 v47, v0
	v_mov_b32_e32 v56, v0
	v_mov_b32_e32 v57, v0
	v_mov_b32_e32 v58, v0
	v_mov_b32_e32 v59, v0
	v_mov_b32_e32 v60, v0
	v_mov_b32_e32 v61, v0
	v_mov_b32_e32 v62, v0
	v_mov_b32_e32 v63, v0
	v_mov_b32_e32 v64, v0
	v_mov_b32_e32 v65, v0
	v_mov_b32_e32 v66, v0
	v_mov_b32_e32 v67, v0
	v_mov_b32_e32 v68, v0
	v_mov_b32_e32 v69, v0
	v_mov_b32_e32 v70, v0
	v_mov_b32_e32 v71, v0
	v_mov_b32_e32 v102, v0
	v_mov_b32_e32 v103, v0
	v_mov_b32_e32 v104, v0
	v_mov_b32_e32 v105, v0
	v_mov_b32_e32 v106, v0
	v_mov_b32_e32 v107, v0
	v_mov_b32_e32 v108, v0
	v_mov_b32_e32 v109, v0
	v_mov_b32_e32 v162, v0
	v_mov_b32_e32 v163, v0
	v_mov_b32_e32 v164, v0
	v_mov_b32_e32 v165, v0
	v_mov_b32_e32 v166, v0
	v_mov_b32_e32 v167, v0
	v_mov_b32_e32 v168, v0
	v_mov_b32_e32 v169, v0
	v_mov_b32_e32 v190, v0
	v_mov_b32_e32 v191, v0
	v_mov_b32_e32 v192, v0
	v_mov_b32_e32 v193, v0
	v_mov_b32_e32 v194, v0
	v_mov_b32_e32 v195, v0
	v_mov_b32_e32 v196, v0
	v_mov_b32_e32 v197, v0
	v_mov_b32_e32 v82, v0
	v_mov_b32_e32 v83, v0
	v_mov_b32_e32 v84, v0
	v_mov_b32_e32 v85, v0
	v_mov_b32_e32 v86, v0
	v_mov_b32_e32 v87, v0
	v_mov_b32_e32 v88, v0
	v_mov_b32_e32 v89, v0
	v_mov_b32_e32 v128, v0
	v_mov_b32_e32 v129, v0
	v_mov_b32_e32 v130, v0
	v_mov_b32_e32 v131, v0
	v_mov_b32_e32 v132, v0
	v_mov_b32_e32 v133, v0
	v_mov_b32_e32 v134, v0
	v_mov_b32_e32 v135, v0
	v_mov_b32_e32 v182, v0
	v_mov_b32_e32 v183, v0
	v_mov_b32_e32 v184, v0
	v_mov_b32_e32 v185, v0
	v_mov_b32_e32 v186, v0
	v_mov_b32_e32 v187, v0
	v_mov_b32_e32 v188, v0
	v_mov_b32_e32 v189, v0
	v_mov_b32_e32 v198, v0
	v_mov_b32_e32 v199, v0
	v_mov_b32_e32 v200, v0
	v_mov_b32_e32 v201, v0
	v_mov_b32_e32 v202, v0
	v_mov_b32_e32 v203, v0
	v_mov_b32_e32 v204, v0
	v_mov_b32_e32 v205, v0
	s_cmp_lt_u32 s53, 4
	s_cbranch_scc1 .Lgprio1
	s_setprio 1
.Lgprio1:
.LBB0_671:
	s_add_u32 s4, s18, 0x100
	s_addc_u32 s5, s19, 0
	s_add_i32 s0, 0, 0x10000
	s_waitcnt vmcnt(6)
	v_add_u32_e32 v80, s0, v253
	ds_read_b128 v[72:75], v80
	ds_read_b128 v[76:79], v80 offset:1024
	ds_read_b128 v[90:93], v80 offset:2048
	ds_read_b128 v[98:101], v80 offset:3072
	s_cmp_eq_u32 s46, 4
	s_cselect_b32 s23, s13, s5
	s_cselect_b32 s22, s12, s4
	s_cselect_b32 s21, s11, s45
	s_cselect_b32 s20, s17, s44
	v_lshl_add_u64 v[80:81], s[18:19], 0, v[230:231]
	s_add_i32 m0, s34, 0xc000
	ds_read_b128 v[110:113], v244
	ds_read_b128 v[114:117], v244 offset:1024
	ds_read_b128 v[118:121], v244 offset:2048
	ds_read_b128 v[122:125], v244 offset:3072
	ds_read_b128 v[136:139], v244 offset:4096
	ds_read_b128 v[140:143], v244 offset:5120
	ds_read_b128 v[144:147], v244 offset:6144
	ds_read_b128 v[148:151], v244 offset:7168
	global_load_lds_dwordx4 v[80:81], off
	v_lshl_add_u64 v[80:81], s[18:19], 0, v[232:233]
	s_add_i32 m0, s34, 0xe000
	s_nop 0
	global_load_lds_dwordx4 v[80:81], off
	s_waitcnt lgkmcnt(8)
	s_barrier
	s_waitcnt lgkmcnt(0)
	s_waitcnt lgkmcnt(0)
	v_mfma_f32_16x16x32_bf16 v[132:135], v[72:75], v[136:139], v[132:135]
	v_mfma_f32_16x16x32_bf16 v[126:129], v[90:93], v[136:139], v[128:131]
	v_mfma_f32_16x16x32_bf16 v[86:89], v[72:75], v[144:147], v[86:89]
	v_mfma_f32_16x16x32_bf16 v[80:83], v[90:93], v[144:147], v[82:85]
	v_mfma_f32_16x16x32_bf16 v[152:155], v[72:75], v[110:113], v[202:205]
	v_mfma_f32_16x16x32_bf16 v[156:159], v[90:93], v[110:113], v[198:201]
	v_mfma_f32_16x16x32_bf16 v[170:173], v[72:75], v[118:121], v[186:189]
	v_mfma_f32_16x16x32_bf16 v[174:177], v[90:93], v[118:121], v[182:185]
	v_mfma_f32_16x16x32_bf16 v[132:135], v[76:79], v[140:143], v[132:135]
	v_mfma_f32_16x16x32_bf16 v[126:129], v[98:101], v[140:143], v[126:129]
	v_mfma_f32_16x16x32_bf16 v[86:89], v[76:79], v[148:151], v[86:89]
	v_mfma_f32_16x16x32_bf16 v[80:83], v[98:101], v[148:151], v[80:83]
	v_mfma_f32_16x16x32_bf16 v[152:155], v[76:79], v[114:117], v[152:155]
	v_mfma_f32_16x16x32_bf16 v[156:159], v[98:101], v[114:117], v[156:159]
	v_mfma_f32_16x16x32_bf16 v[170:173], v[76:79], v[122:125], v[170:173]
	v_mfma_f32_16x16x32_bf16 v[174:177], v[98:101], v[122:125], v[174:177]
	s_barrier
; #define PG8_STAGE(bufoff, gbase, voff) do { _Pragma("unroll") for (int _i = 0; _i < 2; ++_i) \
;     __builtin_amdgcn_global_load_lds((const unsigned*)((const char*)(gbase) + (voff)[_i]), (LAS unsigned*)(lds + (bufoff) + ldsw + _i * 8192), 16, 0, 0); } while (0)
; #define PG8_LDA(dst, b, h) do { _Pragma("unroll") for (int m = 0; m < 4; ++m) _Pragma("unroll") for (int k = 0; k < 2; ++k) dst[m][k] = *(const LAS bf16x8*)(lds + PG8_SA(b, h) + aoff + m * 2048 + k * 1024); } while (0)
; #define PG8_LDB(dst, b, h) do { _Pragma("unroll") for (int n = 0; n < 2; ++n) _Pragma("unroll") for (int k = 0; k < 2; ++k) dst[n][k] = *(const LAS bf16x8*)(lds + PG8_SB(b, h) + boff + n * 2048 + k * 1024); } while (0)
; #define PG8_MMA(ai, bj, At, Bt) do { __builtin_amdgcn_s_setprio(1); _Pragma("unroll") for (int m = 0; m < 4; ++m) _Pragma("unroll") for (int n = 0; n < 2; ++n) _Pragma("unroll") for (int k = 0; k < 2; ++k) \
;     acc[ai][bj][m][n] = __builtin_amdgcn_mfma_f32_16x16x32_bf16(Bt[n][k], At[m][k], acc[ai][bj][m][n], 0, 0, 0); __builtin_amdgcn_s_setprio(0); } while (0)
; #define PG8_WAIT_V(n) asm volatile("s_waitcnt vmcnt(" #n ")" ::: "memory")
; #define PG8_WAIT_L(n) asm volatile("s_waitcnt lgkmcnt(" #n ")" ::: "memory")
; #define PG8_BAR __builtin_amdgcn_s_barrier()
; #define PG8_SCHED __builtin_amdgcn_sched_barrier(0)
; template <class Epi>
; __device__ __forceinline__ void gemm_phase(LAS unsigned char* lds, const Gemm g, const StaticOrder& S, const Epi& E, int wv0) {
;     ...
;       PG8_LDB(B1, 0, 1); PG8_STAGE(PG8_SB(0, 0), b2, voffB);
;       PG8_BAR; PG8_WAIT_L(0); PG8_MMA(0, 1, At, B1); PG8_BAR;
;       PG8_LDA(At, 0, 1); PG8_STAGE(PG8_SA(0, 0), a2, voffA);
;       PG8_BAR; PG8_WAIT_L(0); PG8_MMA(1, 0, At, B0); PG8_BAR; PG8_SCHED;
;       PG8_STAGE(PG8_SB(0, 1), b2 + hstepB, voffB);
;       PG8_WAIT_V(6); PG8_BAR; PG8_MMA(1, 1, At, B1); PG8_BAR;
;       PG8_LDB(B0, 1, 0); PG8_SCHED; PG8_LDA(At, 1, 0); PG8_STAGE(PG8_SA(0, 1), a2 + hstepA, voffA);
;       PG8_WAIT_L(8); PG8_BAR; PG8_WAIT_L(0); PG8_MMA(0, 0, At, B0); PG8_BAR; PG8_SCHED;
	s_add_i32 s47, 0, 0x14000
	s_add_i32 s0, s0, s31
	v_add_u32_e32 v84, s47, v253
	v_lshl_add_u64 v[214:215], s[20:21], 0, v[224:225]
	s_mov_b32 m0, s0
	ds_read_b128 v[178:181], v84
	ds_read_b128 v[182:185], v84 offset:1024
	ds_read_b128 v[186:189], v84 offset:2048
	ds_read_b128 v[198:201], v84 offset:3072
	global_load_lds_dwordx4 v[214:215], off
	v_lshl_add_u64 v[216:217], s[20:21], 0, v[228:229]
	s_add_i32 m0, s0, 0x2000
	s_nop 0
	global_load_lds_dwordx4 v[216:217], off
	s_barrier
	s_waitcnt lgkmcnt(0)
	s_waitcnt lgkmcnt(0)
	v_mfma_f32_16x16x32_bf16 v[194:197], v[178:181], v[110:113], v[194:197]
	v_mfma_f32_16x16x32_bf16 v[110:113], v[186:189], v[110:113], v[190:193]
	v_mfma_f32_16x16x32_bf16 v[106:109], v[178:181], v[136:139], v[106:109]
	v_mfma_f32_16x16x32_bf16 v[102:105], v[186:189], v[136:139], v[102:105]
	v_mfma_f32_16x16x32_bf16 v[68:71], v[178:181], v[144:147], v[68:71]
	v_mfma_f32_16x16x32_bf16 v[64:67], v[186:189], v[144:147], v[64:67]
	v_mfma_f32_16x16x32_bf16 v[194:197], v[182:185], v[114:117], v[194:197]
	v_mfma_f32_16x16x32_bf16 v[110:113], v[198:201], v[114:117], v[110:113]
	v_mfma_f32_16x16x32_bf16 v[114:117], v[178:181], v[118:121], v[166:169]
	v_mfma_f32_16x16x32_bf16 v[118:121], v[186:189], v[118:121], v[162:165]
	v_mfma_f32_16x16x32_bf16 v[106:109], v[182:185], v[140:143], v[106:109]
	v_mfma_f32_16x16x32_bf16 v[102:105], v[198:201], v[140:143], v[102:105]
	v_mfma_f32_16x16x32_bf16 v[68:71], v[182:185], v[148:151], v[68:71]
	v_mfma_f32_16x16x32_bf16 v[64:67], v[198:201], v[148:151], v[64:67]
	v_mfma_f32_16x16x32_bf16 v[114:117], v[182:185], v[122:125], v[114:117]
	v_mfma_f32_16x16x32_bf16 v[118:121], v[198:201], v[122:125], v[118:121]
	s_mov_b32 m0, s34
	v_lshl_add_u64 v[218:219], s[22:23], 0, v[94:95]
	s_barrier
	ds_read_b128 v[122:125], v244 offset:16384
	ds_read_b128 v[136:139], v244 offset:17408
	ds_read_b128 v[140:143], v244 offset:18432
	ds_read_b128 v[144:147], v244 offset:19456
	ds_read_b128 v[148:151], v244 offset:20480
	ds_read_b128 v[160:163], v244 offset:21504
	ds_read_b128 v[164:167], v244 offset:22528
	ds_read_b128 v[190:193], v244 offset:23552
	global_load_lds_dwordx4 v[218:219], off
	v_lshl_add_u64 v[220:221], s[22:23], 0, v[226:227]
	s_mov_b32 m0, s35
	s_nop 0
	global_load_lds_dwordx4 v[220:221], off
	s_barrier
	s_waitcnt lgkmcnt(0)
	s_waitcnt lgkmcnt(0)
	v_mfma_f32_16x16x32_bf16 v[60:63], v[72:75], v[122:125], v[60:63]
	v_mfma_f32_16x16x32_bf16 v[56:59], v[90:93], v[122:125], v[56:59]
	v_mfma_f32_16x16x32_bf16 v[44:47], v[72:75], v[140:143], v[44:47]
	v_mfma_f32_16x16x32_bf16 v[40:43], v[90:93], v[140:143], v[40:43]
	v_mfma_f32_16x16x32_bf16 v[28:31], v[72:75], v[148:151], v[28:31]
	v_mfma_f32_16x16x32_bf16 v[24:27], v[90:93], v[148:151], v[24:27]
	v_mfma_f32_16x16x32_bf16 v[12:15], v[72:75], v[164:167], v[12:15]
	v_mfma_f32_16x16x32_bf16 v[8:11], v[90:93], v[164:167], v[8:11]
	v_mfma_f32_16x16x32_bf16 v[60:63], v[76:79], v[136:139], v[60:63]
	v_mfma_f32_16x16x32_bf16 v[56:59], v[98:101], v[136:139], v[56:59]
	v_mfma_f32_16x16x32_bf16 v[44:47], v[76:79], v[144:147], v[44:47]
	v_mfma_f32_16x16x32_bf16 v[40:43], v[98:101], v[144:147], v[40:43]
	v_mfma_f32_16x16x32_bf16 v[28:31], v[76:79], v[160:163], v[28:31]
	v_mfma_f32_16x16x32_bf16 v[24:27], v[98:101], v[160:163], v[24:27]
	v_mfma_f32_16x16x32_bf16 v[12:15], v[76:79], v[190:193], v[12:15]
	v_mfma_f32_16x16x32_bf16 v[8:11], v[98:101], v[190:193], v[8:11]
	s_barrier
	s_add_u32 s18, s20, 0x20000
	s_addc_u32 s19, s21, 0
	s_add_i32 s0, s47, s31
	v_lshl_add_u64 v[72:73], s[18:19], 0, v[224:225]
	s_mov_b32 m0, s0
	s_nop 0
	global_load_lds_dwordx4 v[72:73], off
	v_lshl_add_u64 v[72:73], s[18:19], 0, v[228:229]
	s_add_i32 m0, s0, 0x2000
	s_nop 0
	global_load_lds_dwordx4 v[72:73], off
	s_waitcnt vmcnt(6)
	s_barrier
	v_mfma_f32_16x16x32_bf16 v[52:55], v[178:181], v[122:125], v[52:55]
	v_mfma_f32_16x16x32_bf16 v[48:51], v[186:189], v[122:125], v[48:51]
	v_mfma_f32_16x16x32_bf16 v[36:39], v[178:181], v[140:143], v[36:39]
	v_mfma_f32_16x16x32_bf16 v[32:35], v[186:189], v[140:143], v[32:35]
	v_mfma_f32_16x16x32_bf16 v[20:23], v[178:181], v[148:151], v[20:23]
	v_mfma_f32_16x16x32_bf16 v[16:19], v[186:189], v[148:151], v[16:19]
	v_mfma_f32_16x16x32_bf16 v[4:7], v[178:181], v[164:167], v[4:7]
	v_mfma_f32_16x16x32_bf16 v[0:3], v[186:189], v[164:167], v[0:3]
	v_mfma_f32_16x16x32_bf16 v[52:55], v[182:185], v[136:139], v[52:55]
	v_mfma_f32_16x16x32_bf16 v[48:51], v[198:201], v[136:139], v[48:51]
	v_mfma_f32_16x16x32_bf16 v[36:39], v[182:185], v[144:147], v[36:39]
	v_mfma_f32_16x16x32_bf16 v[32:35], v[198:201], v[144:147], v[32:35]
	v_mfma_f32_16x16x32_bf16 v[20:23], v[182:185], v[160:163], v[20:23]
	v_mfma_f32_16x16x32_bf16 v[16:19], v[198:201], v[160:163], v[16:19]
	v_mfma_f32_16x16x32_bf16 v[4:7], v[182:185], v[190:193], v[4:7]
	v_mfma_f32_16x16x32_bf16 v[0:3], v[198:201], v[190:193], v[0:3]
	s_add_i32 s0, 0, 0x18000
	v_add_u32_e32 v84, s0, v253
	s_barrier
	ds_read_b128 v[72:75], v84
	ds_read_b128 v[76:79], v84 offset:1024
	ds_read_b128 v[90:93], v84 offset:2048
	ds_read_b128 v[98:101], v84 offset:3072
	s_add_u32 s18, s22, 0x114000
	s_addc_u32 s19, s23, 0
	s_mov_b32 m0, s36
	v_lshl_add_u64 v[84:85], s[18:19], 0, v[94:95]
	ds_read_b128 v[122:125], v244 offset:32768
	ds_read_b128 v[136:139], v244 offset:33792
	ds_read_b128 v[140:143], v244 offset:34816
	ds_read_b128 v[144:147], v244 offset:35840
	ds_read_b128 v[148:151], v244 offset:36864
	ds_read_b128 v[178:181], v244 offset:37888
	ds_read_b128 v[206:209], v244 offset:38912
	ds_read_b128 v[210:213], v244 offset:39936
	global_load_lds_dwordx4 v[84:85], off
	v_lshl_add_u64 v[84:85], s[18:19], 0, v[226:227]
	s_mov_b32 m0, s37
	s_nop 0
	global_load_lds_dwordx4 v[84:85], off
	s_waitcnt lgkmcnt(8)
	s_barrier
; #define PG8_STAGE(bufoff, gbase, voff) do { _Pragma("unroll") for (int _i = 0; _i < 2; ++_i) \
;     __builtin_amdgcn_global_load_lds((const unsigned*)((const char*)(gbase) + (voff)[_i]), (LAS unsigned*)(lds + (bufoff) + ldsw + _i * 8192), 16, 0, 0); } while (0)
; #define PG8_LDA(dst, b, h) do { _Pragma("unroll") for (int m = 0; m < 4; ++m) _Pragma("unroll") for (int k = 0; k < 2; ++k) dst[m][k] = *(const LAS bf16x8*)(lds + PG8_SA(b, h) + aoff + m * 2048 + k * 1024); } while (0)
; #define PG8_LDB(dst, b, h) do { _Pragma("unroll") for (int n = 0; n < 2; ++n) _Pragma("unroll") for (int k = 0; k < 2; ++k) dst[n][k] = *(const LAS bf16x8*)(lds + PG8_SB(b, h) + boff + n * 2048 + k * 1024); } while (0)
; #define PG8_MMA(ai, bj, At, Bt) do { __builtin_amdgcn_s_setprio(1); _Pragma("unroll") for (int m = 0; m < 4; ++m) _Pragma("unroll") for (int n = 0; n < 2; ++n) _Pragma("unroll") for (int k = 0; k < 2; ++k) \
;     acc[ai][bj][m][n] = __builtin_amdgcn_mfma_f32_16x16x32_bf16(Bt[n][k], At[m][k], acc[ai][bj][m][n], 0, 0, 0); __builtin_amdgcn_s_setprio(0); } while (0)
; #define PG8_WAIT_L(n) asm volatile("s_waitcnt lgkmcnt(" #n ")" ::: "memory")
; #define PG8_BAR __builtin_amdgcn_s_barrier()
; #define PG8_SCHED __builtin_amdgcn_sched_barrier(0)
; template <class Epi>
; __device__ __forceinline__ void gemm_phase(LAS unsigned char* lds, const Gemm g, const StaticOrder& S, const Epi& E, int wv0) {
;     ...
;       PG8_WAIT_L(8); PG8_BAR; PG8_WAIT_L(0); PG8_MMA(0, 0, At, B0); PG8_BAR; PG8_SCHED;
;       PG8_LDB(B1, 1, 1); PG8_STAGE(PG8_SB(1, 0), b3, voffB);
;       PG8_BAR; PG8_WAIT_L(0); PG8_MMA(0, 1, At, B1); PG8_BAR;
;       PG8_LDA(At, 1, 1); PG8_STAGE(PG8_SA(1, 0), a3, voffA);
;       PG8_BAR; PG8_WAIT_L(0); PG8_MMA(1, 0, At, B0); PG8_BAR; PG8_SCHED;
	s_waitcnt lgkmcnt(0)
	s_waitcnt lgkmcnt(0)
	v_mfma_f32_16x16x32_bf16 v[152:155], v[72:75], v[122:125], v[152:155]
	v_mfma_f32_16x16x32_bf16 v[202:205], v[76:79], v[136:139], v[152:155]
	v_mfma_f32_16x16x32_bf16 v[152:155], v[90:93], v[122:125], v[156:159]
	v_mfma_f32_16x16x32_bf16 v[198:201], v[98:101], v[136:139], v[152:155]
	v_mfma_f32_16x16x32_bf16 v[152:155], v[72:75], v[140:143], v[170:173]
	v_mfma_f32_16x16x32_bf16 v[186:189], v[76:79], v[144:147], v[152:155]
	v_mfma_f32_16x16x32_bf16 v[152:155], v[90:93], v[140:143], v[174:177]
	v_mfma_f32_16x16x32_bf16 v[130:133], v[72:75], v[148:151], v[132:135]
	v_mfma_f32_16x16x32_bf16 v[126:129], v[90:93], v[148:151], v[126:129]
	v_mfma_f32_16x16x32_bf16 v[84:87], v[72:75], v[206:209], v[86:89]
	v_mfma_f32_16x16x32_bf16 v[80:83], v[90:93], v[206:209], v[80:83]
	v_mfma_f32_16x16x32_bf16 v[182:185], v[98:101], v[144:147], v[152:155]
	v_mfma_f32_16x16x32_bf16 v[132:135], v[76:79], v[178:181], v[130:133]
	v_mfma_f32_16x16x32_bf16 v[128:131], v[98:101], v[178:181], v[126:129]
	v_mfma_f32_16x16x32_bf16 v[86:89], v[76:79], v[210:213], v[84:87]
	v_mfma_f32_16x16x32_bf16 v[82:85], v[98:101], v[210:213], v[80:83]
	s_barrier
	s_add_i32 s22, 0, 0x1c000
	v_add_u32_e32 v80, s22, v253
	s_add_i32 s0, s0, s31
	ds_read_b128 v[152:155], v80
	ds_read_b128 v[156:159], v80 offset:1024
	ds_read_b128 v[170:173], v80 offset:2048
	ds_read_b128 v[174:177], v80 offset:3072
	v_lshl_add_u64 v[80:81], v[214:215], 0, s[72:73]
	s_mov_b32 m0, s0
	s_nop 0
	global_load_lds_dwordx4 v[80:81], off
	v_lshl_add_u64 v[80:81], v[216:217], 0, s[72:73]
	s_add_i32 m0, s0, 0x2000
	s_nop 0
	global_load_lds_dwordx4 v[80:81], off
	s_barrier
	s_waitcnt lgkmcnt(0)
	s_waitcnt lgkmcnt(0)
	v_mfma_f32_16x16x32_bf16 v[110:113], v[170:173], v[122:125], v[110:113]
	v_mfma_f32_16x16x32_bf16 v[190:193], v[174:177], v[136:139], v[110:113]
	v_mfma_f32_16x16x32_bf16 v[110:113], v[152:155], v[140:143], v[114:117]
	v_mfma_f32_16x16x32_bf16 v[160:163], v[152:155], v[122:125], v[194:197]
	v_mfma_f32_16x16x32_bf16 v[166:169], v[156:159], v[144:147], v[110:113]
	v_mfma_f32_16x16x32_bf16 v[110:113], v[170:173], v[140:143], v[118:121]
	v_mfma_f32_16x16x32_bf16 v[106:109], v[152:155], v[148:151], v[106:109]
	v_mfma_f32_16x16x32_bf16 v[102:105], v[170:173], v[148:151], v[102:105]
	v_mfma_f32_16x16x32_bf16 v[68:71], v[152:155], v[206:209], v[68:71]
	v_mfma_f32_16x16x32_bf16 v[64:67], v[170:173], v[206:209], v[64:67]
	v_mfma_f32_16x16x32_bf16 v[194:197], v[156:159], v[136:139], v[160:163]
	v_mfma_f32_16x16x32_bf16 v[162:165], v[174:177], v[144:147], v[110:113]
	v_mfma_f32_16x16x32_bf16 v[106:109], v[156:159], v[178:181], v[106:109]
	v_mfma_f32_16x16x32_bf16 v[102:105], v[174:177], v[178:181], v[102:105]
	v_mfma_f32_16x16x32_bf16 v[68:71], v[156:159], v[210:213], v[68:71]
	v_mfma_f32_16x16x32_bf16 v[64:67], v[174:177], v[210:213], v[64:67]
	s_mov_b32 m0, s38
	v_lshl_add_u64 v[80:81], v[218:219], 0, s[72:73]
	s_barrier
	ds_read_b128 v[110:113], v244 offset:49152
	ds_read_b128 v[114:117], v244 offset:50176
	ds_read_b128 v[118:121], v244 offset:51200
	ds_read_b128 v[122:125], v244 offset:52224
	ds_read_b128 v[136:139], v244 offset:53248
	ds_read_b128 v[140:143], v244 offset:54272
	ds_read_b128 v[144:147], v244 offset:55296
	ds_read_b128 v[148:151], v244 offset:56320
	global_load_lds_dwordx4 v[80:81], off
	v_lshl_add_u64 v[80:81], v[220:221], 0, s[72:73]
	s_mov_b32 m0, s39
	s_nop 0
	global_load_lds_dwordx4 v[80:81], off
	s_barrier
; #define PG8_STAGE(bufoff, gbase, voff) do { _Pragma("unroll") for (int _i = 0; _i < 2; ++_i) \
;     __builtin_amdgcn_global_load_lds((const unsigned*)((const char*)(gbase) + (voff)[_i]), (LAS unsigned*)(lds + (bufoff) + ldsw + _i * 8192), 16, 0, 0); } while (0)
; #define PG8_MMA(ai, bj, At, Bt) do { __builtin_amdgcn_s_setprio(1); _Pragma("unroll") for (int m = 0; m < 4; ++m) _Pragma("unroll") for (int n = 0; n < 2; ++n) _Pragma("unroll") for (int k = 0; k < 2; ++k) \
;     acc[ai][bj][m][n] = __builtin_amdgcn_mfma_f32_16x16x32_bf16(Bt[n][k], At[m][k], acc[ai][bj][m][n], 0, 0, 0); __builtin_amdgcn_s_setprio(0); } while (0)
; #define PG8_WAIT_V(n) asm volatile("s_waitcnt vmcnt(" #n ")" ::: "memory")
; #define PG8_WAIT_L(n) asm volatile("s_waitcnt lgkmcnt(" #n ")" ::: "memory")
; #define PG8_BAR __builtin_amdgcn_s_barrier()
; #define PG8_SCHED __builtin_amdgcn_sched_barrier(0)
; template <class Epi>
; __device__ __forceinline__ void gemm_phase(LAS unsigned char* lds, const Gemm g, const StaticOrder& S, const Epi& E, int wv0) {
;     ...
;       PG8_BAR; PG8_WAIT_L(0); PG8_MMA(1, 0, At, B0); PG8_BAR; PG8_SCHED;
;       PG8_STAGE(PG8_SB(1, 1), b3 + hstepB, voffB);
;       PG8_WAIT_V(6); PG8_BAR; PG8_MMA(1, 1, At, B1); PG8_BAR;
;     }
;     E(acc, cur, wr, wc, fr, fq);
;   __device__ __forceinline__ void operator()(const f32x4 (&acc)[2][2][4][2], const pg8::Unit& u, int wr, int wc, int fr, int fq) const {
;     ...
;     const int row0 = u.pm * 256 + wr * 64 + fr, col0 = u.pn * 256 + wc * 32 + 8 * fq;
;     f32x4 hb[2][2]; float hs[2][4];
; #pragma unroll
;     for (int bj = 0; bj < 2; ++bj) { hb[bj][0] = (f32x4){0.f, 0.f, 0.f, 0.f}; hb[bj][1] = hb[bj][0];
;       if (MODE == E_GATE) { hb[bj][0] = *(const f32x4*)(e.f0 + col0 + bj * 128) * (-LOG2E); hb[bj][1] = *(const f32x4*)(e.f0 + col0 + bj * 128 + 4) * (-LOG2E); } }
; #pragma unroll
;     for (int ai = 0; ai < 2; ++ai)
; #pragma unroll
;       for (int m = 0; m < 4; ++m) { hs[ai][m] = 0.f;
;         if (MODE == E_UQ) hs[ai][m] = ((const f32x4*)e.f0)[row0 + ai * 128 + m * 16].x * MLA_QSCALE;
;         if (MODE == E_UKV) hs[ai][m] = ((const f32x4*)e.f0)[row0 + ai * 128 + m * 16].y; }
;     EpiPre q[2][4];
; #pragma unroll
;     for (int i = 0; i < 4; ++i) preload(q[0][i], row0 + (i >> 1) * 16, col0 + (i & 1) * 128);
	s_waitcnt lgkmcnt(0)
	s_waitcnt lgkmcnt(0)
	v_mfma_f32_16x16x32_bf16 v[60:63], v[72:75], v[110:113], v[60:63]
	v_mfma_f32_16x16x32_bf16 v[56:59], v[90:93], v[110:113], v[56:59]
	v_mfma_f32_16x16x32_bf16 v[44:47], v[72:75], v[118:121], v[44:47]
	v_mfma_f32_16x16x32_bf16 v[40:43], v[90:93], v[118:121], v[40:43]
	v_mfma_f32_16x16x32_bf16 v[28:31], v[72:75], v[136:139], v[28:31]
	v_mfma_f32_16x16x32_bf16 v[24:27], v[90:93], v[136:139], v[24:27]
	v_mfma_f32_16x16x32_bf16 v[12:15], v[72:75], v[144:147], v[12:15]
	v_mfma_f32_16x16x32_bf16 v[8:11], v[90:93], v[144:147], v[8:11]
	v_mfma_f32_16x16x32_bf16 v[60:63], v[76:79], v[114:117], v[60:63]
	v_mfma_f32_16x16x32_bf16 v[56:59], v[98:101], v[114:117], v[56:59]
	v_mfma_f32_16x16x32_bf16 v[44:47], v[76:79], v[122:125], v[44:47]
	v_mfma_f32_16x16x32_bf16 v[40:43], v[98:101], v[122:125], v[40:43]
	v_mfma_f32_16x16x32_bf16 v[28:31], v[76:79], v[140:143], v[28:31]
	v_mfma_f32_16x16x32_bf16 v[24:27], v[98:101], v[140:143], v[24:27]
	v_mfma_f32_16x16x32_bf16 v[12:15], v[76:79], v[148:151], v[12:15]
	v_mfma_f32_16x16x32_bf16 v[8:11], v[98:101], v[148:151], v[8:11]
	s_barrier
	s_add_u32 s18, s20, 0x20080
	s_addc_u32 s19, s21, 0
	s_add_i32 s0, s22, s31
	v_lshl_add_u64 v[72:73], s[18:19], 0, v[224:225]
	s_mov_b32 m0, s0
	s_nop 0
	global_load_lds_dwordx4 v[72:73], off
	v_lshl_add_u64 v[72:73], s[18:19], 0, v[228:229]
	s_add_i32 m0, s0, 0x2000
	s_nop 0
	global_load_lds_dwordx4 v[72:73], off
	s_waitcnt vmcnt(6)
	s_barrier
	v_mfma_f32_16x16x32_bf16 v[52:55], v[152:155], v[110:113], v[52:55]
	v_mfma_f32_16x16x32_bf16 v[48:51], v[170:173], v[110:113], v[48:51]
	v_mfma_f32_16x16x32_bf16 v[36:39], v[152:155], v[118:121], v[36:39]
	v_mfma_f32_16x16x32_bf16 v[32:35], v[170:173], v[118:121], v[32:35]
	v_mfma_f32_16x16x32_bf16 v[20:23], v[152:155], v[136:139], v[20:23]
	v_mfma_f32_16x16x32_bf16 v[16:19], v[170:173], v[136:139], v[16:19]
	v_mfma_f32_16x16x32_bf16 v[4:7], v[152:155], v[144:147], v[4:7]
	v_mfma_f32_16x16x32_bf16 v[0:3], v[170:173], v[144:147], v[0:3]
	v_mfma_f32_16x16x32_bf16 v[52:55], v[156:159], v[114:117], v[52:55]
	v_mfma_f32_16x16x32_bf16 v[48:51], v[174:177], v[114:117], v[48:51]
	v_mfma_f32_16x16x32_bf16 v[36:39], v[156:159], v[122:125], v[36:39]
	v_mfma_f32_16x16x32_bf16 v[32:35], v[174:177], v[122:125], v[32:35]
	v_mfma_f32_16x16x32_bf16 v[20:23], v[156:159], v[140:143], v[20:23]
	v_mfma_f32_16x16x32_bf16 v[16:19], v[174:177], v[140:143], v[16:19]
	v_mfma_f32_16x16x32_bf16 v[4:7], v[156:159], v[148:151], v[4:7]
	v_mfma_f32_16x16x32_bf16 v[0:3], v[174:177], v[148:151], v[0:3]
	s_add_i32 s46, s46, 2
	s_add_u32 s44, s44, 0x100
	s_addc_u32 s45, s45, 0
	s_cmp_gt_u32 s46, 5
	s_mov_b64 s[18:19], s[4:5]
	s_barrier
	s_cbranch_scc0 .LBB0_671
	s_setprio 0
	v_lshl_add_u32 v234, s1, 8, v252
	v_or_b32_e32 v238, 32, v234
	v_ashrrev_i32_e32 v239, 31, v238
	v_or_b32_e32 v236, 48, v234
	v_ashrrev_i32_e32 v235, 31, v234
	v_lshl_add_u64 v[76:77], v[238:239], 4, s[68:69]
	v_ashrrev_i32_e32 v237, 31, v236
	v_lshl_add_u64 v[72:73], v[234:235], 4, s[68:69]
	v_lshl_add_u64 v[78:79], v[236:237], 4, s[68:69]
	global_load_dwordx4 v[210:213], v[76:77], off
	global_load_dwordx4 v[206:209], v[78:79], off
	global_load_dwordx4 v[216:219], v[72:73], off
	global_load_dwordx4 v[178:181], v[72:73], off offset:2048
	global_load_dwordx4 v[144:147], v[72:73], off offset:2304
	global_load_dwordx4 v[110:113], v[72:73], off offset:2560
	v_or_b32_e32 v240, 16, v234
	v_ashrrev_i32_e32 v241, 31, v240
	v_lshl_add_u64 v[74:75], v[240:241], 4, s[68:69]
	global_load_dwordx4 v[212:215], v[74:75], off
	s_nop 0
	global_load_dwordx4 v[72:75], v[72:73], off offset:2816
	s_waitcnt vmcnt(0)
	v_lshl_or_b32 v180, s16, 8, v254
	v_mul_hi_i32 v73, v180, s71
	v_lshrrev_b32_e32 v74, 31, v73
	v_lshrrev_b32_e32 v73, 5, v73
	v_add_u32_e32 v73, v73, v74
	v_mul_lo_u32 v73, v73, s59
	v_sub_u32_e32 v96, v180, v73
	v_lshlrev_b64 v[74:75], 8, v[234:235]
	v_cmp_lt_i32_e64 s[4:5], s67, v96
	v_lshl_add_u64 v[74:75], s[8:9], 0, v[74:75]
	s_and_saveexec_b64 s[16:17], s[4:5]
	s_cbranch_execz .LBB0_674
	v_lshl_add_u64 v[76:77], v[96:97], 2, v[74:75]
	global_load_dwordx4 v[170:173], v[76:77], off offset:-496
	global_load_dwordx4 v[174:177], v[76:77], off offset:-512

; #define PG8_STAGE(bufoff, gbase, voff) do { _Pragma("unroll") for (int _i = 0; _i < 2; ++_i) \
;     __builtin_amdgcn_global_load_lds((const unsigned*)((const char*)(gbase) + (voff)[_i]), (LAS unsigned*)(lds + (bufoff) + ldsw + _i * 8192), 16, 0, 0); } while (0)
; #define PG8_LDA(dst, b, h) do { _Pragma("unroll") for (int m = 0; m < 4; ++m) _Pragma("unroll") for (int k = 0; k < 2; ++k) dst[m][k] = *(const LAS bf16x8*)(lds + PG8_SA(b, h) + aoff + m * 2048 + k * 1024); } while (0)
; #define PG8_LDB(dst, b, h) do { _Pragma("unroll") for (int n = 0; n < 2; ++n) _Pragma("unroll") for (int k = 0; k < 2; ++k) dst[n][k] = *(const LAS bf16x8*)(lds + PG8_SB(b, h) + boff + n * 2048 + k * 1024); } while (0)
; #define PG8_MMA(ai, bj, At, Bt) do { __builtin_amdgcn_s_setprio(1); _Pragma("unroll") for (int m = 0; m < 4; ++m) _Pragma("unroll") for (int n = 0; n < 2; ++n) _Pragma("unroll") for (int k = 0; k < 2; ++k) \
;     acc[ai][bj][m][n] = __builtin_amdgcn_mfma_f32_16x16x32_bf16(Bt[n][k], At[m][k], acc[ai][bj][m][n], 0, 0, 0); __builtin_amdgcn_s_setprio(0); } while (0)
; #define PG8_WAIT_L(n) asm volatile("s_waitcnt lgkmcnt(" #n ")" ::: "memory")
; #define PG8_BAR __builtin_amdgcn_s_barrier()
; template <class Epi>
; __device__ __forceinline__ void gemm_phase(LAS unsigned char* lds, const Gemm g, const StaticOrder& S, const Epi& E, int wv0) {
;     ...
;     const bool has_next = S.next(ui + 1, nxt);
;     const char* nA = has_next ? (const char*)g.A + (size_t)nxt.pm * tstepA : cA; const char* nB = has_next ? (const char*)g.Bt + (size_t)nxt.pn * tstepB : cB;
;     for (int t = 0; t < nt; t += 2) {
;       const bool last = (t == nt - 2);
;       const char* a1 = cA + (size_t)(t + 1) * kstep;
;       const char* a2 = last ? nA : cA + (size_t)(t + 2) * kstep; const char* b2 = last ? nB : cB + (size_t)(t + 2) * kstep;
;       const char* a3 = a2 + kstep; const char* b3 = b2 + kstep;
;       PG8_LDB(B0, 0, 0); PG8_SCHED; PG8_LDA(At, 0, 0); PG8_STAGE(PG8_SA(1, 1), a1 + hstepA, voffA);
;       PG8_WAIT_L(8); PG8_BAR; PG8_WAIT_L(0); PG8_MMA(0, 0, At, B0); PG8_BAR; PG8_SCHED;
;     ...
; #pragma unroll
;     for (int a = 0; a < 2; ++a)
; #pragma unroll
;       for (int b = 0; b < 2; ++b)
; #pragma unroll
;         for (int m = 0; m < 4; ++m)
; #pragma unroll
;           for (int n = 0; n < 2; ++n) acc[a][b][m][n] = (f32x4){0.f, 0.f, 0.f, 0.f};
.LBB0_755:
	s_ashr_i32 s9, s8, 31
	s_lshl_b64 s[12:13], s[8:9], 18
	s_add_u32 s12, s26, s12
	s_addc_u32 s13, s27, s13
	s_and_b64 s[4:5], s[4:5], exec
	s_cselect_b32 s9, s13, s17
	s_cselect_b32 s41, s12, s16
	s_add_u32 s42, s16, 0x100
	v_mov_b32_e32 v0, 0
	s_addc_u32 s43, s17, 0
	s_mov_b32 s44, -2
	v_mov_b32_e32 v1, v0
	v_mov_b32_e32 v2, v0
	v_mov_b32_e32 v3, v0
	v_mov_b32_e32 v4, v0
	v_mov_b32_e32 v5, v0
	v_mov_b32_e32 v6, v0
	v_mov_b32_e32 v7, v0
	v_mov_b32_e32 v8, v0
	v_mov_b32_e32 v9, v0
	v_mov_b32_e32 v10, v0
	v_mov_b32_e32 v11, v0
	v_mov_b32_e32 v16, v0
	v_mov_b32_e32 v17, v0
	v_mov_b32_e32 v18, v0
	v_mov_b32_e32 v19, v0
	v_mov_b32_e32 v24, v0
	v_mov_b32_e32 v25, v0
	v_mov_b32_e32 v26, v0
	v_mov_b32_e32 v27, v0
	v_mov_b32_e32 v32, v0
	v_mov_b32_e32 v33, v0
	v_mov_b32_e32 v34, v0
	v_mov_b32_e32 v35, v0
	v_mov_b32_e32 v40, v0
	v_mov_b32_e32 v41, v0
	v_mov_b32_e32 v42, v0
	v_mov_b32_e32 v43, v0
	v_mov_b32_e32 v48, v0
	v_mov_b32_e32 v49, v0
	v_mov_b32_e32 v50, v0
	v_mov_b32_e32 v51, v0
	v_mov_b32_e32 v12, v0
	v_mov_b32_e32 v13, v0
	v_mov_b32_e32 v14, v0
	v_mov_b32_e32 v15, v0
	v_mov_b32_e32 v20, v0
	v_mov_b32_e32 v21, v0
	v_mov_b32_e32 v22, v0
	v_mov_b32_e32 v23, v0
	v_mov_b32_e32 v28, v0
	v_mov_b32_e32 v29, v0
	v_mov_b32_e32 v30, v0
	v_mov_b32_e32 v31, v0
	v_mov_b32_e32 v36, v0
	v_mov_b32_e32 v37, v0
	v_mov_b32_e32 v38, v0
	v_mov_b32_e32 v39, v0
	v_mov_b32_e32 v44, v0
	v_mov_b32_e32 v45, v0
	v_mov_b32_e32 v46, v0
	v_mov_b32_e32 v47, v0
	v_mov_b32_e32 v52, v0
	v_mov_b32_e32 v53, v0
	v_mov_b32_e32 v54, v0
	v_mov_b32_e32 v55, v0
	v_mov_b32_e32 v56, v0
	v_mov_b32_e32 v57, v0
	v_mov_b32_e32 v58, v0
	v_mov_b32_e32 v59, v0
	v_mov_b32_e32 v60, v0
	v_mov_b32_e32 v61, v0
	v_mov_b32_e32 v62, v0
	v_mov_b32_e32 v63, v0
	v_mov_b32_e32 v64, v0
	v_mov_b32_e32 v65, v0
	v_mov_b32_e32 v66, v0
	v_mov_b32_e32 v67, v0
	v_mov_b32_e32 v68, v0
	v_mov_b32_e32 v69, v0
	v_mov_b32_e32 v70, v0
	v_mov_b32_e32 v71, v0
	v_mov_b32_e32 v80, v0
	v_mov_b32_e32 v81, v0
	v_mov_b32_e32 v82, v0
	v_mov_b32_e32 v83, v0
	v_mov_b32_e32 v84, v0
	v_mov_b32_e32 v85, v0
	v_mov_b32_e32 v86, v0
	v_mov_b32_e32 v87, v0
	v_mov_b32_e32 v88, v0
	v_mov_b32_e32 v89, v0
	v_mov_b32_e32 v90, v0
	v_mov_b32_e32 v91, v0
	v_mov_b32_e32 v92, v0
	v_mov_b32_e32 v93, v0
	v_mov_b32_e32 v94, v0
	v_mov_b32_e32 v95, v0
	v_mov_b32_e32 v102, v0
	v_mov_b32_e32 v103, v0
	v_mov_b32_e32 v104, v0
	v_mov_b32_e32 v105, v0
	v_mov_b32_e32 v110, v0
	v_mov_b32_e32 v111, v0
	v_mov_b32_e32 v112, v0
	v_mov_b32_e32 v113, v0
	v_mov_b32_e32 v72, v0
	v_mov_b32_e32 v73, v0
	v_mov_b32_e32 v74, v0
	v_mov_b32_e32 v75, v0
	v_mov_b32_e32 v76, v0
	v_mov_b32_e32 v77, v0
	v_mov_b32_e32 v78, v0
	v_mov_b32_e32 v79, v0
	v_mov_b32_e32 v98, v0
	v_mov_b32_e32 v99, v0
	v_mov_b32_e32 v100, v0
	v_mov_b32_e32 v101, v0
	v_mov_b32_e32 v106, v0
	v_mov_b32_e32 v107, v0
	v_mov_b32_e32 v108, v0
	v_mov_b32_e32 v109, v0
	v_mov_b32_e32 v114, v0
	v_mov_b32_e32 v115, v0
	v_mov_b32_e32 v116, v0
	v_mov_b32_e32 v117, v0
	v_mov_b32_e32 v118, v0
	v_mov_b32_e32 v119, v0
	v_mov_b32_e32 v120, v0
	v_mov_b32_e32 v121, v0
	v_mov_b32_e32 v122, v0
	v_mov_b32_e32 v123, v0
	v_mov_b32_e32 v124, v0
	v_mov_b32_e32 v125, v0
	v_mov_b32_e32 v126, v0
	v_mov_b32_e32 v127, v0
	v_mov_b32_e32 v128, v0
	v_mov_b32_e32 v129, v0
	s_cmp_lt_u32 s53, 4
	s_cbranch_scc1 .Lgprio2
	s_setprio 1
.Lgprio2:
.LBB0_756:
	s_add_u32 s4, s14, 0x100
	s_addc_u32 s5, s15, 0
	s_add_i32 s0, 0, 0x10000
	v_add_u32_e32 v156, s0, v149
	ds_read_b128 v[140:143], v156
	ds_read_b128 v[144:147], v156 offset:1024
	ds_read_b128 v[152:155], v156 offset:2048
	ds_read_b128 v[156:159], v156 offset:3072
	s_cmp_eq_u32 s44, 4
	s_cselect_b32 s19, s11, s5
	s_cselect_b32 s18, s10, s4
	s_cselect_b32 s17, s9, s43
	s_cselect_b32 s16, s41, s42
	v_lshl_add_u64 v[192:193], s[14:15], 0, v[136:137]
	s_add_i32 m0, s29, 0xc000
	ds_read_b128 v[160:163], v151
	ds_read_b128 v[164:167], v151 offset:1024
	ds_read_b128 v[168:171], v151 offset:2048
	ds_read_b128 v[172:175], v151 offset:3072
	ds_read_b128 v[176:179], v151 offset:4096
	ds_read_b128 v[180:183], v151 offset:5120
	ds_read_b128 v[184:187], v151 offset:6144
	ds_read_b128 v[188:191], v151 offset:7168
	global_load_lds_dwordx4 v[192:193], off
	v_lshl_add_u64 v[192:193], s[14:15], 0, v[138:139]
	s_add_i32 m0, s29, 0xe000
	s_nop 0
	global_load_lds_dwordx4 v[192:193], off
	s_waitcnt lgkmcnt(8)
	s_barrier
	s_waitcnt lgkmcnt(0)
	s_waitcnt lgkmcnt(0)
	v_mfma_f32_16x16x32_bf16 v[126:129], v[140:143], v[160:163], v[126:129]
	v_mfma_f32_16x16x32_bf16 v[122:125], v[152:155], v[160:163], v[122:125]
	v_mfma_f32_16x16x32_bf16 v[118:121], v[140:143], v[168:171], v[118:121]
	v_mfma_f32_16x16x32_bf16 v[114:117], v[152:155], v[168:171], v[114:117]
	v_mfma_f32_16x16x32_bf16 v[106:109], v[140:143], v[176:179], v[106:109]
	v_mfma_f32_16x16x32_bf16 v[98:101], v[152:155], v[176:179], v[98:101]
	v_mfma_f32_16x16x32_bf16 v[76:79], v[140:143], v[184:187], v[76:79]
	v_mfma_f32_16x16x32_bf16 v[72:75], v[152:155], v[184:187], v[72:75]
	v_mfma_f32_16x16x32_bf16 v[126:129], v[144:147], v[164:167], v[126:129]
	v_mfma_f32_16x16x32_bf16 v[122:125], v[156:159], v[164:167], v[122:125]
	v_mfma_f32_16x16x32_bf16 v[118:121], v[144:147], v[172:175], v[118:121]
	v_mfma_f32_16x16x32_bf16 v[114:117], v[156:159], v[172:175], v[114:117]
	v_mfma_f32_16x16x32_bf16 v[106:109], v[144:147], v[180:183], v[106:109]
	v_mfma_f32_16x16x32_bf16 v[98:101], v[156:159], v[180:183], v[98:101]
	v_mfma_f32_16x16x32_bf16 v[76:79], v[144:147], v[188:191], v[76:79]
	v_mfma_f32_16x16x32_bf16 v[72:75], v[156:159], v[188:191], v[72:75]
	s_barrier
; #define PG8_STAGE(bufoff, gbase, voff) do { _Pragma("unroll") for (int _i = 0; _i < 2; ++_i) \
;     __builtin_amdgcn_global_load_lds((const unsigned*)((const char*)(gbase) + (voff)[_i]), (LAS unsigned*)(lds + (bufoff) + ldsw + _i * 8192), 16, 0, 0); } while (0)
; #define PG8_LDA(dst, b, h) do { _Pragma("unroll") for (int m = 0; m < 4; ++m) _Pragma("unroll") for (int k = 0; k < 2; ++k) dst[m][k] = *(const LAS bf16x8*)(lds + PG8_SA(b, h) + aoff + m * 2048 + k * 1024); } while (0)
; #define PG8_LDB(dst, b, h) do { _Pragma("unroll") for (int n = 0; n < 2; ++n) _Pragma("unroll") for (int k = 0; k < 2; ++k) dst[n][k] = *(const LAS bf16x8*)(lds + PG8_SB(b, h) + boff + n * 2048 + k * 1024); } while (0)
; #define PG8_MMA(ai, bj, At, Bt) do { __builtin_amdgcn_s_setprio(1); _Pragma("unroll") for (int m = 0; m < 4; ++m) _Pragma("unroll") for (int n = 0; n < 2; ++n) _Pragma("unroll") for (int k = 0; k < 2; ++k) \
;     acc[ai][bj][m][n] = __builtin_amdgcn_mfma_f32_16x16x32_bf16(Bt[n][k], At[m][k], acc[ai][bj][m][n], 0, 0, 0); __builtin_amdgcn_s_setprio(0); } while (0)
; #define PG8_WAIT_V(n) asm volatile("s_waitcnt vmcnt(" #n ")" ::: "memory")
; #define PG8_WAIT_L(n) asm volatile("s_waitcnt lgkmcnt(" #n ")" ::: "memory")
; #define PG8_BAR __builtin_amdgcn_s_barrier()
; #define PG8_SCHED __builtin_amdgcn_sched_barrier(0)
; template <class Epi>
; __device__ __forceinline__ void gemm_phase(LAS unsigned char* lds, const Gemm g, const StaticOrder& S, const Epi& E, int wv0) {
;     ...
;       PG8_LDB(B1, 0, 1); PG8_STAGE(PG8_SB(0, 0), b2, voffB);
;       PG8_BAR; PG8_WAIT_L(0); PG8_MMA(0, 1, At, B1); PG8_BAR;
;       PG8_LDA(At, 0, 1); PG8_STAGE(PG8_SA(0, 0), a2, voffA);
;       PG8_BAR; PG8_WAIT_L(0); PG8_MMA(1, 0, At, B0); PG8_BAR; PG8_SCHED;
;       PG8_STAGE(PG8_SB(0, 1), b2 + hstepB, voffB);
;       PG8_WAIT_V(6); PG8_BAR; PG8_MMA(1, 1, At, B1); PG8_BAR;
;       PG8_LDB(B0, 1, 0); PG8_SCHED; PG8_LDA(At, 1, 0); PG8_STAGE(PG8_SA(0, 1), a2 + hstepA, voffA);
;       PG8_WAIT_L(8); PG8_BAR; PG8_WAIT_L(0); PG8_MMA(0, 0, At, B0); PG8_BAR; PG8_SCHED;
	s_add_i32 s45, 0, 0x14000
	s_add_i32 s0, s0, s28
	v_add_u32_e32 v204, s45, v149
	v_lshl_add_u64 v[208:209], s[16:17], 0, v[96:97]
	s_mov_b32 m0, s0
	ds_read_b128 v[192:195], v204
	ds_read_b128 v[196:199], v204 offset:1024
	ds_read_b128 v[200:203], v204 offset:2048
	ds_read_b128 v[204:207], v204 offset:3072
	global_load_lds_dwordx4 v[208:209], off
	v_lshl_add_u64 v[210:211], s[16:17], 0, v[134:135]
	s_add_i32 m0, s0, 0x2000
	s_nop 0
	global_load_lds_dwordx4 v[210:211], off
	s_barrier
	s_waitcnt lgkmcnt(0)
	s_waitcnt lgkmcnt(0)
	v_mfma_f32_16x16x32_bf16 v[110:113], v[192:195], v[160:163], v[110:113]
	v_mfma_f32_16x16x32_bf16 v[102:105], v[200:203], v[160:163], v[102:105]
	v_mfma_f32_16x16x32_bf16 v[92:95], v[192:195], v[168:171], v[92:95]
	v_mfma_f32_16x16x32_bf16 v[88:91], v[200:203], v[168:171], v[88:91]
	v_mfma_f32_16x16x32_bf16 v[84:87], v[192:195], v[176:179], v[84:87]
	v_mfma_f32_16x16x32_bf16 v[80:83], v[200:203], v[176:179], v[80:83]
	v_mfma_f32_16x16x32_bf16 v[68:71], v[192:195], v[184:187], v[68:71]
	v_mfma_f32_16x16x32_bf16 v[64:67], v[200:203], v[184:187], v[64:67]
	v_mfma_f32_16x16x32_bf16 v[110:113], v[196:199], v[164:167], v[110:113]
	v_mfma_f32_16x16x32_bf16 v[102:105], v[204:207], v[164:167], v[102:105]
	v_mfma_f32_16x16x32_bf16 v[92:95], v[196:199], v[172:175], v[92:95]
	v_mfma_f32_16x16x32_bf16 v[88:91], v[204:207], v[172:175], v[88:91]
	v_mfma_f32_16x16x32_bf16 v[84:87], v[196:199], v[180:183], v[84:87]
	v_mfma_f32_16x16x32_bf16 v[80:83], v[204:207], v[180:183], v[80:83]
	v_mfma_f32_16x16x32_bf16 v[68:71], v[196:199], v[188:191], v[68:71]
	v_mfma_f32_16x16x32_bf16 v[64:67], v[204:207], v[188:191], v[64:67]
	s_mov_b32 m0, s29
	v_lshl_add_u64 v[212:213], s[18:19], 0, v[130:131]
	s_barrier
	ds_read_b128 v[160:163], v151 offset:16384
	ds_read_b128 v[164:167], v151 offset:17408
	ds_read_b128 v[168:171], v151 offset:18432
	ds_read_b128 v[172:175], v151 offset:19456
	ds_read_b128 v[176:179], v151 offset:20480
	ds_read_b128 v[180:183], v151 offset:21504
	ds_read_b128 v[184:187], v151 offset:22528
	ds_read_b128 v[188:191], v151 offset:23552
	global_load_lds_dwordx4 v[212:213], off
	v_lshl_add_u64 v[214:215], s[18:19], 0, v[132:133]
	s_mov_b32 m0, s30
	s_nop 0
	global_load_lds_dwordx4 v[214:215], off
	s_barrier
	s_waitcnt lgkmcnt(0)
	s_waitcnt lgkmcnt(0)
	v_mfma_f32_16x16x32_bf16 v[60:63], v[140:143], v[160:163], v[60:63]
	v_mfma_f32_16x16x32_bf16 v[56:59], v[152:155], v[160:163], v[56:59]
	v_mfma_f32_16x16x32_bf16 v[52:55], v[140:143], v[168:171], v[52:55]
	v_mfma_f32_16x16x32_bf16 v[44:47], v[152:155], v[168:171], v[44:47]
	v_mfma_f32_16x16x32_bf16 v[36:39], v[140:143], v[176:179], v[36:39]
	v_mfma_f32_16x16x32_bf16 v[28:31], v[152:155], v[176:179], v[28:31]
	v_mfma_f32_16x16x32_bf16 v[20:23], v[140:143], v[184:187], v[20:23]
	v_mfma_f32_16x16x32_bf16 v[12:15], v[152:155], v[184:187], v[12:15]
	v_mfma_f32_16x16x32_bf16 v[60:63], v[144:147], v[164:167], v[60:63]
	v_mfma_f32_16x16x32_bf16 v[56:59], v[156:159], v[164:167], v[56:59]
	v_mfma_f32_16x16x32_bf16 v[52:55], v[144:147], v[172:175], v[52:55]
	v_mfma_f32_16x16x32_bf16 v[44:47], v[156:159], v[172:175], v[44:47]
	v_mfma_f32_16x16x32_bf16 v[36:39], v[144:147], v[180:183], v[36:39]
	v_mfma_f32_16x16x32_bf16 v[28:31], v[156:159], v[180:183], v[28:31]
	v_mfma_f32_16x16x32_bf16 v[20:23], v[144:147], v[188:191], v[20:23]
	v_mfma_f32_16x16x32_bf16 v[12:15], v[156:159], v[188:191], v[12:15]
	s_barrier
	s_add_u32 s14, s16, 0x20000
	s_addc_u32 s15, s17, 0
	s_add_i32 s0, s45, s28
	v_lshl_add_u64 v[140:141], s[14:15], 0, v[96:97]
	s_mov_b32 m0, s0
	s_nop 0
	global_load_lds_dwordx4 v[140:141], off
	v_lshl_add_u64 v[140:141], s[14:15], 0, v[134:135]
	s_add_i32 m0, s0, 0x2000
	s_nop 0
	global_load_lds_dwordx4 v[140:141], off
	s_waitcnt vmcnt(6)
	s_barrier
	v_mfma_f32_16x16x32_bf16 v[48:51], v[192:195], v[160:163], v[48:51]
	v_mfma_f32_16x16x32_bf16 v[40:43], v[200:203], v[160:163], v[40:43]
	v_mfma_f32_16x16x32_bf16 v[32:35], v[192:195], v[168:171], v[32:35]
	v_mfma_f32_16x16x32_bf16 v[24:27], v[200:203], v[168:171], v[24:27]
	v_mfma_f32_16x16x32_bf16 v[16:19], v[192:195], v[176:179], v[16:19]
	v_mfma_f32_16x16x32_bf16 v[8:11], v[200:203], v[176:179], v[8:11]
	v_mfma_f32_16x16x32_bf16 v[4:7], v[192:195], v[184:187], v[4:7]
	v_mfma_f32_16x16x32_bf16 v[0:3], v[200:203], v[184:187], v[0:3]
	v_mfma_f32_16x16x32_bf16 v[48:51], v[196:199], v[164:167], v[48:51]
	v_mfma_f32_16x16x32_bf16 v[40:43], v[204:207], v[164:167], v[40:43]
	v_mfma_f32_16x16x32_bf16 v[32:35], v[196:199], v[172:175], v[32:35]
	v_mfma_f32_16x16x32_bf16 v[24:27], v[204:207], v[172:175], v[24:27]
	v_mfma_f32_16x16x32_bf16 v[16:19], v[196:199], v[180:183], v[16:19]
	v_mfma_f32_16x16x32_bf16 v[8:11], v[204:207], v[180:183], v[8:11]
	v_mfma_f32_16x16x32_bf16 v[4:7], v[196:199], v[188:191], v[4:7]
	v_mfma_f32_16x16x32_bf16 v[0:3], v[204:207], v[188:191], v[0:3]
	s_add_i32 s0, 0, 0x18000
	v_add_u32_e32 v156, s0, v149
	s_barrier
	ds_read_b128 v[140:143], v156
	ds_read_b128 v[144:147], v156 offset:1024
	ds_read_b128 v[152:155], v156 offset:2048
	ds_read_b128 v[156:159], v156 offset:3072
	s_add_u32 s14, s18, 0x114000
	s_addc_u32 s15, s19, 0
	s_mov_b32 m0, s31
	v_lshl_add_u64 v[192:193], s[14:15], 0, v[130:131]
	ds_read_b128 v[160:163], v151 offset:32768
	ds_read_b128 v[164:167], v151 offset:33792
	ds_read_b128 v[168:171], v151 offset:34816
	ds_read_b128 v[172:175], v151 offset:35840
	ds_read_b128 v[176:179], v151 offset:36864
	ds_read_b128 v[180:183], v151 offset:37888
	ds_read_b128 v[184:187], v151 offset:38912
	ds_read_b128 v[188:191], v151 offset:39936
	global_load_lds_dwordx4 v[192:193], off
	v_lshl_add_u64 v[192:193], s[14:15], 0, v[132:133]
	s_mov_b32 m0, s34
	s_nop 0
	global_load_lds_dwordx4 v[192:193], off
	s_waitcnt lgkmcnt(8)
	s_barrier
; #define PG8_STAGE(bufoff, gbase, voff) do { _Pragma("unroll") for (int _i = 0; _i < 2; ++_i) \
;     __builtin_amdgcn_global_load_lds((const unsigned*)((const char*)(gbase) + (voff)[_i]), (LAS unsigned*)(lds + (bufoff) + ldsw + _i * 8192), 16, 0, 0); } while (0)
; #define PG8_LDA(dst, b, h) do { _Pragma("unroll") for (int m = 0; m < 4; ++m) _Pragma("unroll") for (int k = 0; k < 2; ++k) dst[m][k] = *(const LAS bf16x8*)(lds + PG8_SA(b, h) + aoff + m * 2048 + k * 1024); } while (0)
; #define PG8_LDB(dst, b, h) do { _Pragma("unroll") for (int n = 0; n < 2; ++n) _Pragma("unroll") for (int k = 0; k < 2; ++k) dst[n][k] = *(const LAS bf16x8*)(lds + PG8_SB(b, h) + boff + n * 2048 + k * 1024); } while (0)
; #define PG8_MMA(ai, bj, At, Bt) do { __builtin_amdgcn_s_setprio(1); _Pragma("unroll") for (int m = 0; m < 4; ++m) _Pragma("unroll") for (int n = 0; n < 2; ++n) _Pragma("unroll") for (int k = 0; k < 2; ++k) \
;     acc[ai][bj][m][n] = __builtin_amdgcn_mfma_f32_16x16x32_bf16(Bt[n][k], At[m][k], acc[ai][bj][m][n], 0, 0, 0); __builtin_amdgcn_s_setprio(0); } while (0)
; #define PG8_WAIT_V(n) asm volatile("s_waitcnt vmcnt(" #n ")" ::: "memory")
; #define PG8_WAIT_L(n) asm volatile("s_waitcnt lgkmcnt(" #n ")" ::: "memory")
; #define PG8_BAR __builtin_amdgcn_s_barrier()
; #define PG8_SCHED __builtin_amdgcn_sched_barrier(0)
; template <class Epi>
; __device__ __forceinline__ void gemm_phase(LAS unsigned char* lds, const Gemm g, const StaticOrder& S, const Epi& E, int wv0) {
;     ...
;       PG8_WAIT_L(8); PG8_BAR; PG8_WAIT_L(0); PG8_MMA(0, 0, At, B0); PG8_BAR; PG8_SCHED;
;       PG8_LDB(B1, 1, 1); PG8_STAGE(PG8_SB(1, 0), b3, voffB);
;       PG8_BAR; PG8_WAIT_L(0); PG8_MMA(0, 1, At, B1); PG8_BAR;
;       PG8_LDA(At, 1, 1); PG8_STAGE(PG8_SA(1, 0), a3, voffA);
;       PG8_BAR; PG8_WAIT_L(0); PG8_MMA(1, 0, At, B0); PG8_BAR; PG8_SCHED;
;       PG8_STAGE(PG8_SB(1, 1), b3 + hstepB, voffB);
;       PG8_WAIT_V(6); PG8_BAR; PG8_MMA(1, 1, At, B1); PG8_BAR;
	s_waitcnt lgkmcnt(0)
	s_waitcnt lgkmcnt(0)
	v_mfma_f32_16x16x32_bf16 v[126:129], v[140:143], v[160:163], v[126:129]
	v_mfma_f32_16x16x32_bf16 v[122:125], v[152:155], v[160:163], v[122:125]
	v_mfma_f32_16x16x32_bf16 v[118:121], v[140:143], v[168:171], v[118:121]
	v_mfma_f32_16x16x32_bf16 v[114:117], v[152:155], v[168:171], v[114:117]
	v_mfma_f32_16x16x32_bf16 v[106:109], v[140:143], v[176:179], v[106:109]
	v_mfma_f32_16x16x32_bf16 v[98:101], v[152:155], v[176:179], v[98:101]
	v_mfma_f32_16x16x32_bf16 v[76:79], v[140:143], v[184:187], v[76:79]
	v_mfma_f32_16x16x32_bf16 v[72:75], v[152:155], v[184:187], v[72:75]
	v_mfma_f32_16x16x32_bf16 v[126:129], v[144:147], v[164:167], v[126:129]
	v_mfma_f32_16x16x32_bf16 v[122:125], v[156:159], v[164:167], v[122:125]
	v_mfma_f32_16x16x32_bf16 v[118:121], v[144:147], v[172:175], v[118:121]
	v_mfma_f32_16x16x32_bf16 v[114:117], v[156:159], v[172:175], v[114:117]
	v_mfma_f32_16x16x32_bf16 v[106:109], v[144:147], v[180:183], v[106:109]
	v_mfma_f32_16x16x32_bf16 v[98:101], v[156:159], v[180:183], v[98:101]
	v_mfma_f32_16x16x32_bf16 v[76:79], v[144:147], v[188:191], v[76:79]
	v_mfma_f32_16x16x32_bf16 v[72:75], v[156:159], v[188:191], v[72:75]
	s_barrier
	s_add_i32 s18, 0, 0x1c000
	s_add_i32 s0, s0, s28
	v_add_u32_e32 v204, s18, v149
	v_lshl_add_u64 v[208:209], v[208:209], 0, s[72:73]
	s_mov_b32 m0, s0
	ds_read_b128 v[192:195], v204
	ds_read_b128 v[196:199], v204 offset:1024
	ds_read_b128 v[200:203], v204 offset:2048
	ds_read_b128 v[204:207], v204 offset:3072
	global_load_lds_dwordx4 v[208:209], off
	v_lshl_add_u64 v[208:209], v[210:211], 0, s[72:73]
	s_add_i32 m0, s0, 0x2000
	s_nop 0
	global_load_lds_dwordx4 v[208:209], off
	s_barrier
	s_waitcnt lgkmcnt(0)
	s_waitcnt lgkmcnt(0)
	v_mfma_f32_16x16x32_bf16 v[110:113], v[192:195], v[160:163], v[110:113]
	v_mfma_f32_16x16x32_bf16 v[102:105], v[200:203], v[160:163], v[102:105]
	v_mfma_f32_16x16x32_bf16 v[92:95], v[192:195], v[168:171], v[92:95]
	v_mfma_f32_16x16x32_bf16 v[88:91], v[200:203], v[168:171], v[88:91]
	v_mfma_f32_16x16x32_bf16 v[84:87], v[192:195], v[176:179], v[84:87]
	v_mfma_f32_16x16x32_bf16 v[80:83], v[200:203], v[176:179], v[80:83]
	v_mfma_f32_16x16x32_bf16 v[68:71], v[192:195], v[184:187], v[68:71]
	v_mfma_f32_16x16x32_bf16 v[64:67], v[200:203], v[184:187], v[64:67]
	v_mfma_f32_16x16x32_bf16 v[110:113], v[196:199], v[164:167], v[110:113]
	v_mfma_f32_16x16x32_bf16 v[102:105], v[204:207], v[164:167], v[102:105]
	v_mfma_f32_16x16x32_bf16 v[92:95], v[196:199], v[172:175], v[92:95]
	v_mfma_f32_16x16x32_bf16 v[88:91], v[204:207], v[172:175], v[88:91]
	v_mfma_f32_16x16x32_bf16 v[84:87], v[196:199], v[180:183], v[84:87]
	v_mfma_f32_16x16x32_bf16 v[80:83], v[204:207], v[180:183], v[80:83]
	v_mfma_f32_16x16x32_bf16 v[68:71], v[196:199], v[188:191], v[68:71]
	v_mfma_f32_16x16x32_bf16 v[64:67], v[204:207], v[188:191], v[64:67]
	s_mov_b32 m0, s35
	v_lshl_add_u64 v[208:209], v[212:213], 0, s[72:73]
	s_barrier
	ds_read_b128 v[160:163], v151 offset:49152
	ds_read_b128 v[164:167], v151 offset:50176
	ds_read_b128 v[168:171], v151 offset:51200
	ds_read_b128 v[172:175], v151 offset:52224
	ds_read_b128 v[176:179], v151 offset:53248
	ds_read_b128 v[180:183], v151 offset:54272
	ds_read_b128 v[184:187], v151 offset:55296
	ds_read_b128 v[188:191], v151 offset:56320
	global_load_lds_dwordx4 v[208:209], off
	v_lshl_add_u64 v[208:209], v[214:215], 0, s[72:73]
	s_mov_b32 m0, s36
	s_nop 0
	global_load_lds_dwordx4 v[208:209], off
	s_barrier
	s_waitcnt lgkmcnt(0)
	s_waitcnt lgkmcnt(0)
	v_mfma_f32_16x16x32_bf16 v[60:63], v[140:143], v[160:163], v[60:63]
	v_mfma_f32_16x16x32_bf16 v[56:59], v[152:155], v[160:163], v[56:59]
	v_mfma_f32_16x16x32_bf16 v[52:55], v[140:143], v[168:171], v[52:55]
	v_mfma_f32_16x16x32_bf16 v[44:47], v[152:155], v[168:171], v[44:47]
	v_mfma_f32_16x16x32_bf16 v[36:39], v[140:143], v[176:179], v[36:39]
	v_mfma_f32_16x16x32_bf16 v[28:31], v[152:155], v[176:179], v[28:31]
	v_mfma_f32_16x16x32_bf16 v[20:23], v[140:143], v[184:187], v[20:23]
	v_mfma_f32_16x16x32_bf16 v[12:15], v[152:155], v[184:187], v[12:15]
	v_mfma_f32_16x16x32_bf16 v[60:63], v[144:147], v[164:167], v[60:63]
	v_mfma_f32_16x16x32_bf16 v[56:59], v[156:159], v[164:167], v[56:59]
	v_mfma_f32_16x16x32_bf16 v[52:55], v[144:147], v[172:175], v[52:55]
	v_mfma_f32_16x16x32_bf16 v[44:47], v[156:159], v[172:175], v[44:47]
	v_mfma_f32_16x16x32_bf16 v[36:39], v[144:147], v[180:183], v[36:39]
	v_mfma_f32_16x16x32_bf16 v[28:31], v[156:159], v[180:183], v[28:31]
	v_mfma_f32_16x16x32_bf16 v[20:23], v[144:147], v[188:191], v[20:23]
	v_mfma_f32_16x16x32_bf16 v[12:15], v[156:159], v[188:191], v[12:15]
	s_barrier
	s_add_u32 s14, s16, 0x20080
	s_addc_u32 s15, s17, 0
	s_add_i32 s0, s18, s28
	v_lshl_add_u64 v[140:141], s[14:15], 0, v[96:97]
	s_mov_b32 m0, s0
	s_nop 0
	global_load_lds_dwordx4 v[140:141], off
	v_lshl_add_u64 v[140:141], s[14:15], 0, v[134:135]
	s_add_i32 m0, s0, 0x2000
	s_nop 0
	global_load_lds_dwordx4 v[140:141], off
	s_waitcnt vmcnt(6)
	s_barrier
	v_mfma_f32_16x16x32_bf16 v[48:51], v[192:195], v[160:163], v[48:51]
	v_mfma_f32_16x16x32_bf16 v[40:43], v[200:203], v[160:163], v[40:43]
	v_mfma_f32_16x16x32_bf16 v[32:35], v[192:195], v[168:171], v[32:35]
	v_mfma_f32_16x16x32_bf16 v[24:27], v[200:203], v[168:171], v[24:27]
	v_mfma_f32_16x16x32_bf16 v[16:19], v[192:195], v[176:179], v[16:19]
	v_mfma_f32_16x16x32_bf16 v[8:11], v[200:203], v[176:179], v[8:11]
	v_mfma_f32_16x16x32_bf16 v[4:7], v[192:195], v[184:187], v[4:7]
	v_mfma_f32_16x16x32_bf16 v[0:3], v[200:203], v[184:187], v[0:3]
	v_mfma_f32_16x16x32_bf16 v[48:51], v[196:199], v[164:167], v[48:51]
	v_mfma_f32_16x16x32_bf16 v[40:43], v[204:207], v[164:167], v[40:43]
	v_mfma_f32_16x16x32_bf16 v[32:35], v[196:199], v[172:175], v[32:35]
	v_mfma_f32_16x16x32_bf16 v[24:27], v[204:207], v[172:175], v[24:27]
	v_mfma_f32_16x16x32_bf16 v[16:19], v[196:199], v[180:183], v[16:19]
	v_mfma_f32_16x16x32_bf16 v[8:11], v[204:207], v[180:183], v[8:11]
	v_mfma_f32_16x16x32_bf16 v[4:7], v[196:199], v[188:191], v[4:7]
	v_mfma_f32_16x16x32_bf16 v[0:3], v[204:207], v[188:191], v[0:3]
	s_add_i32 s44, s44, 2
	s_add_u32 s42, s42, 0x100
	s_addc_u32 s43, s43, 0
	s_cmp_gt_u32 s44, 5
	s_mov_b64 s[14:15], s[4:5]
	s_barrier
; template <class Epi>
; __device__ __forceinline__ void gemm_phase(LAS unsigned char* lds, const Gemm g, const StaticOrder& S, const Epi& E, int wv0) {
;     ...
;     E(acc, cur, wr, wc, fr, fq);
;   __device__ __forceinline__ void emit(const EpiPre& q0, int row, int col, f32x4 a, f32x4 b, const f32x4 (&hb)[2][2], const float (&hs)[2][4], int ai_, int m_, int bj_) const {
;     ...
;     } else if (MODE == E_UKV) {
; #pragma unroll
;       for (int j = 0; j < 8; ++j) v[j] *= q.s;
;       store8bf((bf16_t*)e.out + (size_t)row * NKV + col, v);
;   __device__ __forceinline__ void operator()(const f32x4 (&acc)[2][2][4][2], const pg8::Unit& u, int wr, int wc, int fr, int fq) const {
;     if (MODE == E_UPC) { epi_upc(e, acc, u, wr, wc, fr, fq); return; }
;     const int row0 = u.pm * 256 + wr * 64 + fr, col0 = u.pn * 256 + wc * 32 + 8 * fq;
;     f32x4 hb[2][2]; float hs[2][4];
; #pragma unroll
;     for (int bj = 0; bj < 2; ++bj) { hb[bj][0] = (f32x4){0.f, 0.f, 0.f, 0.f}; hb[bj][1] = hb[bj][0];
;       if (MODE == E_GATE) { hb[bj][0] = *(const f32x4*)(e.f0 + col0 + bj * 128) * (-LOG2E); hb[bj][1] = *(const f32x4*)(e.f0 + col0 + bj * 128 + 4) * (-LOG2E); } }
; #pragma unroll
;     for (int ai = 0; ai < 2; ++ai)
; #pragma unroll
;       for (int m = 0; m < 4; ++m) { hs[ai][m] = 0.f;
;         if (MODE == E_UQ) hs[ai][m] = ((const f32x4*)e.f0)[row0 + ai * 128 + m * 16].x * MLA_QSCALE;
;         if (MODE == E_UKV) hs[ai][m] = ((const f32x4*)e.f0)[row0 + ai * 128 + m * 16].y; }
;     EpiPre q[2][4];
; #pragma unroll
;     for (int i = 0; i < 4; ++i) preload(q[0][i], row0 + (i >> 1) * 16, col0 + (i & 1) * 128);
; #pragma unroll
;     for (int gi = 0; gi < 4; ++gi) {
;       const int ai = gi >> 1, mp = gi & 1;
;       if (gi + 1 < 4) { const int ai2 = (gi + 1) >> 1, mp2 = (gi + 1) & 1;
; #pragma unroll
;         for (int i = 0; i < 4; ++i) preload(q[(gi + 1) & 1][i], row0 + ai2 * 128 + (2 * mp2 + (i >> 1)) * 16, col0 + (i & 1) * 128); }
;       asm volatile("" ::: "memory");
; #pragma unroll
;       for (int i = 0; i < 4; ++i) { const int m = 2 * mp + (i >> 1), bj = i & 1; emit(q[gi & 1][i], row0 + ai * 128 + m * 16, col0 + bj * 128, acc[ai][bj][m][0], acc[ai][bj][m][1], hb, hs, ai, m, bj); }
	s_cbranch_scc0 .LBB0_756
	s_setprio 0
	v_lshl_add_u32 v140, s39, 8, v148
	v_or_b32_e32 v146, 16, v140
	v_ashrrev_i32_e32 v141, 31, v140
	v_ashrrev_i32_e32 v147, 31, v146
	v_or_b32_e32 v156, 32, v140
	v_lshl_add_u64 v[142:143], v[140:141], 4, s[68:69]
	v_lshl_add_u64 v[144:145], v[146:147], 4, s[68:69]
	v_ashrrev_i32_e32 v157, 31, v156
	v_or_b32_e32 v160, 48, v140
	global_load_dwordx2 v[152:153], v[142:143], off
	global_load_dwordx2 v[154:155], v[144:145], off
	v_lshl_add_u64 v[144:145], v[156:157], 4, s[68:69]
	v_ashrrev_i32_e32 v161, 31, v160
	global_load_dwordx2 v[158:159], v[144:145], off
	v_lshl_add_u64 v[144:145], v[160:161], 4, s[68:69]
	global_load_dwordx2 v[162:163], v[144:145], off
	v_lshl_or_b32 v144, s40, 8, v150
	v_ashrrev_i32_e32 v145, 31, v144
	v_lshlrev_b64 v[164:165], 13, v[140:141]
	v_lshlrev_b64 v[166:167], 1, v[144:145]
	global_load_dwordx2 v[168:169], v[142:143], off offset:2048
	global_load_dwordx2 v[144:145], v[142:143], off offset:2304
	global_load_dwordx2 v[140:141], v[142:143], off offset:2560
	v_lshl_add_u64 v[164:165], s[6:7], 0, v[164:165]
	global_load_dwordx2 v[142:143], v[142:143], off offset:2816
	v_lshlrev_b64 v[170:171], 13, v[146:147]
	v_lshl_add_u64 v[146:147], v[164:165], 0, v[166:167]
	v_lshl_add_u64 v[164:165], s[6:7], 0, v[170:171]
	v_lshl_add_u64 v[164:165], v[164:165], 0, v[166:167]
	v_lshlrev_b64 v[156:157], 13, v[156:157]
	v_lshl_add_u64 v[156:157], s[6:7], 0, v[156:157]
	v_lshl_add_u64 v[156:157], v[156:157], 0, v[166:167]
	s_mov_b64 s[4:5], 0x100000
	s_mov_b32 s0, 0x140000
	s_mov_b32 s40, s8
	s_mov_b32 s39, s1
	s_mov_b64 s[16:17], s[12:13]
	s_mov_b64 s[14:15], s[10:11]
	s_waitcnt vmcnt(0)
	v_pk_mul_f32 v[126:127], v[126:127], v[152:153] op_sel:[0,1]
	v_pk_mul_f32 v[128:129], v[128:129], v[152:153] op_sel:[0,1]
	v_pk_mul_f32 v[122:123], v[122:123], v[152:153] op_sel:[0,1]
	v_pk_mul_f32 v[124:125], v[124:125], v[152:153] op_sel:[0,1]
	v_pk_mul_f32 v[118:119], v[118:119], v[154:155] op_sel:[0,1]
	v_pk_mul_f32 v[120:121], v[120:121], v[154:155] op_sel:[0,1]
	v_pk_mul_f32 v[114:115], v[114:115], v[154:155] op_sel:[0,1]
	v_pk_mul_f32 v[116:117], v[116:117], v[154:155] op_sel:[0,1]
	v_pk_mul_f32 v[110:111], v[110:111], v[152:153] op_sel:[0,1]
	v_pk_mul_f32 v[112:113], v[112:113], v[152:153] op_sel:[0,1]
	v_pk_mul_f32 v[170:171], v[102:103], v[152:153] op_sel:[0,1]
	v_pk_mul_f32 v[152:153], v[104:105], v[152:153] op_sel:[0,1]
	v_cvt_pk_bf16_f32 v102, v126, v127
	v_cvt_pk_bf16_f32 v103, v128, v129
	v_cvt_pk_bf16_f32 v104, v122, v123
	v_cvt_pk_bf16_f32 v105, v124, v125
	v_pk_mul_f32 v[92:93], v[92:93], v[154:155] op_sel:[0,1]
	v_pk_mul_f32 v[94:95], v[94:95], v[154:155] op_sel:[0,1]
	v_pk_mul_f32 v[88:89], v[88:89], v[154:155] op_sel:[0,1]
	v_pk_mul_f32 v[90:91], v[90:91], v[154:155] op_sel:[0,1]
	v_pk_mul_f32 v[126:127], v[80:81], v[158:159] op_sel:[0,1]
	v_pk_mul_f32 v[128:129], v[82:83], v[158:159] op_sel:[0,1]
	v_cvt_pk_bf16_f32 v80, v118, v119
	v_cvt_pk_bf16_f32 v81, v120, v121
	v_cvt_pk_bf16_f32 v82, v114, v115
	v_cvt_pk_bf16_f32 v83, v116, v117
	v_cvt_pk_bf16_f32 v110, v110, v111
	v_cvt_pk_bf16_f32 v111, v112, v113
	v_cvt_pk_bf16_f32 v112, v170, v171
	v_cvt_pk_bf16_f32 v113, v152, v153
	v_pk_mul_f32 v[122:123], v[84:85], v[158:159] op_sel:[0,1]
	v_pk_mul_f32 v[124:125], v[86:87], v[158:159] op_sel:[0,1]
	global_store_dwordx4 v[146:147], v[102:105], off
	global_store_dwordx4 v[146:147], v[110:113], off offset:256
	v_cvt_pk_bf16_f32 v84, v92, v93
	v_cvt_pk_bf16_f32 v85, v94, v95
	v_cvt_pk_bf16_f32 v86, v88, v89
	v_cvt_pk_bf16_f32 v87, v90, v91
	global_store_dwordx4 v[164:165], v[80:83], off
	global_store_dwordx4 v[164:165], v[84:87], off offset:256
	v_pk_mul_f32 v[106:107], v[106:107], v[158:159] op_sel:[0,1]
	v_pk_mul_f32 v[80:81], v[72:73], v[162:163] op_sel:[0,1]
	v_lshlrev_b64 v[72:73], 13, v[160:161]
	v_pk_mul_f32 v[108:109], v[108:109], v[158:159] op_sel:[0,1]
	v_pk_mul_f32 v[98:99], v[98:99], v[158:159] op_sel:[0,1]
	v_pk_mul_f32 v[100:101], v[100:101], v[158:159] op_sel:[0,1]
	v_pk_mul_f32 v[76:77], v[76:77], v[162:163] op_sel:[0,1]
	v_pk_mul_f32 v[78:79], v[78:79], v[162:163] op_sel:[0,1]
	v_pk_mul_f32 v[82:83], v[74:75], v[162:163] op_sel:[0,1]
	v_lshl_add_u64 v[72:73], s[6:7], 0, v[72:73]
	v_cvt_pk_bf16_f32 v88, v106, v107
	v_cvt_pk_bf16_f32 v89, v108, v109
	v_cvt_pk_bf16_f32 v90, v98, v99
	v_cvt_pk_bf16_f32 v91, v100, v101
	v_lshl_add_u64 v[84:85], v[72:73], 0, v[166:167]
	v_cvt_pk_bf16_f32 v72, v76, v77
	v_cvt_pk_bf16_f32 v73, v78, v79
	v_cvt_pk_bf16_f32 v74, v80, v81
	v_cvt_pk_bf16_f32 v75, v82, v83
	v_cvt_pk_bf16_f32 v92, v122, v123
	v_cvt_pk_bf16_f32 v93, v124, v125
	v_cvt_pk_bf16_f32 v94, v126, v127
; template <class Epi>
; __device__ __forceinline__ void gemm_phase(LAS unsigned char* lds, const Gemm g, const StaticOrder& S, const Epi& E, int wv0) {
;     ...
;     if (!has_next) break;
; __device__ __forceinline__ void store8bf(bf16_t* dst, const float (&v)[8]) {
;   u32x4 w; w.x = pk2(v[0], v[1]); w.y = pk2(v[2], v[3]); w.z = pk2(v[4], v[5]); w.w = pk2(v[6], v[7]);
;   *(u32x4*)dst = w;
; }
;   __device__ __forceinline__ void emit(const EpiPre& q0, int row, int col, f32x4 a, f32x4 b, const f32x4 (&hb)[2][2], const float (&hs)[2][4], int ai_, int m_, int bj_) const {
;     ...
;     } else if (MODE == E_UKV) {
; #pragma unroll
;       for (int j = 0; j < 8; ++j) v[j] *= q.s;
;       store8bf((bf16_t*)e.out + (size_t)row * NKV + col, v);
	v_cvt_pk_bf16_f32 v95, v128, v129
	global_store_dwordx4 v[156:157], v[88:91], off
	global_store_dwordx4 v[156:157], v[92:95], off offset:256
	global_store_dwordx4 v[84:85], v[72:75], off
	v_pk_mul_f32 v[68:69], v[68:69], v[162:163] op_sel:[0,1]
	v_pk_mul_f32 v[70:71], v[70:71], v[162:163] op_sel:[0,1]
	v_pk_mul_f32 v[72:73], v[64:65], v[162:163] op_sel:[0,1]
	v_pk_mul_f32 v[74:75], v[66:67], v[162:163] op_sel:[0,1]
	v_cvt_pk_bf16_f32 v64, v68, v69
	v_cvt_pk_bf16_f32 v65, v70, v71
	v_cvt_pk_bf16_f32 v66, v72, v73
	v_cvt_pk_bf16_f32 v67, v74, v75
	v_pk_mul_f32 v[60:61], v[60:61], v[168:169] op_sel:[0,1]
	global_store_dwordx4 v[84:85], v[64:67], off offset:256
	v_pk_mul_f32 v[62:63], v[62:63], v[168:169] op_sel:[0,1]
	v_pk_mul_f32 v[48:49], v[48:49], v[168:169] op_sel:[0,1]
	v_pk_mul_f32 v[64:65], v[56:57], v[168:169] op_sel:[0,1]
	v_pk_mul_f32 v[66:67], v[58:59], v[168:169] op_sel:[0,1]
	v_cvt_pk_bf16_f32 v56, v60, v61
	v_add_co_u32_e32 v60, vcc, s94, v146
	v_cvt_pk_bf16_f32 v57, v62, v63
	v_cvt_pk_bf16_f32 v58, v64, v65
	v_cvt_pk_bf16_f32 v59, v66, v67
	v_addc_co_u32_e32 v61, vcc, 0, v147, vcc
	global_store_dwordx4 v[60:61], v[56:59], off
	v_pk_mul_f32 v[50:51], v[50:51], v[168:169] op_sel:[0,1]
	v_lshl_add_u64 v[68:69], v[146:147], 0, s[4:5]
	v_pk_mul_f32 v[56:57], v[40:41], v[168:169] op_sel:[0,1]
	v_pk_mul_f32 v[58:59], v[42:43], v[168:169] op_sel:[0,1]
	v_cvt_pk_bf16_f32 v40, v48, v49
	v_cvt_pk_bf16_f32 v41, v50, v51
	v_cvt_pk_bf16_f32 v42, v56, v57
	v_cvt_pk_bf16_f32 v43, v58, v59
	global_store_dwordx4 v[68:69], v[40:43], off offset:256
	v_pk_mul_f32 v[44:45], v[44:45], v[144:145] op_sel:[0,1]
	v_pk_mul_f32 v[46:47], v[46:47], v[144:145] op_sel:[0,1]
	v_pk_mul_f32 v[40:41], v[52:53], v[144:145] op_sel:[0,1]
	v_pk_mul_f32 v[42:43], v[54:55], v[144:145] op_sel:[0,1]
	v_cvt_pk_bf16_f32 v40, v40, v41
	v_cvt_pk_bf16_f32 v41, v42, v43
	v_cvt_pk_bf16_f32 v42, v44, v45
	v_add_co_u32_e32 v44, vcc, s95, v146
	v_cvt_pk_bf16_f32 v43, v46, v47
	s_nop 0
	v_addc_co_u32_e32 v45, vcc, 0, v147, vcc
	s_mov_b64 s[4:5], 0x120000
	global_store_dwordx4 v[44:45], v[40:43], off
	v_pk_mul_f32 v[32:33], v[32:33], v[144:145] op_sel:[0,1]
	v_pk_mul_f32 v[34:35], v[34:35], v[144:145] op_sel:[0,1]
	v_pk_mul_f32 v[40:41], v[24:25], v[144:145] op_sel:[0,1]
	v_pk_mul_f32 v[42:43], v[26:27], v[144:145] op_sel:[0,1]
	v_lshl_add_u64 v[48:49], v[146:147], 0, s[4:5]
	v_cvt_pk_bf16_f32 v24, v32, v33
	v_cvt_pk_bf16_f32 v25, v34, v35
	v_cvt_pk_bf16_f32 v26, v40, v41
	v_cvt_pk_bf16_f32 v27, v42, v43
	global_store_dwordx4 v[48:49], v[24:27], off offset:256
	v_pk_mul_f32 v[28:29], v[28:29], v[140:141] op_sel:[0,1]
	v_pk_mul_f32 v[30:31], v[30:31], v[140:141] op_sel:[0,1]
	v_pk_mul_f32 v[24:25], v[36:37], v[140:141] op_sel:[0,1]
	v_pk_mul_f32 v[26:27], v[38:39], v[140:141] op_sel:[0,1]
	v_cvt_pk_bf16_f32 v24, v24, v25
	v_cvt_pk_bf16_f32 v25, v26, v27
	v_cvt_pk_bf16_f32 v26, v28, v29
	v_add_co_u32_e32 v28, vcc, s0, v146
	v_cvt_pk_bf16_f32 v27, v30, v31
	s_nop 0
	v_addc_co_u32_e32 v29, vcc, 0, v147, vcc
	s_mov_b64 s[4:5], 0x140000
	global_store_dwordx4 v[28:29], v[24:27], off
	v_pk_mul_f32 v[16:17], v[16:17], v[140:141] op_sel:[0,1]
	v_pk_mul_f32 v[18:19], v[18:19], v[140:141] op_sel:[0,1]
	v_pk_mul_f32 v[24:25], v[8:9], v[140:141] op_sel:[0,1]
	v_pk_mul_f32 v[26:27], v[10:11], v[140:141] op_sel:[0,1]
	v_lshl_add_u64 v[32:33], v[146:147], 0, s[4:5]
	v_cvt_pk_bf16_f32 v8, v16, v17
	v_cvt_pk_bf16_f32 v9, v18, v19
	v_cvt_pk_bf16_f32 v10, v24, v25
	v_cvt_pk_bf16_f32 v11, v26, v27
	global_store_dwordx4 v[32:33], v[8:11], off offset:256
	v_pk_mul_f32 v[12:13], v[12:13], v[142:143] op_sel:[0,1]
	s_mov_b32 s0, 0x160000
	v_pk_mul_f32 v[8:9], v[20:21], v[142:143] op_sel:[0,1]
	v_pk_mul_f32 v[10:11], v[22:23], v[142:143] op_sel:[0,1]
	v_pk_mul_f32 v[14:15], v[14:15], v[142:143] op_sel:[0,1]
	v_cvt_pk_bf16_f32 v8, v8, v9
	v_cvt_pk_bf16_f32 v9, v10, v11
	v_cvt_pk_bf16_f32 v10, v12, v13
	v_add_co_u32_e32 v12, vcc, s0, v146
	v_cvt_pk_bf16_f32 v11, v14, v15
	s_nop 0
	v_addc_co_u32_e32 v13, vcc, 0, v147, vcc
	s_mov_b64 s[4:5], 0x160000
	global_store_dwordx4 v[12:13], v[8:11], off
	v_pk_mul_f32 v[4:5], v[4:5], v[142:143] op_sel:[0,1]
	v_pk_mul_f32 v[6:7], v[6:7], v[142:143] op_sel:[0,1]
	v_pk_mul_f32 v[8:9], v[0:1], v[142:143] op_sel:[0,1]
	v_pk_mul_f32 v[10:11], v[2:3], v[142:143] op_sel:[0,1]
	v_lshl_add_u64 v[16:17], v[146:147], 0, s[4:5]
	v_cvt_pk_bf16_f32 v0, v4, v5
	v_cvt_pk_bf16_f32 v1, v6, v7
	v_cvt_pk_bf16_f32 v2, v8, v9
	v_cvt_pk_bf16_f32 v3, v10, v11
	global_store_dwordx4 v[16:17], v[0:3], off offset:256
	s_and_b64 vcc, exec, s[2:3]
	s_cbranch_vccz .LBB0_747
	s_waitcnt vmcnt(0)
	s_cmpk_gt_u32 s22, 0xff
	s_cbranch_scc1 .LBB0_760
	s_barrier

; #define PG8_STAGE(bufoff, gbase, voff) do { _Pragma("unroll") for (int _i = 0; _i < 2; ++_i) \
;     __builtin_amdgcn_global_load_lds((const unsigned*)((const char*)(gbase) + (voff)[_i]), (LAS unsigned*)(lds + (bufoff) + ldsw + _i * 8192), 16, 0, 0); } while (0)
; #define PG8_LDA(dst, b, h) do { _Pragma("unroll") for (int m = 0; m < 4; ++m) _Pragma("unroll") for (int k = 0; k < 2; ++k) dst[m][k] = *(const LAS bf16x8*)(lds + PG8_SA(b, h) + aoff + m * 2048 + k * 1024); } while (0)
; #define PG8_LDB(dst, b, h) do { _Pragma("unroll") for (int n = 0; n < 2; ++n) _Pragma("unroll") for (int k = 0; k < 2; ++k) dst[n][k] = *(const LAS bf16x8*)(lds + PG8_SB(b, h) + boff + n * 2048 + k * 1024); } while (0)
; #define PG8_MMA(ai, bj, At, Bt) do { __builtin_amdgcn_s_setprio(1); _Pragma("unroll") for (int m = 0; m < 4; ++m) _Pragma("unroll") for (int n = 0; n < 2; ++n) _Pragma("unroll") for (int k = 0; k < 2; ++k) \
;     acc[ai][bj][m][n] = __builtin_amdgcn_mfma_f32_16x16x32_bf16(Bt[n][k], At[m][k], acc[ai][bj][m][n], 0, 0, 0); __builtin_amdgcn_s_setprio(0); } while (0)
; #define PG8_WAIT_L(n) asm volatile("s_waitcnt lgkmcnt(" #n ")" ::: "memory")
; #define PG8_BAR __builtin_amdgcn_s_barrier()
; template <class Epi>
; __device__ __forceinline__ void gemm_phase(LAS unsigned char* lds, const Gemm g, const StaticOrder& S, const Epi& E, int wv0) {
;     ...
;     const bool has_next = S.next(ui + 1, nxt);
;     const char* nA = has_next ? (const char*)g.A + (size_t)nxt.pm * tstepA : cA; const char* nB = has_next ? (const char*)g.Bt + (size_t)nxt.pn * tstepB : cB;
;     for (int t = 0; t < nt; t += 2) {
;       const bool last = (t == nt - 2);
;       const char* a1 = cA + (size_t)(t + 1) * kstep;
;       const char* a2 = last ? nA : cA + (size_t)(t + 2) * kstep; const char* b2 = last ? nB : cB + (size_t)(t + 2) * kstep;
;       const char* a3 = a2 + kstep; const char* b3 = b2 + kstep;
;       PG8_LDB(B0, 0, 0); PG8_SCHED; PG8_LDA(At, 0, 0); PG8_STAGE(PG8_SA(1, 1), a1 + hstepA, voffA);
;       PG8_WAIT_L(8); PG8_BAR; PG8_WAIT_L(0); PG8_MMA(0, 0, At, B0); PG8_BAR; PG8_SCHED;
;     ...
; #pragma unroll
;     for (int a = 0; a < 2; ++a)
; #pragma unroll
;       for (int b = 0; b < 2; ++b)
; #pragma unroll
;         for (int m = 0; m < 4; ++m)
; #pragma unroll
;           for (int n = 0; n < 2; ++n) acc[a][b][m][n] = (f32x4){0.f, 0.f, 0.f, 0.f};
.LBB0_905:
	v_mov_b64_e32 v[0:1], 0x600
	s_ashr_i32 s13, s12, 31
	v_cmp_lt_i64_e32 vcc, s[14:15], v[0:1]
	s_lshl_b64 s[14:15], s[12:13], 20
	s_add_u32 s14, s30, s14
	s_addc_u32 s15, s31, s15
	s_and_b64 s[16:17], vcc, exec
	s_cselect_b32 s13, s15, s21
	s_cselect_b32 s45, s14, s20
	s_ashr_i32 s11, s10, 31
	s_lshl_b64 s[16:17], s[10:11], 20
	s_add_u32 s16, s34, s16
	s_addc_u32 s17, s35, s17
	s_and_b64 s[24:25], vcc, exec
	s_cselect_b32 s11, s17, s23
	s_cselect_b32 s46, s16, s22
	s_add_u32 s20, s20, 0x80080
	s_addc_u32 s21, s21, 0
	s_add_u32 s47, s22, 0x100
	v_mov_b32_e32 v0, 0
	s_addc_u32 s48, s23, 0
	s_mov_b32 s49, -2
	v_mov_b32_e32 v1, v0
	v_mov_b32_e32 v2, v0
	v_mov_b32_e32 v3, v0
	v_mov_b32_e32 v4, v0
	v_mov_b32_e32 v5, v0
	v_mov_b32_e32 v6, v0
	v_mov_b32_e32 v7, v0
	v_mov_b32_e32 v16, v0
	v_mov_b32_e32 v17, v0
	v_mov_b32_e32 v18, v0
	v_mov_b32_e32 v19, v0
	v_mov_b32_e32 v20, v0
	v_mov_b32_e32 v21, v0
	v_mov_b32_e32 v22, v0
	v_mov_b32_e32 v23, v0
	v_mov_b32_e32 v32, v0
	v_mov_b32_e32 v33, v0
	v_mov_b32_e32 v34, v0
	v_mov_b32_e32 v35, v0
	v_mov_b32_e32 v36, v0
	v_mov_b32_e32 v37, v0
	v_mov_b32_e32 v38, v0
	v_mov_b32_e32 v39, v0
	v_mov_b32_e32 v48, v0
	v_mov_b32_e32 v49, v0
	v_mov_b32_e32 v50, v0
	v_mov_b32_e32 v51, v0
	v_mov_b32_e32 v52, v0
	v_mov_b32_e32 v53, v0
	v_mov_b32_e32 v54, v0
	v_mov_b32_e32 v55, v0
	v_mov_b32_e32 v8, v0
	v_mov_b32_e32 v9, v0
	v_mov_b32_e32 v10, v0
	v_mov_b32_e32 v11, v0
	v_mov_b32_e32 v12, v0
	v_mov_b32_e32 v13, v0
	v_mov_b32_e32 v14, v0
	v_mov_b32_e32 v15, v0
	v_mov_b32_e32 v24, v0
	v_mov_b32_e32 v25, v0
	v_mov_b32_e32 v26, v0
	v_mov_b32_e32 v27, v0
	v_mov_b32_e32 v28, v0
	v_mov_b32_e32 v29, v0
	v_mov_b32_e32 v30, v0
	v_mov_b32_e32 v31, v0
	v_mov_b32_e32 v40, v0
	v_mov_b32_e32 v41, v0
	v_mov_b32_e32 v42, v0
	v_mov_b32_e32 v43, v0
	v_mov_b32_e32 v44, v0
	v_mov_b32_e32 v45, v0
	v_mov_b32_e32 v46, v0
	v_mov_b32_e32 v47, v0
	v_mov_b32_e32 v56, v0
	v_mov_b32_e32 v57, v0
	v_mov_b32_e32 v58, v0
	v_mov_b32_e32 v59, v0
	v_mov_b32_e32 v60, v0
	v_mov_b32_e32 v61, v0
	v_mov_b32_e32 v62, v0
	v_mov_b32_e32 v63, v0
	v_mov_b32_e32 v64, v0
	v_mov_b32_e32 v65, v0
	v_mov_b32_e32 v66, v0
	v_mov_b32_e32 v67, v0
	v_mov_b32_e32 v68, v0
	v_mov_b32_e32 v69, v0
	v_mov_b32_e32 v70, v0
	v_mov_b32_e32 v71, v0
	v_mov_b32_e32 v80, v0
	v_mov_b32_e32 v81, v0
	v_mov_b32_e32 v82, v0
	v_mov_b32_e32 v83, v0
	v_mov_b32_e32 v84, v0
	v_mov_b32_e32 v85, v0
	v_mov_b32_e32 v86, v0
	v_mov_b32_e32 v87, v0
	v_mov_b32_e32 v98, v0
	v_mov_b32_e32 v99, v0
	v_mov_b32_e32 v100, v0
	v_mov_b32_e32 v101, v0
	v_mov_b32_e32 v102, v0
	v_mov_b32_e32 v103, v0
	v_mov_b32_e32 v104, v0
	v_mov_b32_e32 v105, v0
	v_mov_b32_e32 v114, v0
	v_mov_b32_e32 v115, v0
	v_mov_b32_e32 v116, v0
	v_mov_b32_e32 v117, v0
	v_mov_b32_e32 v118, v0
	v_mov_b32_e32 v119, v0
	v_mov_b32_e32 v120, v0
	v_mov_b32_e32 v121, v0
	v_mov_b32_e32 v72, v0
	v_mov_b32_e32 v73, v0
	v_mov_b32_e32 v74, v0
	v_mov_b32_e32 v75, v0
	v_mov_b32_e32 v76, v0
	v_mov_b32_e32 v77, v0
	v_mov_b32_e32 v78, v0
	v_mov_b32_e32 v79, v0
	v_mov_b32_e32 v88, v0
	v_mov_b32_e32 v89, v0
	v_mov_b32_e32 v90, v0
	v_mov_b32_e32 v91, v0
	v_mov_b32_e32 v92, v0
	v_mov_b32_e32 v93, v0
	v_mov_b32_e32 v94, v0
	v_mov_b32_e32 v95, v0
	v_mov_b32_e32 v106, v0
	v_mov_b32_e32 v107, v0
	v_mov_b32_e32 v108, v0
	v_mov_b32_e32 v109, v0
	v_mov_b32_e32 v110, v0
	v_mov_b32_e32 v111, v0
	v_mov_b32_e32 v112, v0
	v_mov_b32_e32 v113, v0
	v_mov_b32_e32 v122, v0
	v_mov_b32_e32 v123, v0
	v_mov_b32_e32 v124, v0
	v_mov_b32_e32 v125, v0
	v_mov_b32_e32 v126, v0
	v_mov_b32_e32 v127, v0
	v_mov_b32_e32 v128, v0
	v_mov_b32_e32 v129, v0
	s_cmp_lt_u32 s53, 4
	s_cbranch_scc1 .Lgprio3
	s_setprio 1
.Lgprio3:
.LBB0_906:
	s_add_u32 s0, s20, 0xfff80080
	s_addc_u32 s22, s21, -1
	s_add_i32 s50, 0, 0x10000
	v_add_u32_e32 v152, s50, v157
	ds_read_b128 v[140:143], v152
	ds_read_b128 v[144:147], v152 offset:1024
	ds_read_b128 v[148:151], v152 offset:2048
	ds_read_b128 v[152:155], v152 offset:3072
	s_cmp_eq_u32 s49, 28
	s_cselect_b32 s25, s13, s22
	s_cselect_b32 s24, s45, s0
	s_cselect_b32 s23, s11, s48
	s_cselect_b32 s22, s46, s47
	v_lshl_add_u64 v[192:193], s[20:21], 0, v[136:137]
	s_add_i32 m0, s19, 0xc000
	ds_read_b128 v[160:163], v159
	ds_read_b128 v[164:167], v159 offset:1024
	ds_read_b128 v[168:171], v159 offset:2048
	ds_read_b128 v[172:175], v159 offset:3072
	ds_read_b128 v[176:179], v159 offset:4096
	ds_read_b128 v[180:183], v159 offset:5120
	ds_read_b128 v[184:187], v159 offset:6144
	ds_read_b128 v[188:191], v159 offset:7168
	global_load_lds_dwordx4 v[192:193], off
	v_lshl_add_u64 v[192:193], s[20:21], 0, v[138:139]
	s_add_i32 m0, s19, 0xe000
	s_nop 0
	global_load_lds_dwordx4 v[192:193], off
	s_waitcnt lgkmcnt(8)
	s_barrier
	s_waitcnt lgkmcnt(0)
	s_waitcnt lgkmcnt(0)
	v_mfma_f32_16x16x32_bf16 v[126:129], v[140:143], v[160:163], v[126:129]
	v_mfma_f32_16x16x32_bf16 v[122:125], v[148:151], v[160:163], v[122:125]
	v_mfma_f32_16x16x32_bf16 v[110:113], v[140:143], v[168:171], v[110:113]
	v_mfma_f32_16x16x32_bf16 v[106:109], v[148:151], v[168:171], v[106:109]
	v_mfma_f32_16x16x32_bf16 v[92:95], v[140:143], v[176:179], v[92:95]
	v_mfma_f32_16x16x32_bf16 v[88:91], v[148:151], v[176:179], v[88:91]
	v_mfma_f32_16x16x32_bf16 v[76:79], v[140:143], v[184:187], v[76:79]
	v_mfma_f32_16x16x32_bf16 v[72:75], v[148:151], v[184:187], v[72:75]
	v_mfma_f32_16x16x32_bf16 v[126:129], v[144:147], v[164:167], v[126:129]
	v_mfma_f32_16x16x32_bf16 v[122:125], v[152:155], v[164:167], v[122:125]
	v_mfma_f32_16x16x32_bf16 v[110:113], v[144:147], v[172:175], v[110:113]
	v_mfma_f32_16x16x32_bf16 v[106:109], v[152:155], v[172:175], v[106:109]
	v_mfma_f32_16x16x32_bf16 v[92:95], v[144:147], v[180:183], v[92:95]
	v_mfma_f32_16x16x32_bf16 v[88:91], v[152:155], v[180:183], v[88:91]
	v_mfma_f32_16x16x32_bf16 v[76:79], v[144:147], v[188:191], v[76:79]
	v_mfma_f32_16x16x32_bf16 v[72:75], v[152:155], v[188:191], v[72:75]
	s_barrier
; #define PG8_STAGE(bufoff, gbase, voff) do { _Pragma("unroll") for (int _i = 0; _i < 2; ++_i) \
;     __builtin_amdgcn_global_load_lds((const unsigned*)((const char*)(gbase) + (voff)[_i]), (LAS unsigned*)(lds + (bufoff) + ldsw + _i * 8192), 16, 0, 0); } while (0)
; #define PG8_LDA(dst, b, h) do { _Pragma("unroll") for (int m = 0; m < 4; ++m) _Pragma("unroll") for (int k = 0; k < 2; ++k) dst[m][k] = *(const LAS bf16x8*)(lds + PG8_SA(b, h) + aoff + m * 2048 + k * 1024); } while (0)
; #define PG8_LDB(dst, b, h) do { _Pragma("unroll") for (int n = 0; n < 2; ++n) _Pragma("unroll") for (int k = 0; k < 2; ++k) dst[n][k] = *(const LAS bf16x8*)(lds + PG8_SB(b, h) + boff + n * 2048 + k * 1024); } while (0)
; #define PG8_MMA(ai, bj, At, Bt) do { __builtin_amdgcn_s_setprio(1); _Pragma("unroll") for (int m = 0; m < 4; ++m) _Pragma("unroll") for (int n = 0; n < 2; ++n) _Pragma("unroll") for (int k = 0; k < 2; ++k) \
;     acc[ai][bj][m][n] = __builtin_amdgcn_mfma_f32_16x16x32_bf16(Bt[n][k], At[m][k], acc[ai][bj][m][n], 0, 0, 0); __builtin_amdgcn_s_setprio(0); } while (0)
; #define PG8_WAIT_V(n) asm volatile("s_waitcnt vmcnt(" #n ")" ::: "memory")
; #define PG8_WAIT_L(n) asm volatile("s_waitcnt lgkmcnt(" #n ")" ::: "memory")
; #define PG8_BAR __builtin_amdgcn_s_barrier()
; #define PG8_SCHED __builtin_amdgcn_sched_barrier(0)
; template <class Epi>
; __device__ __forceinline__ void gemm_phase(LAS unsigned char* lds, const Gemm g, const StaticOrder& S, const Epi& E, int wv0) {
;     ...
;       PG8_LDB(B1, 0, 1); PG8_STAGE(PG8_SB(0, 0), b2, voffB);
;       PG8_BAR; PG8_WAIT_L(0); PG8_MMA(0, 1, At, B1); PG8_BAR;
;       PG8_LDA(At, 0, 1); PG8_STAGE(PG8_SA(0, 0), a2, voffA);
;       PG8_BAR; PG8_WAIT_L(0); PG8_MMA(1, 0, At, B0); PG8_BAR; PG8_SCHED;
;       PG8_STAGE(PG8_SB(0, 1), b2 + hstepB, voffB);
;       PG8_WAIT_V(6); PG8_BAR; PG8_MMA(1, 1, At, B1); PG8_BAR;
;       PG8_LDB(B0, 1, 0); PG8_SCHED; PG8_LDA(At, 1, 0); PG8_STAGE(PG8_SA(0, 1), a2 + hstepA, voffA);
;       PG8_WAIT_L(8); PG8_BAR; PG8_WAIT_L(0); PG8_MMA(0, 0, At, B0); PG8_BAR; PG8_SCHED;
	s_add_i32 s0, 0, 0x14000
	s_add_i32 s50, s50, s36
	v_add_u32_e32 v204, s0, v157
	v_lshl_add_u64 v[208:209], s[22:23], 0, v[96:97]
	s_mov_b32 m0, s50
	ds_read_b128 v[192:195], v204
	ds_read_b128 v[196:199], v204 offset:1024
	ds_read_b128 v[200:203], v204 offset:2048
	ds_read_b128 v[204:207], v204 offset:3072
	global_load_lds_dwordx4 v[208:209], off
	v_lshl_add_u64 v[210:211], s[22:23], 0, v[130:131]
	s_add_i32 m0, s50, 0x2000
	s_nop 0
	global_load_lds_dwordx4 v[210:211], off
	s_barrier
	s_waitcnt lgkmcnt(0)
	s_waitcnt lgkmcnt(0)
	v_mfma_f32_16x16x32_bf16 v[118:121], v[192:195], v[160:163], v[118:121]
	v_mfma_f32_16x16x32_bf16 v[114:117], v[200:203], v[160:163], v[114:117]
	v_mfma_f32_16x16x32_bf16 v[102:105], v[192:195], v[168:171], v[102:105]
	v_mfma_f32_16x16x32_bf16 v[98:101], v[200:203], v[168:171], v[98:101]
	v_mfma_f32_16x16x32_bf16 v[84:87], v[192:195], v[176:179], v[84:87]
	v_mfma_f32_16x16x32_bf16 v[80:83], v[200:203], v[176:179], v[80:83]
	v_mfma_f32_16x16x32_bf16 v[68:71], v[192:195], v[184:187], v[68:71]
	v_mfma_f32_16x16x32_bf16 v[64:67], v[200:203], v[184:187], v[64:67]
	v_mfma_f32_16x16x32_bf16 v[118:121], v[196:199], v[164:167], v[118:121]
	v_mfma_f32_16x16x32_bf16 v[114:117], v[204:207], v[164:167], v[114:117]
	v_mfma_f32_16x16x32_bf16 v[102:105], v[196:199], v[172:175], v[102:105]
	v_mfma_f32_16x16x32_bf16 v[98:101], v[204:207], v[172:175], v[98:101]
	v_mfma_f32_16x16x32_bf16 v[84:87], v[196:199], v[180:183], v[84:87]
	v_mfma_f32_16x16x32_bf16 v[80:83], v[204:207], v[180:183], v[80:83]
	v_mfma_f32_16x16x32_bf16 v[68:71], v[196:199], v[188:191], v[68:71]
	v_mfma_f32_16x16x32_bf16 v[64:67], v[204:207], v[188:191], v[64:67]
	s_mov_b32 m0, s19
	v_lshl_add_u64 v[212:213], s[24:25], 0, v[134:135]
	s_barrier
	ds_read_b128 v[160:163], v159 offset:16384
	ds_read_b128 v[164:167], v159 offset:17408
	ds_read_b128 v[168:171], v159 offset:18432
	ds_read_b128 v[172:175], v159 offset:19456
	ds_read_b128 v[176:179], v159 offset:20480
	ds_read_b128 v[180:183], v159 offset:21504
	ds_read_b128 v[184:187], v159 offset:22528
	ds_read_b128 v[188:191], v159 offset:23552
	global_load_lds_dwordx4 v[212:213], off
	v_lshl_add_u64 v[214:215], s[24:25], 0, v[132:133]
	s_mov_b32 m0, s38
	s_nop 0
	global_load_lds_dwordx4 v[214:215], off
	s_barrier
	s_waitcnt lgkmcnt(0)
	s_waitcnt lgkmcnt(0)
	v_mfma_f32_16x16x32_bf16 v[60:63], v[140:143], v[160:163], v[60:63]
	v_mfma_f32_16x16x32_bf16 v[56:59], v[148:151], v[160:163], v[56:59]
	v_mfma_f32_16x16x32_bf16 v[44:47], v[140:143], v[168:171], v[44:47]
	v_mfma_f32_16x16x32_bf16 v[40:43], v[148:151], v[168:171], v[40:43]
	v_mfma_f32_16x16x32_bf16 v[28:31], v[140:143], v[176:179], v[28:31]
	v_mfma_f32_16x16x32_bf16 v[24:27], v[148:151], v[176:179], v[24:27]
	v_mfma_f32_16x16x32_bf16 v[12:15], v[140:143], v[184:187], v[12:15]
	v_mfma_f32_16x16x32_bf16 v[8:11], v[148:151], v[184:187], v[8:11]
	v_mfma_f32_16x16x32_bf16 v[60:63], v[144:147], v[164:167], v[60:63]
	v_mfma_f32_16x16x32_bf16 v[56:59], v[152:155], v[164:167], v[56:59]
	v_mfma_f32_16x16x32_bf16 v[44:47], v[144:147], v[172:175], v[44:47]
	v_mfma_f32_16x16x32_bf16 v[40:43], v[152:155], v[172:175], v[40:43]
	v_mfma_f32_16x16x32_bf16 v[28:31], v[144:147], v[180:183], v[28:31]
	v_mfma_f32_16x16x32_bf16 v[24:27], v[152:155], v[180:183], v[24:27]
	v_mfma_f32_16x16x32_bf16 v[12:15], v[144:147], v[188:191], v[12:15]
	v_mfma_f32_16x16x32_bf16 v[8:11], v[152:155], v[188:191], v[8:11]
	s_barrier
	s_add_u32 s50, s22, 0x80000
	s_addc_u32 s51, s23, 0
	s_add_i32 s0, s0, s36
	v_lshl_add_u64 v[140:141], s[50:51], 0, v[96:97]
	s_mov_b32 m0, s0
	s_nop 0
	global_load_lds_dwordx4 v[140:141], off
	v_lshl_add_u64 v[140:141], s[50:51], 0, v[130:131]
	s_add_i32 m0, s0, 0x2000
	s_nop 0
	global_load_lds_dwordx4 v[140:141], off
	s_waitcnt vmcnt(6)
	s_barrier
	v_mfma_f32_16x16x32_bf16 v[52:55], v[192:195], v[160:163], v[52:55]
	v_mfma_f32_16x16x32_bf16 v[48:51], v[200:203], v[160:163], v[48:51]
	v_mfma_f32_16x16x32_bf16 v[36:39], v[192:195], v[168:171], v[36:39]
	v_mfma_f32_16x16x32_bf16 v[32:35], v[200:203], v[168:171], v[32:35]
	v_mfma_f32_16x16x32_bf16 v[20:23], v[192:195], v[176:179], v[20:23]
	v_mfma_f32_16x16x32_bf16 v[16:19], v[200:203], v[176:179], v[16:19]
	v_mfma_f32_16x16x32_bf16 v[4:7], v[192:195], v[184:187], v[4:7]
	v_mfma_f32_16x16x32_bf16 v[0:3], v[200:203], v[184:187], v[0:3]
	v_mfma_f32_16x16x32_bf16 v[52:55], v[196:199], v[164:167], v[52:55]
	v_mfma_f32_16x16x32_bf16 v[48:51], v[204:207], v[164:167], v[48:51]
	v_mfma_f32_16x16x32_bf16 v[36:39], v[196:199], v[172:175], v[36:39]
	v_mfma_f32_16x16x32_bf16 v[32:35], v[204:207], v[172:175], v[32:35]
	v_mfma_f32_16x16x32_bf16 v[20:23], v[196:199], v[180:183], v[20:23]
	v_mfma_f32_16x16x32_bf16 v[16:19], v[204:207], v[180:183], v[16:19]
	v_mfma_f32_16x16x32_bf16 v[4:7], v[196:199], v[188:191], v[4:7]
	v_mfma_f32_16x16x32_bf16 v[0:3], v[204:207], v[188:191], v[0:3]
	s_add_i32 s0, 0, 0x18000
	v_add_u32_e32 v152, s0, v157
	s_barrier
	ds_read_b128 v[140:143], v152
	ds_read_b128 v[144:147], v152 offset:1024
	ds_read_b128 v[148:151], v152 offset:2048
	ds_read_b128 v[152:155], v152 offset:3072
	s_add_u32 s24, s24, 0x80000
	s_addc_u32 s25, s25, 0
	s_mov_b32 m0, s39
	v_lshl_add_u64 v[192:193], s[24:25], 0, v[134:135]
	ds_read_b128 v[160:163], v159 offset:32768
	ds_read_b128 v[164:167], v159 offset:33792
	ds_read_b128 v[168:171], v159 offset:34816
	ds_read_b128 v[172:175], v159 offset:35840
	ds_read_b128 v[176:179], v159 offset:36864
	ds_read_b128 v[180:183], v159 offset:37888
	ds_read_b128 v[184:187], v159 offset:38912
	ds_read_b128 v[188:191], v159 offset:39936
	global_load_lds_dwordx4 v[192:193], off
	v_lshl_add_u64 v[192:193], s[24:25], 0, v[132:133]
	s_mov_b32 m0, s40
	s_nop 0
	global_load_lds_dwordx4 v[192:193], off
	s_waitcnt lgkmcnt(8)
	s_barrier
; #define PG8_STAGE(bufoff, gbase, voff) do { _Pragma("unroll") for (int _i = 0; _i < 2; ++_i) \
;     __builtin_amdgcn_global_load_lds((const unsigned*)((const char*)(gbase) + (voff)[_i]), (LAS unsigned*)(lds + (bufoff) + ldsw + _i * 8192), 16, 0, 0); } while (0)
; #define PG8_LDA(dst, b, h) do { _Pragma("unroll") for (int m = 0; m < 4; ++m) _Pragma("unroll") for (int k = 0; k < 2; ++k) dst[m][k] = *(const LAS bf16x8*)(lds + PG8_SA(b, h) + aoff + m * 2048 + k * 1024); } while (0)
; #define PG8_LDB(dst, b, h) do { _Pragma("unroll") for (int n = 0; n < 2; ++n) _Pragma("unroll") for (int k = 0; k < 2; ++k) dst[n][k] = *(const LAS bf16x8*)(lds + PG8_SB(b, h) + boff + n * 2048 + k * 1024); } while (0)
; #define PG8_MMA(ai, bj, At, Bt) do { __builtin_amdgcn_s_setprio(1); _Pragma("unroll") for (int m = 0; m < 4; ++m) _Pragma("unroll") for (int n = 0; n < 2; ++n) _Pragma("unroll") for (int k = 0; k < 2; ++k) \
;     acc[ai][bj][m][n] = __builtin_amdgcn_mfma_f32_16x16x32_bf16(Bt[n][k], At[m][k], acc[ai][bj][m][n], 0, 0, 0); __builtin_amdgcn_s_setprio(0); } while (0)
; #define PG8_WAIT_V(n) asm volatile("s_waitcnt vmcnt(" #n ")" ::: "memory")
; #define PG8_WAIT_L(n) asm volatile("s_waitcnt lgkmcnt(" #n ")" ::: "memory")
; #define PG8_BAR __builtin_amdgcn_s_barrier()
; #define PG8_SCHED __builtin_amdgcn_sched_barrier(0)
; template <class Epi>
; __device__ __forceinline__ void gemm_phase(LAS unsigned char* lds, const Gemm g, const StaticOrder& S, const Epi& E, int wv0) {
;     ...
;       PG8_WAIT_L(8); PG8_BAR; PG8_WAIT_L(0); PG8_MMA(0, 0, At, B0); PG8_BAR; PG8_SCHED;
;       PG8_LDB(B1, 1, 1); PG8_STAGE(PG8_SB(1, 0), b3, voffB);
;       PG8_BAR; PG8_WAIT_L(0); PG8_MMA(0, 1, At, B1); PG8_BAR;
;       PG8_LDA(At, 1, 1); PG8_STAGE(PG8_SA(1, 0), a3, voffA);
;       PG8_BAR; PG8_WAIT_L(0); PG8_MMA(1, 0, At, B0); PG8_BAR; PG8_SCHED;
;       PG8_STAGE(PG8_SB(1, 1), b3 + hstepB, voffB);
;       PG8_WAIT_V(6); PG8_BAR; PG8_MMA(1, 1, At, B1); PG8_BAR;
	s_waitcnt lgkmcnt(0)
	s_waitcnt lgkmcnt(0)
	v_mfma_f32_16x16x32_bf16 v[126:129], v[140:143], v[160:163], v[126:129]
	v_mfma_f32_16x16x32_bf16 v[122:125], v[148:151], v[160:163], v[122:125]
	v_mfma_f32_16x16x32_bf16 v[110:113], v[140:143], v[168:171], v[110:113]
	v_mfma_f32_16x16x32_bf16 v[106:109], v[148:151], v[168:171], v[106:109]
	v_mfma_f32_16x16x32_bf16 v[92:95], v[140:143], v[176:179], v[92:95]
	v_mfma_f32_16x16x32_bf16 v[88:91], v[148:151], v[176:179], v[88:91]
	v_mfma_f32_16x16x32_bf16 v[76:79], v[140:143], v[184:187], v[76:79]
	v_mfma_f32_16x16x32_bf16 v[72:75], v[148:151], v[184:187], v[72:75]
	v_mfma_f32_16x16x32_bf16 v[126:129], v[144:147], v[164:167], v[126:129]
	v_mfma_f32_16x16x32_bf16 v[122:125], v[152:155], v[164:167], v[122:125]
	v_mfma_f32_16x16x32_bf16 v[110:113], v[144:147], v[172:175], v[110:113]
	v_mfma_f32_16x16x32_bf16 v[106:109], v[152:155], v[172:175], v[106:109]
	v_mfma_f32_16x16x32_bf16 v[92:95], v[144:147], v[180:183], v[92:95]
	v_mfma_f32_16x16x32_bf16 v[88:91], v[152:155], v[180:183], v[88:91]
	v_mfma_f32_16x16x32_bf16 v[76:79], v[144:147], v[188:191], v[76:79]
	v_mfma_f32_16x16x32_bf16 v[72:75], v[152:155], v[188:191], v[72:75]
	s_barrier
	s_add_i32 s24, 0, 0x1c000
	s_add_i32 s0, s0, s36
	v_add_u32_e32 v204, s24, v157
	v_lshl_add_u64 v[208:209], v[208:209], 0, s[72:73]
	s_mov_b32 m0, s0
	ds_read_b128 v[192:195], v204
	ds_read_b128 v[196:199], v204 offset:1024
	ds_read_b128 v[200:203], v204 offset:2048
	ds_read_b128 v[204:207], v204 offset:3072
	global_load_lds_dwordx4 v[208:209], off
	v_lshl_add_u64 v[208:209], v[210:211], 0, s[72:73]
	s_add_i32 m0, s0, 0x2000
	s_nop 0
	global_load_lds_dwordx4 v[208:209], off
	s_barrier
	s_waitcnt lgkmcnt(0)
	s_waitcnt lgkmcnt(0)
	v_mfma_f32_16x16x32_bf16 v[118:121], v[192:195], v[160:163], v[118:121]
	v_mfma_f32_16x16x32_bf16 v[114:117], v[200:203], v[160:163], v[114:117]
	v_mfma_f32_16x16x32_bf16 v[102:105], v[192:195], v[168:171], v[102:105]
	v_mfma_f32_16x16x32_bf16 v[98:101], v[200:203], v[168:171], v[98:101]
	v_mfma_f32_16x16x32_bf16 v[84:87], v[192:195], v[176:179], v[84:87]
	v_mfma_f32_16x16x32_bf16 v[80:83], v[200:203], v[176:179], v[80:83]
	v_mfma_f32_16x16x32_bf16 v[68:71], v[192:195], v[184:187], v[68:71]
	v_mfma_f32_16x16x32_bf16 v[64:67], v[200:203], v[184:187], v[64:67]
	v_mfma_f32_16x16x32_bf16 v[118:121], v[196:199], v[164:167], v[118:121]
	v_mfma_f32_16x16x32_bf16 v[114:117], v[204:207], v[164:167], v[114:117]
	v_mfma_f32_16x16x32_bf16 v[102:105], v[196:199], v[172:175], v[102:105]
	v_mfma_f32_16x16x32_bf16 v[98:101], v[204:207], v[172:175], v[98:101]
	v_mfma_f32_16x16x32_bf16 v[84:87], v[196:199], v[180:183], v[84:87]
	v_mfma_f32_16x16x32_bf16 v[80:83], v[204:207], v[180:183], v[80:83]
	v_mfma_f32_16x16x32_bf16 v[68:71], v[196:199], v[188:191], v[68:71]
	v_mfma_f32_16x16x32_bf16 v[64:67], v[204:207], v[188:191], v[64:67]
	s_mov_b32 m0, s41
	v_lshl_add_u64 v[208:209], v[212:213], 0, s[72:73]
	s_barrier
	ds_read_b128 v[160:163], v159 offset:49152
	ds_read_b128 v[164:167], v159 offset:50176
	ds_read_b128 v[168:171], v159 offset:51200
	ds_read_b128 v[172:175], v159 offset:52224
	ds_read_b128 v[176:179], v159 offset:53248
	ds_read_b128 v[180:183], v159 offset:54272
	ds_read_b128 v[184:187], v159 offset:55296
	ds_read_b128 v[188:191], v159 offset:56320
	global_load_lds_dwordx4 v[208:209], off
	v_lshl_add_u64 v[208:209], v[214:215], 0, s[72:73]
	s_mov_b32 m0, s42
	s_nop 0
	global_load_lds_dwordx4 v[208:209], off
	s_barrier
	s_waitcnt lgkmcnt(0)
	s_waitcnt lgkmcnt(0)
	v_mfma_f32_16x16x32_bf16 v[60:63], v[140:143], v[160:163], v[60:63]
	v_mfma_f32_16x16x32_bf16 v[56:59], v[148:151], v[160:163], v[56:59]
	v_mfma_f32_16x16x32_bf16 v[44:47], v[140:143], v[168:171], v[44:47]
	v_mfma_f32_16x16x32_bf16 v[40:43], v[148:151], v[168:171], v[40:43]
	v_mfma_f32_16x16x32_bf16 v[28:31], v[140:143], v[176:179], v[28:31]
	v_mfma_f32_16x16x32_bf16 v[24:27], v[148:151], v[176:179], v[24:27]
	v_mfma_f32_16x16x32_bf16 v[12:15], v[140:143], v[184:187], v[12:15]
	v_mfma_f32_16x16x32_bf16 v[8:11], v[148:151], v[184:187], v[8:11]
	v_mfma_f32_16x16x32_bf16 v[60:63], v[144:147], v[164:167], v[60:63]
	v_mfma_f32_16x16x32_bf16 v[56:59], v[152:155], v[164:167], v[56:59]
	v_mfma_f32_16x16x32_bf16 v[44:47], v[144:147], v[172:175], v[44:47]
	v_mfma_f32_16x16x32_bf16 v[40:43], v[152:155], v[172:175], v[40:43]
	v_mfma_f32_16x16x32_bf16 v[28:31], v[144:147], v[180:183], v[28:31]
	v_mfma_f32_16x16x32_bf16 v[24:27], v[152:155], v[180:183], v[24:27]
	v_mfma_f32_16x16x32_bf16 v[12:15], v[144:147], v[188:191], v[12:15]
	v_mfma_f32_16x16x32_bf16 v[8:11], v[152:155], v[188:191], v[8:11]
	s_barrier
	s_add_u32 s22, s22, 0x80080
	s_addc_u32 s23, s23, 0
	s_add_i32 s0, s24, s36
	v_lshl_add_u64 v[140:141], s[22:23], 0, v[96:97]
	s_mov_b32 m0, s0
	s_nop 0
	global_load_lds_dwordx4 v[140:141], off
	v_lshl_add_u64 v[140:141], s[22:23], 0, v[130:131]
	s_add_i32 m0, s0, 0x2000
	s_nop 0
	global_load_lds_dwordx4 v[140:141], off
	s_waitcnt vmcnt(6)
	s_barrier
	v_mfma_f32_16x16x32_bf16 v[52:55], v[192:195], v[160:163], v[52:55]
	v_mfma_f32_16x16x32_bf16 v[48:51], v[200:203], v[160:163], v[48:51]
	v_mfma_f32_16x16x32_bf16 v[36:39], v[192:195], v[168:171], v[36:39]
	v_mfma_f32_16x16x32_bf16 v[32:35], v[200:203], v[168:171], v[32:35]
	v_mfma_f32_16x16x32_bf16 v[20:23], v[192:195], v[176:179], v[20:23]
	v_mfma_f32_16x16x32_bf16 v[16:19], v[200:203], v[176:179], v[16:19]
	v_mfma_f32_16x16x32_bf16 v[4:7], v[192:195], v[184:187], v[4:7]
	v_mfma_f32_16x16x32_bf16 v[0:3], v[200:203], v[184:187], v[0:3]
	v_mfma_f32_16x16x32_bf16 v[52:55], v[196:199], v[164:167], v[52:55]
	v_mfma_f32_16x16x32_bf16 v[48:51], v[204:207], v[164:167], v[48:51]
	v_mfma_f32_16x16x32_bf16 v[36:39], v[196:199], v[172:175], v[36:39]
	v_mfma_f32_16x16x32_bf16 v[32:35], v[204:207], v[172:175], v[32:35]
	v_mfma_f32_16x16x32_bf16 v[20:23], v[196:199], v[180:183], v[20:23]
	v_mfma_f32_16x16x32_bf16 v[16:19], v[204:207], v[180:183], v[16:19]
	v_mfma_f32_16x16x32_bf16 v[4:7], v[196:199], v[188:191], v[4:7]
	v_mfma_f32_16x16x32_bf16 v[0:3], v[204:207], v[188:191], v[0:3]
	s_add_i32 s49, s49, 2
	s_add_u32 s20, s20, 0x100
	s_addc_u32 s21, s21, 0
	s_add_u32 s47, s47, 0x100
	s_addc_u32 s48, s48, 0
	s_cmp_gt_u32 s49, 29
	s_barrier
; __device__ __forceinline__ float fexp2(float x) { return __builtin_amdgcn_exp2f(x); }
; __device__ __forceinline__ float frcp(float x) { return __builtin_amdgcn_rcpf(x); }
; template <class Epi>
; __device__ __forceinline__ void gemm_phase(LAS unsigned char* lds, const Gemm g, const StaticOrder& S, const Epi& E, int wv0) {
;     ...
;     if (!has_next) break;
;   __device__ __forceinline__ void emit(const EpiPre& q0, int row, int col, f32x4 a, f32x4 b, const f32x4 (&hb)[2][2], const float (&hs)[2][4], int ai_, int m_, int bj_) const {
;     ...
;     if (MODE == E_GATE) { q.a0 = hb[bj_][0]; q.a1 = hb[bj_][1]; }
;     ...
;     } else if (MODE == E_GATE) {
;       const float bb[8] = {q.a0[0], q.a0[1], q.a0[2], q.a0[3], q.a1[0], q.a1[1], q.a1[2], q.a1[3]};
; #pragma unroll
;       for (int j = 0; j < 8; ++j) v[j] = frcp(1.0f + fexp2(__builtin_fmaf(v[j], -LOG2E, bb[j])));
;       store8bf((bf16_t*)e.out + (size_t)row * NG + col, v);
;   __device__ __forceinline__ void operator()(const f32x4 (&acc)[2][2][4][2], const pg8::Unit& u, int wr, int wc, int fr, int fq) const {
;     ...
;     for (int bj = 0; bj < 2; ++bj) { hb[bj][0] = (f32x4){0.f, 0.f, 0.f, 0.f}; hb[bj][1] = hb[bj][0];
;       if (MODE == E_GATE) { hb[bj][0] = *(const f32x4*)(e.f0 + col0 + bj * 128) * (-LOG2E); hb[bj][1] = *(const f32x4*)(e.f0 + col0 + bj * 128 + 4) * (-LOG2E); } }
	s_cbranch_scc0 .LBB0_906
	s_setprio 0
	v_lshl_or_b32 v164, s1, 8, v158
	v_ashrrev_i32_e32 v165, 31, v164
	v_lshl_add_u64 v[166:167], v[164:165], 2, s[8:9]
	global_load_dwordx4 v[140:143], v[166:167], off offset:16
	global_load_dwordx4 v[144:147], v[166:167], off
	s_mov_b32 s0, 0xbfb8aa3b
	s_and_b64 vcc, exec, s[2:3]
	s_mov_b64 s[22:23], s[16:17]
	s_mov_b64 s[20:21], s[14:15]
	s_waitcnt vmcnt(0)
	v_pk_mul_f32 v[148:149], v[142:143], s[0:1] op_sel_hi:[1,0]
	v_pk_mul_f32 v[150:151], v[140:141], s[0:1] op_sel_hi:[1,0]
	global_load_dwordx4 v[160:163], v[166:167], off offset:528
	global_load_dwordx4 v[140:143], v[166:167], off offset:512
	v_pk_mul_f32 v[154:155], v[144:145], s[0:1] op_sel_hi:[1,0]
	v_pk_mul_f32 v[152:153], v[146:147], s[0:1] op_sel_hi:[1,0]
	v_fmamk_f32 v126, v126, 0xbfb8aa3b, v154
	v_exp_f32_e32 v126, v126
	v_fmamk_f32 v122, v122, 0xbfb8aa3b, v150
	v_exp_f32_e32 v122, v122
	v_fmamk_f32 v110, v110, 0xbfb8aa3b, v154
	v_add_f32_e32 v126, 1.0, v126
	v_fmamk_f32 v106, v106, 0xbfb8aa3b, v150
	v_add_f32_e32 v122, 1.0, v122
	v_rcp_f32_e32 v166, v122
	v_fmamk_f32 v122, v123, 0xbfb8aa3b, v151
	v_exp_f32_e32 v122, v122
	v_exp_f32_e32 v110, v110
	v_exp_f32_e32 v106, v106
	v_add_f32_e32 v122, 1.0, v122
	v_rcp_f32_e32 v167, v122
	v_fmamk_f32 v122, v124, 0xbfb8aa3b, v148
	v_exp_f32_e32 v122, v122
	v_add_f32_e32 v110, 1.0, v110
	v_add_f32_e32 v106, 1.0, v106
	v_fmamk_f32 v92, v92, 0xbfb8aa3b, v154
	v_add_f32_e32 v122, 1.0, v122
	v_rcp_f32_e32 v168, v122
	v_fmamk_f32 v122, v125, 0xbfb8aa3b, v149
	v_exp_f32_e32 v122, v122
	v_lshlrev_b64 v[124:125], 1, v[164:165]
	v_fmamk_f32 v88, v88, 0xbfb8aa3b, v150
	v_exp_f32_e32 v92, v92
	v_add_f32_e32 v122, 1.0, v122
	v_rcp_f32_e32 v169, v122
	v_mov_b64_e32 v[122:123], s[6:7]
	v_exp_f32_e32 v88, v88
	v_add_f32_e32 v92, 1.0, v92
	v_cvt_pk_bf16_f32 v164, v166, v167
	v_cvt_pk_bf16_f32 v165, v168, v169
	v_add_f32_e32 v88, 1.0, v88
	v_fmamk_f32 v76, v76, 0xbfb8aa3b, v154
	v_fmamk_f32 v72, v72, 0xbfb8aa3b, v150
	v_exp_f32_e32 v76, v76
	v_exp_f32_e32 v72, v72
	v_fmamk_f32 v60, v60, 0xbfb8aa3b, v154
	v_fmamk_f32 v56, v56, 0xbfb8aa3b, v150
	v_add_f32_e32 v76, 1.0, v76
	v_add_f32_e32 v72, 1.0, v72
	v_exp_f32_e32 v60, v60
	v_exp_f32_e32 v56, v56
	v_fmamk_f32 v44, v44, 0xbfb8aa3b, v154
	v_fmamk_f32 v40, v40, 0xbfb8aa3b, v150
	v_add_f32_e32 v60, 1.0, v60
	v_add_f32_e32 v56, 1.0, v56
	v_exp_f32_e32 v44, v44
	v_exp_f32_e32 v40, v40
	v_fmamk_f32 v28, v28, 0xbfb8aa3b, v154
	v_fmamk_f32 v24, v24, 0xbfb8aa3b, v150
	v_add_f32_e32 v44, 1.0, v44
	v_add_f32_e32 v40, 1.0, v40
	v_exp_f32_e32 v28, v28
	v_exp_f32_e32 v24, v24
	v_fmamk_f32 v12, v12, 0xbfb8aa3b, v154
	v_fmamk_f32 v8, v8, 0xbfb8aa3b, v150
	v_add_f32_e32 v28, 1.0, v28
	v_add_f32_e32 v24, 1.0, v24
	v_exp_f32_e32 v12, v12
	v_exp_f32_e32 v8, v8
	v_add_f32_e32 v12, 1.0, v12
	v_add_f32_e32 v8, 1.0, v8
	s_waitcnt vmcnt(0)
	v_pk_mul_f32 v[144:145], v[142:143], s[0:1] op_sel_hi:[1,0]
	v_pk_mul_f32 v[142:143], v[160:161], s[0:1] op_sel_hi:[1,0]
	v_rcp_f32_e32 v161, v126
	v_fmamk_f32 v126, v127, 0xbfb8aa3b, v155
	v_exp_f32_e32 v126, v126
	v_pk_mul_f32 v[146:147], v[140:141], s[0:1] op_sel_hi:[1,0]
	v_pk_mul_f32 v[140:141], v[162:163], s[0:1] op_sel_hi:[1,0]
	v_fmamk_f32 v114, v114, 0xbfb8aa3b, v142
	v_add_f32_e32 v126, 1.0, v126
	v_rcp_f32_e32 v162, v126
	v_fmamk_f32 v126, v128, 0xbfb8aa3b, v152
	v_exp_f32_e32 v126, v126
	v_exp_f32_e32 v114, v114
	v_cvt_pk_bf16_f32 v162, v161, v162
	v_fmamk_f32 v118, v118, 0xbfb8aa3b, v146
	v_add_f32_e32 v126, 1.0, v126
	v_rcp_f32_e32 v128, v126
	v_fmamk_f32 v126, v129, 0xbfb8aa3b, v153
	v_exp_f32_e32 v126, v126
	v_add_f32_e32 v114, 1.0, v114
	v_fmamk_f32 v119, v119, 0xbfb8aa3b, v147
	v_fmamk_f32 v120, v120, 0xbfb8aa3b, v144
	v_add_f32_e32 v126, 1.0, v126
	v_rcp_f32_e32 v129, v126
	v_fmamk_f32 v121, v121, 0xbfb8aa3b, v145
	v_exp_f32_e32 v118, v118
	v_exp_f32_e32 v119, v119
	v_cvt_pk_bf16_f32 v163, v128, v129
	v_rcp_f32_e32 v128, v114
	v_fmamk_f32 v114, v115, 0xbfb8aa3b, v143
	v_exp_f32_e32 v114, v114
	v_exp_f32_e32 v120, v120
	v_exp_f32_e32 v121, v121
	v_add_f32_e32 v118, 1.0, v118
	v_add_f32_e32 v114, 1.0, v114
	v_rcp_f32_e32 v129, v114
	v_fmamk_f32 v114, v116, 0xbfb8aa3b, v140
	v_exp_f32_e32 v114, v114
	v_add_f32_e32 v119, 1.0, v119
	v_add_f32_e32 v120, 1.0, v120
	v_add_f32_e32 v121, 1.0, v121
	v_add_f32_e32 v114, 1.0, v114
	v_rcp_f32_e32 v161, v114
	v_fmamk_f32 v114, v117, 0xbfb8aa3b, v141
	v_exp_f32_e32 v114, v114
	v_rcp_f32_e32 v118, v118
	v_rcp_f32_e32 v119, v119
	v_rcp_f32_e32 v120, v120
	v_add_f32_e32 v114, 1.0, v114
	v_rcp_f32_e32 v121, v121
	v_rcp_f32_e32 v117, v114
	v_lshl_add_u32 v160, s18, 8, v156
	v_mad_i64_i32 v[126:127], s[0:1], v160, s33, v[122:123]
	v_lshl_add_u64 v[126:127], v[126:127], 0, v[124:125]
	v_cvt_pk_bf16_f32 v114, v118, v119
	v_cvt_pk_bf16_f32 v115, v120, v121
	v_cvt_pk_bf16_f32 v116, v128, v129
	v_cvt_pk_bf16_f32 v117, v161, v117
	global_store_dwordx4 v[126:127], v[114:117], off offset:256
	v_fmamk_f32 v98, v98, 0xbfb8aa3b, v142
	v_exp_f32_e32 v98, v98
	v_rcp_f32_e32 v115, v110
	v_fmamk_f32 v110, v111, 0xbfb8aa3b, v155
	v_rcp_f32_e32 v117, v106
	v_fmamk_f32 v106, v107, 0xbfb8aa3b, v151
	v_exp_f32_e32 v110, v110
	v_exp_f32_e32 v106, v106
	v_or_b32_e32 v114, 16, v160
	v_add_f32_e32 v98, 1.0, v98
	v_add_f32_e32 v110, 1.0, v110
	v_add_f32_e32 v106, 1.0, v106
	v_rcp_f32_e32 v116, v110
	v_fmamk_f32 v110, v112, 0xbfb8aa3b, v152
	v_rcp_f32_e32 v118, v106
	v_fmamk_f32 v106, v108, 0xbfb8aa3b, v148
	v_exp_f32_e32 v110, v110
	v_exp_f32_e32 v106, v106
	v_cvt_pk_bf16_f32 v108, v117, v118
	v_fmamk_f32 v102, v102, 0xbfb8aa3b, v146
	v_add_f32_e32 v110, 1.0, v110
	v_add_f32_e32 v106, 1.0, v106
	v_rcp_f32_e32 v112, v110
; __device__ __forceinline__ float fexp2(float x) { return __builtin_amdgcn_exp2f(x); }
; __device__ __forceinline__ float frcp(float x) { return __builtin_amdgcn_rcpf(x); }
; __device__ __forceinline__ void store8bf(bf16_t* dst, const float (&v)[8]) {
;   u32x4 w; w.x = pk2(v[0], v[1]); w.y = pk2(v[2], v[3]); w.z = pk2(v[4], v[5]); w.w = pk2(v[6], v[7]);
;   *(u32x4*)dst = w;
; }
;   __device__ __forceinline__ void emit(const EpiPre& q0, int row, int col, f32x4 a, f32x4 b, const f32x4 (&hb)[2][2], const float (&hs)[2][4], int ai_, int m_, int bj_) const {
;     ...
;     } else if (MODE == E_GATE) {
;       const float bb[8] = {q.a0[0], q.a0[1], q.a0[2], q.a0[3], q.a1[0], q.a1[1], q.a1[2], q.a1[3]};
; #pragma unroll
;       for (int j = 0; j < 8; ++j) v[j] = frcp(1.0f + fexp2(__builtin_fmaf(v[j], -LOG2E, bb[j])));
;       store8bf((bf16_t*)e.out + (size_t)row * NG + col, v);
	v_fmamk_f32 v110, v113, 0xbfb8aa3b, v153
	v_rcp_f32_e32 v119, v106
	v_fmamk_f32 v106, v109, 0xbfb8aa3b, v149
	v_exp_f32_e32 v110, v110
	v_exp_f32_e32 v106, v106
	v_fmamk_f32 v103, v103, 0xbfb8aa3b, v147
	v_fmamk_f32 v104, v104, 0xbfb8aa3b, v144
	v_add_f32_e32 v110, 1.0, v110
	v_add_f32_e32 v106, 1.0, v106
	v_rcp_f32_e32 v113, v110
	v_rcp_f32_e32 v109, v106
	v_mad_i64_i32 v[106:107], s[0:1], v114, s33, v[122:123]
	v_lshl_add_u64 v[110:111], v[106:107], 0, v[124:125]
	v_cvt_pk_bf16_f32 v106, v115, v116
	v_cvt_pk_bf16_f32 v107, v112, v113
	v_cvt_pk_bf16_f32 v109, v119, v109
	global_store_dwordx4 v[110:111], v[106:109], off
	v_fmamk_f32 v105, v105, 0xbfb8aa3b, v145
	v_exp_f32_e32 v102, v102
	v_rcp_f32_e32 v106, v98
	v_fmamk_f32 v98, v99, 0xbfb8aa3b, v143
	v_exp_f32_e32 v98, v98
	v_exp_f32_e32 v103, v103
	v_exp_f32_e32 v104, v104
	v_exp_f32_e32 v105, v105
	v_add_f32_e32 v98, 1.0, v98
	v_rcp_f32_e32 v107, v98
	v_fmamk_f32 v98, v100, 0xbfb8aa3b, v140
	v_exp_f32_e32 v98, v98
	v_add_f32_e32 v102, 1.0, v102
	v_add_f32_e32 v103, 1.0, v103
	v_add_f32_e32 v104, 1.0, v104
	v_add_f32_e32 v98, 1.0, v98
	v_rcp_f32_e32 v108, v98
	v_fmamk_f32 v98, v101, 0xbfb8aa3b, v141
	v_exp_f32_e32 v98, v98
	v_add_f32_e32 v105, 1.0, v105
	v_rcp_f32_e32 v102, v102
	v_rcp_f32_e32 v103, v103
	v_add_f32_e32 v98, 1.0, v98
	v_rcp_f32_e32 v104, v104
	v_rcp_f32_e32 v105, v105
	v_rcp_f32_e32 v101, v98
	v_cvt_pk_bf16_f32 v98, v102, v103
	v_cvt_pk_bf16_f32 v100, v106, v107
	v_cvt_pk_bf16_f32 v99, v104, v105
	v_cvt_pk_bf16_f32 v101, v108, v101
	global_store_dwordx4 v[110:111], v[98:101], off offset:256
	v_fmamk_f32 v80, v80, 0xbfb8aa3b, v142
	v_exp_f32_e32 v80, v80
	v_rcp_f32_e32 v99, v92
	v_fmamk_f32 v92, v93, 0xbfb8aa3b, v155
	v_rcp_f32_e32 v101, v88
	v_fmamk_f32 v88, v89, 0xbfb8aa3b, v151
	v_exp_f32_e32 v92, v92
	v_exp_f32_e32 v88, v88
	v_or_b32_e32 v98, 32, v160
	global_store_dwordx4 v[126:127], v[162:165], off
	v_add_f32_e32 v92, 1.0, v92
	v_add_f32_e32 v88, 1.0, v88
	v_rcp_f32_e32 v100, v92
	v_fmamk_f32 v92, v94, 0xbfb8aa3b, v152
	v_rcp_f32_e32 v102, v88
	v_fmamk_f32 v88, v90, 0xbfb8aa3b, v148
	v_exp_f32_e32 v92, v92
	v_exp_f32_e32 v88, v88
	v_cvt_pk_bf16_f32 v90, v101, v102
	v_add_f32_e32 v92, 1.0, v92
	v_add_f32_e32 v88, 1.0, v88
	v_rcp_f32_e32 v94, v92
	v_fmamk_f32 v92, v95, 0xbfb8aa3b, v153
	v_rcp_f32_e32 v103, v88
	v_fmamk_f32 v88, v91, 0xbfb8aa3b, v149
	v_exp_f32_e32 v92, v92
	v_exp_f32_e32 v88, v88
	v_add_f32_e32 v80, 1.0, v80
	v_add_f32_e32 v92, 1.0, v92
	v_add_f32_e32 v88, 1.0, v88
	v_rcp_f32_e32 v95, v92
	v_rcp_f32_e32 v91, v88
	v_mad_i64_i32 v[88:89], s[0:1], v98, s33, v[122:123]
	v_lshl_add_u64 v[92:93], v[88:89], 0, v[124:125]
	v_cvt_pk_bf16_f32 v88, v99, v100
	v_cvt_pk_bf16_f32 v89, v94, v95
	v_cvt_pk_bf16_f32 v91, v103, v91
	global_store_dwordx4 v[92:93], v[88:91], off
	v_fmamk_f32 v84, v84, 0xbfb8aa3b, v146
	v_fmamk_f32 v85, v85, 0xbfb8aa3b, v147
	v_rcp_f32_e32 v88, v80
	v_fmamk_f32 v80, v81, 0xbfb8aa3b, v143
	v_exp_f32_e32 v80, v80
	v_fmamk_f32 v86, v86, 0xbfb8aa3b, v144
	v_fmamk_f32 v87, v87, 0xbfb8aa3b, v145
	v_exp_f32_e32 v84, v84
	v_add_f32_e32 v80, 1.0, v80
	v_rcp_f32_e32 v89, v80
	v_fmamk_f32 v80, v82, 0xbfb8aa3b, v140
	v_exp_f32_e32 v80, v80
	v_exp_f32_e32 v85, v85
	v_exp_f32_e32 v86, v86
	v_exp_f32_e32 v87, v87
	v_add_f32_e32 v80, 1.0, v80
	v_rcp_f32_e32 v90, v80
	v_fmamk_f32 v80, v83, 0xbfb8aa3b, v141
	v_exp_f32_e32 v80, v80
	v_add_f32_e32 v84, 1.0, v84
	v_add_f32_e32 v85, 1.0, v85
	v_add_f32_e32 v86, 1.0, v86
	v_add_f32_e32 v87, 1.0, v87
	v_add_f32_e32 v80, 1.0, v80
	v_rcp_f32_e32 v84, v84
	v_rcp_f32_e32 v85, v85
	v_rcp_f32_e32 v86, v86
	v_rcp_f32_e32 v87, v87
	v_rcp_f32_e32 v83, v80
	v_cvt_pk_bf16_f32 v80, v84, v85
	v_cvt_pk_bf16_f32 v82, v88, v89
	v_cvt_pk_bf16_f32 v81, v86, v87
	v_cvt_pk_bf16_f32 v83, v90, v83
	global_store_dwordx4 v[92:93], v[80:83], off offset:256
	v_fmamk_f32 v64, v64, 0xbfb8aa3b, v142
	v_exp_f32_e32 v64, v64
	v_rcp_f32_e32 v81, v76
	v_fmamk_f32 v76, v77, 0xbfb8aa3b, v155
	v_rcp_f32_e32 v83, v72
	v_fmamk_f32 v72, v73, 0xbfb8aa3b, v151
	v_exp_f32_e32 v76, v76
	v_exp_f32_e32 v72, v72
	v_or_b32_e32 v80, 48, v160
	v_add_f32_e32 v64, 1.0, v64
	v_add_f32_e32 v76, 1.0, v76
	v_add_f32_e32 v72, 1.0, v72
	v_rcp_f32_e32 v82, v76
	v_fmamk_f32 v76, v78, 0xbfb8aa3b, v152
	v_rcp_f32_e32 v84, v72
	v_fmamk_f32 v72, v74, 0xbfb8aa3b, v148
	v_exp_f32_e32 v76, v76
	v_exp_f32_e32 v72, v72
	v_cvt_pk_bf16_f32 v74, v83, v84
	v_fmamk_f32 v68, v68, 0xbfb8aa3b, v146
	v_add_f32_e32 v76, 1.0, v76
	v_add_f32_e32 v72, 1.0, v72
	v_rcp_f32_e32 v78, v76
	v_fmamk_f32 v76, v79, 0xbfb8aa3b, v153
	v_rcp_f32_e32 v85, v72
	v_fmamk_f32 v72, v75, 0xbfb8aa3b, v149
	v_exp_f32_e32 v76, v76
	v_exp_f32_e32 v72, v72
	v_fmamk_f32 v69, v69, 0xbfb8aa3b, v147
	v_fmamk_f32 v70, v70, 0xbfb8aa3b, v144
	v_add_f32_e32 v76, 1.0, v76
	v_add_f32_e32 v72, 1.0, v72
	v_rcp_f32_e32 v79, v76
	v_rcp_f32_e32 v75, v72
	v_mad_i64_i32 v[72:73], s[0:1], v80, s33, v[122:123]
	v_lshl_add_u64 v[76:77], v[72:73], 0, v[124:125]
	v_cvt_pk_bf16_f32 v72, v81, v82
	v_cvt_pk_bf16_f32 v73, v78, v79
	v_cvt_pk_bf16_f32 v75, v85, v75
	global_store_dwordx4 v[76:77], v[72:75], off
	v_fmamk_f32 v71, v71, 0xbfb8aa3b, v145
	v_exp_f32_e32 v68, v68
	v_rcp_f32_e32 v72, v64
	v_fmamk_f32 v64, v65, 0xbfb8aa3b, v143
	v_exp_f32_e32 v64, v64
	v_exp_f32_e32 v69, v69
	v_exp_f32_e32 v70, v70
	v_exp_f32_e32 v71, v71
	v_add_f32_e32 v64, 1.0, v64
	v_rcp_f32_e32 v73, v64
	v_fmamk_f32 v64, v66, 0xbfb8aa3b, v140
	v_exp_f32_e32 v64, v64
	v_add_f32_e32 v68, 1.0, v68
	v_add_f32_e32 v69, 1.0, v69
	v_add_f32_e32 v70, 1.0, v70
	v_add_f32_e32 v64, 1.0, v64
	v_rcp_f32_e32 v74, v64
	v_fmamk_f32 v64, v67, 0xbfb8aa3b, v141
	v_exp_f32_e32 v64, v64
; __device__ __forceinline__ float fexp2(float x) { return __builtin_amdgcn_exp2f(x); }
; __device__ __forceinline__ float frcp(float x) { return __builtin_amdgcn_rcpf(x); }
; __device__ __forceinline__ void store8bf(bf16_t* dst, const float (&v)[8]) {
;   u32x4 w; w.x = pk2(v[0], v[1]); w.y = pk2(v[2], v[3]); w.z = pk2(v[4], v[5]); w.w = pk2(v[6], v[7]);
;   *(u32x4*)dst = w;
; }
;   __device__ __forceinline__ void emit(const EpiPre& q0, int row, int col, f32x4 a, f32x4 b, const f32x4 (&hb)[2][2], const float (&hs)[2][4], int ai_, int m_, int bj_) const {
;     ...
;     } else if (MODE == E_GATE) {
;       const float bb[8] = {q.a0[0], q.a0[1], q.a0[2], q.a0[3], q.a1[0], q.a1[1], q.a1[2], q.a1[3]};
; #pragma unroll
;       for (int j = 0; j < 8; ++j) v[j] = frcp(1.0f + fexp2(__builtin_fmaf(v[j], -LOG2E, bb[j])));
;       store8bf((bf16_t*)e.out + (size_t)row * NG + col, v);
	v_add_f32_e32 v71, 1.0, v71
	v_rcp_f32_e32 v68, v68
	v_rcp_f32_e32 v69, v69
	v_add_f32_e32 v64, 1.0, v64
	v_rcp_f32_e32 v70, v70
	v_rcp_f32_e32 v71, v71
	v_rcp_f32_e32 v67, v64
	v_cvt_pk_bf16_f32 v64, v68, v69
	v_cvt_pk_bf16_f32 v66, v72, v73
	v_cvt_pk_bf16_f32 v65, v70, v71
	v_cvt_pk_bf16_f32 v67, v74, v67
	global_store_dwordx4 v[76:77], v[64:67], off offset:256
	v_fmamk_f32 v48, v48, 0xbfb8aa3b, v142
	v_exp_f32_e32 v48, v48
	v_rcp_f32_e32 v65, v60
	v_fmamk_f32 v60, v61, 0xbfb8aa3b, v155
	v_rcp_f32_e32 v67, v56
	v_fmamk_f32 v56, v57, 0xbfb8aa3b, v151
	v_exp_f32_e32 v60, v60
	v_exp_f32_e32 v56, v56
	v_add_u32_e32 v64, 0x80, v160
	v_add_f32_e32 v60, 1.0, v60
	v_add_f32_e32 v56, 1.0, v56
	v_rcp_f32_e32 v66, v60
	v_fmamk_f32 v60, v62, 0xbfb8aa3b, v152
	v_rcp_f32_e32 v68, v56
	v_fmamk_f32 v56, v58, 0xbfb8aa3b, v148
	v_exp_f32_e32 v60, v60
	v_exp_f32_e32 v56, v56
	v_cvt_pk_bf16_f32 v58, v67, v68
	v_add_f32_e32 v48, 1.0, v48
	v_add_f32_e32 v60, 1.0, v60
	v_add_f32_e32 v56, 1.0, v56
	v_rcp_f32_e32 v62, v60
	v_fmamk_f32 v60, v63, 0xbfb8aa3b, v153
	v_rcp_f32_e32 v69, v56
	v_fmamk_f32 v56, v59, 0xbfb8aa3b, v149
	v_exp_f32_e32 v60, v60
	v_exp_f32_e32 v56, v56
	v_fmamk_f32 v52, v52, 0xbfb8aa3b, v146
	v_add_f32_e32 v60, 1.0, v60
	v_add_f32_e32 v56, 1.0, v56
	v_rcp_f32_e32 v63, v60
	v_rcp_f32_e32 v59, v56
	v_mad_i64_i32 v[56:57], s[0:1], v64, s33, v[122:123]
	v_lshl_add_u64 v[60:61], v[56:57], 0, v[124:125]
	v_cvt_pk_bf16_f32 v56, v65, v66
	v_cvt_pk_bf16_f32 v57, v62, v63
	v_cvt_pk_bf16_f32 v59, v69, v59
	global_store_dwordx4 v[60:61], v[56:59], off
	v_fmamk_f32 v53, v53, 0xbfb8aa3b, v147
	v_fmamk_f32 v54, v54, 0xbfb8aa3b, v144
	v_rcp_f32_e32 v56, v48
	v_fmamk_f32 v48, v49, 0xbfb8aa3b, v143
	v_exp_f32_e32 v48, v48
	v_fmamk_f32 v55, v55, 0xbfb8aa3b, v145
	v_exp_f32_e32 v52, v52
	v_exp_f32_e32 v53, v53
	v_add_f32_e32 v48, 1.0, v48
	v_rcp_f32_e32 v57, v48
	v_fmamk_f32 v48, v50, 0xbfb8aa3b, v140
	v_exp_f32_e32 v48, v48
	v_exp_f32_e32 v54, v54
	v_exp_f32_e32 v55, v55
	v_add_f32_e32 v52, 1.0, v52
	v_add_f32_e32 v48, 1.0, v48
	v_rcp_f32_e32 v58, v48
	v_fmamk_f32 v48, v51, 0xbfb8aa3b, v141
	v_exp_f32_e32 v48, v48
	v_add_f32_e32 v53, 1.0, v53
	v_add_f32_e32 v54, 1.0, v54
	v_add_f32_e32 v55, 1.0, v55
	v_add_f32_e32 v48, 1.0, v48
	v_rcp_f32_e32 v52, v52
	v_rcp_f32_e32 v53, v53
	v_rcp_f32_e32 v54, v54
	v_rcp_f32_e32 v55, v55
	v_rcp_f32_e32 v51, v48
	v_cvt_pk_bf16_f32 v48, v52, v53
	v_cvt_pk_bf16_f32 v50, v56, v57
	v_cvt_pk_bf16_f32 v49, v54, v55
	v_cvt_pk_bf16_f32 v51, v58, v51
	global_store_dwordx4 v[60:61], v[48:51], off offset:256
	v_fmamk_f32 v32, v32, 0xbfb8aa3b, v142
	v_exp_f32_e32 v32, v32
	v_rcp_f32_e32 v49, v44
	v_fmamk_f32 v44, v45, 0xbfb8aa3b, v155
	v_rcp_f32_e32 v51, v40
	v_fmamk_f32 v40, v41, 0xbfb8aa3b, v151
	v_exp_f32_e32 v44, v44
	v_exp_f32_e32 v40, v40
	v_add_u32_e32 v48, 0x90, v160
	v_add_f32_e32 v32, 1.0, v32
	v_add_f32_e32 v44, 1.0, v44
	v_add_f32_e32 v40, 1.0, v40
	v_rcp_f32_e32 v50, v44
	v_fmamk_f32 v44, v46, 0xbfb8aa3b, v152
	v_rcp_f32_e32 v52, v40
	v_fmamk_f32 v40, v42, 0xbfb8aa3b, v148
	v_exp_f32_e32 v44, v44
	v_exp_f32_e32 v40, v40
	v_cvt_pk_bf16_f32 v42, v51, v52
	v_fmamk_f32 v36, v36, 0xbfb8aa3b, v146
	v_add_f32_e32 v44, 1.0, v44
	v_add_f32_e32 v40, 1.0, v40
	v_rcp_f32_e32 v46, v44
	v_fmamk_f32 v44, v47, 0xbfb8aa3b, v153
	v_rcp_f32_e32 v53, v40
	v_fmamk_f32 v40, v43, 0xbfb8aa3b, v149
	v_exp_f32_e32 v44, v44
	v_exp_f32_e32 v40, v40
	v_fmamk_f32 v37, v37, 0xbfb8aa3b, v147
	v_fmamk_f32 v38, v38, 0xbfb8aa3b, v144
	v_add_f32_e32 v44, 1.0, v44
	v_add_f32_e32 v40, 1.0, v40
	v_rcp_f32_e32 v47, v44
	v_rcp_f32_e32 v43, v40
	v_mad_i64_i32 v[40:41], s[0:1], v48, s33, v[122:123]
	v_lshl_add_u64 v[44:45], v[40:41], 0, v[124:125]
	v_cvt_pk_bf16_f32 v40, v49, v50
	v_cvt_pk_bf16_f32 v41, v46, v47
	v_cvt_pk_bf16_f32 v43, v53, v43
	global_store_dwordx4 v[44:45], v[40:43], off
	v_fmamk_f32 v39, v39, 0xbfb8aa3b, v145
	v_exp_f32_e32 v36, v36
	v_rcp_f32_e32 v40, v32
	v_fmamk_f32 v32, v33, 0xbfb8aa3b, v143
	v_exp_f32_e32 v32, v32
	v_exp_f32_e32 v37, v37
	v_exp_f32_e32 v38, v38
	v_exp_f32_e32 v39, v39
	v_add_f32_e32 v32, 1.0, v32
	v_rcp_f32_e32 v41, v32
	v_fmamk_f32 v32, v34, 0xbfb8aa3b, v140
	v_exp_f32_e32 v32, v32
	v_add_f32_e32 v36, 1.0, v36
	v_add_f32_e32 v37, 1.0, v37
	v_add_f32_e32 v38, 1.0, v38
	v_add_f32_e32 v32, 1.0, v32
	v_rcp_f32_e32 v42, v32
	v_fmamk_f32 v32, v35, 0xbfb8aa3b, v141
	v_exp_f32_e32 v32, v32
	v_add_f32_e32 v39, 1.0, v39
	v_rcp_f32_e32 v36, v36
	v_rcp_f32_e32 v37, v37
	v_add_f32_e32 v32, 1.0, v32
	v_rcp_f32_e32 v38, v38
	v_rcp_f32_e32 v39, v39
	v_rcp_f32_e32 v35, v32
	v_cvt_pk_bf16_f32 v32, v36, v37
; __device__ __forceinline__ float fexp2(float x) { return __builtin_amdgcn_exp2f(x); }
; __device__ __forceinline__ float frcp(float x) { return __builtin_amdgcn_rcpf(x); }
; template <class Epi>
; __device__ __forceinline__ void gemm_phase(LAS unsigned char* lds, const Gemm g, const StaticOrder& S, const Epi& E, int wv0) {
;     ...
;     if (!has_next) break;
; __device__ __forceinline__ void store8bf(bf16_t* dst, const float (&v)[8]) {
;   u32x4 w; w.x = pk2(v[0], v[1]); w.y = pk2(v[2], v[3]); w.z = pk2(v[4], v[5]); w.w = pk2(v[6], v[7]);
;   *(u32x4*)dst = w;
; }
;   __device__ __forceinline__ void emit(const EpiPre& q0, int row, int col, f32x4 a, f32x4 b, const f32x4 (&hb)[2][2], const float (&hs)[2][4], int ai_, int m_, int bj_) const {
;     ...
;     } else if (MODE == E_GATE) {
;       const float bb[8] = {q.a0[0], q.a0[1], q.a0[2], q.a0[3], q.a1[0], q.a1[1], q.a1[2], q.a1[3]};
; #pragma unroll
;       for (int j = 0; j < 8; ++j) v[j] = frcp(1.0f + fexp2(__builtin_fmaf(v[j], -LOG2E, bb[j])));
;       store8bf((bf16_t*)e.out + (size_t)row * NG + col, v);
	v_cvt_pk_bf16_f32 v34, v40, v41
	v_cvt_pk_bf16_f32 v33, v38, v39
	v_cvt_pk_bf16_f32 v35, v42, v35
	global_store_dwordx4 v[44:45], v[32:35], off offset:256
	v_fmamk_f32 v16, v16, 0xbfb8aa3b, v142
	v_exp_f32_e32 v16, v16
	v_rcp_f32_e32 v33, v28
	v_fmamk_f32 v28, v29, 0xbfb8aa3b, v155
	v_rcp_f32_e32 v35, v24
	v_fmamk_f32 v24, v25, 0xbfb8aa3b, v151
	v_exp_f32_e32 v28, v28
	v_exp_f32_e32 v24, v24
	v_add_u32_e32 v32, 0xa0, v160
	v_add_f32_e32 v28, 1.0, v28
	v_add_f32_e32 v24, 1.0, v24
	v_rcp_f32_e32 v34, v28
	v_fmamk_f32 v28, v30, 0xbfb8aa3b, v152
	v_rcp_f32_e32 v36, v24
	v_fmamk_f32 v24, v26, 0xbfb8aa3b, v148
	v_exp_f32_e32 v28, v28
	v_exp_f32_e32 v24, v24
	v_cvt_pk_bf16_f32 v26, v35, v36
	v_add_f32_e32 v16, 1.0, v16
	v_add_f32_e32 v28, 1.0, v28
	v_add_f32_e32 v24, 1.0, v24
	v_rcp_f32_e32 v30, v28
	v_fmamk_f32 v28, v31, 0xbfb8aa3b, v153
	v_rcp_f32_e32 v37, v24
	v_fmamk_f32 v24, v27, 0xbfb8aa3b, v149
	v_exp_f32_e32 v28, v28
	v_exp_f32_e32 v24, v24
	v_fmamk_f32 v20, v20, 0xbfb8aa3b, v146
	v_add_f32_e32 v28, 1.0, v28
	v_add_f32_e32 v24, 1.0, v24
	v_rcp_f32_e32 v31, v28
	v_rcp_f32_e32 v27, v24
	v_mad_i64_i32 v[24:25], s[0:1], v32, s33, v[122:123]
	v_lshl_add_u64 v[28:29], v[24:25], 0, v[124:125]
	v_cvt_pk_bf16_f32 v24, v33, v34
	v_cvt_pk_bf16_f32 v25, v30, v31
	v_cvt_pk_bf16_f32 v27, v37, v27
	global_store_dwordx4 v[28:29], v[24:27], off
	v_fmamk_f32 v21, v21, 0xbfb8aa3b, v147
	v_fmamk_f32 v22, v22, 0xbfb8aa3b, v144
	v_rcp_f32_e32 v24, v16
	v_fmamk_f32 v16, v17, 0xbfb8aa3b, v143
	v_exp_f32_e32 v16, v16
	v_fmamk_f32 v23, v23, 0xbfb8aa3b, v145
	v_exp_f32_e32 v20, v20
	v_exp_f32_e32 v21, v21
	v_add_f32_e32 v16, 1.0, v16
	v_rcp_f32_e32 v25, v16
	v_fmamk_f32 v16, v18, 0xbfb8aa3b, v140
	v_exp_f32_e32 v16, v16
	v_exp_f32_e32 v22, v22
	v_exp_f32_e32 v23, v23
	v_add_f32_e32 v20, 1.0, v20
	v_add_f32_e32 v16, 1.0, v16
	v_rcp_f32_e32 v26, v16
	v_fmamk_f32 v16, v19, 0xbfb8aa3b, v141
	v_exp_f32_e32 v16, v16
	v_add_f32_e32 v21, 1.0, v21
	v_add_f32_e32 v22, 1.0, v22
	v_add_f32_e32 v23, 1.0, v23
	v_add_f32_e32 v16, 1.0, v16
	v_rcp_f32_e32 v20, v20
	v_rcp_f32_e32 v21, v21
	v_rcp_f32_e32 v22, v22
	v_rcp_f32_e32 v23, v23
	v_rcp_f32_e32 v19, v16
	v_cvt_pk_bf16_f32 v16, v20, v21
	v_cvt_pk_bf16_f32 v18, v24, v25
	v_cvt_pk_bf16_f32 v17, v22, v23
	v_cvt_pk_bf16_f32 v19, v26, v19
	v_fmac_f32_e32 v155, 0xbfb8aa3b, v13
	v_fmac_f32_e32 v151, 0xbfb8aa3b, v9
	global_store_dwordx4 v[28:29], v[16:19], off offset:256
	v_fmac_f32_e32 v153, 0xbfb8aa3b, v15
	v_fmac_f32_e32 v149, 0xbfb8aa3b, v11
	v_rcp_f32_e32 v17, v12
	v_exp_f32_e32 v12, v155
	v_rcp_f32_e32 v19, v8
	v_exp_f32_e32 v8, v151
	v_fmamk_f32 v0, v0, 0xbfb8aa3b, v142
	v_add_f32_e32 v12, 1.0, v12
	v_rcp_f32_e32 v18, v12
	v_add_f32_e32 v8, 1.0, v8
	v_fmamk_f32 v12, v14, 0xbfb8aa3b, v152
	v_rcp_f32_e32 v20, v8
	v_fmamk_f32 v8, v10, 0xbfb8aa3b, v148
	v_exp_f32_e32 v12, v12
	v_exp_f32_e32 v8, v8
	v_exp_f32_e32 v0, v0
	v_add_u32_e32 v16, 0xb0, v160
	v_add_f32_e32 v12, 1.0, v12
	v_add_f32_e32 v8, 1.0, v8
	v_rcp_f32_e32 v14, v12
	v_exp_f32_e32 v12, v153
	v_rcp_f32_e32 v21, v8
	v_exp_f32_e32 v8, v149
	v_cvt_pk_bf16_f32 v10, v19, v20
	v_add_f32_e32 v12, 1.0, v12
	v_rcp_f32_e32 v15, v12
	v_add_f32_e32 v8, 1.0, v8
	v_rcp_f32_e32 v11, v8
	v_mad_i64_i32 v[8:9], s[0:1], v16, s33, v[122:123]
	v_lshl_add_u64 v[12:13], v[8:9], 0, v[124:125]
	v_cvt_pk_bf16_f32 v8, v17, v18
	v_cvt_pk_bf16_f32 v9, v14, v15
	v_cvt_pk_bf16_f32 v11, v21, v11
	v_add_f32_e32 v0, 1.0, v0
	v_fmac_f32_e32 v143, 0xbfb8aa3b, v1
	global_store_dwordx4 v[12:13], v[8:11], off
	v_fmamk_f32 v4, v4, 0xbfb8aa3b, v146
	v_fmac_f32_e32 v147, 0xbfb8aa3b, v5
	v_rcp_f32_e32 v8, v0
	v_exp_f32_e32 v0, v143
	v_fmamk_f32 v6, v6, 0xbfb8aa3b, v144
	v_fmac_f32_e32 v145, 0xbfb8aa3b, v7
	v_fmac_f32_e32 v141, 0xbfb8aa3b, v3
	v_add_f32_e32 v0, 1.0, v0
	v_rcp_f32_e32 v9, v0
	v_fmamk_f32 v0, v2, 0xbfb8aa3b, v140
	v_exp_f32_e32 v0, v0
	v_exp_f32_e32 v4, v4
	v_exp_f32_e32 v5, v147
	v_exp_f32_e32 v6, v6
	v_add_f32_e32 v0, 1.0, v0
	v_exp_f32_e32 v7, v145
	v_rcp_f32_e32 v10, v0
	v_exp_f32_e32 v0, v141
	v_add_f32_e32 v4, 1.0, v4
	v_add_f32_e32 v5, 1.0, v5
	v_add_f32_e32 v6, 1.0, v6
	v_add_f32_e32 v7, 1.0, v7
	v_add_f32_e32 v0, 1.0, v0
	v_rcp_f32_e32 v4, v4
	v_rcp_f32_e32 v5, v5
	v_rcp_f32_e32 v6, v6
	v_rcp_f32_e32 v7, v7
	v_rcp_f32_e32 v3, v0
	v_cvt_pk_bf16_f32 v0, v4, v5
	v_cvt_pk_bf16_f32 v2, v8, v9
	v_cvt_pk_bf16_f32 v1, v6, v7
	v_cvt_pk_bf16_f32 v3, v10, v3
	global_store_dwordx4 v[12:13], v[0:3], off offset:256
	s_mov_b32 s1, s10
	s_mov_b32 s18, s12
	s_cbranch_vccz .LBB0_903
	s_waitcnt vmcnt(0)
	s_cmpk_gt_u32 s29, 0xff
	s_cbranch_scc1 .LBB0_910
	s_barrier

; #define PG8_STAGE(bufoff, gbase, voff) do { _Pragma("unroll") for (int _i = 0; _i < 2; ++_i) \
;     __builtin_amdgcn_global_load_lds((const unsigned*)((const char*)(gbase) + (voff)[_i]), (LAS unsigned*)(lds + (bufoff) + ldsw + _i * 8192), 16, 0, 0); } while (0)
; #define PG8_LDA(dst, b, h) do { _Pragma("unroll") for (int m = 0; m < 4; ++m) _Pragma("unroll") for (int k = 0; k < 2; ++k) dst[m][k] = *(const LAS bf16x8*)(lds + PG8_SA(b, h) + aoff + m * 2048 + k * 1024); } while (0)
; #define PG8_LDB(dst, b, h) do { _Pragma("unroll") for (int n = 0; n < 2; ++n) _Pragma("unroll") for (int k = 0; k < 2; ++k) dst[n][k] = *(const LAS bf16x8*)(lds + PG8_SB(b, h) + boff + n * 2048 + k * 1024); } while (0)
; #define PG8_MMA(ai, bj, At, Bt) do { __builtin_amdgcn_s_setprio(1); _Pragma("unroll") for (int m = 0; m < 4; ++m) _Pragma("unroll") for (int n = 0; n < 2; ++n) _Pragma("unroll") for (int k = 0; k < 2; ++k) \
;     acc[ai][bj][m][n] = __builtin_amdgcn_mfma_f32_16x16x32_bf16(Bt[n][k], At[m][k], acc[ai][bj][m][n], 0, 0, 0); __builtin_amdgcn_s_setprio(0); } while (0)
; #define PG8_WAIT_L(n) asm volatile("s_waitcnt lgkmcnt(" #n ")" ::: "memory")
; #define PG8_BAR __builtin_amdgcn_s_barrier()
; template <class Epi>
; __device__ __forceinline__ void gemm_phase(LAS unsigned char* lds, const Gemm g, const StaticOrder& S, const Epi& E, int wv0) {
;     ...
;     const bool has_next = S.next(ui + 1, nxt);
;     const char* nA = has_next ? (const char*)g.A + (size_t)nxt.pm * tstepA : cA; const char* nB = has_next ? (const char*)g.Bt + (size_t)nxt.pn * tstepB : cB;
;     for (int t = 0; t < nt; t += 2) {
;       const bool last = (t == nt - 2);
;       const char* a1 = cA + (size_t)(t + 1) * kstep;
;       const char* a2 = last ? nA : cA + (size_t)(t + 2) * kstep; const char* b2 = last ? nB : cB + (size_t)(t + 2) * kstep;
;       const char* a3 = a2 + kstep; const char* b3 = b2 + kstep;
;       PG8_LDB(B0, 0, 0); PG8_SCHED; PG8_LDA(At, 0, 0); PG8_STAGE(PG8_SA(1, 1), a1 + hstepA, voffA);
;       PG8_WAIT_L(8); PG8_BAR; PG8_WAIT_L(0); PG8_MMA(0, 0, At, B0); PG8_BAR; PG8_SCHED;
;     ...
; #pragma unroll
;     for (int a = 0; a < 2; ++a)
; #pragma unroll
;       for (int b = 0; b < 2; ++b)
; #pragma unroll
;         for (int m = 0; m < 4; ++m)
; #pragma unroll
;           for (int n = 0; n < 2; ++n) acc[a][b][m][n] = (f32x4){0.f, 0.f, 0.f, 0.f};
.LBB0_980:
	s_ashr_i32 s13, s12, 31
	s_lshl_b64 s[16:17], s[12:13], 19
	s_add_u32 s16, s31, s16
	s_addc_u32 s17, s34, s17
	s_and_b64 s[4:5], s[4:5], exec
	s_cselect_b32 s13, s17, s21
	s_cselect_b32 s46, s16, s20
	s_add_u32 s47, s20, 0x100
	v_mov_b32_e32 v0, 0
	s_addc_u32 s48, s21, 0
	s_mov_b32 s49, -2
	v_mov_b32_e32 v1, v0
	v_mov_b32_e32 v2, v0
	v_mov_b32_e32 v3, v0
	v_mov_b32_e32 v4, v0
	v_mov_b32_e32 v5, v0
	v_mov_b32_e32 v6, v0
	v_mov_b32_e32 v7, v0
	v_mov_b32_e32 v12, v0
	v_mov_b32_e32 v13, v0
	v_mov_b32_e32 v14, v0
	v_mov_b32_e32 v15, v0
	v_mov_b32_e32 v20, v0
	v_mov_b32_e32 v21, v0
	v_mov_b32_e32 v22, v0
	v_mov_b32_e32 v23, v0
	v_mov_b32_e32 v28, v0
	v_mov_b32_e32 v29, v0
	v_mov_b32_e32 v30, v0
	v_mov_b32_e32 v31, v0
	v_mov_b32_e32 v36, v0
	v_mov_b32_e32 v37, v0
	v_mov_b32_e32 v38, v0
	v_mov_b32_e32 v39, v0
	v_mov_b32_e32 v44, v0
	v_mov_b32_e32 v45, v0
	v_mov_b32_e32 v46, v0
	v_mov_b32_e32 v47, v0
	v_mov_b32_e32 v52, v0
	v_mov_b32_e32 v53, v0
	v_mov_b32_e32 v54, v0
	v_mov_b32_e32 v55, v0
	v_mov_b32_e32 v8, v0
	v_mov_b32_e32 v9, v0
	v_mov_b32_e32 v10, v0
	v_mov_b32_e32 v11, v0
	v_mov_b32_e32 v16, v0
	v_mov_b32_e32 v17, v0
	v_mov_b32_e32 v18, v0
	v_mov_b32_e32 v19, v0
	v_mov_b32_e32 v24, v0
	v_mov_b32_e32 v25, v0
	v_mov_b32_e32 v26, v0
	v_mov_b32_e32 v27, v0
	v_mov_b32_e32 v32, v0
	v_mov_b32_e32 v33, v0
	v_mov_b32_e32 v34, v0
	v_mov_b32_e32 v35, v0
	v_mov_b32_e32 v40, v0
	v_mov_b32_e32 v41, v0
	v_mov_b32_e32 v42, v0
	v_mov_b32_e32 v43, v0
	v_mov_b32_e32 v48, v0
	v_mov_b32_e32 v49, v0
	v_mov_b32_e32 v50, v0
	v_mov_b32_e32 v51, v0
	v_mov_b32_e32 v56, v0
	v_mov_b32_e32 v57, v0
	v_mov_b32_e32 v58, v0
	v_mov_b32_e32 v59, v0
	v_mov_b32_e32 v60, v0
	v_mov_b32_e32 v61, v0
	v_mov_b32_e32 v62, v0
	v_mov_b32_e32 v63, v0
	v_mov_b32_e32 v64, v0
	v_mov_b32_e32 v65, v0
	v_mov_b32_e32 v66, v0
	v_mov_b32_e32 v67, v0
	v_mov_b32_e32 v68, v0
	v_mov_b32_e32 v69, v0
	v_mov_b32_e32 v70, v0
	v_mov_b32_e32 v71, v0
	s_waitcnt vmcnt(0)
	v_mov_b32_e32 v76, v0
	v_mov_b32_e32 v77, v0
	v_mov_b32_e32 v78, v0
	v_mov_b32_e32 v79, v0
	v_mov_b32_e32 v84, v0
	v_mov_b32_e32 v85, v0
	v_mov_b32_e32 v86, v0
	v_mov_b32_e32 v87, v0
	v_mov_b32_e32 v98, v0
	v_mov_b32_e32 v99, v0
	v_mov_b32_e32 v100, v0
	v_mov_b32_e32 v101, v0
	v_mov_b32_e32 v102, v0
	v_mov_b32_e32 v103, v0
	v_mov_b32_e32 v104, v0
	v_mov_b32_e32 v105, v0
	v_mov_b32_e32 v106, v0
	v_mov_b32_e32 v107, v0
	v_mov_b32_e32 v108, v0
	v_mov_b32_e32 v109, v0
	v_mov_b32_e32 v114, v0
	v_mov_b32_e32 v115, v0
	v_mov_b32_e32 v116, v0
	v_mov_b32_e32 v117, v0
	v_mov_b32_e32 v72, v0
	v_mov_b32_e32 v73, v0
	v_mov_b32_e32 v74, v0
	v_mov_b32_e32 v75, v0
	v_mov_b32_e32 v80, v0
	v_mov_b32_e32 v81, v0
	v_mov_b32_e32 v82, v0
	v_mov_b32_e32 v83, v0
	v_mov_b32_e32 v88, v0
	v_mov_b32_e32 v89, v0
	v_mov_b32_e32 v90, v0
	v_mov_b32_e32 v91, v0
	v_mov_b32_e32 v92, v0
	v_mov_b32_e32 v93, v0
	v_mov_b32_e32 v94, v0
	v_mov_b32_e32 v95, v0
	v_mov_b32_e32 v110, v0
	v_mov_b32_e32 v111, v0
	v_mov_b32_e32 v112, v0
	v_mov_b32_e32 v113, v0
	v_mov_b32_e32 v118, v0
	v_mov_b32_e32 v119, v0
	v_mov_b32_e32 v120, v0
	v_mov_b32_e32 v121, v0
	v_mov_b32_e32 v122, v0
	v_mov_b32_e32 v123, v0
	v_mov_b32_e32 v124, v0
	v_mov_b32_e32 v125, v0
	v_mov_b32_e32 v126, v0
	v_mov_b32_e32 v127, v0
	v_mov_b32_e32 v128, v0
	v_mov_b32_e32 v129, v0
	s_cmp_lt_u32 s53, 4
	s_cbranch_scc1 .Lgprio4
	s_setprio 1
.Lgprio4:
.LBB0_981:
	s_add_u32 s4, s18, 0x100
	s_addc_u32 s5, s19, 0
	s_add_i32 s0, 0, 0x10000
	v_add_u32_e32 v142, s0, v173
	ds_read_b128 v[130:133], v142
	ds_read_b128 v[134:137], v142 offset:1024
	ds_read_b128 v[138:141], v142 offset:2048
	ds_read_b128 v[142:145], v142 offset:3072
	s_cmp_eq_u32 s49, 12
	s_cselect_b32 s23, s15, s5
	s_cselect_b32 s22, s14, s4
	s_cselect_b32 s21, s13, s48
	s_cselect_b32 s20, s46, s47
	v_lshl_add_u64 v[192:193], s[18:19], 0, v[156:157]
	s_add_i32 m0, s36, 0xc000
	ds_read_b128 v[146:149], v175
	ds_read_b128 v[160:163], v175 offset:1024
	ds_read_b128 v[164:167], v175 offset:2048
	ds_read_b128 v[168:171], v175 offset:3072
	ds_read_b128 v[176:179], v175 offset:4096
	ds_read_b128 v[180:183], v175 offset:5120
	ds_read_b128 v[184:187], v175 offset:6144
	ds_read_b128 v[188:191], v175 offset:7168
	global_load_lds_dwordx4 v[192:193], off
	v_lshl_add_u64 v[192:193], s[18:19], 0, v[158:159]
	s_add_i32 m0, s36, 0xe000
	s_nop 0
	global_load_lds_dwordx4 v[192:193], off
	s_waitcnt lgkmcnt(8)
	s_barrier
	s_waitcnt lgkmcnt(0)
	s_waitcnt lgkmcnt(0)
	v_mfma_f32_16x16x32_bf16 v[126:129], v[130:133], v[146:149], v[126:129]
	v_mfma_f32_16x16x32_bf16 v[122:125], v[138:141], v[146:149], v[122:125]
	v_mfma_f32_16x16x32_bf16 v[118:121], v[130:133], v[164:167], v[118:121]
	v_mfma_f32_16x16x32_bf16 v[110:113], v[138:141], v[164:167], v[110:113]
	v_mfma_f32_16x16x32_bf16 v[92:95], v[130:133], v[176:179], v[92:95]
	v_mfma_f32_16x16x32_bf16 v[88:91], v[138:141], v[176:179], v[88:91]
	v_mfma_f32_16x16x32_bf16 v[80:83], v[130:133], v[184:187], v[80:83]
	v_mfma_f32_16x16x32_bf16 v[72:75], v[138:141], v[184:187], v[72:75]
	v_mfma_f32_16x16x32_bf16 v[126:129], v[134:137], v[160:163], v[126:129]
	v_mfma_f32_16x16x32_bf16 v[122:125], v[142:145], v[160:163], v[122:125]
	v_mfma_f32_16x16x32_bf16 v[118:121], v[134:137], v[168:171], v[118:121]
	v_mfma_f32_16x16x32_bf16 v[110:113], v[142:145], v[168:171], v[110:113]
	v_mfma_f32_16x16x32_bf16 v[92:95], v[134:137], v[180:183], v[92:95]
	v_mfma_f32_16x16x32_bf16 v[88:91], v[142:145], v[180:183], v[88:91]
	v_mfma_f32_16x16x32_bf16 v[80:83], v[134:137], v[188:191], v[80:83]
	v_mfma_f32_16x16x32_bf16 v[72:75], v[142:145], v[188:191], v[72:75]
	s_barrier
; #define PG8_STAGE(bufoff, gbase, voff) do { _Pragma("unroll") for (int _i = 0; _i < 2; ++_i) \
;     __builtin_amdgcn_global_load_lds((const unsigned*)((const char*)(gbase) + (voff)[_i]), (LAS unsigned*)(lds + (bufoff) + ldsw + _i * 8192), 16, 0, 0); } while (0)
; #define PG8_LDA(dst, b, h) do { _Pragma("unroll") for (int m = 0; m < 4; ++m) _Pragma("unroll") for (int k = 0; k < 2; ++k) dst[m][k] = *(const LAS bf16x8*)(lds + PG8_SA(b, h) + aoff + m * 2048 + k * 1024); } while (0)
; #define PG8_LDB(dst, b, h) do { _Pragma("unroll") for (int n = 0; n < 2; ++n) _Pragma("unroll") for (int k = 0; k < 2; ++k) dst[n][k] = *(const LAS bf16x8*)(lds + PG8_SB(b, h) + boff + n * 2048 + k * 1024); } while (0)
; #define PG8_MMA(ai, bj, At, Bt) do { __builtin_amdgcn_s_setprio(1); _Pragma("unroll") for (int m = 0; m < 4; ++m) _Pragma("unroll") for (int n = 0; n < 2; ++n) _Pragma("unroll") for (int k = 0; k < 2; ++k) \
;     acc[ai][bj][m][n] = __builtin_amdgcn_mfma_f32_16x16x32_bf16(Bt[n][k], At[m][k], acc[ai][bj][m][n], 0, 0, 0); __builtin_amdgcn_s_setprio(0); } while (0)
; #define PG8_WAIT_V(n) asm volatile("s_waitcnt vmcnt(" #n ")" ::: "memory")
; #define PG8_WAIT_L(n) asm volatile("s_waitcnt lgkmcnt(" #n ")" ::: "memory")
; #define PG8_BAR __builtin_amdgcn_s_barrier()
; #define PG8_SCHED __builtin_amdgcn_sched_barrier(0)
; template <class Epi>
; __device__ __forceinline__ void gemm_phase(LAS unsigned char* lds, const Gemm g, const StaticOrder& S, const Epi& E, int wv0) {
;     ...
;       PG8_LDB(B1, 0, 1); PG8_STAGE(PG8_SB(0, 0), b2, voffB);
;       PG8_BAR; PG8_WAIT_L(0); PG8_MMA(0, 1, At, B1); PG8_BAR;
;       PG8_LDA(At, 0, 1); PG8_STAGE(PG8_SA(0, 0), a2, voffA);
;       PG8_BAR; PG8_WAIT_L(0); PG8_MMA(1, 0, At, B0); PG8_BAR; PG8_SCHED;
;       PG8_STAGE(PG8_SB(0, 1), b2 + hstepB, voffB);
;       PG8_WAIT_V(6); PG8_BAR; PG8_MMA(1, 1, At, B1); PG8_BAR;
;       PG8_LDB(B0, 1, 0); PG8_SCHED; PG8_LDA(At, 1, 0); PG8_STAGE(PG8_SA(0, 1), a2 + hstepA, voffA);
;       PG8_WAIT_L(8); PG8_BAR; PG8_WAIT_L(0); PG8_MMA(0, 0, At, B0); PG8_BAR; PG8_SCHED;
	s_add_i32 s50, 0, 0x14000
	s_add_i32 s0, s0, s35
	v_add_u32_e32 v204, s50, v173
	v_lshl_add_u64 v[208:209], s[20:21], 0, v[96:97]
	s_mov_b32 m0, s0
	ds_read_b128 v[192:195], v204
	ds_read_b128 v[196:199], v204 offset:1024
	ds_read_b128 v[200:203], v204 offset:2048
	ds_read_b128 v[204:207], v204 offset:3072
	global_load_lds_dwordx4 v[208:209], off
	v_lshl_add_u64 v[210:211], s[20:21], 0, v[154:155]
	s_add_i32 m0, s0, 0x2000
	s_nop 0
	global_load_lds_dwordx4 v[210:211], off
	s_barrier
	s_waitcnt lgkmcnt(0)
	s_waitcnt lgkmcnt(0)
	v_mfma_f32_16x16x32_bf16 v[114:117], v[192:195], v[146:149], v[114:117]
	v_mfma_f32_16x16x32_bf16 v[106:109], v[200:203], v[146:149], v[106:109]
	v_mfma_f32_16x16x32_bf16 v[102:105], v[192:195], v[164:167], v[102:105]
	v_mfma_f32_16x16x32_bf16 v[98:101], v[200:203], v[164:167], v[98:101]
	v_mfma_f32_16x16x32_bf16 v[84:87], v[192:195], v[176:179], v[84:87]
	v_mfma_f32_16x16x32_bf16 v[76:79], v[200:203], v[176:179], v[76:79]
	v_mfma_f32_16x16x32_bf16 v[68:71], v[192:195], v[184:187], v[68:71]
	v_mfma_f32_16x16x32_bf16 v[64:67], v[200:203], v[184:187], v[64:67]
	v_mfma_f32_16x16x32_bf16 v[114:117], v[196:199], v[160:163], v[114:117]
	v_mfma_f32_16x16x32_bf16 v[106:109], v[204:207], v[160:163], v[106:109]
	v_mfma_f32_16x16x32_bf16 v[102:105], v[196:199], v[168:171], v[102:105]
	v_mfma_f32_16x16x32_bf16 v[98:101], v[204:207], v[168:171], v[98:101]
	v_mfma_f32_16x16x32_bf16 v[84:87], v[196:199], v[180:183], v[84:87]
	v_mfma_f32_16x16x32_bf16 v[76:79], v[204:207], v[180:183], v[76:79]
	v_mfma_f32_16x16x32_bf16 v[68:71], v[196:199], v[188:191], v[68:71]
	v_mfma_f32_16x16x32_bf16 v[64:67], v[204:207], v[188:191], v[64:67]
	s_mov_b32 m0, s36
	v_lshl_add_u64 v[212:213], s[22:23], 0, v[150:151]
	s_barrier
	ds_read_b128 v[146:149], v175 offset:16384
	ds_read_b128 v[160:163], v175 offset:17408
	ds_read_b128 v[164:167], v175 offset:18432
	ds_read_b128 v[168:171], v175 offset:19456
	ds_read_b128 v[176:179], v175 offset:20480
	ds_read_b128 v[180:183], v175 offset:21504
	ds_read_b128 v[184:187], v175 offset:22528
	ds_read_b128 v[188:191], v175 offset:23552
	global_load_lds_dwordx4 v[212:213], off
	v_lshl_add_u64 v[214:215], s[22:23], 0, v[152:153]
	s_mov_b32 m0, s37
	s_nop 0
	global_load_lds_dwordx4 v[214:215], off
	s_barrier
	s_waitcnt lgkmcnt(0)
	s_waitcnt lgkmcnt(0)
	v_mfma_f32_16x16x32_bf16 v[60:63], v[130:133], v[146:149], v[60:63]
	v_mfma_f32_16x16x32_bf16 v[56:59], v[138:141], v[146:149], v[56:59]
	v_mfma_f32_16x16x32_bf16 v[48:51], v[130:133], v[164:167], v[48:51]
	v_mfma_f32_16x16x32_bf16 v[40:43], v[138:141], v[164:167], v[40:43]
	v_mfma_f32_16x16x32_bf16 v[32:35], v[130:133], v[176:179], v[32:35]
	v_mfma_f32_16x16x32_bf16 v[24:27], v[138:141], v[176:179], v[24:27]
	v_mfma_f32_16x16x32_bf16 v[16:19], v[130:133], v[184:187], v[16:19]
	v_mfma_f32_16x16x32_bf16 v[8:11], v[138:141], v[184:187], v[8:11]
	v_mfma_f32_16x16x32_bf16 v[60:63], v[134:137], v[160:163], v[60:63]
	v_mfma_f32_16x16x32_bf16 v[56:59], v[142:145], v[160:163], v[56:59]
	v_mfma_f32_16x16x32_bf16 v[48:51], v[134:137], v[168:171], v[48:51]
	v_mfma_f32_16x16x32_bf16 v[40:43], v[142:145], v[168:171], v[40:43]
	v_mfma_f32_16x16x32_bf16 v[32:35], v[134:137], v[180:183], v[32:35]
	v_mfma_f32_16x16x32_bf16 v[24:27], v[142:145], v[180:183], v[24:27]
	v_mfma_f32_16x16x32_bf16 v[16:19], v[134:137], v[188:191], v[16:19]
	v_mfma_f32_16x16x32_bf16 v[8:11], v[142:145], v[188:191], v[8:11]
	s_barrier
	s_add_u32 s18, s20, 0x40000
	s_addc_u32 s19, s21, 0
	s_add_i32 s0, s50, s35
	v_lshl_add_u64 v[130:131], s[18:19], 0, v[96:97]
	s_mov_b32 m0, s0
	s_nop 0
	global_load_lds_dwordx4 v[130:131], off
	v_lshl_add_u64 v[130:131], s[18:19], 0, v[154:155]
	s_add_i32 m0, s0, 0x2000
	s_nop 0
	global_load_lds_dwordx4 v[130:131], off
	s_waitcnt vmcnt(6)
	s_barrier
	v_mfma_f32_16x16x32_bf16 v[52:55], v[192:195], v[146:149], v[52:55]
	v_mfma_f32_16x16x32_bf16 v[44:47], v[200:203], v[146:149], v[44:47]
	v_mfma_f32_16x16x32_bf16 v[36:39], v[192:195], v[164:167], v[36:39]
	v_mfma_f32_16x16x32_bf16 v[28:31], v[200:203], v[164:167], v[28:31]
	v_mfma_f32_16x16x32_bf16 v[20:23], v[192:195], v[176:179], v[20:23]
	v_mfma_f32_16x16x32_bf16 v[12:15], v[200:203], v[176:179], v[12:15]
	v_mfma_f32_16x16x32_bf16 v[4:7], v[192:195], v[184:187], v[4:7]
	v_mfma_f32_16x16x32_bf16 v[0:3], v[200:203], v[184:187], v[0:3]
	v_mfma_f32_16x16x32_bf16 v[52:55], v[196:199], v[160:163], v[52:55]
	v_mfma_f32_16x16x32_bf16 v[44:47], v[204:207], v[160:163], v[44:47]
	v_mfma_f32_16x16x32_bf16 v[36:39], v[196:199], v[168:171], v[36:39]
	v_mfma_f32_16x16x32_bf16 v[28:31], v[204:207], v[168:171], v[28:31]
	v_mfma_f32_16x16x32_bf16 v[20:23], v[196:199], v[180:183], v[20:23]
	v_mfma_f32_16x16x32_bf16 v[12:15], v[204:207], v[180:183], v[12:15]
	v_mfma_f32_16x16x32_bf16 v[4:7], v[196:199], v[188:191], v[4:7]
	v_mfma_f32_16x16x32_bf16 v[0:3], v[204:207], v[188:191], v[0:3]
	s_add_i32 s0, 0, 0x18000
	v_add_u32_e32 v142, s0, v173
	s_barrier
	ds_read_b128 v[130:133], v142
	ds_read_b128 v[134:137], v142 offset:1024
	ds_read_b128 v[138:141], v142 offset:2048
	ds_read_b128 v[142:145], v142 offset:3072
	s_add_u32 s18, s22, 0x114000
	s_addc_u32 s19, s23, 0
	s_mov_b32 m0, s38
	v_lshl_add_u64 v[192:193], s[18:19], 0, v[150:151]
	ds_read_b128 v[146:149], v175 offset:32768
	ds_read_b128 v[160:163], v175 offset:33792
	ds_read_b128 v[164:167], v175 offset:34816
	ds_read_b128 v[168:171], v175 offset:35840
	ds_read_b128 v[176:179], v175 offset:36864
	ds_read_b128 v[180:183], v175 offset:37888
	ds_read_b128 v[184:187], v175 offset:38912
	ds_read_b128 v[188:191], v175 offset:39936
	global_load_lds_dwordx4 v[192:193], off
	v_lshl_add_u64 v[192:193], s[18:19], 0, v[152:153]
	s_mov_b32 m0, s39
	s_nop 0
	global_load_lds_dwordx4 v[192:193], off
	s_waitcnt lgkmcnt(8)
	s_barrier
; #define PG8_STAGE(bufoff, gbase, voff) do { _Pragma("unroll") for (int _i = 0; _i < 2; ++_i) \
;     __builtin_amdgcn_global_load_lds((const unsigned*)((const char*)(gbase) + (voff)[_i]), (LAS unsigned*)(lds + (bufoff) + ldsw + _i * 8192), 16, 0, 0); } while (0)
; #define PG8_LDA(dst, b, h) do { _Pragma("unroll") for (int m = 0; m < 4; ++m) _Pragma("unroll") for (int k = 0; k < 2; ++k) dst[m][k] = *(const LAS bf16x8*)(lds + PG8_SA(b, h) + aoff + m * 2048 + k * 1024); } while (0)
; #define PG8_LDB(dst, b, h) do { _Pragma("unroll") for (int n = 0; n < 2; ++n) _Pragma("unroll") for (int k = 0; k < 2; ++k) dst[n][k] = *(const LAS bf16x8*)(lds + PG8_SB(b, h) + boff + n * 2048 + k * 1024); } while (0)
; #define PG8_MMA(ai, bj, At, Bt) do { __builtin_amdgcn_s_setprio(1); _Pragma("unroll") for (int m = 0; m < 4; ++m) _Pragma("unroll") for (int n = 0; n < 2; ++n) _Pragma("unroll") for (int k = 0; k < 2; ++k) \
;     acc[ai][bj][m][n] = __builtin_amdgcn_mfma_f32_16x16x32_bf16(Bt[n][k], At[m][k], acc[ai][bj][m][n], 0, 0, 0); __builtin_amdgcn_s_setprio(0); } while (0)
; #define PG8_WAIT_V(n) asm volatile("s_waitcnt vmcnt(" #n ")" ::: "memory")
; #define PG8_WAIT_L(n) asm volatile("s_waitcnt lgkmcnt(" #n ")" ::: "memory")
; #define PG8_BAR __builtin_amdgcn_s_barrier()
; #define PG8_SCHED __builtin_amdgcn_sched_barrier(0)
; template <class Epi>
; __device__ __forceinline__ void gemm_phase(LAS unsigned char* lds, const Gemm g, const StaticOrder& S, const Epi& E, int wv0) {
;     ...
;       PG8_WAIT_L(8); PG8_BAR; PG8_WAIT_L(0); PG8_MMA(0, 0, At, B0); PG8_BAR; PG8_SCHED;
;       PG8_LDB(B1, 1, 1); PG8_STAGE(PG8_SB(1, 0), b3, voffB);
;       PG8_BAR; PG8_WAIT_L(0); PG8_MMA(0, 1, At, B1); PG8_BAR;
;       PG8_LDA(At, 1, 1); PG8_STAGE(PG8_SA(1, 0), a3, voffA);
;       PG8_BAR; PG8_WAIT_L(0); PG8_MMA(1, 0, At, B0); PG8_BAR; PG8_SCHED;
;       PG8_STAGE(PG8_SB(1, 1), b3 + hstepB, voffB);
;       PG8_WAIT_V(6); PG8_BAR; PG8_MMA(1, 1, At, B1); PG8_BAR;
	s_waitcnt lgkmcnt(0)
	s_waitcnt lgkmcnt(0)
	v_mfma_f32_16x16x32_bf16 v[126:129], v[130:133], v[146:149], v[126:129]
	v_mfma_f32_16x16x32_bf16 v[122:125], v[138:141], v[146:149], v[122:125]
	v_mfma_f32_16x16x32_bf16 v[118:121], v[130:133], v[164:167], v[118:121]
	v_mfma_f32_16x16x32_bf16 v[110:113], v[138:141], v[164:167], v[110:113]
	v_mfma_f32_16x16x32_bf16 v[92:95], v[130:133], v[176:179], v[92:95]
	v_mfma_f32_16x16x32_bf16 v[88:91], v[138:141], v[176:179], v[88:91]
	v_mfma_f32_16x16x32_bf16 v[80:83], v[130:133], v[184:187], v[80:83]
	v_mfma_f32_16x16x32_bf16 v[72:75], v[138:141], v[184:187], v[72:75]
	v_mfma_f32_16x16x32_bf16 v[126:129], v[134:137], v[160:163], v[126:129]
	v_mfma_f32_16x16x32_bf16 v[122:125], v[142:145], v[160:163], v[122:125]
	v_mfma_f32_16x16x32_bf16 v[118:121], v[134:137], v[168:171], v[118:121]
	v_mfma_f32_16x16x32_bf16 v[110:113], v[142:145], v[168:171], v[110:113]
	v_mfma_f32_16x16x32_bf16 v[92:95], v[134:137], v[180:183], v[92:95]
	v_mfma_f32_16x16x32_bf16 v[88:91], v[142:145], v[180:183], v[88:91]
	v_mfma_f32_16x16x32_bf16 v[80:83], v[134:137], v[188:191], v[80:83]
	v_mfma_f32_16x16x32_bf16 v[72:75], v[142:145], v[188:191], v[72:75]
	s_barrier
	s_add_i32 s22, 0, 0x1c000
	s_add_i32 s0, s0, s35
	v_add_u32_e32 v204, s22, v173
	v_lshl_add_u64 v[208:209], v[208:209], 0, s[72:73]
	s_mov_b32 m0, s0
	ds_read_b128 v[192:195], v204
	ds_read_b128 v[196:199], v204 offset:1024
	ds_read_b128 v[200:203], v204 offset:2048
	ds_read_b128 v[204:207], v204 offset:3072
	global_load_lds_dwordx4 v[208:209], off
	v_lshl_add_u64 v[208:209], v[210:211], 0, s[72:73]
	s_add_i32 m0, s0, 0x2000
	s_nop 0
	global_load_lds_dwordx4 v[208:209], off
	s_barrier
	s_waitcnt lgkmcnt(0)
	s_waitcnt lgkmcnt(0)
	v_mfma_f32_16x16x32_bf16 v[114:117], v[192:195], v[146:149], v[114:117]
	v_mfma_f32_16x16x32_bf16 v[106:109], v[200:203], v[146:149], v[106:109]
	v_mfma_f32_16x16x32_bf16 v[102:105], v[192:195], v[164:167], v[102:105]
	v_mfma_f32_16x16x32_bf16 v[98:101], v[200:203], v[164:167], v[98:101]
	v_mfma_f32_16x16x32_bf16 v[84:87], v[192:195], v[176:179], v[84:87]
	v_mfma_f32_16x16x32_bf16 v[76:79], v[200:203], v[176:179], v[76:79]
	v_mfma_f32_16x16x32_bf16 v[68:71], v[192:195], v[184:187], v[68:71]
	v_mfma_f32_16x16x32_bf16 v[64:67], v[200:203], v[184:187], v[64:67]
	v_mfma_f32_16x16x32_bf16 v[114:117], v[196:199], v[160:163], v[114:117]
	v_mfma_f32_16x16x32_bf16 v[106:109], v[204:207], v[160:163], v[106:109]
	v_mfma_f32_16x16x32_bf16 v[102:105], v[196:199], v[168:171], v[102:105]
	v_mfma_f32_16x16x32_bf16 v[98:101], v[204:207], v[168:171], v[98:101]
	v_mfma_f32_16x16x32_bf16 v[84:87], v[196:199], v[180:183], v[84:87]
	v_mfma_f32_16x16x32_bf16 v[76:79], v[204:207], v[180:183], v[76:79]
	v_mfma_f32_16x16x32_bf16 v[68:71], v[196:199], v[188:191], v[68:71]
	v_mfma_f32_16x16x32_bf16 v[64:67], v[204:207], v[188:191], v[64:67]
	s_mov_b32 m0, s40
	v_lshl_add_u64 v[208:209], v[212:213], 0, s[72:73]
	s_barrier
	ds_read_b128 v[146:149], v175 offset:49152
	ds_read_b128 v[160:163], v175 offset:50176
	ds_read_b128 v[164:167], v175 offset:51200
	ds_read_b128 v[168:171], v175 offset:52224
	ds_read_b128 v[176:179], v175 offset:53248
	ds_read_b128 v[180:183], v175 offset:54272
	ds_read_b128 v[184:187], v175 offset:55296
	ds_read_b128 v[188:191], v175 offset:56320
	global_load_lds_dwordx4 v[208:209], off
	v_lshl_add_u64 v[208:209], v[214:215], 0, s[72:73]
	s_mov_b32 m0, s41
	s_nop 0
	global_load_lds_dwordx4 v[208:209], off
	s_barrier
	s_waitcnt lgkmcnt(0)
	s_waitcnt lgkmcnt(0)
	v_mfma_f32_16x16x32_bf16 v[60:63], v[130:133], v[146:149], v[60:63]
	v_mfma_f32_16x16x32_bf16 v[56:59], v[138:141], v[146:149], v[56:59]
	v_mfma_f32_16x16x32_bf16 v[48:51], v[130:133], v[164:167], v[48:51]
	v_mfma_f32_16x16x32_bf16 v[40:43], v[138:141], v[164:167], v[40:43]
	v_mfma_f32_16x16x32_bf16 v[32:35], v[130:133], v[176:179], v[32:35]
	v_mfma_f32_16x16x32_bf16 v[24:27], v[138:141], v[176:179], v[24:27]
	v_mfma_f32_16x16x32_bf16 v[16:19], v[130:133], v[184:187], v[16:19]
	v_mfma_f32_16x16x32_bf16 v[8:11], v[138:141], v[184:187], v[8:11]
	v_mfma_f32_16x16x32_bf16 v[60:63], v[134:137], v[160:163], v[60:63]
	v_mfma_f32_16x16x32_bf16 v[56:59], v[142:145], v[160:163], v[56:59]
	v_mfma_f32_16x16x32_bf16 v[48:51], v[134:137], v[168:171], v[48:51]
	v_mfma_f32_16x16x32_bf16 v[40:43], v[142:145], v[168:171], v[40:43]
	v_mfma_f32_16x16x32_bf16 v[32:35], v[134:137], v[180:183], v[32:35]
	v_mfma_f32_16x16x32_bf16 v[24:27], v[142:145], v[180:183], v[24:27]
	v_mfma_f32_16x16x32_bf16 v[16:19], v[134:137], v[188:191], v[16:19]
	v_mfma_f32_16x16x32_bf16 v[8:11], v[142:145], v[188:191], v[8:11]
	s_barrier
	s_add_u32 s18, s20, 0x40080
	s_addc_u32 s19, s21, 0
	s_add_i32 s0, s22, s35
	v_lshl_add_u64 v[130:131], s[18:19], 0, v[96:97]
	s_mov_b32 m0, s0
	s_nop 0
	global_load_lds_dwordx4 v[130:131], off
	v_lshl_add_u64 v[130:131], s[18:19], 0, v[154:155]
	s_add_i32 m0, s0, 0x2000
	s_nop 0
	global_load_lds_dwordx4 v[130:131], off
	s_waitcnt vmcnt(6)
	s_barrier
	v_mfma_f32_16x16x32_bf16 v[52:55], v[192:195], v[146:149], v[52:55]
	v_mfma_f32_16x16x32_bf16 v[44:47], v[200:203], v[146:149], v[44:47]
	v_mfma_f32_16x16x32_bf16 v[36:39], v[192:195], v[164:167], v[36:39]
	v_mfma_f32_16x16x32_bf16 v[28:31], v[200:203], v[164:167], v[28:31]
	v_mfma_f32_16x16x32_bf16 v[20:23], v[192:195], v[176:179], v[20:23]
	v_mfma_f32_16x16x32_bf16 v[12:15], v[200:203], v[176:179], v[12:15]
	v_mfma_f32_16x16x32_bf16 v[4:7], v[192:195], v[184:187], v[4:7]
	v_mfma_f32_16x16x32_bf16 v[0:3], v[200:203], v[184:187], v[0:3]
	v_mfma_f32_16x16x32_bf16 v[52:55], v[196:199], v[160:163], v[52:55]
	v_mfma_f32_16x16x32_bf16 v[44:47], v[204:207], v[160:163], v[44:47]
	v_mfma_f32_16x16x32_bf16 v[36:39], v[196:199], v[168:171], v[36:39]
	v_mfma_f32_16x16x32_bf16 v[28:31], v[204:207], v[168:171], v[28:31]
	v_mfma_f32_16x16x32_bf16 v[20:23], v[196:199], v[180:183], v[20:23]
	v_mfma_f32_16x16x32_bf16 v[12:15], v[204:207], v[180:183], v[12:15]
	v_mfma_f32_16x16x32_bf16 v[4:7], v[196:199], v[188:191], v[4:7]
	v_mfma_f32_16x16x32_bf16 v[0:3], v[204:207], v[188:191], v[0:3]
	s_add_i32 s49, s49, 2
	s_add_u32 s47, s47, 0x100
	s_addc_u32 s48, s48, 0
	s_cmp_gt_u32 s49, 13
	s_mov_b64 s[18:19], s[4:5]
	s_barrier
; __device__ __forceinline__ float bf_lo(unsigned u) { return __uint_as_float(u << 16); }
; __device__ __forceinline__ float bf_hi(unsigned u) { return __uint_as_float(u & 0xffff0000u); }
; template <class Epi>
; __device__ __forceinline__ void gemm_phase(LAS unsigned char* lds, const Gemm g, const StaticOrder& S, const Epi& E, int wv0) {
;     ...
;     if (!has_next) break;
;   __device__ __forceinline__ void emit(const EpiPre& q0, int row, int col, f32x4 a, f32x4 b, const f32x4 (&hb)[2][2], const float (&hs)[2][4], int ai_, int m_, int bj_) const {
;     ...
;     } else if (MODE == E_PROJ) {
;       const int br = e.aux; const u32x4 gw = q.u0;
;       v[0] *= bf_lo(gw.x); v[1] *= bf_hi(gw.x); v[2] *= bf_lo(gw.y); v[3] *= bf_hi(gw.y);
;       v[4] *= bf_lo(gw.z); v[5] *= bf_hi(gw.z); v[6] *= bf_lo(gw.w); v[7] *= bf_hi(gw.w);
;       bf16_t* fa = (bf16_t*)e.facc + (size_t)row * DM + col;
;       if (br > 0) { const u32x4 pw = q.u1;
;         v[0] += bf_lo(pw.x); v[1] += bf_hi(pw.x); v[2] += bf_lo(pw.y); v[3] += bf_hi(pw.y); v[4] += bf_lo(pw.z); v[5] += bf_hi(pw.z); v[6] += bf_lo(pw.w); v[7] += bf_hi(pw.w); }
;       if (br == 2) store8bf((bf16_t*)e.out + (size_t)row * DM + col, v);
;       else store8bf(fa, v);
	s_cbranch_scc0 .LBB0_981
	s_setprio 0
	v_lshl_add_u32 v213, s1, 8, v172
	v_lshl_or_b32 v214, s45, 8, v174
	v_mul_u32_u24_e32 v212, 0x3000, v213
	v_lshlrev_b32_e32 v213, 12, v213
	v_lshl_add_u32 v212, v214, 1, v212
	v_lshl_add_u32 v213, v214, 1, v213
	v_add_u32_e32 v214, 0x0, v212
	global_load_dwordx4 v[130:133], v214, s[6:7]
	global_load_dwordx4 v[134:137], v214, s[6:7] offset:256
	v_add_u32_e32 v214, 0x30000, v212
	global_load_dwordx4 v[138:141], v214, s[6:7]
	global_load_dwordx4 v[142:145], v214, s[6:7] offset:256
	v_add_u32_e32 v214, 0x60000, v212
	global_load_dwordx4 v[146:149], v214, s[6:7]
	global_load_dwordx4 v[160:163], v214, s[6:7] offset:256
	v_add_u32_e32 v214, 0x90000, v212
	global_load_dwordx4 v[164:167], v214, s[6:7]
	global_load_dwordx4 v[168:171], v214, s[6:7] offset:256
	v_add_u32_e32 v214, 0x180000, v212
	global_load_dwordx4 v[176:179], v214, s[6:7]
	global_load_dwordx4 v[180:183], v214, s[6:7] offset:256
	v_add_u32_e32 v214, 0x1b0000, v212
	global_load_dwordx4 v[184:187], v214, s[6:7]
	global_load_dwordx4 v[188:191], v214, s[6:7] offset:256
	v_add_u32_e32 v214, 0x1e0000, v212
	global_load_dwordx4 v[192:195], v214, s[6:7]
	global_load_dwordx4 v[196:199], v214, s[6:7] offset:256
	v_add_u32_e32 v214, 0x210000, v212
	global_load_dwordx4 v[200:203], v214, s[6:7]
	global_load_dwordx4 v[204:207], v214, s[6:7] offset:256
	s_waitcnt vmcnt(15)
	v_lshlrev_b32_e32 v208, 16, v130
	v_and_b32_e32 v209, 0xffff0000, v130
	v_pk_mul_f32 v[126:127], v[126:127], v[208:209]
	v_lshlrev_b32_e32 v208, 16, v131
	v_and_b32_e32 v209, 0xffff0000, v131
	v_pk_mul_f32 v[128:129], v[128:129], v[208:209]
	v_lshlrev_b32_e32 v208, 16, v132
	v_and_b32_e32 v209, 0xffff0000, v132
	v_pk_mul_f32 v[122:123], v[122:123], v[208:209]
	v_lshlrev_b32_e32 v208, 16, v133
	v_and_b32_e32 v209, 0xffff0000, v133
	v_pk_mul_f32 v[124:125], v[124:125], v[208:209]
	v_cvt_pk_bf16_f32 v126, v126, v127
	v_cvt_pk_bf16_f32 v127, v128, v129
	v_cvt_pk_bf16_f32 v128, v122, v123
	v_cvt_pk_bf16_f32 v129, v124, v125
	v_add_u32_e32 v215, 0x0, v213
	global_store_dwordx4 v215, v[126:129], s[8:9]
	s_waitcnt vmcnt(15)
	v_lshlrev_b32_e32 v208, 16, v134
	v_and_b32_e32 v209, 0xffff0000, v134
	v_pk_mul_f32 v[114:115], v[114:115], v[208:209]
	v_lshlrev_b32_e32 v208, 16, v135
	v_and_b32_e32 v209, 0xffff0000, v135
	v_pk_mul_f32 v[116:117], v[116:117], v[208:209]
	v_lshlrev_b32_e32 v208, 16, v136
	v_and_b32_e32 v209, 0xffff0000, v136
	v_pk_mul_f32 v[106:107], v[106:107], v[208:209]
	v_lshlrev_b32_e32 v208, 16, v137
	v_and_b32_e32 v209, 0xffff0000, v137
	v_pk_mul_f32 v[108:109], v[108:109], v[208:209]
	v_cvt_pk_bf16_f32 v114, v114, v115
	v_cvt_pk_bf16_f32 v115, v116, v117
	v_cvt_pk_bf16_f32 v116, v106, v107
	v_cvt_pk_bf16_f32 v117, v108, v109
	global_store_dwordx4 v215, v[114:117], s[8:9] offset:256
	s_waitcnt vmcnt(15)
	v_lshlrev_b32_e32 v208, 16, v138
	v_and_b32_e32 v209, 0xffff0000, v138
	v_pk_mul_f32 v[118:119], v[118:119], v[208:209]
	v_lshlrev_b32_e32 v208, 16, v139
	v_and_b32_e32 v209, 0xffff0000, v139
	v_pk_mul_f32 v[120:121], v[120:121], v[208:209]
	v_lshlrev_b32_e32 v208, 16, v140
	v_and_b32_e32 v209, 0xffff0000, v140
	v_pk_mul_f32 v[110:111], v[110:111], v[208:209]
	v_lshlrev_b32_e32 v208, 16, v141
	v_and_b32_e32 v209, 0xffff0000, v141
	v_pk_mul_f32 v[112:113], v[112:113], v[208:209]
	v_cvt_pk_bf16_f32 v118, v118, v119
	v_cvt_pk_bf16_f32 v119, v120, v121
	v_cvt_pk_bf16_f32 v120, v110, v111
	v_cvt_pk_bf16_f32 v121, v112, v113
	v_add_u32_e32 v215, 0x10000, v213
	global_store_dwordx4 v215, v[118:121], s[8:9]
	s_waitcnt vmcnt(15)
	v_lshlrev_b32_e32 v208, 16, v142
	v_and_b32_e32 v209, 0xffff0000, v142
	v_pk_mul_f32 v[102:103], v[102:103], v[208:209]
	v_lshlrev_b32_e32 v208, 16, v143
	v_and_b32_e32 v209, 0xffff0000, v143
	v_pk_mul_f32 v[104:105], v[104:105], v[208:209]
	v_lshlrev_b32_e32 v208, 16, v144
	v_and_b32_e32 v209, 0xffff0000, v144
	v_pk_mul_f32 v[98:99], v[98:99], v[208:209]
	v_lshlrev_b32_e32 v208, 16, v145
	v_and_b32_e32 v209, 0xffff0000, v145
	v_pk_mul_f32 v[100:101], v[100:101], v[208:209]
	v_cvt_pk_bf16_f32 v102, v102, v103
	v_cvt_pk_bf16_f32 v103, v104, v105
	v_cvt_pk_bf16_f32 v104, v98, v99
	v_cvt_pk_bf16_f32 v105, v100, v101
	global_store_dwordx4 v215, v[102:105], s[8:9] offset:256
	s_waitcnt vmcnt(15)
	v_lshlrev_b32_e32 v208, 16, v146
	v_and_b32_e32 v209, 0xffff0000, v146
	v_pk_mul_f32 v[92:93], v[92:93], v[208:209]
	v_lshlrev_b32_e32 v208, 16, v147
	v_and_b32_e32 v209, 0xffff0000, v147
	v_pk_mul_f32 v[94:95], v[94:95], v[208:209]
	v_lshlrev_b32_e32 v208, 16, v148
	v_and_b32_e32 v209, 0xffff0000, v148
	v_pk_mul_f32 v[88:89], v[88:89], v[208:209]
	v_lshlrev_b32_e32 v208, 16, v149
	v_and_b32_e32 v209, 0xffff0000, v149
	v_pk_mul_f32 v[90:91], v[90:91], v[208:209]
	v_cvt_pk_bf16_f32 v92, v92, v93
	v_cvt_pk_bf16_f32 v93, v94, v95
	v_cvt_pk_bf16_f32 v94, v88, v89
	v_cvt_pk_bf16_f32 v95, v90, v91
	v_add_u32_e32 v215, 0x20000, v213
	global_store_dwordx4 v215, v[92:95], s[8:9]
	s_waitcnt vmcnt(15)
	v_lshlrev_b32_e32 v208, 16, v160
	v_and_b32_e32 v209, 0xffff0000, v160
	v_pk_mul_f32 v[84:85], v[84:85], v[208:209]
	v_lshlrev_b32_e32 v208, 16, v161
	v_and_b32_e32 v209, 0xffff0000, v161
	v_pk_mul_f32 v[86:87], v[86:87], v[208:209]
	v_lshlrev_b32_e32 v208, 16, v162
	v_and_b32_e32 v209, 0xffff0000, v162
	v_pk_mul_f32 v[76:77], v[76:77], v[208:209]
	v_lshlrev_b32_e32 v208, 16, v163
	v_and_b32_e32 v209, 0xffff0000, v163
	v_pk_mul_f32 v[78:79], v[78:79], v[208:209]
	v_cvt_pk_bf16_f32 v84, v84, v85
	v_cvt_pk_bf16_f32 v85, v86, v87
	v_cvt_pk_bf16_f32 v86, v76, v77
	v_cvt_pk_bf16_f32 v87, v78, v79
	global_store_dwordx4 v215, v[84:87], s[8:9] offset:256
	s_waitcnt vmcnt(15)
; __device__ __forceinline__ float bf_lo(unsigned u) { return __uint_as_float(u << 16); }
; __device__ __forceinline__ float bf_hi(unsigned u) { return __uint_as_float(u & 0xffff0000u); }
;   __device__ __forceinline__ void emit(const EpiPre& q0, int row, int col, f32x4 a, f32x4 b, const f32x4 (&hb)[2][2], const float (&hs)[2][4], int ai_, int m_, int bj_) const {
;     ...
;     } else if (MODE == E_PROJ) {
;       const int br = e.aux; const u32x4 gw = q.u0;
;       v[0] *= bf_lo(gw.x); v[1] *= bf_hi(gw.x); v[2] *= bf_lo(gw.y); v[3] *= bf_hi(gw.y);
;       v[4] *= bf_lo(gw.z); v[5] *= bf_hi(gw.z); v[6] *= bf_lo(gw.w); v[7] *= bf_hi(gw.w);
;       bf16_t* fa = (bf16_t*)e.facc + (size_t)row * DM + col;
;       if (br > 0) { const u32x4 pw = q.u1;
;         v[0] += bf_lo(pw.x); v[1] += bf_hi(pw.x); v[2] += bf_lo(pw.y); v[3] += bf_hi(pw.y); v[4] += bf_lo(pw.z); v[5] += bf_hi(pw.z); v[6] += bf_lo(pw.w); v[7] += bf_hi(pw.w); }
;       if (br == 2) store8bf((bf16_t*)e.out + (size_t)row * DM + col, v);
;       else store8bf(fa, v);
	v_lshlrev_b32_e32 v208, 16, v164
	v_and_b32_e32 v209, 0xffff0000, v164
	v_pk_mul_f32 v[80:81], v[80:81], v[208:209]
	v_lshlrev_b32_e32 v208, 16, v165
	v_and_b32_e32 v209, 0xffff0000, v165
	v_pk_mul_f32 v[82:83], v[82:83], v[208:209]
	v_lshlrev_b32_e32 v208, 16, v166
	v_and_b32_e32 v209, 0xffff0000, v166
	v_pk_mul_f32 v[72:73], v[72:73], v[208:209]
	v_lshlrev_b32_e32 v208, 16, v167
	v_and_b32_e32 v209, 0xffff0000, v167
	v_pk_mul_f32 v[74:75], v[74:75], v[208:209]
	v_cvt_pk_bf16_f32 v80, v80, v81
	v_cvt_pk_bf16_f32 v81, v82, v83
	v_cvt_pk_bf16_f32 v82, v72, v73
	v_cvt_pk_bf16_f32 v83, v74, v75
	v_add_u32_e32 v215, 0x30000, v213
	global_store_dwordx4 v215, v[80:83], s[8:9]
	s_waitcnt vmcnt(15)
	v_lshlrev_b32_e32 v208, 16, v168
	v_and_b32_e32 v209, 0xffff0000, v168
	v_pk_mul_f32 v[68:69], v[68:69], v[208:209]
	v_lshlrev_b32_e32 v208, 16, v169
	v_and_b32_e32 v209, 0xffff0000, v169
	v_pk_mul_f32 v[70:71], v[70:71], v[208:209]
	v_lshlrev_b32_e32 v208, 16, v170
	v_and_b32_e32 v209, 0xffff0000, v170
	v_pk_mul_f32 v[64:65], v[64:65], v[208:209]
	v_lshlrev_b32_e32 v208, 16, v171
	v_and_b32_e32 v209, 0xffff0000, v171
	v_pk_mul_f32 v[66:67], v[66:67], v[208:209]
	v_cvt_pk_bf16_f32 v68, v68, v69
	v_cvt_pk_bf16_f32 v69, v70, v71
	v_cvt_pk_bf16_f32 v70, v64, v65
	v_cvt_pk_bf16_f32 v71, v66, v67
	global_store_dwordx4 v215, v[68:71], s[8:9] offset:256
	s_waitcnt vmcnt(15)
	v_lshlrev_b32_e32 v208, 16, v176
	v_and_b32_e32 v209, 0xffff0000, v176
	v_pk_mul_f32 v[60:61], v[60:61], v[208:209]
	v_lshlrev_b32_e32 v208, 16, v177
	v_and_b32_e32 v209, 0xffff0000, v177
	v_pk_mul_f32 v[62:63], v[62:63], v[208:209]
	v_lshlrev_b32_e32 v208, 16, v178
	v_and_b32_e32 v209, 0xffff0000, v178
	v_pk_mul_f32 v[56:57], v[56:57], v[208:209]
	v_lshlrev_b32_e32 v208, 16, v179
	v_and_b32_e32 v209, 0xffff0000, v179
	v_pk_mul_f32 v[58:59], v[58:59], v[208:209]
	v_cvt_pk_bf16_f32 v60, v60, v61
	v_cvt_pk_bf16_f32 v61, v62, v63
	v_cvt_pk_bf16_f32 v62, v56, v57
	v_cvt_pk_bf16_f32 v63, v58, v59
	v_add_u32_e32 v215, 0x80000, v213
	global_store_dwordx4 v215, v[60:63], s[8:9]
	s_waitcnt vmcnt(15)
	v_lshlrev_b32_e32 v208, 16, v180
	v_and_b32_e32 v209, 0xffff0000, v180
	v_pk_mul_f32 v[52:53], v[52:53], v[208:209]
	v_lshlrev_b32_e32 v208, 16, v181
	v_and_b32_e32 v209, 0xffff0000, v181
	v_pk_mul_f32 v[54:55], v[54:55], v[208:209]
	v_lshlrev_b32_e32 v208, 16, v182
	v_and_b32_e32 v209, 0xffff0000, v182
	v_pk_mul_f32 v[44:45], v[44:45], v[208:209]
	v_lshlrev_b32_e32 v208, 16, v183
	v_and_b32_e32 v209, 0xffff0000, v183
	v_pk_mul_f32 v[46:47], v[46:47], v[208:209]
	v_cvt_pk_bf16_f32 v52, v52, v53
	v_cvt_pk_bf16_f32 v53, v54, v55
	v_cvt_pk_bf16_f32 v54, v44, v45
	v_cvt_pk_bf16_f32 v55, v46, v47
	global_store_dwordx4 v215, v[52:55], s[8:9] offset:256
	s_waitcnt vmcnt(15)
	v_lshlrev_b32_e32 v208, 16, v184
	v_and_b32_e32 v209, 0xffff0000, v184
	v_pk_mul_f32 v[48:49], v[48:49], v[208:209]
	v_lshlrev_b32_e32 v208, 16, v185
	v_and_b32_e32 v209, 0xffff0000, v185
	v_pk_mul_f32 v[50:51], v[50:51], v[208:209]
	v_lshlrev_b32_e32 v208, 16, v186
	v_and_b32_e32 v209, 0xffff0000, v186
	v_pk_mul_f32 v[40:41], v[40:41], v[208:209]
	v_lshlrev_b32_e32 v208, 16, v187
	v_and_b32_e32 v209, 0xffff0000, v187
	v_pk_mul_f32 v[42:43], v[42:43], v[208:209]
	v_cvt_pk_bf16_f32 v48, v48, v49
	v_cvt_pk_bf16_f32 v49, v50, v51
	v_cvt_pk_bf16_f32 v50, v40, v41
	v_cvt_pk_bf16_f32 v51, v42, v43
	v_add_u32_e32 v215, 0x90000, v213
	global_store_dwordx4 v215, v[48:51], s[8:9]
	s_waitcnt vmcnt(15)
	v_lshlrev_b32_e32 v208, 16, v188
	v_and_b32_e32 v209, 0xffff0000, v188
	v_pk_mul_f32 v[36:37], v[36:37], v[208:209]
	v_lshlrev_b32_e32 v208, 16, v189
	v_and_b32_e32 v209, 0xffff0000, v189
	v_pk_mul_f32 v[38:39], v[38:39], v[208:209]
	v_lshlrev_b32_e32 v208, 16, v190
	v_and_b32_e32 v209, 0xffff0000, v190
	v_pk_mul_f32 v[28:29], v[28:29], v[208:209]
	v_lshlrev_b32_e32 v208, 16, v191
	v_and_b32_e32 v209, 0xffff0000, v191
	v_pk_mul_f32 v[30:31], v[30:31], v[208:209]
	v_cvt_pk_bf16_f32 v36, v36, v37
	v_cvt_pk_bf16_f32 v37, v38, v39
	v_cvt_pk_bf16_f32 v38, v28, v29
	v_cvt_pk_bf16_f32 v39, v30, v31
	global_store_dwordx4 v215, v[36:39], s[8:9] offset:256
	s_waitcnt vmcnt(15)
	v_lshlrev_b32_e32 v208, 16, v192
	v_and_b32_e32 v209, 0xffff0000, v192
	v_pk_mul_f32 v[32:33], v[32:33], v[208:209]
	v_lshlrev_b32_e32 v208, 16, v193
	v_and_b32_e32 v209, 0xffff0000, v193
	v_pk_mul_f32 v[34:35], v[34:35], v[208:209]
	v_lshlrev_b32_e32 v208, 16, v194
	v_and_b32_e32 v209, 0xffff0000, v194
	v_pk_mul_f32 v[24:25], v[24:25], v[208:209]
	v_lshlrev_b32_e32 v208, 16, v195
	v_and_b32_e32 v209, 0xffff0000, v195
	v_pk_mul_f32 v[26:27], v[26:27], v[208:209]
	v_cvt_pk_bf16_f32 v32, v32, v33
	v_cvt_pk_bf16_f32 v33, v34, v35
	v_cvt_pk_bf16_f32 v34, v24, v25
	v_cvt_pk_bf16_f32 v35, v26, v27
	v_add_u32_e32 v215, 0xa0000, v213
	global_store_dwordx4 v215, v[32:35], s[8:9]
	s_waitcnt vmcnt(15)
	v_lshlrev_b32_e32 v208, 16, v196
	v_and_b32_e32 v209, 0xffff0000, v196
	v_pk_mul_f32 v[20:21], v[20:21], v[208:209]
	v_lshlrev_b32_e32 v208, 16, v197
	v_and_b32_e32 v209, 0xffff0000, v197
	v_pk_mul_f32 v[22:23], v[22:23], v[208:209]
	v_lshlrev_b32_e32 v208, 16, v198
	v_and_b32_e32 v209, 0xffff0000, v198
	v_pk_mul_f32 v[12:13], v[12:13], v[208:209]
	v_lshlrev_b32_e32 v208, 16, v199
	v_and_b32_e32 v209, 0xffff0000, v199
	v_pk_mul_f32 v[14:15], v[14:15], v[208:209]
	v_cvt_pk_bf16_f32 v20, v20, v21
	v_cvt_pk_bf16_f32 v21, v22, v23
	v_cvt_pk_bf16_f32 v22, v12, v13
	v_cvt_pk_bf16_f32 v23, v14, v15
	global_store_dwordx4 v215, v[20:23], s[8:9] offset:256
	s_waitcnt vmcnt(15)
	v_lshlrev_b32_e32 v208, 16, v200
	v_and_b32_e32 v209, 0xffff0000, v200
	v_pk_mul_f32 v[16:17], v[16:17], v[208:209]
	v_lshlrev_b32_e32 v208, 16, v201
	v_and_b32_e32 v209, 0xffff0000, v201
	v_pk_mul_f32 v[18:19], v[18:19], v[208:209]
	v_lshlrev_b32_e32 v208, 16, v202
	v_and_b32_e32 v209, 0xffff0000, v202
	v_pk_mul_f32 v[8:9], v[8:9], v[208:209]
	v_lshlrev_b32_e32 v208, 16, v203
	v_and_b32_e32 v209, 0xffff0000, v203
	v_pk_mul_f32 v[10:11], v[10:11], v[208:209]
	v_cvt_pk_bf16_f32 v16, v16, v17
	v_cvt_pk_bf16_f32 v17, v18, v19
	v_cvt_pk_bf16_f32 v18, v8, v9
	v_cvt_pk_bf16_f32 v19, v10, v11
	v_add_u32_e32 v215, 0xb0000, v213
	global_store_dwordx4 v215, v[16:19], s[8:9]
	s_waitcnt vmcnt(15)
	v_lshlrev_b32_e32 v208, 16, v204
	v_and_b32_e32 v209, 0xffff0000, v204
	v_pk_mul_f32 v[4:5], v[4:5], v[208:209]
	v_lshlrev_b32_e32 v208, 16, v205
	v_and_b32_e32 v209, 0xffff0000, v205
	v_pk_mul_f32 v[6:7], v[6:7], v[208:209]
	v_lshlrev_b32_e32 v208, 16, v206
	v_and_b32_e32 v209, 0xffff0000, v206
	v_pk_mul_f32 v[0:1], v[0:1], v[208:209]
	v_lshlrev_b32_e32 v208, 16, v207
	v_and_b32_e32 v209, 0xffff0000, v207
	v_pk_mul_f32 v[2:3], v[2:3], v[208:209]
	v_cvt_pk_bf16_f32 v4, v4, v5
	v_cvt_pk_bf16_f32 v5, v6, v7
	v_cvt_pk_bf16_f32 v6, v0, v1
	v_cvt_pk_bf16_f32 v7, v2, v3
	global_store_dwordx4 v215, v[4:7], s[8:9] offset:256
	s_mov_b32 s45, s12
	s_mov_b64 s[20:21], s[16:17]
	s_mov_b64 s[18:19], s[14:15]
	s_and_b64 vcc, exec, s[2:3]
	s_mov_b32 s1, s44
	s_cbranch_vccz .LBB0_972
; #define PG8_WAIT_V(n) asm volatile("s_waitcnt vmcnt(" #n ")" ::: "memory")
; #define PG8_BAR __builtin_amdgcn_s_barrier()
; template <class Epi>
; __device__ __forceinline__ void gemm_phase(LAS unsigned char* lds, const Gemm g, const StaticOrder& S, const Epi& E, int wv0) {
;     ...
;   PG8_WAIT_V(0);
;   if (wr == 0) PG8_BAR;
;   PG8_BAR;
	s_waitcnt vmcnt(0)
	s_cmpk_gt_u32 s27, 0xff
	s_cbranch_scc1 .LBB0_985
	s_barrier

; #define PG8_STAGE(bufoff, gbase, voff) do { _Pragma("unroll") for (int _i = 0; _i < 2; ++_i) \
;     __builtin_amdgcn_global_load_lds((const unsigned*)((const char*)(gbase) + (voff)[_i]), (LAS unsigned*)(lds + (bufoff) + ldsw + _i * 8192), 16, 0, 0); } while (0)
; #define PG8_LDA(dst, b, h) do { _Pragma("unroll") for (int m = 0; m < 4; ++m) _Pragma("unroll") for (int k = 0; k < 2; ++k) dst[m][k] = *(const LAS bf16x8*)(lds + PG8_SA(b, h) + aoff + m * 2048 + k * 1024); } while (0)
; #define PG8_LDB(dst, b, h) do { _Pragma("unroll") for (int n = 0; n < 2; ++n) _Pragma("unroll") for (int k = 0; k < 2; ++k) dst[n][k] = *(const LAS bf16x8*)(lds + PG8_SB(b, h) + boff + n * 2048 + k * 1024); } while (0)
; #define PG8_MMA(ai, bj, At, Bt) do { __builtin_amdgcn_s_setprio(1); _Pragma("unroll") for (int m = 0; m < 4; ++m) _Pragma("unroll") for (int n = 0; n < 2; ++n) _Pragma("unroll") for (int k = 0; k < 2; ++k) \
;     acc[ai][bj][m][n] = __builtin_amdgcn_mfma_f32_16x16x32_bf16(Bt[n][k], At[m][k], acc[ai][bj][m][n], 0, 0, 0); __builtin_amdgcn_s_setprio(0); } while (0)
; #define PG8_WAIT_L(n) asm volatile("s_waitcnt lgkmcnt(" #n ")" ::: "memory")
; #define PG8_BAR __builtin_amdgcn_s_barrier()
; template <class Epi>
; __device__ __forceinline__ void gemm_phase(LAS unsigned char* lds, const Gemm g, const StaticOrder& S, const Epi& E, int wv0) {
;     ...
;     const bool has_next = S.next(ui + 1, nxt);
;     const char* nA = has_next ? (const char*)g.A + (size_t)nxt.pm * tstepA : cA; const char* nB = has_next ? (const char*)g.Bt + (size_t)nxt.pn * tstepB : cB;
;     for (int t = 0; t < nt; t += 2) {
;       const bool last = (t == nt - 2);
;       const char* a1 = cA + (size_t)(t + 1) * kstep;
;       const char* a2 = last ? nA : cA + (size_t)(t + 2) * kstep; const char* b2 = last ? nB : cB + (size_t)(t + 2) * kstep;
;       const char* a3 = a2 + kstep; const char* b3 = b2 + kstep;
;       PG8_LDB(B0, 0, 0); PG8_SCHED; PG8_LDA(At, 0, 0); PG8_STAGE(PG8_SA(1, 1), a1 + hstepA, voffA);
;       PG8_WAIT_L(8); PG8_BAR; PG8_WAIT_L(0); PG8_MMA(0, 0, At, B0); PG8_BAR; PG8_SCHED;
;     ...
; #pragma unroll
;     for (int a = 0; a < 2; ++a)
; #pragma unroll
;       for (int b = 0; b < 2; ++b)
; #pragma unroll
;         for (int m = 0; m < 4; ++m)
; #pragma unroll
;           for (int n = 0; n < 2; ++n) acc[a][b][m][n] = (f32x4){0.f, 0.f, 0.f, 0.f};
.LBB0_1002:
	s_ashr_i32 s13, s12, 31
	s_lshl_b64 s[16:17], s[12:13], 20
	s_add_u32 s16, s31, s16
	s_addc_u32 s17, s34, s17
	s_and_b64 s[4:5], s[4:5], exec
	s_cselect_b32 s13, s17, s21
	s_cselect_b32 s46, s16, s20
	s_add_u32 s47, s20, 0x100
	v_mov_b32_e32 v0, 0
	s_addc_u32 s48, s21, 0
	s_mov_b32 s49, -2
	v_mov_b32_e32 v1, v0
	v_mov_b32_e32 v2, v0
	v_mov_b32_e32 v3, v0
	v_mov_b32_e32 v4, v0
	v_mov_b32_e32 v5, v0
	v_mov_b32_e32 v6, v0
	v_mov_b32_e32 v7, v0
	v_mov_b32_e32 v16, v0
	v_mov_b32_e32 v17, v0
	v_mov_b32_e32 v18, v0
	v_mov_b32_e32 v19, v0
	v_mov_b32_e32 v20, v0
	v_mov_b32_e32 v21, v0
	v_mov_b32_e32 v22, v0
	v_mov_b32_e32 v23, v0
	v_mov_b32_e32 v32, v0
	v_mov_b32_e32 v33, v0
	v_mov_b32_e32 v34, v0
	v_mov_b32_e32 v35, v0
	v_mov_b32_e32 v36, v0
	v_mov_b32_e32 v37, v0
	v_mov_b32_e32 v38, v0
	v_mov_b32_e32 v39, v0
	v_mov_b32_e32 v48, v0
	v_mov_b32_e32 v49, v0
	v_mov_b32_e32 v50, v0
	v_mov_b32_e32 v51, v0
	v_mov_b32_e32 v52, v0
	v_mov_b32_e32 v53, v0
	v_mov_b32_e32 v54, v0
	v_mov_b32_e32 v55, v0
	v_mov_b32_e32 v8, v0
	v_mov_b32_e32 v9, v0
	v_mov_b32_e32 v10, v0
	v_mov_b32_e32 v11, v0
	v_mov_b32_e32 v12, v0
	v_mov_b32_e32 v13, v0
	v_mov_b32_e32 v14, v0
	v_mov_b32_e32 v15, v0
	v_mov_b32_e32 v24, v0
	v_mov_b32_e32 v25, v0
	v_mov_b32_e32 v26, v0
	v_mov_b32_e32 v27, v0
	v_mov_b32_e32 v28, v0
	v_mov_b32_e32 v29, v0
	v_mov_b32_e32 v30, v0
	v_mov_b32_e32 v31, v0
	v_mov_b32_e32 v40, v0
	v_mov_b32_e32 v41, v0
	v_mov_b32_e32 v42, v0
	v_mov_b32_e32 v43, v0
	v_mov_b32_e32 v44, v0
	v_mov_b32_e32 v45, v0
	v_mov_b32_e32 v46, v0
	v_mov_b32_e32 v47, v0
	v_mov_b32_e32 v56, v0
	v_mov_b32_e32 v57, v0
	v_mov_b32_e32 v58, v0
	v_mov_b32_e32 v59, v0
	v_mov_b32_e32 v60, v0
	v_mov_b32_e32 v61, v0
	v_mov_b32_e32 v62, v0
	v_mov_b32_e32 v63, v0
	v_mov_b32_e32 v64, v0
	v_mov_b32_e32 v65, v0
	v_mov_b32_e32 v66, v0
	v_mov_b32_e32 v67, v0
	v_mov_b32_e32 v68, v0
	v_mov_b32_e32 v69, v0
	v_mov_b32_e32 v70, v0
	v_mov_b32_e32 v71, v0
	s_waitcnt vmcnt(0)
	v_mov_b32_e32 v80, v0
	v_mov_b32_e32 v81, v0
	v_mov_b32_e32 v82, v0
	v_mov_b32_e32 v83, v0
	v_mov_b32_e32 v84, v0
	v_mov_b32_e32 v85, v0
	v_mov_b32_e32 v86, v0
	v_mov_b32_e32 v87, v0
	v_mov_b32_e32 v98, v0
	v_mov_b32_e32 v99, v0
	v_mov_b32_e32 v100, v0
	v_mov_b32_e32 v101, v0
	v_mov_b32_e32 v102, v0
	v_mov_b32_e32 v103, v0
	v_mov_b32_e32 v104, v0
	v_mov_b32_e32 v105, v0
	v_mov_b32_e32 v114, v0
	v_mov_b32_e32 v115, v0
	v_mov_b32_e32 v116, v0
	v_mov_b32_e32 v117, v0
	v_mov_b32_e32 v118, v0
	v_mov_b32_e32 v119, v0
	v_mov_b32_e32 v120, v0
	v_mov_b32_e32 v121, v0
	v_mov_b32_e32 v72, v0
	v_mov_b32_e32 v73, v0
	v_mov_b32_e32 v74, v0
	v_mov_b32_e32 v75, v0
	v_mov_b32_e32 v76, v0
	v_mov_b32_e32 v77, v0
	v_mov_b32_e32 v78, v0
	v_mov_b32_e32 v79, v0
	v_mov_b32_e32 v88, v0
	v_mov_b32_e32 v89, v0
	v_mov_b32_e32 v90, v0
	v_mov_b32_e32 v91, v0
	v_mov_b32_e32 v92, v0
	v_mov_b32_e32 v93, v0
	v_mov_b32_e32 v94, v0
	v_mov_b32_e32 v95, v0
	v_mov_b32_e32 v106, v0
	v_mov_b32_e32 v107, v0
	v_mov_b32_e32 v108, v0
	v_mov_b32_e32 v109, v0
	v_mov_b32_e32 v110, v0
	v_mov_b32_e32 v111, v0
	v_mov_b32_e32 v112, v0
	v_mov_b32_e32 v113, v0
	v_mov_b32_e32 v122, v0
	v_mov_b32_e32 v123, v0
	v_mov_b32_e32 v124, v0
	v_mov_b32_e32 v125, v0
	v_mov_b32_e32 v126, v0
	v_mov_b32_e32 v127, v0
	v_mov_b32_e32 v128, v0
	v_mov_b32_e32 v129, v0
	s_cmp_lt_u32 s53, 4
	s_cbranch_scc1 .Lgprio5
	s_setprio 1
.Lgprio5:
.LBB0_1003:
	s_add_u32 s4, s18, 0x100
	s_addc_u32 s5, s19, 0
	s_add_i32 s0, 0, 0x10000
	v_add_u32_e32 v142, s0, v219
	ds_read_b128 v[130:133], v142
	ds_read_b128 v[134:137], v142 offset:1024
	ds_read_b128 v[138:141], v142 offset:2048
	ds_read_b128 v[142:145], v142 offset:3072
	s_cmp_eq_u32 s49, 28
	s_cselect_b32 s23, s15, s5
	s_cselect_b32 s22, s14, s4
	s_cselect_b32 s21, s13, s48
	s_cselect_b32 s20, s46, s47
	v_lshl_add_u64 v[178:179], s[18:19], 0, v[200:201]
	s_add_i32 m0, s36, 0xc000
	ds_read_b128 v[146:149], v225
	ds_read_b128 v[150:153], v225 offset:1024
	ds_read_b128 v[154:157], v225 offset:2048
	ds_read_b128 v[158:161], v225 offset:3072
	ds_read_b128 v[162:165], v225 offset:4096
	ds_read_b128 v[166:169], v225 offset:5120
	ds_read_b128 v[170:173], v225 offset:6144
	ds_read_b128 v[174:177], v225 offset:7168
	global_load_lds_dwordx4 v[178:179], off
	v_lshl_add_u64 v[178:179], s[18:19], 0, v[202:203]
	s_add_i32 m0, s36, 0xe000
	s_nop 0
	global_load_lds_dwordx4 v[178:179], off
	s_waitcnt lgkmcnt(8)
	s_barrier
	s_waitcnt lgkmcnt(0)
	s_waitcnt lgkmcnt(0)
	v_mfma_f32_16x16x32_bf16 v[126:129], v[130:133], v[146:149], v[126:129]
	v_mfma_f32_16x16x32_bf16 v[122:125], v[138:141], v[146:149], v[122:125]
	v_mfma_f32_16x16x32_bf16 v[110:113], v[130:133], v[154:157], v[110:113]
	v_mfma_f32_16x16x32_bf16 v[106:109], v[138:141], v[154:157], v[106:109]
	v_mfma_f32_16x16x32_bf16 v[92:95], v[130:133], v[162:165], v[92:95]
	v_mfma_f32_16x16x32_bf16 v[88:91], v[138:141], v[162:165], v[88:91]
	v_mfma_f32_16x16x32_bf16 v[76:79], v[130:133], v[170:173], v[76:79]
	v_mfma_f32_16x16x32_bf16 v[72:75], v[138:141], v[170:173], v[72:75]
	v_mfma_f32_16x16x32_bf16 v[126:129], v[134:137], v[150:153], v[126:129]
	v_mfma_f32_16x16x32_bf16 v[122:125], v[142:145], v[150:153], v[122:125]
	v_mfma_f32_16x16x32_bf16 v[110:113], v[134:137], v[158:161], v[110:113]
	v_mfma_f32_16x16x32_bf16 v[106:109], v[142:145], v[158:161], v[106:109]
	v_mfma_f32_16x16x32_bf16 v[92:95], v[134:137], v[166:169], v[92:95]
	v_mfma_f32_16x16x32_bf16 v[88:91], v[142:145], v[166:169], v[88:91]
	v_mfma_f32_16x16x32_bf16 v[76:79], v[134:137], v[174:177], v[76:79]
	v_mfma_f32_16x16x32_bf16 v[72:75], v[142:145], v[174:177], v[72:75]
	s_barrier
; #define PG8_STAGE(bufoff, gbase, voff) do { _Pragma("unroll") for (int _i = 0; _i < 2; ++_i) \
;     __builtin_amdgcn_global_load_lds((const unsigned*)((const char*)(gbase) + (voff)[_i]), (LAS unsigned*)(lds + (bufoff) + ldsw + _i * 8192), 16, 0, 0); } while (0)
; #define PG8_LDA(dst, b, h) do { _Pragma("unroll") for (int m = 0; m < 4; ++m) _Pragma("unroll") for (int k = 0; k < 2; ++k) dst[m][k] = *(const LAS bf16x8*)(lds + PG8_SA(b, h) + aoff + m * 2048 + k * 1024); } while (0)
; #define PG8_LDB(dst, b, h) do { _Pragma("unroll") for (int n = 0; n < 2; ++n) _Pragma("unroll") for (int k = 0; k < 2; ++k) dst[n][k] = *(const LAS bf16x8*)(lds + PG8_SB(b, h) + boff + n * 2048 + k * 1024); } while (0)
; #define PG8_MMA(ai, bj, At, Bt) do { __builtin_amdgcn_s_setprio(1); _Pragma("unroll") for (int m = 0; m < 4; ++m) _Pragma("unroll") for (int n = 0; n < 2; ++n) _Pragma("unroll") for (int k = 0; k < 2; ++k) \
;     acc[ai][bj][m][n] = __builtin_amdgcn_mfma_f32_16x16x32_bf16(Bt[n][k], At[m][k], acc[ai][bj][m][n], 0, 0, 0); __builtin_amdgcn_s_setprio(0); } while (0)
; template <class Epi>
; __device__ __forceinline__ void gemm_phase(LAS unsigned char* lds, const Gemm g, const StaticOrder& S, const Epi& E, int wv0) {
;     ...
;       PG8_LDB(B0, 0, 0); PG8_SCHED; PG8_LDA(At, 0, 0); PG8_STAGE(PG8_SA(1, 1), a1 + hstepA, voffA);
;       PG8_WAIT_L(8); PG8_BAR; PG8_WAIT_L(0); PG8_MMA(0, 0, At, B0); PG8_BAR; PG8_SCHED;
;       PG8_LDB(B1, 0, 1); PG8_STAGE(PG8_SB(0, 0), b2, voffB);
;       PG8_BAR; PG8_WAIT_L(0); PG8_MMA(0, 1, At, B1); PG8_BAR;
;       PG8_LDA(At, 0, 1); PG8_STAGE(PG8_SA(0, 0), a2, voffA);
;       PG8_BAR; PG8_WAIT_L(0); PG8_MMA(1, 0, At, B0); PG8_BAR; PG8_SCHED;
;       PG8_STAGE(PG8_SB(0, 1), b2 + hstepB, voffB);
;       PG8_WAIT_V(6); PG8_BAR; PG8_MMA(1, 1, At, B1); PG8_BAR;
;       PG8_LDB(B0, 1, 0); PG8_SCHED; PG8_LDA(At, 1, 0); PG8_STAGE(PG8_SA(0, 1), a2 + hstepA, voffA);
;       PG8_WAIT_L(8); PG8_BAR; PG8_WAIT_L(0); PG8_MMA(0, 0, At, B0); PG8_BAR; PG8_SCHED;
;       PG8_LDB(B1, 1, 1); PG8_STAGE(PG8_SB(1, 0), b3, voffB);
;       PG8_BAR; PG8_WAIT_L(0); PG8_MMA(0, 1, At, B1); PG8_BAR;
;       PG8_LDA(At, 1, 1); PG8_STAGE(PG8_SA(1, 0), a3, voffA);
;       PG8_BAR; PG8_WAIT_L(0); PG8_MMA(1, 0, At, B0); PG8_BAR; PG8_SCHED;
;       PG8_STAGE(PG8_SB(1, 1), b3 + hstepB, voffB);
;       PG8_WAIT_V(6); PG8_BAR; PG8_MMA(1, 1, At, B1); PG8_BAR;
	s_add_i32 s50, 0, 0x14000
	s_add_i32 s0, s0, s35
	v_add_u32_e32 v190, s50, v219
	v_lshl_add_u64 v[204:205], s[20:21], 0, v[96:97]
	s_mov_b32 m0, s0
	ds_read_b128 v[178:181], v190
	ds_read_b128 v[182:185], v190 offset:1024
	ds_read_b128 v[186:189], v190 offset:2048
	ds_read_b128 v[190:193], v190 offset:3072
	global_load_lds_dwordx4 v[204:205], off
	v_lshl_add_u64 v[206:207], s[20:21], 0, v[198:199]
	s_add_i32 m0, s0, 0x2000
	s_nop 0
	global_load_lds_dwordx4 v[206:207], off
	s_barrier
	s_waitcnt lgkmcnt(0)
	s_waitcnt lgkmcnt(0)
	v_mfma_f32_16x16x32_bf16 v[118:121], v[178:181], v[146:149], v[118:121]
	v_mfma_f32_16x16x32_bf16 v[114:117], v[186:189], v[146:149], v[114:117]
	v_mfma_f32_16x16x32_bf16 v[102:105], v[178:181], v[154:157], v[102:105]
	v_mfma_f32_16x16x32_bf16 v[98:101], v[186:189], v[154:157], v[98:101]
	v_mfma_f32_16x16x32_bf16 v[84:87], v[178:181], v[162:165], v[84:87]
	v_mfma_f32_16x16x32_bf16 v[80:83], v[186:189], v[162:165], v[80:83]
	v_mfma_f32_16x16x32_bf16 v[68:71], v[178:181], v[170:173], v[68:71]
	v_mfma_f32_16x16x32_bf16 v[64:67], v[186:189], v[170:173], v[64:67]
	v_mfma_f32_16x16x32_bf16 v[118:121], v[182:185], v[150:153], v[118:121]
	v_mfma_f32_16x16x32_bf16 v[114:117], v[190:193], v[150:153], v[114:117]
	v_mfma_f32_16x16x32_bf16 v[102:105], v[182:185], v[158:161], v[102:105]
	v_mfma_f32_16x16x32_bf16 v[98:101], v[190:193], v[158:161], v[98:101]
	v_mfma_f32_16x16x32_bf16 v[84:87], v[182:185], v[166:169], v[84:87]
	v_mfma_f32_16x16x32_bf16 v[80:83], v[190:193], v[166:169], v[80:83]
	v_mfma_f32_16x16x32_bf16 v[68:71], v[182:185], v[174:177], v[68:71]
	v_mfma_f32_16x16x32_bf16 v[64:67], v[190:193], v[174:177], v[64:67]
	s_mov_b32 m0, s36
	v_lshl_add_u64 v[208:209], s[22:23], 0, v[194:195]
	s_barrier
	ds_read_b128 v[146:149], v225 offset:16384
	ds_read_b128 v[150:153], v225 offset:17408
	ds_read_b128 v[154:157], v225 offset:18432
	ds_read_b128 v[158:161], v225 offset:19456
	ds_read_b128 v[162:165], v225 offset:20480
	ds_read_b128 v[166:169], v225 offset:21504
	ds_read_b128 v[170:173], v225 offset:22528
	ds_read_b128 v[174:177], v225 offset:23552
	global_load_lds_dwordx4 v[208:209], off
	v_lshl_add_u64 v[210:211], s[22:23], 0, v[196:197]
	s_mov_b32 m0, s37
	s_nop 0
	global_load_lds_dwordx4 v[210:211], off
	s_barrier
	s_waitcnt lgkmcnt(0)
	s_waitcnt lgkmcnt(0)
	v_mfma_f32_16x16x32_bf16 v[60:63], v[130:133], v[146:149], v[60:63]
	v_mfma_f32_16x16x32_bf16 v[56:59], v[138:141], v[146:149], v[56:59]
	v_mfma_f32_16x16x32_bf16 v[44:47], v[130:133], v[154:157], v[44:47]
	v_mfma_f32_16x16x32_bf16 v[40:43], v[138:141], v[154:157], v[40:43]
	v_mfma_f32_16x16x32_bf16 v[28:31], v[130:133], v[162:165], v[28:31]
	v_mfma_f32_16x16x32_bf16 v[24:27], v[138:141], v[162:165], v[24:27]
	v_mfma_f32_16x16x32_bf16 v[12:15], v[130:133], v[170:173], v[12:15]
	v_mfma_f32_16x16x32_bf16 v[8:11], v[138:141], v[170:173], v[8:11]
	v_mfma_f32_16x16x32_bf16 v[60:63], v[134:137], v[150:153], v[60:63]
	v_mfma_f32_16x16x32_bf16 v[56:59], v[142:145], v[150:153], v[56:59]
	v_mfma_f32_16x16x32_bf16 v[44:47], v[134:137], v[158:161], v[44:47]
	v_mfma_f32_16x16x32_bf16 v[40:43], v[142:145], v[158:161], v[40:43]
	v_mfma_f32_16x16x32_bf16 v[28:31], v[134:137], v[166:169], v[28:31]
	v_mfma_f32_16x16x32_bf16 v[24:27], v[142:145], v[166:169], v[24:27]
	v_mfma_f32_16x16x32_bf16 v[12:15], v[134:137], v[174:177], v[12:15]
	v_mfma_f32_16x16x32_bf16 v[8:11], v[142:145], v[174:177], v[8:11]
	s_barrier
	s_add_u32 s18, s20, 0x80000
	s_addc_u32 s19, s21, 0
	s_add_i32 s0, s50, s35
	v_lshl_add_u64 v[130:131], s[18:19], 0, v[96:97]
	s_mov_b32 m0, s0
	s_nop 0
	global_load_lds_dwordx4 v[130:131], off
	v_lshl_add_u64 v[130:131], s[18:19], 0, v[198:199]
	s_add_i32 m0, s0, 0x2000
	s_nop 0
	global_load_lds_dwordx4 v[130:131], off
	s_waitcnt vmcnt(6)
	s_barrier
	v_mfma_f32_16x16x32_bf16 v[52:55], v[178:181], v[146:149], v[52:55]
	v_mfma_f32_16x16x32_bf16 v[48:51], v[186:189], v[146:149], v[48:51]
	v_mfma_f32_16x16x32_bf16 v[36:39], v[178:181], v[154:157], v[36:39]
	v_mfma_f32_16x16x32_bf16 v[32:35], v[186:189], v[154:157], v[32:35]
	v_mfma_f32_16x16x32_bf16 v[20:23], v[178:181], v[162:165], v[20:23]
	v_mfma_f32_16x16x32_bf16 v[16:19], v[186:189], v[162:165], v[16:19]
	v_mfma_f32_16x16x32_bf16 v[4:7], v[178:181], v[170:173], v[4:7]
	v_mfma_f32_16x16x32_bf16 v[0:3], v[186:189], v[170:173], v[0:3]
	v_mfma_f32_16x16x32_bf16 v[52:55], v[182:185], v[150:153], v[52:55]
	v_mfma_f32_16x16x32_bf16 v[48:51], v[190:193], v[150:153], v[48:51]
	v_mfma_f32_16x16x32_bf16 v[36:39], v[182:185], v[158:161], v[36:39]
	v_mfma_f32_16x16x32_bf16 v[32:35], v[190:193], v[158:161], v[32:35]
	v_mfma_f32_16x16x32_bf16 v[20:23], v[182:185], v[166:169], v[20:23]
	v_mfma_f32_16x16x32_bf16 v[16:19], v[190:193], v[166:169], v[16:19]
	v_mfma_f32_16x16x32_bf16 v[4:7], v[182:185], v[174:177], v[4:7]
	v_mfma_f32_16x16x32_bf16 v[0:3], v[190:193], v[174:177], v[0:3]
	s_add_i32 s0, 0, 0x18000
	v_add_u32_e32 v142, s0, v219
	s_barrier
	ds_read_b128 v[130:133], v142
	ds_read_b128 v[134:137], v142 offset:1024
	ds_read_b128 v[138:141], v142 offset:2048
	ds_read_b128 v[142:145], v142 offset:3072
	s_add_u32 s18, s22, 0x114000
	s_addc_u32 s19, s23, 0
	s_mov_b32 m0, s38
	v_lshl_add_u64 v[178:179], s[18:19], 0, v[194:195]
	ds_read_b128 v[146:149], v225 offset:32768
	ds_read_b128 v[150:153], v225 offset:33792
	ds_read_b128 v[154:157], v225 offset:34816
	ds_read_b128 v[158:161], v225 offset:35840
	ds_read_b128 v[162:165], v225 offset:36864
	ds_read_b128 v[166:169], v225 offset:37888
	ds_read_b128 v[170:173], v225 offset:38912
	ds_read_b128 v[174:177], v225 offset:39936
	global_load_lds_dwordx4 v[178:179], off
	v_lshl_add_u64 v[178:179], s[18:19], 0, v[196:197]
	s_mov_b32 m0, s39
	s_nop 0
	global_load_lds_dwordx4 v[178:179], off
	s_waitcnt lgkmcnt(8)
	s_barrier
; #define PG8_STAGE(bufoff, gbase, voff) do { _Pragma("unroll") for (int _i = 0; _i < 2; ++_i) \
;     __builtin_amdgcn_global_load_lds((const unsigned*)((const char*)(gbase) + (voff)[_i]), (LAS unsigned*)(lds + (bufoff) + ldsw + _i * 8192), 16, 0, 0); } while (0)
; #define PG8_LDA(dst, b, h) do { _Pragma("unroll") for (int m = 0; m < 4; ++m) _Pragma("unroll") for (int k = 0; k < 2; ++k) dst[m][k] = *(const LAS bf16x8*)(lds + PG8_SA(b, h) + aoff + m * 2048 + k * 1024); } while (0)
; #define PG8_LDB(dst, b, h) do { _Pragma("unroll") for (int n = 0; n < 2; ++n) _Pragma("unroll") for (int k = 0; k < 2; ++k) dst[n][k] = *(const LAS bf16x8*)(lds + PG8_SB(b, h) + boff + n * 2048 + k * 1024); } while (0)
; #define PG8_MMA(ai, bj, At, Bt) do { __builtin_amdgcn_s_setprio(1); _Pragma("unroll") for (int m = 0; m < 4; ++m) _Pragma("unroll") for (int n = 0; n < 2; ++n) _Pragma("unroll") for (int k = 0; k < 2; ++k) \
;     acc[ai][bj][m][n] = __builtin_amdgcn_mfma_f32_16x16x32_bf16(Bt[n][k], At[m][k], acc[ai][bj][m][n], 0, 0, 0); __builtin_amdgcn_s_setprio(0); } while (0)
; template <class Epi>
; __device__ __forceinline__ void gemm_phase(LAS unsigned char* lds, const Gemm g, const StaticOrder& S, const Epi& E, int wv0) {
;     ...
;       PG8_LDB(B0, 0, 0); PG8_SCHED; PG8_LDA(At, 0, 0); PG8_STAGE(PG8_SA(1, 1), a1 + hstepA, voffA);
;       PG8_WAIT_L(8); PG8_BAR; PG8_WAIT_L(0); PG8_MMA(0, 0, At, B0); PG8_BAR; PG8_SCHED;
;       PG8_LDB(B1, 0, 1); PG8_STAGE(PG8_SB(0, 0), b2, voffB);
;       PG8_BAR; PG8_WAIT_L(0); PG8_MMA(0, 1, At, B1); PG8_BAR;
;       PG8_LDA(At, 0, 1); PG8_STAGE(PG8_SA(0, 0), a2, voffA);
;       PG8_BAR; PG8_WAIT_L(0); PG8_MMA(1, 0, At, B0); PG8_BAR; PG8_SCHED;
;       PG8_STAGE(PG8_SB(0, 1), b2 + hstepB, voffB);
;       PG8_WAIT_V(6); PG8_BAR; PG8_MMA(1, 1, At, B1); PG8_BAR;
;       PG8_LDB(B0, 1, 0); PG8_SCHED; PG8_LDA(At, 1, 0); PG8_STAGE(PG8_SA(0, 1), a2 + hstepA, voffA);
;       PG8_WAIT_L(8); PG8_BAR; PG8_WAIT_L(0); PG8_MMA(0, 0, At, B0); PG8_BAR; PG8_SCHED;
;       PG8_LDB(B1, 1, 1); PG8_STAGE(PG8_SB(1, 0), b3, voffB);
;       PG8_BAR; PG8_WAIT_L(0); PG8_MMA(0, 1, At, B1); PG8_BAR;
;       PG8_LDA(At, 1, 1); PG8_STAGE(PG8_SA(1, 0), a3, voffA);
;       PG8_BAR; PG8_WAIT_L(0); PG8_MMA(1, 0, At, B0); PG8_BAR; PG8_SCHED;
;       PG8_STAGE(PG8_SB(1, 1), b3 + hstepB, voffB);
;       PG8_WAIT_V(6); PG8_BAR; PG8_MMA(1, 1, At, B1); PG8_BAR;
	s_waitcnt lgkmcnt(0)
	s_waitcnt lgkmcnt(0)
	v_mfma_f32_16x16x32_bf16 v[126:129], v[130:133], v[146:149], v[126:129]
	v_mfma_f32_16x16x32_bf16 v[122:125], v[138:141], v[146:149], v[122:125]
	v_mfma_f32_16x16x32_bf16 v[110:113], v[130:133], v[154:157], v[110:113]
	v_mfma_f32_16x16x32_bf16 v[106:109], v[138:141], v[154:157], v[106:109]
	v_mfma_f32_16x16x32_bf16 v[92:95], v[130:133], v[162:165], v[92:95]
	v_mfma_f32_16x16x32_bf16 v[88:91], v[138:141], v[162:165], v[88:91]
	v_mfma_f32_16x16x32_bf16 v[76:79], v[130:133], v[170:173], v[76:79]
	v_mfma_f32_16x16x32_bf16 v[72:75], v[138:141], v[170:173], v[72:75]
	v_mfma_f32_16x16x32_bf16 v[126:129], v[134:137], v[150:153], v[126:129]
	v_mfma_f32_16x16x32_bf16 v[122:125], v[142:145], v[150:153], v[122:125]
	v_mfma_f32_16x16x32_bf16 v[110:113], v[134:137], v[158:161], v[110:113]
	v_mfma_f32_16x16x32_bf16 v[106:109], v[142:145], v[158:161], v[106:109]
	v_mfma_f32_16x16x32_bf16 v[92:95], v[134:137], v[166:169], v[92:95]
	v_mfma_f32_16x16x32_bf16 v[88:91], v[142:145], v[166:169], v[88:91]
	v_mfma_f32_16x16x32_bf16 v[76:79], v[134:137], v[174:177], v[76:79]
	v_mfma_f32_16x16x32_bf16 v[72:75], v[142:145], v[174:177], v[72:75]
	s_barrier
	s_add_i32 s22, 0, 0x1c000
	s_add_i32 s0, s0, s35
	v_add_u32_e32 v190, s22, v219
	v_lshl_add_u64 v[204:205], v[204:205], 0, s[72:73]
	s_mov_b32 m0, s0
	ds_read_b128 v[178:181], v190
	ds_read_b128 v[182:185], v190 offset:1024
	ds_read_b128 v[186:189], v190 offset:2048
	ds_read_b128 v[190:193], v190 offset:3072
	global_load_lds_dwordx4 v[204:205], off
	v_lshl_add_u64 v[204:205], v[206:207], 0, s[72:73]
	s_add_i32 m0, s0, 0x2000
	s_nop 0
	global_load_lds_dwordx4 v[204:205], off
	s_barrier
	s_waitcnt lgkmcnt(0)
	s_waitcnt lgkmcnt(0)
	v_mfma_f32_16x16x32_bf16 v[118:121], v[178:181], v[146:149], v[118:121]
	v_mfma_f32_16x16x32_bf16 v[114:117], v[186:189], v[146:149], v[114:117]
	v_mfma_f32_16x16x32_bf16 v[102:105], v[178:181], v[154:157], v[102:105]
	v_mfma_f32_16x16x32_bf16 v[98:101], v[186:189], v[154:157], v[98:101]
	v_mfma_f32_16x16x32_bf16 v[84:87], v[178:181], v[162:165], v[84:87]
	v_mfma_f32_16x16x32_bf16 v[80:83], v[186:189], v[162:165], v[80:83]
	v_mfma_f32_16x16x32_bf16 v[68:71], v[178:181], v[170:173], v[68:71]
	v_mfma_f32_16x16x32_bf16 v[64:67], v[186:189], v[170:173], v[64:67]
	v_mfma_f32_16x16x32_bf16 v[118:121], v[182:185], v[150:153], v[118:121]
	v_mfma_f32_16x16x32_bf16 v[114:117], v[190:193], v[150:153], v[114:117]
	v_mfma_f32_16x16x32_bf16 v[102:105], v[182:185], v[158:161], v[102:105]
	v_mfma_f32_16x16x32_bf16 v[98:101], v[190:193], v[158:161], v[98:101]
	v_mfma_f32_16x16x32_bf16 v[84:87], v[182:185], v[166:169], v[84:87]
	v_mfma_f32_16x16x32_bf16 v[80:83], v[190:193], v[166:169], v[80:83]
	v_mfma_f32_16x16x32_bf16 v[68:71], v[182:185], v[174:177], v[68:71]
	v_mfma_f32_16x16x32_bf16 v[64:67], v[190:193], v[174:177], v[64:67]
	s_mov_b32 m0, s40
	v_lshl_add_u64 v[204:205], v[208:209], 0, s[72:73]
	s_barrier
	ds_read_b128 v[146:149], v225 offset:49152
	ds_read_b128 v[150:153], v225 offset:50176
	ds_read_b128 v[154:157], v225 offset:51200
	ds_read_b128 v[158:161], v225 offset:52224
	ds_read_b128 v[162:165], v225 offset:53248
	ds_read_b128 v[166:169], v225 offset:54272
	ds_read_b128 v[170:173], v225 offset:55296
	ds_read_b128 v[174:177], v225 offset:56320
	global_load_lds_dwordx4 v[204:205], off
	v_lshl_add_u64 v[204:205], v[210:211], 0, s[72:73]
	s_mov_b32 m0, s41
	s_nop 0
	global_load_lds_dwordx4 v[204:205], off
	s_barrier
	s_waitcnt lgkmcnt(0)
	s_waitcnt lgkmcnt(0)
	v_mfma_f32_16x16x32_bf16 v[60:63], v[130:133], v[146:149], v[60:63]
	v_mfma_f32_16x16x32_bf16 v[56:59], v[138:141], v[146:149], v[56:59]
	v_mfma_f32_16x16x32_bf16 v[44:47], v[130:133], v[154:157], v[44:47]
	v_mfma_f32_16x16x32_bf16 v[40:43], v[138:141], v[154:157], v[40:43]
	v_mfma_f32_16x16x32_bf16 v[28:31], v[130:133], v[162:165], v[28:31]
	v_mfma_f32_16x16x32_bf16 v[24:27], v[138:141], v[162:165], v[24:27]
	v_mfma_f32_16x16x32_bf16 v[12:15], v[130:133], v[170:173], v[12:15]
	v_mfma_f32_16x16x32_bf16 v[8:11], v[138:141], v[170:173], v[8:11]
	v_mfma_f32_16x16x32_bf16 v[60:63], v[134:137], v[150:153], v[60:63]
	v_mfma_f32_16x16x32_bf16 v[56:59], v[142:145], v[150:153], v[56:59]
	v_mfma_f32_16x16x32_bf16 v[44:47], v[134:137], v[158:161], v[44:47]
	v_mfma_f32_16x16x32_bf16 v[40:43], v[142:145], v[158:161], v[40:43]
	v_mfma_f32_16x16x32_bf16 v[28:31], v[134:137], v[166:169], v[28:31]
	v_mfma_f32_16x16x32_bf16 v[24:27], v[142:145], v[166:169], v[24:27]
	v_mfma_f32_16x16x32_bf16 v[12:15], v[134:137], v[174:177], v[12:15]
	v_mfma_f32_16x16x32_bf16 v[8:11], v[142:145], v[174:177], v[8:11]
	s_barrier
	s_add_u32 s18, s20, 0x80080
	s_addc_u32 s19, s21, 0
	s_add_i32 s0, s22, s35
	v_lshl_add_u64 v[130:131], s[18:19], 0, v[96:97]
	s_mov_b32 m0, s0
	s_nop 0
	global_load_lds_dwordx4 v[130:131], off
	v_lshl_add_u64 v[130:131], s[18:19], 0, v[198:199]
	s_add_i32 m0, s0, 0x2000
	s_nop 0
	global_load_lds_dwordx4 v[130:131], off
	s_waitcnt vmcnt(6)
	s_barrier
	v_mfma_f32_16x16x32_bf16 v[52:55], v[178:181], v[146:149], v[52:55]
	v_mfma_f32_16x16x32_bf16 v[48:51], v[186:189], v[146:149], v[48:51]
	v_mfma_f32_16x16x32_bf16 v[36:39], v[178:181], v[154:157], v[36:39]
	v_mfma_f32_16x16x32_bf16 v[32:35], v[186:189], v[154:157], v[32:35]
	v_mfma_f32_16x16x32_bf16 v[20:23], v[178:181], v[162:165], v[20:23]
	v_mfma_f32_16x16x32_bf16 v[16:19], v[186:189], v[162:165], v[16:19]
	v_mfma_f32_16x16x32_bf16 v[4:7], v[178:181], v[170:173], v[4:7]
	v_mfma_f32_16x16x32_bf16 v[0:3], v[186:189], v[170:173], v[0:3]
	v_mfma_f32_16x16x32_bf16 v[52:55], v[182:185], v[150:153], v[52:55]
	v_mfma_f32_16x16x32_bf16 v[48:51], v[190:193], v[150:153], v[48:51]
	v_mfma_f32_16x16x32_bf16 v[36:39], v[182:185], v[158:161], v[36:39]
	v_mfma_f32_16x16x32_bf16 v[32:35], v[190:193], v[158:161], v[32:35]
	v_mfma_f32_16x16x32_bf16 v[20:23], v[182:185], v[166:169], v[20:23]
	v_mfma_f32_16x16x32_bf16 v[16:19], v[190:193], v[166:169], v[16:19]
	v_mfma_f32_16x16x32_bf16 v[4:7], v[182:185], v[174:177], v[4:7]
	v_mfma_f32_16x16x32_bf16 v[0:3], v[190:193], v[174:177], v[0:3]
	s_add_i32 s49, s49, 2
	s_add_u32 s47, s47, 0x100
	s_addc_u32 s48, s48, 0
	s_cmp_gt_u32 s49, 29
	s_mov_b64 s[18:19], s[4:5]
	s_barrier
; __device__ __forceinline__ float bf_lo(unsigned u) { return __uint_as_float(u << 16); }
; __device__ __forceinline__ float bf_hi(unsigned u) { return __uint_as_float(u & 0xffff0000u); }
;   __device__ __forceinline__ void emit(const EpiPre& q0, int row, int col, f32x4 a, f32x4 b, const f32x4 (&hb)[2][2], const float (&hs)[2][4], int ai_, int m_, int bj_) const {
;     ...
;     } else if (MODE == E_PROJ) {
;       const int br = e.aux; const u32x4 gw = q.u0;
;       v[0] *= bf_lo(gw.x); v[1] *= bf_hi(gw.x); v[2] *= bf_lo(gw.y); v[3] *= bf_hi(gw.y);
;       v[4] *= bf_lo(gw.z); v[5] *= bf_hi(gw.z); v[6] *= bf_lo(gw.w); v[7] *= bf_hi(gw.w);
;       bf16_t* fa = (bf16_t*)e.facc + (size_t)row * DM + col;
;       if (br > 0) { const u32x4 pw = q.u1;
;         v[0] += bf_lo(pw.x); v[1] += bf_hi(pw.x); v[2] += bf_lo(pw.y); v[3] += bf_hi(pw.y); v[4] += bf_lo(pw.z); v[5] += bf_hi(pw.z); v[6] += bf_lo(pw.w); v[7] += bf_hi(pw.w); }
;       if (br == 2) store8bf((bf16_t*)e.out + (size_t)row * DM + col, v);
;       else store8bf(fa, v);
;   __device__ __forceinline__ void operator()(const f32x4 (&acc)[2][2][4][2], const pg8::Unit& u, int wr, int wc, int fr, int fq) const {
;     ...
;     for (int gi = 0; gi < 4; ++gi) {
;       const int ai = gi >> 1, mp = gi & 1;
;       if (gi + 1 < 4) { const int ai2 = (gi + 1) >> 1, mp2 = (gi + 1) & 1;
; #pragma unroll
;         for (int i = 0; i < 4; ++i) preload(q[(gi + 1) & 1][i], row0 + ai2 * 128 + (2 * mp2 + (i >> 1)) * 16, col0 + (i & 1) * 128); }
;       asm volatile("" ::: "memory");
; #pragma unroll
;       for (int i = 0; i < 4; ++i) { const int m = 2 * mp + (i >> 1), bj = i & 1; emit(q[gi & 1][i], row0 + ai * 128 + m * 16, col0 + bj * 128, acc[ai][bj][m][0], acc[ai][bj][m][1], hb, hs, ai, m, bj); }
;       asm volatile("" ::: "memory");
	s_cbranch_scc0 .LBB0_1003
	s_setprio 0
	v_lshl_add_u32 v209, s1, 8, v218
	v_lshl_or_b32 v211, s45, 8, v224
	v_mul_u32_u24_e32 v208, 0x3000, v209
	v_lshlrev_b32_e32 v209, 12, v209
	v_lshl_add_u32 v208, v211, 1, v208
	v_lshl_add_u32 v209, v211, 1, v209
	v_add_u32_e32 v211, 0x0, v208
	global_load_dwordx4 v[130:133], v211, s[8:9]
	v_add_u32_e32 v212, 0x0, v209
	global_load_dwordx4 v[134:137], v212, s[6:7]
	global_load_dwordx4 v[138:141], v211, s[8:9] offset:256
	global_load_dwordx4 v[142:145], v212, s[6:7] offset:256
	v_add_u32_e32 v211, 0x30000, v208
	global_load_dwordx4 v[146:149], v211, s[8:9]
	v_add_u32_e32 v212, 0x10000, v209
	global_load_dwordx4 v[150:153], v212, s[6:7]
	global_load_dwordx4 v[154:157], v211, s[8:9] offset:256
	global_load_dwordx4 v[158:161], v212, s[6:7] offset:256
	v_add_u32_e32 v211, 0x60000, v208
	global_load_dwordx4 v[162:165], v211, s[8:9]
	v_add_u32_e32 v212, 0x20000, v209
	global_load_dwordx4 v[166:169], v212, s[6:7]
	global_load_dwordx4 v[170:173], v211, s[8:9] offset:256
	global_load_dwordx4 v[174:177], v212, s[6:7] offset:256
	v_add_u32_e32 v211, 0x90000, v208
	global_load_dwordx4 v[178:181], v211, s[8:9]
	v_add_u32_e32 v212, 0x30000, v209
	global_load_dwordx4 v[182:185], v212, s[6:7]
	global_load_dwordx4 v[186:189], v211, s[8:9] offset:256
	global_load_dwordx4 v[190:193], v212, s[6:7] offset:256
	s_waitcnt vmcnt(14)
	v_lshlrev_b32_e32 v204, 16, v130
	v_and_b32_e32 v205, 0xffff0000, v130
	v_lshlrev_b32_e32 v206, 16, v134
	v_and_b32_e32 v207, 0xffff0000, v134
	v_pk_fma_f32 v[126:127], v[126:127], v[204:205], v[206:207]
	v_lshlrev_b32_e32 v204, 16, v131
	v_and_b32_e32 v205, 0xffff0000, v131
	v_lshlrev_b32_e32 v206, 16, v135
	v_and_b32_e32 v207, 0xffff0000, v135
	v_pk_fma_f32 v[128:129], v[128:129], v[204:205], v[206:207]
	v_lshlrev_b32_e32 v204, 16, v132
	v_and_b32_e32 v205, 0xffff0000, v132
	v_lshlrev_b32_e32 v206, 16, v136
	v_and_b32_e32 v207, 0xffff0000, v136
	v_pk_fma_f32 v[122:123], v[122:123], v[204:205], v[206:207]
	v_lshlrev_b32_e32 v204, 16, v133
	v_and_b32_e32 v205, 0xffff0000, v133
	v_lshlrev_b32_e32 v206, 16, v137
	v_and_b32_e32 v207, 0xffff0000, v137
	v_pk_fma_f32 v[124:125], v[124:125], v[204:205], v[206:207]
	v_cvt_pk_bf16_f32 v126, v126, v127
	v_cvt_pk_bf16_f32 v127, v128, v129
	v_cvt_pk_bf16_f32 v128, v122, v123
	v_cvt_pk_bf16_f32 v129, v124, v125
	v_add_u32_e32 v211, 0x180000, v208
	global_load_dwordx4 v[130:133], v211, s[8:9]
	v_add_u32_e32 v212, 0x80000, v209
	global_load_dwordx4 v[134:137], v212, s[6:7]
	s_waitcnt vmcnt(14)
	v_lshlrev_b32_e32 v204, 16, v138
	v_and_b32_e32 v205, 0xffff0000, v138
	v_lshlrev_b32_e32 v206, 16, v142
	v_and_b32_e32 v207, 0xffff0000, v142
	v_pk_fma_f32 v[118:119], v[118:119], v[204:205], v[206:207]
	v_lshlrev_b32_e32 v204, 16, v139
	v_and_b32_e32 v205, 0xffff0000, v139
	v_lshlrev_b32_e32 v206, 16, v143
	v_and_b32_e32 v207, 0xffff0000, v143
	v_pk_fma_f32 v[120:121], v[120:121], v[204:205], v[206:207]
	v_lshlrev_b32_e32 v204, 16, v140
	v_and_b32_e32 v205, 0xffff0000, v140
	v_lshlrev_b32_e32 v206, 16, v144
	v_and_b32_e32 v207, 0xffff0000, v144
	v_pk_fma_f32 v[114:115], v[114:115], v[204:205], v[206:207]
	v_lshlrev_b32_e32 v204, 16, v141
	v_and_b32_e32 v205, 0xffff0000, v141
	v_lshlrev_b32_e32 v206, 16, v145
	v_and_b32_e32 v207, 0xffff0000, v145
	v_pk_fma_f32 v[116:117], v[116:117], v[204:205], v[206:207]
	v_cvt_pk_bf16_f32 v118, v118, v119
	v_cvt_pk_bf16_f32 v119, v120, v121
	v_cvt_pk_bf16_f32 v120, v114, v115
	v_cvt_pk_bf16_f32 v121, v116, v117
	global_load_dwordx4 v[138:141], v211, s[8:9] offset:256
	global_load_dwordx4 v[142:145], v212, s[6:7] offset:256
	s_waitcnt vmcnt(14)
	v_lshlrev_b32_e32 v204, 16, v146
	v_and_b32_e32 v205, 0xffff0000, v146
	v_lshlrev_b32_e32 v206, 16, v150
	v_and_b32_e32 v207, 0xffff0000, v150
	v_pk_fma_f32 v[110:111], v[110:111], v[204:205], v[206:207]
	v_lshlrev_b32_e32 v204, 16, v147
	v_and_b32_e32 v205, 0xffff0000, v147
	v_lshlrev_b32_e32 v206, 16, v151
	v_and_b32_e32 v207, 0xffff0000, v151
	v_pk_fma_f32 v[112:113], v[112:113], v[204:205], v[206:207]
	v_lshlrev_b32_e32 v204, 16, v148
	v_and_b32_e32 v205, 0xffff0000, v148
	v_lshlrev_b32_e32 v206, 16, v152
	v_and_b32_e32 v207, 0xffff0000, v152
	v_pk_fma_f32 v[106:107], v[106:107], v[204:205], v[206:207]
	v_lshlrev_b32_e32 v204, 16, v149
	v_and_b32_e32 v205, 0xffff0000, v149
	v_lshlrev_b32_e32 v206, 16, v153
	v_and_b32_e32 v207, 0xffff0000, v153
	v_pk_fma_f32 v[108:109], v[108:109], v[204:205], v[206:207]
	v_cvt_pk_bf16_f32 v110, v110, v111
	v_cvt_pk_bf16_f32 v111, v112, v113
	v_cvt_pk_bf16_f32 v112, v106, v107
	v_cvt_pk_bf16_f32 v113, v108, v109
	v_add_u32_e32 v211, 0x1b0000, v208
	global_load_dwordx4 v[146:149], v211, s[8:9]
	v_add_u32_e32 v212, 0x90000, v209
	global_load_dwordx4 v[150:153], v212, s[6:7]
	s_waitcnt vmcnt(14)
	v_lshlrev_b32_e32 v204, 16, v154
	v_and_b32_e32 v205, 0xffff0000, v154
	v_lshlrev_b32_e32 v206, 16, v158
	v_and_b32_e32 v207, 0xffff0000, v158
	v_pk_fma_f32 v[102:103], v[102:103], v[204:205], v[206:207]
	v_lshlrev_b32_e32 v204, 16, v155
	v_and_b32_e32 v205, 0xffff0000, v155
	v_lshlrev_b32_e32 v206, 16, v159
	v_and_b32_e32 v207, 0xffff0000, v159
	v_pk_fma_f32 v[104:105], v[104:105], v[204:205], v[206:207]
	v_lshlrev_b32_e32 v204, 16, v156
	v_and_b32_e32 v205, 0xffff0000, v156
	v_lshlrev_b32_e32 v206, 16, v160
	v_and_b32_e32 v207, 0xffff0000, v160
	v_pk_fma_f32 v[98:99], v[98:99], v[204:205], v[206:207]
	v_lshlrev_b32_e32 v204, 16, v157
	v_and_b32_e32 v205, 0xffff0000, v157
	v_lshlrev_b32_e32 v206, 16, v161
	v_and_b32_e32 v207, 0xffff0000, v161
	v_pk_fma_f32 v[100:101], v[100:101], v[204:205], v[206:207]
	v_cvt_pk_bf16_f32 v102, v102, v103
	v_cvt_pk_bf16_f32 v103, v104, v105
	v_cvt_pk_bf16_f32 v104, v98, v99
	v_cvt_pk_bf16_f32 v105, v100, v101
	global_load_dwordx4 v[154:157], v211, s[8:9] offset:256
	global_load_dwordx4 v[158:161], v212, s[6:7] offset:256
	s_waitcnt vmcnt(14)
; __device__ __forceinline__ float bf_lo(unsigned u) { return __uint_as_float(u << 16); }
; __device__ __forceinline__ float bf_hi(unsigned u) { return __uint_as_float(u & 0xffff0000u); }
;   __device__ __forceinline__ void emit(const EpiPre& q0, int row, int col, f32x4 a, f32x4 b, const f32x4 (&hb)[2][2], const float (&hs)[2][4], int ai_, int m_, int bj_) const {
;     ...
;     } else if (MODE == E_PROJ) {
;       const int br = e.aux; const u32x4 gw = q.u0;
;       v[0] *= bf_lo(gw.x); v[1] *= bf_hi(gw.x); v[2] *= bf_lo(gw.y); v[3] *= bf_hi(gw.y);
;       v[4] *= bf_lo(gw.z); v[5] *= bf_hi(gw.z); v[6] *= bf_lo(gw.w); v[7] *= bf_hi(gw.w);
;       bf16_t* fa = (bf16_t*)e.facc + (size_t)row * DM + col;
;       if (br > 0) { const u32x4 pw = q.u1;
;         v[0] += bf_lo(pw.x); v[1] += bf_hi(pw.x); v[2] += bf_lo(pw.y); v[3] += bf_hi(pw.y); v[4] += bf_lo(pw.z); v[5] += bf_hi(pw.z); v[6] += bf_lo(pw.w); v[7] += bf_hi(pw.w); }
;       if (br == 2) store8bf((bf16_t*)e.out + (size_t)row * DM + col, v);
;       else store8bf(fa, v);
	v_lshlrev_b32_e32 v204, 16, v162
	v_and_b32_e32 v205, 0xffff0000, v162
	v_lshlrev_b32_e32 v206, 16, v166
	v_and_b32_e32 v207, 0xffff0000, v166
	v_pk_fma_f32 v[92:93], v[92:93], v[204:205], v[206:207]
	v_lshlrev_b32_e32 v204, 16, v163
	v_and_b32_e32 v205, 0xffff0000, v163
	v_lshlrev_b32_e32 v206, 16, v167
	v_and_b32_e32 v207, 0xffff0000, v167
	v_pk_fma_f32 v[94:95], v[94:95], v[204:205], v[206:207]
	v_lshlrev_b32_e32 v204, 16, v164
	v_and_b32_e32 v205, 0xffff0000, v164
	v_lshlrev_b32_e32 v206, 16, v168
	v_and_b32_e32 v207, 0xffff0000, v168
	v_pk_fma_f32 v[88:89], v[88:89], v[204:205], v[206:207]
	v_lshlrev_b32_e32 v204, 16, v165
	v_and_b32_e32 v205, 0xffff0000, v165
	v_lshlrev_b32_e32 v206, 16, v169
	v_and_b32_e32 v207, 0xffff0000, v169
	v_pk_fma_f32 v[90:91], v[90:91], v[204:205], v[206:207]
	v_cvt_pk_bf16_f32 v92, v92, v93
	v_cvt_pk_bf16_f32 v93, v94, v95
	v_cvt_pk_bf16_f32 v94, v88, v89
	v_cvt_pk_bf16_f32 v95, v90, v91
	v_add_u32_e32 v211, 0x1e0000, v208
	global_load_dwordx4 v[162:165], v211, s[8:9]
	v_add_u32_e32 v212, 0xa0000, v209
	global_load_dwordx4 v[166:169], v212, s[6:7]
	s_waitcnt vmcnt(14)
	v_lshlrev_b32_e32 v204, 16, v170
	v_and_b32_e32 v205, 0xffff0000, v170
	v_lshlrev_b32_e32 v206, 16, v174
	v_and_b32_e32 v207, 0xffff0000, v174
	v_pk_fma_f32 v[84:85], v[84:85], v[204:205], v[206:207]
	v_lshlrev_b32_e32 v204, 16, v171
	v_and_b32_e32 v205, 0xffff0000, v171
	v_lshlrev_b32_e32 v206, 16, v175
	v_and_b32_e32 v207, 0xffff0000, v175
	v_pk_fma_f32 v[86:87], v[86:87], v[204:205], v[206:207]
	v_lshlrev_b32_e32 v204, 16, v172
	v_and_b32_e32 v205, 0xffff0000, v172
	v_lshlrev_b32_e32 v206, 16, v176
	v_and_b32_e32 v207, 0xffff0000, v176
	v_pk_fma_f32 v[80:81], v[80:81], v[204:205], v[206:207]
	v_lshlrev_b32_e32 v204, 16, v173
	v_and_b32_e32 v205, 0xffff0000, v173
	v_lshlrev_b32_e32 v206, 16, v177
	v_and_b32_e32 v207, 0xffff0000, v177
	v_pk_fma_f32 v[82:83], v[82:83], v[204:205], v[206:207]
	v_cvt_pk_bf16_f32 v84, v84, v85
	v_cvt_pk_bf16_f32 v85, v86, v87
	v_cvt_pk_bf16_f32 v86, v80, v81
	v_cvt_pk_bf16_f32 v87, v82, v83
	global_load_dwordx4 v[170:173], v211, s[8:9] offset:256
	global_load_dwordx4 v[174:177], v212, s[6:7] offset:256
	s_waitcnt vmcnt(14)
	v_lshlrev_b32_e32 v204, 16, v178
	v_and_b32_e32 v205, 0xffff0000, v178
	v_lshlrev_b32_e32 v206, 16, v182
	v_and_b32_e32 v207, 0xffff0000, v182
	v_pk_fma_f32 v[76:77], v[76:77], v[204:205], v[206:207]
	v_lshlrev_b32_e32 v204, 16, v179
	v_and_b32_e32 v205, 0xffff0000, v179
	v_lshlrev_b32_e32 v206, 16, v183
	v_and_b32_e32 v207, 0xffff0000, v183
	v_pk_fma_f32 v[78:79], v[78:79], v[204:205], v[206:207]
	v_lshlrev_b32_e32 v204, 16, v180
	v_and_b32_e32 v205, 0xffff0000, v180
	v_lshlrev_b32_e32 v206, 16, v184
	v_and_b32_e32 v207, 0xffff0000, v184
	v_pk_fma_f32 v[72:73], v[72:73], v[204:205], v[206:207]
	v_lshlrev_b32_e32 v204, 16, v181
	v_and_b32_e32 v205, 0xffff0000, v181
	v_lshlrev_b32_e32 v206, 16, v185
	v_and_b32_e32 v207, 0xffff0000, v185
	v_pk_fma_f32 v[74:75], v[74:75], v[204:205], v[206:207]
	v_cvt_pk_bf16_f32 v76, v76, v77
	v_cvt_pk_bf16_f32 v77, v78, v79
	v_cvt_pk_bf16_f32 v78, v72, v73
	v_cvt_pk_bf16_f32 v79, v74, v75
	v_add_u32_e32 v211, 0x210000, v208
	global_load_dwordx4 v[178:181], v211, s[8:9]
	v_add_u32_e32 v212, 0xb0000, v209
	global_load_dwordx4 v[182:185], v212, s[6:7]
	s_waitcnt vmcnt(14)
	v_lshlrev_b32_e32 v204, 16, v186
	v_and_b32_e32 v205, 0xffff0000, v186
	v_lshlrev_b32_e32 v206, 16, v190
	v_and_b32_e32 v207, 0xffff0000, v190
	v_pk_fma_f32 v[68:69], v[68:69], v[204:205], v[206:207]
	v_lshlrev_b32_e32 v204, 16, v187
	v_and_b32_e32 v205, 0xffff0000, v187
	v_lshlrev_b32_e32 v206, 16, v191
	v_and_b32_e32 v207, 0xffff0000, v191
	v_pk_fma_f32 v[70:71], v[70:71], v[204:205], v[206:207]
	v_lshlrev_b32_e32 v204, 16, v188
	v_and_b32_e32 v205, 0xffff0000, v188
	v_lshlrev_b32_e32 v206, 16, v192
	v_and_b32_e32 v207, 0xffff0000, v192
	v_pk_fma_f32 v[64:65], v[64:65], v[204:205], v[206:207]
	v_lshlrev_b32_e32 v204, 16, v189
	v_and_b32_e32 v205, 0xffff0000, v189
	v_lshlrev_b32_e32 v206, 16, v193
	v_and_b32_e32 v207, 0xffff0000, v193
	v_pk_fma_f32 v[66:67], v[66:67], v[204:205], v[206:207]
	v_cvt_pk_bf16_f32 v68, v68, v69
	v_cvt_pk_bf16_f32 v69, v70, v71
	v_cvt_pk_bf16_f32 v70, v64, v65
	v_cvt_pk_bf16_f32 v71, v66, v67
	global_load_dwordx4 v[186:189], v211, s[8:9] offset:256
	global_load_dwordx4 v[190:193], v212, s[6:7] offset:256
	v_add_u32_e32 v212, 0x0, v209
	global_store_dwordx4 v212, v[126:129], s[6:7]
	global_store_dwordx4 v212, v[118:121], s[6:7] offset:256
	v_add_u32_e32 v212, 0x10000, v209
	global_store_dwordx4 v212, v[110:113], s[6:7]
	global_store_dwordx4 v212, v[102:105], s[6:7] offset:256
	v_add_u32_e32 v212, 0x20000, v209
	global_store_dwordx4 v212, v[92:95], s[6:7]
	global_store_dwordx4 v212, v[84:87], s[6:7] offset:256
	v_add_u32_e32 v212, 0x30000, v209
	global_store_dwordx4 v212, v[76:79], s[6:7]
	global_store_dwordx4 v212, v[68:71], s[6:7] offset:256
	s_waitcnt vmcnt(22)
	v_lshlrev_b32_e32 v204, 16, v130
	v_and_b32_e32 v205, 0xffff0000, v130
	v_lshlrev_b32_e32 v206, 16, v134
	v_and_b32_e32 v207, 0xffff0000, v134
	v_pk_fma_f32 v[60:61], v[60:61], v[204:205], v[206:207]
	v_lshlrev_b32_e32 v204, 16, v131
	v_and_b32_e32 v205, 0xffff0000, v131
	v_lshlrev_b32_e32 v206, 16, v135
	v_and_b32_e32 v207, 0xffff0000, v135
	v_pk_fma_f32 v[62:63], v[62:63], v[204:205], v[206:207]
	v_lshlrev_b32_e32 v204, 16, v132
	v_and_b32_e32 v205, 0xffff0000, v132
	v_lshlrev_b32_e32 v206, 16, v136
	v_and_b32_e32 v207, 0xffff0000, v136
	v_pk_fma_f32 v[56:57], v[56:57], v[204:205], v[206:207]
	v_lshlrev_b32_e32 v204, 16, v133
	v_and_b32_e32 v205, 0xffff0000, v133
	v_lshlrev_b32_e32 v206, 16, v137
	v_and_b32_e32 v207, 0xffff0000, v137
	v_pk_fma_f32 v[58:59], v[58:59], v[204:205], v[206:207]
	v_cvt_pk_bf16_f32 v60, v60, v61
	v_cvt_pk_bf16_f32 v61, v62, v63
	v_cvt_pk_bf16_f32 v62, v56, v57
	v_cvt_pk_bf16_f32 v63, v58, v59
	v_add_u32_e32 v212, 0x80000, v209
	global_store_dwordx4 v212, v[60:63], s[6:7]
	s_waitcnt vmcnt(21)
; __device__ __forceinline__ float bf_lo(unsigned u) { return __uint_as_float(u << 16); }
; __device__ __forceinline__ float bf_hi(unsigned u) { return __uint_as_float(u & 0xffff0000u); }
;   __device__ __forceinline__ void emit(const EpiPre& q0, int row, int col, f32x4 a, f32x4 b, const f32x4 (&hb)[2][2], const float (&hs)[2][4], int ai_, int m_, int bj_) const {
;     ...
;     } else if (MODE == E_PROJ) {
;       const int br = e.aux; const u32x4 gw = q.u0;
;       v[0] *= bf_lo(gw.x); v[1] *= bf_hi(gw.x); v[2] *= bf_lo(gw.y); v[3] *= bf_hi(gw.y);
;       v[4] *= bf_lo(gw.z); v[5] *= bf_hi(gw.z); v[6] *= bf_lo(gw.w); v[7] *= bf_hi(gw.w);
;       bf16_t* fa = (bf16_t*)e.facc + (size_t)row * DM + col;
;       if (br > 0) { const u32x4 pw = q.u1;
;         v[0] += bf_lo(pw.x); v[1] += bf_hi(pw.x); v[2] += bf_lo(pw.y); v[3] += bf_hi(pw.y); v[4] += bf_lo(pw.z); v[5] += bf_hi(pw.z); v[6] += bf_lo(pw.w); v[7] += bf_hi(pw.w); }
;       if (br == 2) store8bf((bf16_t*)e.out + (size_t)row * DM + col, v);
;       else store8bf(fa, v);
	v_lshlrev_b32_e32 v204, 16, v138
	v_and_b32_e32 v205, 0xffff0000, v138
	v_lshlrev_b32_e32 v206, 16, v142
	v_and_b32_e32 v207, 0xffff0000, v142
	v_pk_fma_f32 v[52:53], v[52:53], v[204:205], v[206:207]
	v_lshlrev_b32_e32 v204, 16, v139
	v_and_b32_e32 v205, 0xffff0000, v139
	v_lshlrev_b32_e32 v206, 16, v143
	v_and_b32_e32 v207, 0xffff0000, v143
	v_pk_fma_f32 v[54:55], v[54:55], v[204:205], v[206:207]
	v_lshlrev_b32_e32 v204, 16, v140
	v_and_b32_e32 v205, 0xffff0000, v140
	v_lshlrev_b32_e32 v206, 16, v144
	v_and_b32_e32 v207, 0xffff0000, v144
	v_pk_fma_f32 v[48:49], v[48:49], v[204:205], v[206:207]
	v_lshlrev_b32_e32 v204, 16, v141
	v_and_b32_e32 v205, 0xffff0000, v141
	v_lshlrev_b32_e32 v206, 16, v145
	v_and_b32_e32 v207, 0xffff0000, v145
	v_pk_fma_f32 v[50:51], v[50:51], v[204:205], v[206:207]
	v_cvt_pk_bf16_f32 v52, v52, v53
	v_cvt_pk_bf16_f32 v53, v54, v55
	v_cvt_pk_bf16_f32 v54, v48, v49
	v_cvt_pk_bf16_f32 v55, v50, v51
	global_store_dwordx4 v212, v[52:55], s[6:7] offset:256
	s_waitcnt vmcnt(20)
	v_lshlrev_b32_e32 v204, 16, v146
	v_and_b32_e32 v205, 0xffff0000, v146
	v_lshlrev_b32_e32 v206, 16, v150
	v_and_b32_e32 v207, 0xffff0000, v150
	v_pk_fma_f32 v[44:45], v[44:45], v[204:205], v[206:207]
	v_lshlrev_b32_e32 v204, 16, v147
	v_and_b32_e32 v205, 0xffff0000, v147
	v_lshlrev_b32_e32 v206, 16, v151
	v_and_b32_e32 v207, 0xffff0000, v151
	v_pk_fma_f32 v[46:47], v[46:47], v[204:205], v[206:207]
	v_lshlrev_b32_e32 v204, 16, v148
	v_and_b32_e32 v205, 0xffff0000, v148
	v_lshlrev_b32_e32 v206, 16, v152
	v_and_b32_e32 v207, 0xffff0000, v152
	v_pk_fma_f32 v[40:41], v[40:41], v[204:205], v[206:207]
	v_lshlrev_b32_e32 v204, 16, v149
	v_and_b32_e32 v205, 0xffff0000, v149
	v_lshlrev_b32_e32 v206, 16, v153
	v_and_b32_e32 v207, 0xffff0000, v153
	v_pk_fma_f32 v[42:43], v[42:43], v[204:205], v[206:207]
	v_cvt_pk_bf16_f32 v44, v44, v45
	v_cvt_pk_bf16_f32 v45, v46, v47
	v_cvt_pk_bf16_f32 v46, v40, v41
	v_cvt_pk_bf16_f32 v47, v42, v43
	v_add_u32_e32 v212, 0x90000, v209
	global_store_dwordx4 v212, v[44:47], s[6:7]
	s_waitcnt vmcnt(19)
	v_lshlrev_b32_e32 v204, 16, v154
	v_and_b32_e32 v205, 0xffff0000, v154
	v_lshlrev_b32_e32 v206, 16, v158
	v_and_b32_e32 v207, 0xffff0000, v158
	v_pk_fma_f32 v[36:37], v[36:37], v[204:205], v[206:207]
	v_lshlrev_b32_e32 v204, 16, v155
	v_and_b32_e32 v205, 0xffff0000, v155
	v_lshlrev_b32_e32 v206, 16, v159
	v_and_b32_e32 v207, 0xffff0000, v159
	v_pk_fma_f32 v[38:39], v[38:39], v[204:205], v[206:207]
	v_lshlrev_b32_e32 v204, 16, v156
	v_and_b32_e32 v205, 0xffff0000, v156
	v_lshlrev_b32_e32 v206, 16, v160
	v_and_b32_e32 v207, 0xffff0000, v160
	v_pk_fma_f32 v[32:33], v[32:33], v[204:205], v[206:207]
	v_lshlrev_b32_e32 v204, 16, v157
	v_and_b32_e32 v205, 0xffff0000, v157
	v_lshlrev_b32_e32 v206, 16, v161
	v_and_b32_e32 v207, 0xffff0000, v161
	v_pk_fma_f32 v[34:35], v[34:35], v[204:205], v[206:207]
	v_cvt_pk_bf16_f32 v36, v36, v37
	v_cvt_pk_bf16_f32 v37, v38, v39
	v_cvt_pk_bf16_f32 v38, v32, v33
	v_cvt_pk_bf16_f32 v39, v34, v35
	global_store_dwordx4 v212, v[36:39], s[6:7] offset:256
	s_waitcnt vmcnt(18)
	v_lshlrev_b32_e32 v204, 16, v162
	v_and_b32_e32 v205, 0xffff0000, v162
	v_lshlrev_b32_e32 v206, 16, v166
	v_and_b32_e32 v207, 0xffff0000, v166
	v_pk_fma_f32 v[28:29], v[28:29], v[204:205], v[206:207]
	v_lshlrev_b32_e32 v204, 16, v163
	v_and_b32_e32 v205, 0xffff0000, v163
	v_lshlrev_b32_e32 v206, 16, v167
	v_and_b32_e32 v207, 0xffff0000, v167
	v_pk_fma_f32 v[30:31], v[30:31], v[204:205], v[206:207]
	v_lshlrev_b32_e32 v204, 16, v164
	v_and_b32_e32 v205, 0xffff0000, v164
	v_lshlrev_b32_e32 v206, 16, v168
	v_and_b32_e32 v207, 0xffff0000, v168
	v_pk_fma_f32 v[24:25], v[24:25], v[204:205], v[206:207]
	v_lshlrev_b32_e32 v204, 16, v165
	v_and_b32_e32 v205, 0xffff0000, v165
	v_lshlrev_b32_e32 v206, 16, v169
	v_and_b32_e32 v207, 0xffff0000, v169
	v_pk_fma_f32 v[26:27], v[26:27], v[204:205], v[206:207]
	v_cvt_pk_bf16_f32 v28, v28, v29
	v_cvt_pk_bf16_f32 v29, v30, v31
	v_cvt_pk_bf16_f32 v30, v24, v25
	v_cvt_pk_bf16_f32 v31, v26, v27
	v_add_u32_e32 v212, 0xa0000, v209
	global_store_dwordx4 v212, v[28:31], s[6:7]
	s_waitcnt vmcnt(17)
; __device__ __forceinline__ float bf_lo(unsigned u) { return __uint_as_float(u << 16); }
; __device__ __forceinline__ float bf_hi(unsigned u) { return __uint_as_float(u & 0xffff0000u); }
; #define PG8_WAIT_V(n) asm volatile("s_waitcnt vmcnt(" #n ")" ::: "memory")
; #define PG8_BAR __builtin_amdgcn_s_barrier()
; template <class Epi>
; __device__ __forceinline__ void gemm_phase(LAS unsigned char* lds, const Gemm g, const StaticOrder& S, const Epi& E, int wv0) {
;     ...
;   PG8_WAIT_V(0);
;   if (wr == 0) PG8_BAR;
;   PG8_BAR;
;   __device__ __forceinline__ void emit(const EpiPre& q0, int row, int col, f32x4 a, f32x4 b, const f32x4 (&hb)[2][2], const float (&hs)[2][4], int ai_, int m_, int bj_) const {
;     ...
;     } else if (MODE == E_PROJ) {
;       const int br = e.aux; const u32x4 gw = q.u0;
;       v[0] *= bf_lo(gw.x); v[1] *= bf_hi(gw.x); v[2] *= bf_lo(gw.y); v[3] *= bf_hi(gw.y);
;       v[4] *= bf_lo(gw.z); v[5] *= bf_hi(gw.z); v[6] *= bf_lo(gw.w); v[7] *= bf_hi(gw.w);
;       bf16_t* fa = (bf16_t*)e.facc + (size_t)row * DM + col;
;       if (br > 0) { const u32x4 pw = q.u1;
;         v[0] += bf_lo(pw.x); v[1] += bf_hi(pw.x); v[2] += bf_lo(pw.y); v[3] += bf_hi(pw.y); v[4] += bf_lo(pw.z); v[5] += bf_hi(pw.z); v[6] += bf_lo(pw.w); v[7] += bf_hi(pw.w); }
;       if (br == 2) store8bf((bf16_t*)e.out + (size_t)row * DM + col, v);
;       else store8bf(fa, v);
	v_lshlrev_b32_e32 v204, 16, v170
	v_and_b32_e32 v205, 0xffff0000, v170
	v_lshlrev_b32_e32 v206, 16, v174
	v_and_b32_e32 v207, 0xffff0000, v174
	v_pk_fma_f32 v[20:21], v[20:21], v[204:205], v[206:207]
	v_lshlrev_b32_e32 v204, 16, v171
	v_and_b32_e32 v205, 0xffff0000, v171
	v_lshlrev_b32_e32 v206, 16, v175
	v_and_b32_e32 v207, 0xffff0000, v175
	v_pk_fma_f32 v[22:23], v[22:23], v[204:205], v[206:207]
	v_lshlrev_b32_e32 v204, 16, v172
	v_and_b32_e32 v205, 0xffff0000, v172
	v_lshlrev_b32_e32 v206, 16, v176
	v_and_b32_e32 v207, 0xffff0000, v176
	v_pk_fma_f32 v[16:17], v[16:17], v[204:205], v[206:207]
	v_lshlrev_b32_e32 v204, 16, v173
	v_and_b32_e32 v205, 0xffff0000, v173
	v_lshlrev_b32_e32 v206, 16, v177
	v_and_b32_e32 v207, 0xffff0000, v177
	v_pk_fma_f32 v[18:19], v[18:19], v[204:205], v[206:207]
	v_cvt_pk_bf16_f32 v20, v20, v21
	v_cvt_pk_bf16_f32 v21, v22, v23
	v_cvt_pk_bf16_f32 v22, v16, v17
	v_cvt_pk_bf16_f32 v23, v18, v19
	global_store_dwordx4 v212, v[20:23], s[6:7] offset:256
	s_waitcnt vmcnt(16)
	v_lshlrev_b32_e32 v204, 16, v178
	v_and_b32_e32 v205, 0xffff0000, v178
	v_lshlrev_b32_e32 v206, 16, v182
	v_and_b32_e32 v207, 0xffff0000, v182
	v_pk_fma_f32 v[12:13], v[12:13], v[204:205], v[206:207]
	v_lshlrev_b32_e32 v204, 16, v179
	v_and_b32_e32 v205, 0xffff0000, v179
	v_lshlrev_b32_e32 v206, 16, v183
	v_and_b32_e32 v207, 0xffff0000, v183
	v_pk_fma_f32 v[14:15], v[14:15], v[204:205], v[206:207]
	v_lshlrev_b32_e32 v204, 16, v180
	v_and_b32_e32 v205, 0xffff0000, v180
	v_lshlrev_b32_e32 v206, 16, v184
	v_and_b32_e32 v207, 0xffff0000, v184
	v_pk_fma_f32 v[8:9], v[8:9], v[204:205], v[206:207]
	v_lshlrev_b32_e32 v204, 16, v181
	v_and_b32_e32 v205, 0xffff0000, v181
	v_lshlrev_b32_e32 v206, 16, v185
	v_and_b32_e32 v207, 0xffff0000, v185
	v_pk_fma_f32 v[10:11], v[10:11], v[204:205], v[206:207]
	v_cvt_pk_bf16_f32 v12, v12, v13
	v_cvt_pk_bf16_f32 v13, v14, v15
	v_cvt_pk_bf16_f32 v14, v8, v9
	v_cvt_pk_bf16_f32 v15, v10, v11
	v_add_u32_e32 v212, 0xb0000, v209
	global_store_dwordx4 v212, v[12:15], s[6:7]
	s_waitcnt vmcnt(15)
	v_lshlrev_b32_e32 v204, 16, v186
	v_and_b32_e32 v205, 0xffff0000, v186
	v_lshlrev_b32_e32 v206, 16, v190
	v_and_b32_e32 v207, 0xffff0000, v190
	v_pk_fma_f32 v[4:5], v[4:5], v[204:205], v[206:207]
	v_lshlrev_b32_e32 v204, 16, v187
	v_and_b32_e32 v205, 0xffff0000, v187
	v_lshlrev_b32_e32 v206, 16, v191
	v_and_b32_e32 v207, 0xffff0000, v191
	v_pk_fma_f32 v[6:7], v[6:7], v[204:205], v[206:207]
	v_lshlrev_b32_e32 v204, 16, v188
	v_and_b32_e32 v205, 0xffff0000, v188
	v_lshlrev_b32_e32 v206, 16, v192
	v_and_b32_e32 v207, 0xffff0000, v192
	v_pk_fma_f32 v[0:1], v[0:1], v[204:205], v[206:207]
	v_lshlrev_b32_e32 v204, 16, v189
	v_and_b32_e32 v205, 0xffff0000, v189
	v_lshlrev_b32_e32 v206, 16, v193
	v_and_b32_e32 v207, 0xffff0000, v193
	v_pk_fma_f32 v[2:3], v[2:3], v[204:205], v[206:207]
	v_cvt_pk_bf16_f32 v4, v4, v5
	v_cvt_pk_bf16_f32 v5, v6, v7
	v_cvt_pk_bf16_f32 v6, v0, v1
	v_cvt_pk_bf16_f32 v7, v2, v3
	global_store_dwordx4 v212, v[4:7], s[6:7] offset:256
	s_and_b64 vcc, exec, s[2:3]
	s_mov_b32 s45, s12
	s_mov_b64 s[20:21], s[16:17]
	s_mov_b64 s[18:19], s[14:15]
	s_mov_b32 s1, s44
	s_cbranch_vccz .LBB0_994
	s_waitcnt vmcnt(0)
	s_cmpk_gt_u32 s27, 0xff
	s_cbranch_scc1 .LBB0_1007
	s_barrier

; #define PG8_STAGE(bufoff, gbase, voff) do { _Pragma("unroll") for (int _i = 0; _i < 2; ++_i) \
;     __builtin_amdgcn_global_load_lds((const unsigned*)((const char*)(gbase) + (voff)[_i]), (LAS unsigned*)(lds + (bufoff) + ldsw + _i * 8192), 16, 0, 0); } while (0)
; #define PG8_LDA(dst, b, h) do { _Pragma("unroll") for (int m = 0; m < 4; ++m) _Pragma("unroll") for (int k = 0; k < 2; ++k) dst[m][k] = *(const LAS bf16x8*)(lds + PG8_SA(b, h) + aoff + m * 2048 + k * 1024); } while (0)
; #define PG8_LDB(dst, b, h) do { _Pragma("unroll") for (int n = 0; n < 2; ++n) _Pragma("unroll") for (int k = 0; k < 2; ++k) dst[n][k] = *(const LAS bf16x8*)(lds + PG8_SB(b, h) + boff + n * 2048 + k * 1024); } while (0)
; #define PG8_MMA(ai, bj, At, Bt) do { __builtin_amdgcn_s_setprio(1); _Pragma("unroll") for (int m = 0; m < 4; ++m) _Pragma("unroll") for (int n = 0; n < 2; ++n) _Pragma("unroll") for (int k = 0; k < 2; ++k) \
;     acc[ai][bj][m][n] = __builtin_amdgcn_mfma_f32_16x16x32_bf16(Bt[n][k], At[m][k], acc[ai][bj][m][n], 0, 0, 0); __builtin_amdgcn_s_setprio(0); } while (0)
; #define PG8_WAIT_L(n) asm volatile("s_waitcnt lgkmcnt(" #n ")" ::: "memory")
; template <class Epi>
; __device__ __forceinline__ void gemm_phase(LAS unsigned char* lds, const Gemm g, const StaticOrder& S, const Epi& E, int wv0) {
;     ...
;   for (;;) {
;     const bool has_next = S.next(ui + 1, nxt);
;     const char* nA = has_next ? (const char*)g.A + (size_t)nxt.pm * tstepA : cA; const char* nB = has_next ? (const char*)g.Bt + (size_t)nxt.pn * tstepB : cB;
;     for (int t = 0; t < nt; t += 2) {
;       const bool last = (t == nt - 2);
;       const char* a1 = cA + (size_t)(t + 1) * kstep;
;       const char* a2 = last ? nA : cA + (size_t)(t + 2) * kstep; const char* b2 = last ? nB : cB + (size_t)(t + 2) * kstep;
;       const char* a3 = a2 + kstep; const char* b3 = b2 + kstep;
;       PG8_LDB(B0, 0, 0); PG8_SCHED; PG8_LDA(At, 0, 0); PG8_STAGE(PG8_SA(1, 1), a1 + hstepA, voffA);
;       PG8_WAIT_L(8); PG8_BAR; PG8_WAIT_L(0); PG8_MMA(0, 0, At, B0); PG8_BAR; PG8_SCHED;
;     ...
; #pragma unroll
;     for (int a = 0; a < 2; ++a)
; #pragma unroll
;       for (int b = 0; b < 2; ++b)
; #pragma unroll
;         for (int m = 0; m < 4; ++m)
; #pragma unroll
;           for (int n = 0; n < 2; ++n) acc[a][b][m][n] = (f32x4){0.f, 0.f, 0.f, 0.f};
;     cur = nxt; cA = nA; cB = nB; ++ui;
.LBB0_1024:
	s_ashr_i32 s15, s14, 31
	s_lshl_b64 s[18:19], s[14:15], 19
	s_add_u32 s18, s35, s18
	s_addc_u32 s19, s36, s19
	s_and_b64 s[4:5], s[4:5], exec
	s_cselect_b32 s15, s19, s23
	s_cselect_b32 s48, s18, s22
	s_add_u32 s49, s22, 0x100
	v_mov_b32_e32 v0, 0
	s_addc_u32 s50, s23, 0
	s_mov_b32 s51, -2
	v_mov_b32_e32 v1, v0
	v_mov_b32_e32 v2, v0
	v_mov_b32_e32 v3, v0
	v_mov_b32_e32 v4, v0
	v_mov_b32_e32 v5, v0
	v_mov_b32_e32 v6, v0
	v_mov_b32_e32 v7, v0
	v_mov_b32_e32 v16, v0
	v_mov_b32_e32 v17, v0
	v_mov_b32_e32 v18, v0
	v_mov_b32_e32 v19, v0
	v_mov_b32_e32 v20, v0
	v_mov_b32_e32 v21, v0
	v_mov_b32_e32 v22, v0
	v_mov_b32_e32 v23, v0
	v_mov_b32_e32 v32, v0
	v_mov_b32_e32 v33, v0
	v_mov_b32_e32 v34, v0
	v_mov_b32_e32 v35, v0
	v_mov_b32_e32 v36, v0
	v_mov_b32_e32 v37, v0
	v_mov_b32_e32 v38, v0
	v_mov_b32_e32 v39, v0
	v_mov_b32_e32 v48, v0
	v_mov_b32_e32 v49, v0
	v_mov_b32_e32 v50, v0
	v_mov_b32_e32 v51, v0
	v_mov_b32_e32 v52, v0
	v_mov_b32_e32 v53, v0
	v_mov_b32_e32 v54, v0
	v_mov_b32_e32 v55, v0
	v_mov_b32_e32 v8, v0
	v_mov_b32_e32 v9, v0
	v_mov_b32_e32 v10, v0
	v_mov_b32_e32 v11, v0
	v_mov_b32_e32 v12, v0
	v_mov_b32_e32 v13, v0
	v_mov_b32_e32 v14, v0
	v_mov_b32_e32 v15, v0
	v_mov_b32_e32 v24, v0
	v_mov_b32_e32 v25, v0
	v_mov_b32_e32 v26, v0
	v_mov_b32_e32 v27, v0
	v_mov_b32_e32 v28, v0
	v_mov_b32_e32 v29, v0
	v_mov_b32_e32 v30, v0
	v_mov_b32_e32 v31, v0
	v_mov_b32_e32 v40, v0
	v_mov_b32_e32 v41, v0
	v_mov_b32_e32 v42, v0
	v_mov_b32_e32 v43, v0
	v_mov_b32_e32 v44, v0
	v_mov_b32_e32 v45, v0
	v_mov_b32_e32 v46, v0
	v_mov_b32_e32 v47, v0
	v_mov_b32_e32 v56, v0
	v_mov_b32_e32 v57, v0
	v_mov_b32_e32 v58, v0
	v_mov_b32_e32 v59, v0
	v_mov_b32_e32 v60, v0
	v_mov_b32_e32 v61, v0
	v_mov_b32_e32 v62, v0
	v_mov_b32_e32 v63, v0
	v_mov_b32_e32 v64, v0
	v_mov_b32_e32 v65, v0
	v_mov_b32_e32 v66, v0
	v_mov_b32_e32 v67, v0
	v_mov_b32_e32 v68, v0
	v_mov_b32_e32 v69, v0
	v_mov_b32_e32 v70, v0
	v_mov_b32_e32 v71, v0
	s_waitcnt vmcnt(0)
	v_mov_b32_e32 v80, v0
	v_mov_b32_e32 v81, v0
	v_mov_b32_e32 v82, v0
	v_mov_b32_e32 v83, v0
	v_mov_b32_e32 v84, v0
	v_mov_b32_e32 v85, v0
	v_mov_b32_e32 v86, v0
	v_mov_b32_e32 v87, v0
	v_mov_b32_e32 v98, v0
	v_mov_b32_e32 v99, v0
	v_mov_b32_e32 v100, v0
	v_mov_b32_e32 v101, v0
	v_mov_b32_e32 v102, v0
	v_mov_b32_e32 v103, v0
	v_mov_b32_e32 v104, v0
	v_mov_b32_e32 v105, v0
	v_mov_b32_e32 v114, v0
	v_mov_b32_e32 v115, v0
	v_mov_b32_e32 v116, v0
	v_mov_b32_e32 v117, v0
	v_mov_b32_e32 v118, v0
	v_mov_b32_e32 v119, v0
	v_mov_b32_e32 v120, v0
	v_mov_b32_e32 v121, v0
	v_mov_b32_e32 v72, v0
	v_mov_b32_e32 v73, v0
	v_mov_b32_e32 v74, v0
	v_mov_b32_e32 v75, v0
	v_mov_b32_e32 v76, v0
	v_mov_b32_e32 v77, v0
	v_mov_b32_e32 v78, v0
	v_mov_b32_e32 v79, v0
	v_mov_b32_e32 v88, v0
	v_mov_b32_e32 v89, v0
	v_mov_b32_e32 v90, v0
	v_mov_b32_e32 v91, v0
	v_mov_b32_e32 v92, v0
	v_mov_b32_e32 v93, v0
	v_mov_b32_e32 v94, v0
	v_mov_b32_e32 v95, v0
	v_mov_b32_e32 v106, v0
	v_mov_b32_e32 v107, v0
	v_mov_b32_e32 v108, v0
	v_mov_b32_e32 v109, v0
	v_mov_b32_e32 v110, v0
	v_mov_b32_e32 v111, v0
	v_mov_b32_e32 v112, v0
	v_mov_b32_e32 v113, v0
	v_mov_b32_e32 v122, v0
	v_mov_b32_e32 v123, v0
	v_mov_b32_e32 v124, v0
	v_mov_b32_e32 v125, v0
	v_mov_b32_e32 v126, v0
	v_mov_b32_e32 v127, v0
	v_mov_b32_e32 v128, v0
	v_mov_b32_e32 v129, v0
	s_cmp_lt_u32 s53, 4
	s_cbranch_scc1 .Lgprio6
	s_setprio 1
.Lgprio6:
.LBB0_1025:
	s_add_u32 s4, s20, 0x100
	s_addc_u32 s5, s21, 0
	s_add_i32 s0, 0, 0x10000
	v_add_u32_e32 v142, s0, v211
	ds_read_b128 v[130:133], v142
	ds_read_b128 v[134:137], v142 offset:1024
	ds_read_b128 v[138:141], v142 offset:2048
	ds_read_b128 v[142:145], v142 offset:3072
	s_cmp_eq_u32 s51, 12
	s_cselect_b32 s25, s17, s5
	s_cselect_b32 s24, s16, s4
	s_cselect_b32 s23, s15, s50
	s_cselect_b32 s22, s48, s49
	v_lshl_add_u64 v[178:179], s[20:21], 0, v[192:193]
	s_add_i32 m0, s38, 0xc000
	ds_read_b128 v[146:149], v213
	ds_read_b128 v[150:153], v213 offset:1024
	ds_read_b128 v[154:157], v213 offset:2048
	ds_read_b128 v[158:161], v213 offset:3072
	ds_read_b128 v[162:165], v213 offset:4096
	ds_read_b128 v[166:169], v213 offset:5120
	ds_read_b128 v[170:173], v213 offset:6144
	ds_read_b128 v[174:177], v213 offset:7168
	global_load_lds_dwordx4 v[178:179], off
	v_lshl_add_u64 v[178:179], s[20:21], 0, v[194:195]
	s_add_i32 m0, s38, 0xe000
	s_nop 0
	global_load_lds_dwordx4 v[178:179], off
	s_waitcnt lgkmcnt(8)
	s_barrier
	s_waitcnt lgkmcnt(0)
	s_waitcnt lgkmcnt(0)
	v_mfma_f32_16x16x32_bf16 v[126:129], v[130:133], v[146:149], v[126:129]
	v_mfma_f32_16x16x32_bf16 v[122:125], v[138:141], v[146:149], v[122:125]
	v_mfma_f32_16x16x32_bf16 v[110:113], v[130:133], v[154:157], v[110:113]
	v_mfma_f32_16x16x32_bf16 v[106:109], v[138:141], v[154:157], v[106:109]
	v_mfma_f32_16x16x32_bf16 v[92:95], v[130:133], v[162:165], v[92:95]
	v_mfma_f32_16x16x32_bf16 v[88:91], v[138:141], v[162:165], v[88:91]
	v_mfma_f32_16x16x32_bf16 v[76:79], v[130:133], v[170:173], v[76:79]
	v_mfma_f32_16x16x32_bf16 v[72:75], v[138:141], v[170:173], v[72:75]
	v_mfma_f32_16x16x32_bf16 v[126:129], v[134:137], v[150:153], v[126:129]
	v_mfma_f32_16x16x32_bf16 v[122:125], v[142:145], v[150:153], v[122:125]
	v_mfma_f32_16x16x32_bf16 v[110:113], v[134:137], v[158:161], v[110:113]
	v_mfma_f32_16x16x32_bf16 v[106:109], v[142:145], v[158:161], v[106:109]
	v_mfma_f32_16x16x32_bf16 v[92:95], v[134:137], v[166:169], v[92:95]
	v_mfma_f32_16x16x32_bf16 v[88:91], v[142:145], v[166:169], v[88:91]
	v_mfma_f32_16x16x32_bf16 v[76:79], v[134:137], v[174:177], v[76:79]
	v_mfma_f32_16x16x32_bf16 v[72:75], v[142:145], v[174:177], v[72:75]
	s_barrier
; #define PG8_STAGE(bufoff, gbase, voff) do { _Pragma("unroll") for (int _i = 0; _i < 2; ++_i) \
;     __builtin_amdgcn_global_load_lds((const unsigned*)((const char*)(gbase) + (voff)[_i]), (LAS unsigned*)(lds + (bufoff) + ldsw + _i * 8192), 16, 0, 0); } while (0)
; #define PG8_LDA(dst, b, h) do { _Pragma("unroll") for (int m = 0; m < 4; ++m) _Pragma("unroll") for (int k = 0; k < 2; ++k) dst[m][k] = *(const LAS bf16x8*)(lds + PG8_SA(b, h) + aoff + m * 2048 + k * 1024); } while (0)
; #define PG8_LDB(dst, b, h) do { _Pragma("unroll") for (int n = 0; n < 2; ++n) _Pragma("unroll") for (int k = 0; k < 2; ++k) dst[n][k] = *(const LAS bf16x8*)(lds + PG8_SB(b, h) + boff + n * 2048 + k * 1024); } while (0)
; #define PG8_MMA(ai, bj, At, Bt) do { __builtin_amdgcn_s_setprio(1); _Pragma("unroll") for (int m = 0; m < 4; ++m) _Pragma("unroll") for (int n = 0; n < 2; ++n) _Pragma("unroll") for (int k = 0; k < 2; ++k) \
;     acc[ai][bj][m][n] = __builtin_amdgcn_mfma_f32_16x16x32_bf16(Bt[n][k], At[m][k], acc[ai][bj][m][n], 0, 0, 0); __builtin_amdgcn_s_setprio(0); } while (0)
; #define PG8_WAIT_V(n) asm volatile("s_waitcnt vmcnt(" #n ")" ::: "memory")
; #define PG8_WAIT_L(n) asm volatile("s_waitcnt lgkmcnt(" #n ")" ::: "memory")
; #define PG8_BAR __builtin_amdgcn_s_barrier()
; template <class Epi>
; __device__ __forceinline__ void gemm_phase(LAS unsigned char* lds, const Gemm g, const StaticOrder& S, const Epi& E, int wv0) {
;     ...
;       PG8_LDB(B1, 0, 1); PG8_STAGE(PG8_SB(0, 0), b2, voffB);
;       PG8_BAR; PG8_WAIT_L(0); PG8_MMA(0, 1, At, B1); PG8_BAR;
;       PG8_LDA(At, 0, 1); PG8_STAGE(PG8_SA(0, 0), a2, voffA);
;       PG8_BAR; PG8_WAIT_L(0); PG8_MMA(1, 0, At, B0); PG8_BAR; PG8_SCHED;
;       PG8_STAGE(PG8_SB(0, 1), b2 + hstepB, voffB);
;       PG8_WAIT_V(6); PG8_BAR; PG8_MMA(1, 1, At, B1); PG8_BAR;
;       PG8_LDB(B0, 1, 0); PG8_SCHED; PG8_LDA(At, 1, 0); PG8_STAGE(PG8_SA(0, 1), a2 + hstepA, voffA);
;       PG8_WAIT_L(8); PG8_BAR; PG8_WAIT_L(0); PG8_MMA(0, 0, At, B0); PG8_BAR; PG8_SCHED;
;       PG8_LDB(B1, 1, 1); PG8_STAGE(PG8_SB(1, 0), b3, voffB);
;       PG8_BAR; PG8_WAIT_L(0); PG8_MMA(0, 1, At, B1); PG8_BAR;
;       PG8_LDA(At, 1, 1); PG8_STAGE(PG8_SA(1, 0), a3, voffA);
;       PG8_BAR; PG8_WAIT_L(0); PG8_MMA(1, 0, At, B0); PG8_BAR; PG8_SCHED;
;       PG8_STAGE(PG8_SB(1, 1), b3 + hstepB, voffB);
;       PG8_WAIT_V(6); PG8_BAR; PG8_MMA(1, 1, At, B1); PG8_BAR;
	s_add_i32 s52, 0, 0x14000
	s_add_i32 s0, s0, s37
	v_add_u32_e32 v200, s52, v211
	v_lshl_add_u64 v[204:205], s[22:23], 0, v[96:97]
	s_mov_b32 m0, s0
	ds_read_b128 v[178:181], v200
	ds_read_b128 v[182:185], v200 offset:1024
	ds_read_b128 v[196:199], v200 offset:2048
	ds_read_b128 v[200:203], v200 offset:3072
	global_load_lds_dwordx4 v[204:205], off
	v_lshl_add_u64 v[206:207], s[22:23], 0, v[190:191]
	s_add_i32 m0, s0, 0x2000
	s_nop 0
	global_load_lds_dwordx4 v[206:207], off
	s_barrier
	s_waitcnt lgkmcnt(0)
	s_waitcnt lgkmcnt(0)
	v_mfma_f32_16x16x32_bf16 v[118:121], v[178:181], v[146:149], v[118:121]
	v_mfma_f32_16x16x32_bf16 v[114:117], v[196:199], v[146:149], v[114:117]
	v_mfma_f32_16x16x32_bf16 v[102:105], v[178:181], v[154:157], v[102:105]
	v_mfma_f32_16x16x32_bf16 v[98:101], v[196:199], v[154:157], v[98:101]
	v_mfma_f32_16x16x32_bf16 v[84:87], v[178:181], v[162:165], v[84:87]
	v_mfma_f32_16x16x32_bf16 v[80:83], v[196:199], v[162:165], v[80:83]
	v_mfma_f32_16x16x32_bf16 v[68:71], v[178:181], v[170:173], v[68:71]
	v_mfma_f32_16x16x32_bf16 v[64:67], v[196:199], v[170:173], v[64:67]
	v_mfma_f32_16x16x32_bf16 v[118:121], v[182:185], v[150:153], v[118:121]
	v_mfma_f32_16x16x32_bf16 v[114:117], v[200:203], v[150:153], v[114:117]
	v_mfma_f32_16x16x32_bf16 v[102:105], v[182:185], v[158:161], v[102:105]
	v_mfma_f32_16x16x32_bf16 v[98:101], v[200:203], v[158:161], v[98:101]
	v_mfma_f32_16x16x32_bf16 v[84:87], v[182:185], v[166:169], v[84:87]
	v_mfma_f32_16x16x32_bf16 v[80:83], v[200:203], v[166:169], v[80:83]
	v_mfma_f32_16x16x32_bf16 v[68:71], v[182:185], v[174:177], v[68:71]
	v_mfma_f32_16x16x32_bf16 v[64:67], v[200:203], v[174:177], v[64:67]
	s_mov_b32 m0, s38
	v_lshl_add_u64 v[208:209], s[24:25], 0, v[186:187]
	s_barrier
	ds_read_b128 v[146:149], v213 offset:16384
	ds_read_b128 v[150:153], v213 offset:17408
	ds_read_b128 v[154:157], v213 offset:18432
	ds_read_b128 v[158:161], v213 offset:19456
	ds_read_b128 v[162:165], v213 offset:20480
	ds_read_b128 v[166:169], v213 offset:21504
	ds_read_b128 v[170:173], v213 offset:22528
	ds_read_b128 v[174:177], v213 offset:23552
	global_load_lds_dwordx4 v[208:209], off
	v_lshl_add_u64 v[214:215], s[24:25], 0, v[188:189]
	s_mov_b32 m0, s39
	s_nop 0
	global_load_lds_dwordx4 v[214:215], off
	s_barrier
	s_waitcnt lgkmcnt(0)
	s_waitcnt lgkmcnt(0)
	v_mfma_f32_16x16x32_bf16 v[60:63], v[130:133], v[146:149], v[60:63]
	v_mfma_f32_16x16x32_bf16 v[56:59], v[138:141], v[146:149], v[56:59]
	v_mfma_f32_16x16x32_bf16 v[44:47], v[130:133], v[154:157], v[44:47]
	v_mfma_f32_16x16x32_bf16 v[40:43], v[138:141], v[154:157], v[40:43]
	v_mfma_f32_16x16x32_bf16 v[28:31], v[130:133], v[162:165], v[28:31]
	v_mfma_f32_16x16x32_bf16 v[24:27], v[138:141], v[162:165], v[24:27]
	v_mfma_f32_16x16x32_bf16 v[12:15], v[130:133], v[170:173], v[12:15]
	v_mfma_f32_16x16x32_bf16 v[8:11], v[138:141], v[170:173], v[8:11]
	v_mfma_f32_16x16x32_bf16 v[60:63], v[134:137], v[150:153], v[60:63]
	v_mfma_f32_16x16x32_bf16 v[56:59], v[142:145], v[150:153], v[56:59]
	v_mfma_f32_16x16x32_bf16 v[44:47], v[134:137], v[158:161], v[44:47]
	v_mfma_f32_16x16x32_bf16 v[40:43], v[142:145], v[158:161], v[40:43]
	v_mfma_f32_16x16x32_bf16 v[28:31], v[134:137], v[166:169], v[28:31]
	v_mfma_f32_16x16x32_bf16 v[24:27], v[142:145], v[166:169], v[24:27]
	v_mfma_f32_16x16x32_bf16 v[12:15], v[134:137], v[174:177], v[12:15]
	v_mfma_f32_16x16x32_bf16 v[8:11], v[142:145], v[174:177], v[8:11]
	s_barrier
	s_add_u32 s20, s22, 0x40000
	s_addc_u32 s21, s23, 0
	s_add_i32 s0, s52, s37
	v_lshl_add_u64 v[130:131], s[20:21], 0, v[96:97]
	s_mov_b32 m0, s0
	s_nop 0
	global_load_lds_dwordx4 v[130:131], off
	v_lshl_add_u64 v[130:131], s[20:21], 0, v[190:191]
	s_add_i32 m0, s0, 0x2000
	s_nop 0
	global_load_lds_dwordx4 v[130:131], off
	s_waitcnt vmcnt(6)
	s_barrier
	v_mfma_f32_16x16x32_bf16 v[52:55], v[178:181], v[146:149], v[52:55]
	v_mfma_f32_16x16x32_bf16 v[48:51], v[196:199], v[146:149], v[48:51]
	v_mfma_f32_16x16x32_bf16 v[36:39], v[178:181], v[154:157], v[36:39]
	v_mfma_f32_16x16x32_bf16 v[32:35], v[196:199], v[154:157], v[32:35]
	v_mfma_f32_16x16x32_bf16 v[20:23], v[178:181], v[162:165], v[20:23]
	v_mfma_f32_16x16x32_bf16 v[16:19], v[196:199], v[162:165], v[16:19]
	v_mfma_f32_16x16x32_bf16 v[4:7], v[178:181], v[170:173], v[4:7]
	v_mfma_f32_16x16x32_bf16 v[0:3], v[196:199], v[170:173], v[0:3]
	v_mfma_f32_16x16x32_bf16 v[52:55], v[182:185], v[150:153], v[52:55]
	v_mfma_f32_16x16x32_bf16 v[48:51], v[200:203], v[150:153], v[48:51]
	v_mfma_f32_16x16x32_bf16 v[36:39], v[182:185], v[158:161], v[36:39]
	v_mfma_f32_16x16x32_bf16 v[32:35], v[200:203], v[158:161], v[32:35]
	v_mfma_f32_16x16x32_bf16 v[20:23], v[182:185], v[166:169], v[20:23]
	v_mfma_f32_16x16x32_bf16 v[16:19], v[200:203], v[166:169], v[16:19]
	v_mfma_f32_16x16x32_bf16 v[4:7], v[182:185], v[174:177], v[4:7]
	v_mfma_f32_16x16x32_bf16 v[0:3], v[200:203], v[174:177], v[0:3]
	s_add_i32 s0, 0, 0x18000
	v_add_u32_e32 v142, s0, v211
	s_barrier
	ds_read_b128 v[130:133], v142
	ds_read_b128 v[134:137], v142 offset:1024
	ds_read_b128 v[138:141], v142 offset:2048
	ds_read_b128 v[142:145], v142 offset:3072
	s_add_u32 s20, s24, 0x114000
	s_addc_u32 s21, s25, 0
	s_mov_b32 m0, s40
	v_lshl_add_u64 v[178:179], s[20:21], 0, v[186:187]
	ds_read_b128 v[146:149], v213 offset:32768
	ds_read_b128 v[150:153], v213 offset:33792
	ds_read_b128 v[154:157], v213 offset:34816
	ds_read_b128 v[158:161], v213 offset:35840
	ds_read_b128 v[162:165], v213 offset:36864
	ds_read_b128 v[166:169], v213 offset:37888
	ds_read_b128 v[170:173], v213 offset:38912
	ds_read_b128 v[174:177], v213 offset:39936
	global_load_lds_dwordx4 v[178:179], off
	v_lshl_add_u64 v[178:179], s[20:21], 0, v[188:189]
	s_mov_b32 m0, s41
	s_nop 0
	global_load_lds_dwordx4 v[178:179], off
	s_waitcnt lgkmcnt(8)
	s_barrier
; #define PG8_STAGE(bufoff, gbase, voff) do { _Pragma("unroll") for (int _i = 0; _i < 2; ++_i) \
;     __builtin_amdgcn_global_load_lds((const unsigned*)((const char*)(gbase) + (voff)[_i]), (LAS unsigned*)(lds + (bufoff) + ldsw + _i * 8192), 16, 0, 0); } while (0)
; #define PG8_LDA(dst, b, h) do { _Pragma("unroll") for (int m = 0; m < 4; ++m) _Pragma("unroll") for (int k = 0; k < 2; ++k) dst[m][k] = *(const LAS bf16x8*)(lds + PG8_SA(b, h) + aoff + m * 2048 + k * 1024); } while (0)
; #define PG8_LDB(dst, b, h) do { _Pragma("unroll") for (int n = 0; n < 2; ++n) _Pragma("unroll") for (int k = 0; k < 2; ++k) dst[n][k] = *(const LAS bf16x8*)(lds + PG8_SB(b, h) + boff + n * 2048 + k * 1024); } while (0)
; #define PG8_MMA(ai, bj, At, Bt) do { __builtin_amdgcn_s_setprio(1); _Pragma("unroll") for (int m = 0; m < 4; ++m) _Pragma("unroll") for (int n = 0; n < 2; ++n) _Pragma("unroll") for (int k = 0; k < 2; ++k) \
;     acc[ai][bj][m][n] = __builtin_amdgcn_mfma_f32_16x16x32_bf16(Bt[n][k], At[m][k], acc[ai][bj][m][n], 0, 0, 0); __builtin_amdgcn_s_setprio(0); } while (0)
; #define PG8_WAIT_V(n) asm volatile("s_waitcnt vmcnt(" #n ")" ::: "memory")
; #define PG8_WAIT_L(n) asm volatile("s_waitcnt lgkmcnt(" #n ")" ::: "memory")
; #define PG8_BAR __builtin_amdgcn_s_barrier()
; #define PG8_SCHED __builtin_amdgcn_sched_barrier(0)
; template <class Epi>
; __device__ __forceinline__ void gemm_phase(LAS unsigned char* lds, const Gemm g, const StaticOrder& S, const Epi& E, int wv0) {
;     ...
;       PG8_LDB(B0, 1, 0); PG8_SCHED; PG8_LDA(At, 1, 0); PG8_STAGE(PG8_SA(0, 1), a2 + hstepA, voffA);
;       PG8_WAIT_L(8); PG8_BAR; PG8_WAIT_L(0); PG8_MMA(0, 0, At, B0); PG8_BAR; PG8_SCHED;
;       PG8_LDB(B1, 1, 1); PG8_STAGE(PG8_SB(1, 0), b3, voffB);
;       PG8_BAR; PG8_WAIT_L(0); PG8_MMA(0, 1, At, B1); PG8_BAR;
;       PG8_LDA(At, 1, 1); PG8_STAGE(PG8_SA(1, 0), a3, voffA);
;       PG8_BAR; PG8_WAIT_L(0); PG8_MMA(1, 0, At, B0); PG8_BAR; PG8_SCHED;
;       PG8_STAGE(PG8_SB(1, 1), b3 + hstepB, voffB);
;       PG8_WAIT_V(6); PG8_BAR; PG8_MMA(1, 1, At, B1); PG8_BAR;
	s_waitcnt lgkmcnt(0)
	s_waitcnt lgkmcnt(0)
	v_mfma_f32_16x16x32_bf16 v[126:129], v[130:133], v[146:149], v[126:129]
	v_mfma_f32_16x16x32_bf16 v[122:125], v[138:141], v[146:149], v[122:125]
	v_mfma_f32_16x16x32_bf16 v[110:113], v[130:133], v[154:157], v[110:113]
	v_mfma_f32_16x16x32_bf16 v[106:109], v[138:141], v[154:157], v[106:109]
	v_mfma_f32_16x16x32_bf16 v[92:95], v[130:133], v[162:165], v[92:95]
	v_mfma_f32_16x16x32_bf16 v[88:91], v[138:141], v[162:165], v[88:91]
	v_mfma_f32_16x16x32_bf16 v[76:79], v[130:133], v[170:173], v[76:79]
	v_mfma_f32_16x16x32_bf16 v[72:75], v[138:141], v[170:173], v[72:75]
	v_mfma_f32_16x16x32_bf16 v[126:129], v[134:137], v[150:153], v[126:129]
	v_mfma_f32_16x16x32_bf16 v[122:125], v[142:145], v[150:153], v[122:125]
	v_mfma_f32_16x16x32_bf16 v[110:113], v[134:137], v[158:161], v[110:113]
	v_mfma_f32_16x16x32_bf16 v[106:109], v[142:145], v[158:161], v[106:109]
	v_mfma_f32_16x16x32_bf16 v[92:95], v[134:137], v[166:169], v[92:95]
	v_mfma_f32_16x16x32_bf16 v[88:91], v[142:145], v[166:169], v[88:91]
	v_mfma_f32_16x16x32_bf16 v[76:79], v[134:137], v[174:177], v[76:79]
	v_mfma_f32_16x16x32_bf16 v[72:75], v[142:145], v[174:177], v[72:75]
	s_barrier
	s_add_i32 s24, 0, 0x1c000
	s_add_i32 s0, s0, s37
	v_add_u32_e32 v200, s24, v211
	v_lshl_add_u64 v[204:205], v[204:205], 0, s[72:73]
	s_mov_b32 m0, s0
	ds_read_b128 v[178:181], v200
	ds_read_b128 v[182:185], v200 offset:1024
	ds_read_b128 v[196:199], v200 offset:2048
	ds_read_b128 v[200:203], v200 offset:3072
	global_load_lds_dwordx4 v[204:205], off
	v_lshl_add_u64 v[204:205], v[206:207], 0, s[72:73]
	s_add_i32 m0, s0, 0x2000
	s_nop 0
	global_load_lds_dwordx4 v[204:205], off
	s_barrier
	s_waitcnt lgkmcnt(0)
	s_waitcnt lgkmcnt(0)
	v_mfma_f32_16x16x32_bf16 v[118:121], v[178:181], v[146:149], v[118:121]
	v_mfma_f32_16x16x32_bf16 v[114:117], v[196:199], v[146:149], v[114:117]
	v_mfma_f32_16x16x32_bf16 v[102:105], v[178:181], v[154:157], v[102:105]
	v_mfma_f32_16x16x32_bf16 v[98:101], v[196:199], v[154:157], v[98:101]
	v_mfma_f32_16x16x32_bf16 v[84:87], v[178:181], v[162:165], v[84:87]
	v_mfma_f32_16x16x32_bf16 v[80:83], v[196:199], v[162:165], v[80:83]
	v_mfma_f32_16x16x32_bf16 v[68:71], v[178:181], v[170:173], v[68:71]
	v_mfma_f32_16x16x32_bf16 v[64:67], v[196:199], v[170:173], v[64:67]
	v_mfma_f32_16x16x32_bf16 v[118:121], v[182:185], v[150:153], v[118:121]
	v_mfma_f32_16x16x32_bf16 v[114:117], v[200:203], v[150:153], v[114:117]
	v_mfma_f32_16x16x32_bf16 v[102:105], v[182:185], v[158:161], v[102:105]
	v_mfma_f32_16x16x32_bf16 v[98:101], v[200:203], v[158:161], v[98:101]
	v_mfma_f32_16x16x32_bf16 v[84:87], v[182:185], v[166:169], v[84:87]
	v_mfma_f32_16x16x32_bf16 v[80:83], v[200:203], v[166:169], v[80:83]
	v_mfma_f32_16x16x32_bf16 v[68:71], v[182:185], v[174:177], v[68:71]
	v_mfma_f32_16x16x32_bf16 v[64:67], v[200:203], v[174:177], v[64:67]
	s_mov_b32 m0, s42
	v_lshl_add_u64 v[204:205], v[208:209], 0, s[72:73]
	s_barrier
	ds_read_b128 v[146:149], v213 offset:49152
	ds_read_b128 v[150:153], v213 offset:50176
	ds_read_b128 v[154:157], v213 offset:51200
	ds_read_b128 v[158:161], v213 offset:52224
	ds_read_b128 v[162:165], v213 offset:53248
	ds_read_b128 v[166:169], v213 offset:54272
	ds_read_b128 v[170:173], v213 offset:55296
	ds_read_b128 v[174:177], v213 offset:56320
	global_load_lds_dwordx4 v[204:205], off
	v_lshl_add_u64 v[204:205], v[214:215], 0, s[72:73]
	s_mov_b32 m0, s43
	s_nop 0
	global_load_lds_dwordx4 v[204:205], off
	s_barrier
	s_waitcnt lgkmcnt(0)
	s_waitcnt lgkmcnt(0)
	v_mfma_f32_16x16x32_bf16 v[60:63], v[130:133], v[146:149], v[60:63]
	v_mfma_f32_16x16x32_bf16 v[56:59], v[138:141], v[146:149], v[56:59]
	v_mfma_f32_16x16x32_bf16 v[44:47], v[130:133], v[154:157], v[44:47]
	v_mfma_f32_16x16x32_bf16 v[40:43], v[138:141], v[154:157], v[40:43]
	v_mfma_f32_16x16x32_bf16 v[28:31], v[130:133], v[162:165], v[28:31]
	v_mfma_f32_16x16x32_bf16 v[24:27], v[138:141], v[162:165], v[24:27]
	v_mfma_f32_16x16x32_bf16 v[12:15], v[130:133], v[170:173], v[12:15]
	v_mfma_f32_16x16x32_bf16 v[8:11], v[138:141], v[170:173], v[8:11]
	v_mfma_f32_16x16x32_bf16 v[60:63], v[134:137], v[150:153], v[60:63]
	v_mfma_f32_16x16x32_bf16 v[56:59], v[142:145], v[150:153], v[56:59]
	v_mfma_f32_16x16x32_bf16 v[44:47], v[134:137], v[158:161], v[44:47]
	v_mfma_f32_16x16x32_bf16 v[40:43], v[142:145], v[158:161], v[40:43]
	v_mfma_f32_16x16x32_bf16 v[28:31], v[134:137], v[166:169], v[28:31]
	v_mfma_f32_16x16x32_bf16 v[24:27], v[142:145], v[166:169], v[24:27]
	v_mfma_f32_16x16x32_bf16 v[12:15], v[134:137], v[174:177], v[12:15]
	v_mfma_f32_16x16x32_bf16 v[8:11], v[142:145], v[174:177], v[8:11]
	s_barrier
	s_add_u32 s20, s22, 0x40080
	s_addc_u32 s21, s23, 0
	s_add_i32 s0, s24, s37
	v_lshl_add_u64 v[130:131], s[20:21], 0, v[96:97]
	s_mov_b32 m0, s0
	s_nop 0
	global_load_lds_dwordx4 v[130:131], off
	v_lshl_add_u64 v[130:131], s[20:21], 0, v[190:191]
	s_add_i32 m0, s0, 0x2000
	s_nop 0
	global_load_lds_dwordx4 v[130:131], off
	s_waitcnt vmcnt(6)
	s_barrier
	v_mfma_f32_16x16x32_bf16 v[52:55], v[178:181], v[146:149], v[52:55]
	v_mfma_f32_16x16x32_bf16 v[48:51], v[196:199], v[146:149], v[48:51]
	v_mfma_f32_16x16x32_bf16 v[36:39], v[178:181], v[154:157], v[36:39]
	v_mfma_f32_16x16x32_bf16 v[32:35], v[196:199], v[154:157], v[32:35]
	v_mfma_f32_16x16x32_bf16 v[20:23], v[178:181], v[162:165], v[20:23]
	v_mfma_f32_16x16x32_bf16 v[16:19], v[196:199], v[162:165], v[16:19]
	v_mfma_f32_16x16x32_bf16 v[4:7], v[178:181], v[170:173], v[4:7]
	v_mfma_f32_16x16x32_bf16 v[0:3], v[196:199], v[170:173], v[0:3]
	v_mfma_f32_16x16x32_bf16 v[52:55], v[182:185], v[150:153], v[52:55]
	v_mfma_f32_16x16x32_bf16 v[48:51], v[200:203], v[150:153], v[48:51]
	v_mfma_f32_16x16x32_bf16 v[36:39], v[182:185], v[158:161], v[36:39]
	v_mfma_f32_16x16x32_bf16 v[32:35], v[200:203], v[158:161], v[32:35]
	v_mfma_f32_16x16x32_bf16 v[20:23], v[182:185], v[166:169], v[20:23]
	v_mfma_f32_16x16x32_bf16 v[16:19], v[200:203], v[166:169], v[16:19]
	v_mfma_f32_16x16x32_bf16 v[4:7], v[182:185], v[174:177], v[4:7]
	v_mfma_f32_16x16x32_bf16 v[0:3], v[200:203], v[174:177], v[0:3]
	s_add_i32 s51, s51, 2
	s_add_u32 s49, s49, 0x100
	s_addc_u32 s50, s50, 0
	s_cmp_gt_u32 s51, 13
	s_mov_b64 s[20:21], s[4:5]
	s_barrier
; __device__ __forceinline__ float bf_lo(unsigned u) { return __uint_as_float(u << 16); }
; __device__ __forceinline__ float bf_hi(unsigned u) { return __uint_as_float(u & 0xffff0000u); }
;   __device__ __forceinline__ void emit(const EpiPre& q0, int row, int col, f32x4 a, f32x4 b, const f32x4 (&hb)[2][2], const float (&hs)[2][4], int ai_, int m_, int bj_) const {
;     ...
;     } else if (MODE == E_PROJ) {
;       const int br = e.aux; const u32x4 gw = q.u0;
;       v[0] *= bf_lo(gw.x); v[1] *= bf_hi(gw.x); v[2] *= bf_lo(gw.y); v[3] *= bf_hi(gw.y);
;       v[4] *= bf_lo(gw.z); v[5] *= bf_hi(gw.z); v[6] *= bf_lo(gw.w); v[7] *= bf_hi(gw.w);
;       bf16_t* fa = (bf16_t*)e.facc + (size_t)row * DM + col;
;       if (br > 0) { const u32x4 pw = q.u1;
;         v[0] += bf_lo(pw.x); v[1] += bf_hi(pw.x); v[2] += bf_lo(pw.y); v[3] += bf_hi(pw.y); v[4] += bf_lo(pw.z); v[5] += bf_hi(pw.z); v[6] += bf_lo(pw.w); v[7] += bf_hi(pw.w); }
;       if (br == 2) store8bf((bf16_t*)e.out + (size_t)row * DM + col, v);
;       else store8bf(fa, v);
;   __device__ __forceinline__ void operator()(const f32x4 (&acc)[2][2][4][2], const pg8::Unit& u, int wr, int wc, int fr, int fq) const {
;     ...
;     for (int gi = 0; gi < 4; ++gi) {
;       const int ai = gi >> 1, mp = gi & 1;
;       if (gi + 1 < 4) { const int ai2 = (gi + 1) >> 1, mp2 = (gi + 1) & 1;
; #pragma unroll
;         for (int i = 0; i < 4; ++i) preload(q[(gi + 1) & 1][i], row0 + ai2 * 128 + (2 * mp2 + (i >> 1)) * 16, col0 + (i & 1) * 128); }
;       asm volatile("" ::: "memory");
; #pragma unroll
;       for (int i = 0; i < 4; ++i) { const int m = 2 * mp + (i >> 1), bj = i & 1; emit(q[gi & 1][i], row0 + ai * 128 + m * 16, col0 + bj * 128, acc[ai][bj][m][0], acc[ai][bj][m][1], hb, hs, ai, m, bj); }
;       asm volatile("" ::: "memory");
	s_cbranch_scc0 .LBB0_1025
	s_setprio 0
	v_lshl_add_u32 v209, s1, 8, v210
	v_lshl_or_b32 v214, s47, 8, v212
	v_mul_u32_u24_e32 v208, 0x3000, v209
	v_lshlrev_b32_e32 v209, 12, v209
	v_lshl_add_u32 v208, v214, 1, v208
	v_lshl_add_u32 v209, v214, 1, v209
	v_add_u32_e32 v214, 0x0, v208
	global_load_dwordx4 v[130:133], v214, s[8:9]
	v_add_u32_e32 v215, 0x0, v209
	global_load_dwordx4 v[134:137], v215, s[6:7]
	global_load_dwordx4 v[138:141], v214, s[8:9] offset:256
	global_load_dwordx4 v[142:145], v215, s[6:7] offset:256
	v_add_u32_e32 v214, 0x30000, v208
	global_load_dwordx4 v[146:149], v214, s[8:9]
	v_add_u32_e32 v215, 0x10000, v209
	global_load_dwordx4 v[150:153], v215, s[6:7]
	global_load_dwordx4 v[154:157], v214, s[8:9] offset:256
	global_load_dwordx4 v[158:161], v215, s[6:7] offset:256
	v_add_u32_e32 v214, 0x60000, v208
	global_load_dwordx4 v[162:165], v214, s[8:9]
	v_add_u32_e32 v215, 0x20000, v209
	global_load_dwordx4 v[166:169], v215, s[6:7]
	global_load_dwordx4 v[170:173], v214, s[8:9] offset:256
	global_load_dwordx4 v[174:177], v215, s[6:7] offset:256
	v_add_u32_e32 v214, 0x90000, v208
	global_load_dwordx4 v[178:181], v214, s[8:9]
	v_add_u32_e32 v215, 0x30000, v209
	global_load_dwordx4 v[182:185], v215, s[6:7]
	global_load_dwordx4 v[196:199], v214, s[8:9] offset:256
	global_load_dwordx4 v[200:203], v215, s[6:7] offset:256
	s_waitcnt vmcnt(14)
	v_lshlrev_b32_e32 v204, 16, v130
	v_and_b32_e32 v205, 0xffff0000, v130
	v_lshlrev_b32_e32 v206, 16, v134
	v_and_b32_e32 v207, 0xffff0000, v134
	v_pk_fma_f32 v[126:127], v[126:127], v[204:205], v[206:207]
	v_lshlrev_b32_e32 v204, 16, v131
	v_and_b32_e32 v205, 0xffff0000, v131
	v_lshlrev_b32_e32 v206, 16, v135
	v_and_b32_e32 v207, 0xffff0000, v135
	v_pk_fma_f32 v[128:129], v[128:129], v[204:205], v[206:207]
	v_lshlrev_b32_e32 v204, 16, v132
	v_and_b32_e32 v205, 0xffff0000, v132
	v_lshlrev_b32_e32 v206, 16, v136
	v_and_b32_e32 v207, 0xffff0000, v136
	v_pk_fma_f32 v[122:123], v[122:123], v[204:205], v[206:207]
	v_lshlrev_b32_e32 v204, 16, v133
	v_and_b32_e32 v205, 0xffff0000, v133
	v_lshlrev_b32_e32 v206, 16, v137
	v_and_b32_e32 v207, 0xffff0000, v137
	v_pk_fma_f32 v[124:125], v[124:125], v[204:205], v[206:207]
	v_cvt_pk_bf16_f32 v126, v126, v127
	v_cvt_pk_bf16_f32 v127, v128, v129
	v_cvt_pk_bf16_f32 v128, v122, v123
	v_cvt_pk_bf16_f32 v129, v124, v125
	v_add_u32_e32 v214, 0x180000, v208
	global_load_dwordx4 v[130:133], v214, s[8:9]
	v_add_u32_e32 v215, 0x80000, v209
	global_load_dwordx4 v[134:137], v215, s[6:7]
	s_waitcnt vmcnt(14)
	v_lshlrev_b32_e32 v204, 16, v138
	v_and_b32_e32 v205, 0xffff0000, v138
	v_lshlrev_b32_e32 v206, 16, v142
	v_and_b32_e32 v207, 0xffff0000, v142
	v_pk_fma_f32 v[118:119], v[118:119], v[204:205], v[206:207]
	v_lshlrev_b32_e32 v204, 16, v139
	v_and_b32_e32 v205, 0xffff0000, v139
	v_lshlrev_b32_e32 v206, 16, v143
	v_and_b32_e32 v207, 0xffff0000, v143
	v_pk_fma_f32 v[120:121], v[120:121], v[204:205], v[206:207]
	v_lshlrev_b32_e32 v204, 16, v140
	v_and_b32_e32 v205, 0xffff0000, v140
	v_lshlrev_b32_e32 v206, 16, v144
	v_and_b32_e32 v207, 0xffff0000, v144
	v_pk_fma_f32 v[114:115], v[114:115], v[204:205], v[206:207]
	v_lshlrev_b32_e32 v204, 16, v141
	v_and_b32_e32 v205, 0xffff0000, v141
	v_lshlrev_b32_e32 v206, 16, v145
	v_and_b32_e32 v207, 0xffff0000, v145
	v_pk_fma_f32 v[116:117], v[116:117], v[204:205], v[206:207]
	v_cvt_pk_bf16_f32 v118, v118, v119
	v_cvt_pk_bf16_f32 v119, v120, v121
	v_cvt_pk_bf16_f32 v120, v114, v115
	v_cvt_pk_bf16_f32 v121, v116, v117
	global_load_dwordx4 v[138:141], v214, s[8:9] offset:256
	global_load_dwordx4 v[142:145], v215, s[6:7] offset:256
	s_waitcnt vmcnt(14)
	v_lshlrev_b32_e32 v204, 16, v146
	v_and_b32_e32 v205, 0xffff0000, v146
	v_lshlrev_b32_e32 v206, 16, v150
	v_and_b32_e32 v207, 0xffff0000, v150
	v_pk_fma_f32 v[110:111], v[110:111], v[204:205], v[206:207]
	v_lshlrev_b32_e32 v204, 16, v147
	v_and_b32_e32 v205, 0xffff0000, v147
	v_lshlrev_b32_e32 v206, 16, v151
	v_and_b32_e32 v207, 0xffff0000, v151
	v_pk_fma_f32 v[112:113], v[112:113], v[204:205], v[206:207]
	v_lshlrev_b32_e32 v204, 16, v148
	v_and_b32_e32 v205, 0xffff0000, v148
	v_lshlrev_b32_e32 v206, 16, v152
	v_and_b32_e32 v207, 0xffff0000, v152
	v_pk_fma_f32 v[106:107], v[106:107], v[204:205], v[206:207]
	v_lshlrev_b32_e32 v204, 16, v149
	v_and_b32_e32 v205, 0xffff0000, v149
	v_lshlrev_b32_e32 v206, 16, v153
	v_and_b32_e32 v207, 0xffff0000, v153
	v_pk_fma_f32 v[108:109], v[108:109], v[204:205], v[206:207]
	v_cvt_pk_bf16_f32 v110, v110, v111
	v_cvt_pk_bf16_f32 v111, v112, v113
	v_cvt_pk_bf16_f32 v112, v106, v107
	v_cvt_pk_bf16_f32 v113, v108, v109
	v_add_u32_e32 v214, 0x1b0000, v208
	global_load_dwordx4 v[146:149], v214, s[8:9]
	v_add_u32_e32 v215, 0x90000, v209
	global_load_dwordx4 v[150:153], v215, s[6:7]
	s_waitcnt vmcnt(14)
	v_lshlrev_b32_e32 v204, 16, v154
	v_and_b32_e32 v205, 0xffff0000, v154
	v_lshlrev_b32_e32 v206, 16, v158
	v_and_b32_e32 v207, 0xffff0000, v158
	v_pk_fma_f32 v[102:103], v[102:103], v[204:205], v[206:207]
	v_lshlrev_b32_e32 v204, 16, v155
	v_and_b32_e32 v205, 0xffff0000, v155
	v_lshlrev_b32_e32 v206, 16, v159
	v_and_b32_e32 v207, 0xffff0000, v159
	v_pk_fma_f32 v[104:105], v[104:105], v[204:205], v[206:207]
	v_lshlrev_b32_e32 v204, 16, v156
	v_and_b32_e32 v205, 0xffff0000, v156
	v_lshlrev_b32_e32 v206, 16, v160
	v_and_b32_e32 v207, 0xffff0000, v160
	v_pk_fma_f32 v[98:99], v[98:99], v[204:205], v[206:207]
	v_lshlrev_b32_e32 v204, 16, v157
	v_and_b32_e32 v205, 0xffff0000, v157
	v_lshlrev_b32_e32 v206, 16, v161
	v_and_b32_e32 v207, 0xffff0000, v161
	v_pk_fma_f32 v[100:101], v[100:101], v[204:205], v[206:207]
	v_cvt_pk_bf16_f32 v102, v102, v103
	v_cvt_pk_bf16_f32 v103, v104, v105
	v_cvt_pk_bf16_f32 v104, v98, v99
	v_cvt_pk_bf16_f32 v105, v100, v101
	global_load_dwordx4 v[154:157], v214, s[8:9] offset:256
	global_load_dwordx4 v[158:161], v215, s[6:7] offset:256
	s_waitcnt vmcnt(14)
; __device__ __forceinline__ float bf_lo(unsigned u) { return __uint_as_float(u << 16); }
; __device__ __forceinline__ float bf_hi(unsigned u) { return __uint_as_float(u & 0xffff0000u); }
;   __device__ __forceinline__ void emit(const EpiPre& q0, int row, int col, f32x4 a, f32x4 b, const f32x4 (&hb)[2][2], const float (&hs)[2][4], int ai_, int m_, int bj_) const {
;     ...
;     } else if (MODE == E_PROJ) {
;       const int br = e.aux; const u32x4 gw = q.u0;
;       v[0] *= bf_lo(gw.x); v[1] *= bf_hi(gw.x); v[2] *= bf_lo(gw.y); v[3] *= bf_hi(gw.y);
;       v[4] *= bf_lo(gw.z); v[5] *= bf_hi(gw.z); v[6] *= bf_lo(gw.w); v[7] *= bf_hi(gw.w);
;       bf16_t* fa = (bf16_t*)e.facc + (size_t)row * DM + col;
;       if (br > 0) { const u32x4 pw = q.u1;
;         v[0] += bf_lo(pw.x); v[1] += bf_hi(pw.x); v[2] += bf_lo(pw.y); v[3] += bf_hi(pw.y); v[4] += bf_lo(pw.z); v[5] += bf_hi(pw.z); v[6] += bf_lo(pw.w); v[7] += bf_hi(pw.w); }
;       if (br == 2) store8bf((bf16_t*)e.out + (size_t)row * DM + col, v);
;       else store8bf(fa, v);
	v_lshlrev_b32_e32 v204, 16, v162
	v_and_b32_e32 v205, 0xffff0000, v162
	v_lshlrev_b32_e32 v206, 16, v166
	v_and_b32_e32 v207, 0xffff0000, v166
	v_pk_fma_f32 v[92:93], v[92:93], v[204:205], v[206:207]
	v_lshlrev_b32_e32 v204, 16, v163
	v_and_b32_e32 v205, 0xffff0000, v163
	v_lshlrev_b32_e32 v206, 16, v167
	v_and_b32_e32 v207, 0xffff0000, v167
	v_pk_fma_f32 v[94:95], v[94:95], v[204:205], v[206:207]
	v_lshlrev_b32_e32 v204, 16, v164
	v_and_b32_e32 v205, 0xffff0000, v164
	v_lshlrev_b32_e32 v206, 16, v168
	v_and_b32_e32 v207, 0xffff0000, v168
	v_pk_fma_f32 v[88:89], v[88:89], v[204:205], v[206:207]
	v_lshlrev_b32_e32 v204, 16, v165
	v_and_b32_e32 v205, 0xffff0000, v165
	v_lshlrev_b32_e32 v206, 16, v169
	v_and_b32_e32 v207, 0xffff0000, v169
	v_pk_fma_f32 v[90:91], v[90:91], v[204:205], v[206:207]
	v_cvt_pk_bf16_f32 v92, v92, v93
	v_cvt_pk_bf16_f32 v93, v94, v95
	v_cvt_pk_bf16_f32 v94, v88, v89
	v_cvt_pk_bf16_f32 v95, v90, v91
	v_add_u32_e32 v214, 0x1e0000, v208
	global_load_dwordx4 v[162:165], v214, s[8:9]
	v_add_u32_e32 v215, 0xa0000, v209
	global_load_dwordx4 v[166:169], v215, s[6:7]
	s_waitcnt vmcnt(14)
	v_lshlrev_b32_e32 v204, 16, v170
	v_and_b32_e32 v205, 0xffff0000, v170
	v_lshlrev_b32_e32 v206, 16, v174
	v_and_b32_e32 v207, 0xffff0000, v174
	v_pk_fma_f32 v[84:85], v[84:85], v[204:205], v[206:207]
	v_lshlrev_b32_e32 v204, 16, v171
	v_and_b32_e32 v205, 0xffff0000, v171
	v_lshlrev_b32_e32 v206, 16, v175
	v_and_b32_e32 v207, 0xffff0000, v175
	v_pk_fma_f32 v[86:87], v[86:87], v[204:205], v[206:207]
	v_lshlrev_b32_e32 v204, 16, v172
	v_and_b32_e32 v205, 0xffff0000, v172
	v_lshlrev_b32_e32 v206, 16, v176
	v_and_b32_e32 v207, 0xffff0000, v176
	v_pk_fma_f32 v[80:81], v[80:81], v[204:205], v[206:207]
	v_lshlrev_b32_e32 v204, 16, v173
	v_and_b32_e32 v205, 0xffff0000, v173
	v_lshlrev_b32_e32 v206, 16, v177
	v_and_b32_e32 v207, 0xffff0000, v177
	v_pk_fma_f32 v[82:83], v[82:83], v[204:205], v[206:207]
	v_cvt_pk_bf16_f32 v84, v84, v85
	v_cvt_pk_bf16_f32 v85, v86, v87
	v_cvt_pk_bf16_f32 v86, v80, v81
	v_cvt_pk_bf16_f32 v87, v82, v83
	global_load_dwordx4 v[170:173], v214, s[8:9] offset:256
	global_load_dwordx4 v[174:177], v215, s[6:7] offset:256
	s_waitcnt vmcnt(14)
	v_lshlrev_b32_e32 v204, 16, v178
	v_and_b32_e32 v205, 0xffff0000, v178
	v_lshlrev_b32_e32 v206, 16, v182
	v_and_b32_e32 v207, 0xffff0000, v182
	v_pk_fma_f32 v[76:77], v[76:77], v[204:205], v[206:207]
	v_lshlrev_b32_e32 v204, 16, v179
	v_and_b32_e32 v205, 0xffff0000, v179
	v_lshlrev_b32_e32 v206, 16, v183
	v_and_b32_e32 v207, 0xffff0000, v183
	v_pk_fma_f32 v[78:79], v[78:79], v[204:205], v[206:207]
	v_lshlrev_b32_e32 v204, 16, v180
	v_and_b32_e32 v205, 0xffff0000, v180
	v_lshlrev_b32_e32 v206, 16, v184
	v_and_b32_e32 v207, 0xffff0000, v184
	v_pk_fma_f32 v[72:73], v[72:73], v[204:205], v[206:207]
	v_lshlrev_b32_e32 v204, 16, v181
	v_and_b32_e32 v205, 0xffff0000, v181
	v_lshlrev_b32_e32 v206, 16, v185
	v_and_b32_e32 v207, 0xffff0000, v185
	v_pk_fma_f32 v[74:75], v[74:75], v[204:205], v[206:207]
	v_cvt_pk_bf16_f32 v76, v76, v77
	v_cvt_pk_bf16_f32 v77, v78, v79
	v_cvt_pk_bf16_f32 v78, v72, v73
	v_cvt_pk_bf16_f32 v79, v74, v75
	v_add_u32_e32 v214, 0x210000, v208
	global_load_dwordx4 v[178:181], v214, s[8:9]
	v_add_u32_e32 v215, 0xb0000, v209
	global_load_dwordx4 v[182:185], v215, s[6:7]
	s_waitcnt vmcnt(14)
	v_lshlrev_b32_e32 v204, 16, v196
	v_and_b32_e32 v205, 0xffff0000, v196
	v_lshlrev_b32_e32 v206, 16, v200
	v_and_b32_e32 v207, 0xffff0000, v200
	v_pk_fma_f32 v[68:69], v[68:69], v[204:205], v[206:207]
	v_lshlrev_b32_e32 v204, 16, v197
	v_and_b32_e32 v205, 0xffff0000, v197
	v_lshlrev_b32_e32 v206, 16, v201
	v_and_b32_e32 v207, 0xffff0000, v201
	v_pk_fma_f32 v[70:71], v[70:71], v[204:205], v[206:207]
	v_lshlrev_b32_e32 v204, 16, v198
	v_and_b32_e32 v205, 0xffff0000, v198
	v_lshlrev_b32_e32 v206, 16, v202
	v_and_b32_e32 v207, 0xffff0000, v202
	v_pk_fma_f32 v[64:65], v[64:65], v[204:205], v[206:207]
	v_lshlrev_b32_e32 v204, 16, v199
	v_and_b32_e32 v205, 0xffff0000, v199
	v_lshlrev_b32_e32 v206, 16, v203
	v_and_b32_e32 v207, 0xffff0000, v203
	v_pk_fma_f32 v[66:67], v[66:67], v[204:205], v[206:207]
	v_cvt_pk_bf16_f32 v68, v68, v69
	v_cvt_pk_bf16_f32 v69, v70, v71
	v_cvt_pk_bf16_f32 v70, v64, v65
	v_cvt_pk_bf16_f32 v71, v66, v67
	global_load_dwordx4 v[196:199], v214, s[8:9] offset:256
	global_load_dwordx4 v[200:203], v215, s[6:7] offset:256
	v_add_u32_e32 v215, 0x0, v209
	global_store_dwordx4 v215, v[126:129], s[12:13]
	global_store_dwordx4 v215, v[118:121], s[12:13] offset:256
	v_add_u32_e32 v215, 0x10000, v209
	global_store_dwordx4 v215, v[110:113], s[12:13]
	global_store_dwordx4 v215, v[102:105], s[12:13] offset:256
	v_add_u32_e32 v215, 0x20000, v209
	global_store_dwordx4 v215, v[92:95], s[12:13]
	global_store_dwordx4 v215, v[84:87], s[12:13] offset:256
	v_add_u32_e32 v215, 0x30000, v209
	global_store_dwordx4 v215, v[76:79], s[12:13]
	global_store_dwordx4 v215, v[68:71], s[12:13] offset:256
	s_waitcnt vmcnt(22)
	v_lshlrev_b32_e32 v204, 16, v130
	v_and_b32_e32 v205, 0xffff0000, v130
	v_lshlrev_b32_e32 v206, 16, v134
	v_and_b32_e32 v207, 0xffff0000, v134
	v_pk_fma_f32 v[60:61], v[60:61], v[204:205], v[206:207]
	v_lshlrev_b32_e32 v204, 16, v131
	v_and_b32_e32 v205, 0xffff0000, v131
	v_lshlrev_b32_e32 v206, 16, v135
	v_and_b32_e32 v207, 0xffff0000, v135
	v_pk_fma_f32 v[62:63], v[62:63], v[204:205], v[206:207]
	v_lshlrev_b32_e32 v204, 16, v132
	v_and_b32_e32 v205, 0xffff0000, v132
	v_lshlrev_b32_e32 v206, 16, v136
	v_and_b32_e32 v207, 0xffff0000, v136
	v_pk_fma_f32 v[56:57], v[56:57], v[204:205], v[206:207]
	v_lshlrev_b32_e32 v204, 16, v133
	v_and_b32_e32 v205, 0xffff0000, v133
	v_lshlrev_b32_e32 v206, 16, v137
	v_and_b32_e32 v207, 0xffff0000, v137
	v_pk_fma_f32 v[58:59], v[58:59], v[204:205], v[206:207]
	v_cvt_pk_bf16_f32 v60, v60, v61
	v_cvt_pk_bf16_f32 v61, v62, v63
	v_cvt_pk_bf16_f32 v62, v56, v57
	v_cvt_pk_bf16_f32 v63, v58, v59
	v_add_u32_e32 v215, 0x80000, v209
	global_store_dwordx4 v215, v[60:63], s[12:13]
	s_waitcnt vmcnt(21)
; __device__ __forceinline__ float bf_lo(unsigned u) { return __uint_as_float(u << 16); }
; __device__ __forceinline__ float bf_hi(unsigned u) { return __uint_as_float(u & 0xffff0000u); }
;   __device__ __forceinline__ void emit(const EpiPre& q0, int row, int col, f32x4 a, f32x4 b, const f32x4 (&hb)[2][2], const float (&hs)[2][4], int ai_, int m_, int bj_) const {
;     ...
;     } else if (MODE == E_PROJ) {
;       const int br = e.aux; const u32x4 gw = q.u0;
;       v[0] *= bf_lo(gw.x); v[1] *= bf_hi(gw.x); v[2] *= bf_lo(gw.y); v[3] *= bf_hi(gw.y);
;       v[4] *= bf_lo(gw.z); v[5] *= bf_hi(gw.z); v[6] *= bf_lo(gw.w); v[7] *= bf_hi(gw.w);
;       bf16_t* fa = (bf16_t*)e.facc + (size_t)row * DM + col;
;       if (br > 0) { const u32x4 pw = q.u1;
;         v[0] += bf_lo(pw.x); v[1] += bf_hi(pw.x); v[2] += bf_lo(pw.y); v[3] += bf_hi(pw.y); v[4] += bf_lo(pw.z); v[5] += bf_hi(pw.z); v[6] += bf_lo(pw.w); v[7] += bf_hi(pw.w); }
;       if (br == 2) store8bf((bf16_t*)e.out + (size_t)row * DM + col, v);
;       else store8bf(fa, v);
	v_lshlrev_b32_e32 v204, 16, v138
	v_and_b32_e32 v205, 0xffff0000, v138
	v_lshlrev_b32_e32 v206, 16, v142
	v_and_b32_e32 v207, 0xffff0000, v142
	v_pk_fma_f32 v[52:53], v[52:53], v[204:205], v[206:207]
	v_lshlrev_b32_e32 v204, 16, v139
	v_and_b32_e32 v205, 0xffff0000, v139
	v_lshlrev_b32_e32 v206, 16, v143
	v_and_b32_e32 v207, 0xffff0000, v143
	v_pk_fma_f32 v[54:55], v[54:55], v[204:205], v[206:207]
	v_lshlrev_b32_e32 v204, 16, v140
	v_and_b32_e32 v205, 0xffff0000, v140
	v_lshlrev_b32_e32 v206, 16, v144
	v_and_b32_e32 v207, 0xffff0000, v144
	v_pk_fma_f32 v[48:49], v[48:49], v[204:205], v[206:207]
	v_lshlrev_b32_e32 v204, 16, v141
	v_and_b32_e32 v205, 0xffff0000, v141
	v_lshlrev_b32_e32 v206, 16, v145
	v_and_b32_e32 v207, 0xffff0000, v145
	v_pk_fma_f32 v[50:51], v[50:51], v[204:205], v[206:207]
	v_cvt_pk_bf16_f32 v52, v52, v53
	v_cvt_pk_bf16_f32 v53, v54, v55
	v_cvt_pk_bf16_f32 v54, v48, v49
	v_cvt_pk_bf16_f32 v55, v50, v51
	global_store_dwordx4 v215, v[52:55], s[12:13] offset:256
	s_waitcnt vmcnt(20)
	v_lshlrev_b32_e32 v204, 16, v146
	v_and_b32_e32 v205, 0xffff0000, v146
	v_lshlrev_b32_e32 v206, 16, v150
	v_and_b32_e32 v207, 0xffff0000, v150
	v_pk_fma_f32 v[44:45], v[44:45], v[204:205], v[206:207]
	v_lshlrev_b32_e32 v204, 16, v147
	v_and_b32_e32 v205, 0xffff0000, v147
	v_lshlrev_b32_e32 v206, 16, v151
	v_and_b32_e32 v207, 0xffff0000, v151
	v_pk_fma_f32 v[46:47], v[46:47], v[204:205], v[206:207]
	v_lshlrev_b32_e32 v204, 16, v148
	v_and_b32_e32 v205, 0xffff0000, v148
	v_lshlrev_b32_e32 v206, 16, v152
	v_and_b32_e32 v207, 0xffff0000, v152
	v_pk_fma_f32 v[40:41], v[40:41], v[204:205], v[206:207]
	v_lshlrev_b32_e32 v204, 16, v149
	v_and_b32_e32 v205, 0xffff0000, v149
	v_lshlrev_b32_e32 v206, 16, v153
	v_and_b32_e32 v207, 0xffff0000, v153
	v_pk_fma_f32 v[42:43], v[42:43], v[204:205], v[206:207]
	v_cvt_pk_bf16_f32 v44, v44, v45
	v_cvt_pk_bf16_f32 v45, v46, v47
	v_cvt_pk_bf16_f32 v46, v40, v41
	v_cvt_pk_bf16_f32 v47, v42, v43
	v_add_u32_e32 v215, 0x90000, v209
	global_store_dwordx4 v215, v[44:47], s[12:13]
	s_waitcnt vmcnt(19)
	v_lshlrev_b32_e32 v204, 16, v154
	v_and_b32_e32 v205, 0xffff0000, v154
	v_lshlrev_b32_e32 v206, 16, v158
	v_and_b32_e32 v207, 0xffff0000, v158
	v_pk_fma_f32 v[36:37], v[36:37], v[204:205], v[206:207]
	v_lshlrev_b32_e32 v204, 16, v155
	v_and_b32_e32 v205, 0xffff0000, v155
	v_lshlrev_b32_e32 v206, 16, v159
	v_and_b32_e32 v207, 0xffff0000, v159
	v_pk_fma_f32 v[38:39], v[38:39], v[204:205], v[206:207]
	v_lshlrev_b32_e32 v204, 16, v156
	v_and_b32_e32 v205, 0xffff0000, v156
	v_lshlrev_b32_e32 v206, 16, v160
	v_and_b32_e32 v207, 0xffff0000, v160
	v_pk_fma_f32 v[32:33], v[32:33], v[204:205], v[206:207]
	v_lshlrev_b32_e32 v204, 16, v157
	v_and_b32_e32 v205, 0xffff0000, v157
	v_lshlrev_b32_e32 v206, 16, v161
	v_and_b32_e32 v207, 0xffff0000, v161
	v_pk_fma_f32 v[34:35], v[34:35], v[204:205], v[206:207]
	v_cvt_pk_bf16_f32 v36, v36, v37
	v_cvt_pk_bf16_f32 v37, v38, v39
	v_cvt_pk_bf16_f32 v38, v32, v33
	v_cvt_pk_bf16_f32 v39, v34, v35
	global_store_dwordx4 v215, v[36:39], s[12:13] offset:256
	s_waitcnt vmcnt(18)
	v_lshlrev_b32_e32 v204, 16, v162
	v_and_b32_e32 v205, 0xffff0000, v162
	v_lshlrev_b32_e32 v206, 16, v166
	v_and_b32_e32 v207, 0xffff0000, v166
	v_pk_fma_f32 v[28:29], v[28:29], v[204:205], v[206:207]
	v_lshlrev_b32_e32 v204, 16, v163
	v_and_b32_e32 v205, 0xffff0000, v163
	v_lshlrev_b32_e32 v206, 16, v167
	v_and_b32_e32 v207, 0xffff0000, v167
	v_pk_fma_f32 v[30:31], v[30:31], v[204:205], v[206:207]
	v_lshlrev_b32_e32 v204, 16, v164
	v_and_b32_e32 v205, 0xffff0000, v164
	v_lshlrev_b32_e32 v206, 16, v168
	v_and_b32_e32 v207, 0xffff0000, v168
	v_pk_fma_f32 v[24:25], v[24:25], v[204:205], v[206:207]
	v_lshlrev_b32_e32 v204, 16, v165
	v_and_b32_e32 v205, 0xffff0000, v165
	v_lshlrev_b32_e32 v206, 16, v169
	v_and_b32_e32 v207, 0xffff0000, v169
	v_pk_fma_f32 v[26:27], v[26:27], v[204:205], v[206:207]
	v_cvt_pk_bf16_f32 v28, v28, v29
	v_cvt_pk_bf16_f32 v29, v30, v31
	v_cvt_pk_bf16_f32 v30, v24, v25
	v_cvt_pk_bf16_f32 v31, v26, v27
	v_add_u32_e32 v215, 0xa0000, v209
	global_store_dwordx4 v215, v[28:31], s[12:13]
	s_waitcnt vmcnt(17)
; __device__ __forceinline__ float bf_lo(unsigned u) { return __uint_as_float(u << 16); }
; __device__ __forceinline__ float bf_hi(unsigned u) { return __uint_as_float(u & 0xffff0000u); }
; #define PG8_WAIT_V(n) asm volatile("s_waitcnt vmcnt(" #n ")" ::: "memory")
; #define PG8_BAR __builtin_amdgcn_s_barrier()
; template <class Epi>
; __device__ __forceinline__ void gemm_phase(LAS unsigned char* lds, const Gemm g, const StaticOrder& S, const Epi& E, int wv0) {
;     ...
;   PG8_WAIT_V(0);
;   if (wr == 0) PG8_BAR;
;   PG8_BAR;
;   __device__ __forceinline__ void emit(const EpiPre& q0, int row, int col, f32x4 a, f32x4 b, const f32x4 (&hb)[2][2], const float (&hs)[2][4], int ai_, int m_, int bj_) const {
;     ...
;     } else if (MODE == E_PROJ) {
;       const int br = e.aux; const u32x4 gw = q.u0;
;       v[0] *= bf_lo(gw.x); v[1] *= bf_hi(gw.x); v[2] *= bf_lo(gw.y); v[3] *= bf_hi(gw.y);
;       v[4] *= bf_lo(gw.z); v[5] *= bf_hi(gw.z); v[6] *= bf_lo(gw.w); v[7] *= bf_hi(gw.w);
;       bf16_t* fa = (bf16_t*)e.facc + (size_t)row * DM + col;
;       if (br > 0) { const u32x4 pw = q.u1;
;         v[0] += bf_lo(pw.x); v[1] += bf_hi(pw.x); v[2] += bf_lo(pw.y); v[3] += bf_hi(pw.y); v[4] += bf_lo(pw.z); v[5] += bf_hi(pw.z); v[6] += bf_lo(pw.w); v[7] += bf_hi(pw.w); }
;       if (br == 2) store8bf((bf16_t*)e.out + (size_t)row * DM + col, v);
;       else store8bf(fa, v);
	v_lshlrev_b32_e32 v204, 16, v170
	v_and_b32_e32 v205, 0xffff0000, v170
	v_lshlrev_b32_e32 v206, 16, v174
	v_and_b32_e32 v207, 0xffff0000, v174
	v_pk_fma_f32 v[20:21], v[20:21], v[204:205], v[206:207]
	v_lshlrev_b32_e32 v204, 16, v171
	v_and_b32_e32 v205, 0xffff0000, v171
	v_lshlrev_b32_e32 v206, 16, v175
	v_and_b32_e32 v207, 0xffff0000, v175
	v_pk_fma_f32 v[22:23], v[22:23], v[204:205], v[206:207]
	v_lshlrev_b32_e32 v204, 16, v172
	v_and_b32_e32 v205, 0xffff0000, v172
	v_lshlrev_b32_e32 v206, 16, v176
	v_and_b32_e32 v207, 0xffff0000, v176
	v_pk_fma_f32 v[16:17], v[16:17], v[204:205], v[206:207]
	v_lshlrev_b32_e32 v204, 16, v173
	v_and_b32_e32 v205, 0xffff0000, v173
	v_lshlrev_b32_e32 v206, 16, v177
	v_and_b32_e32 v207, 0xffff0000, v177
	v_pk_fma_f32 v[18:19], v[18:19], v[204:205], v[206:207]
	v_cvt_pk_bf16_f32 v20, v20, v21
	v_cvt_pk_bf16_f32 v21, v22, v23
	v_cvt_pk_bf16_f32 v22, v16, v17
	v_cvt_pk_bf16_f32 v23, v18, v19
	global_store_dwordx4 v215, v[20:23], s[12:13] offset:256
	s_waitcnt vmcnt(16)
	v_lshlrev_b32_e32 v204, 16, v178
	v_and_b32_e32 v205, 0xffff0000, v178
	v_lshlrev_b32_e32 v206, 16, v182
	v_and_b32_e32 v207, 0xffff0000, v182
	v_pk_fma_f32 v[12:13], v[12:13], v[204:205], v[206:207]
	v_lshlrev_b32_e32 v204, 16, v179
	v_and_b32_e32 v205, 0xffff0000, v179
	v_lshlrev_b32_e32 v206, 16, v183
	v_and_b32_e32 v207, 0xffff0000, v183
	v_pk_fma_f32 v[14:15], v[14:15], v[204:205], v[206:207]
	v_lshlrev_b32_e32 v204, 16, v180
	v_and_b32_e32 v205, 0xffff0000, v180
	v_lshlrev_b32_e32 v206, 16, v184
	v_and_b32_e32 v207, 0xffff0000, v184
	v_pk_fma_f32 v[8:9], v[8:9], v[204:205], v[206:207]
	v_lshlrev_b32_e32 v204, 16, v181
	v_and_b32_e32 v205, 0xffff0000, v181
	v_lshlrev_b32_e32 v206, 16, v185
	v_and_b32_e32 v207, 0xffff0000, v185
	v_pk_fma_f32 v[10:11], v[10:11], v[204:205], v[206:207]
	v_cvt_pk_bf16_f32 v12, v12, v13
	v_cvt_pk_bf16_f32 v13, v14, v15
	v_cvt_pk_bf16_f32 v14, v8, v9
	v_cvt_pk_bf16_f32 v15, v10, v11
	v_add_u32_e32 v215, 0xb0000, v209
	global_store_dwordx4 v215, v[12:15], s[12:13]
	s_waitcnt vmcnt(15)
	v_lshlrev_b32_e32 v204, 16, v196
	v_and_b32_e32 v205, 0xffff0000, v196
	v_lshlrev_b32_e32 v206, 16, v200
	v_and_b32_e32 v207, 0xffff0000, v200
	v_pk_fma_f32 v[4:5], v[4:5], v[204:205], v[206:207]
	v_lshlrev_b32_e32 v204, 16, v197
	v_and_b32_e32 v205, 0xffff0000, v197
	v_lshlrev_b32_e32 v206, 16, v201
	v_and_b32_e32 v207, 0xffff0000, v201
	v_pk_fma_f32 v[6:7], v[6:7], v[204:205], v[206:207]
	v_lshlrev_b32_e32 v204, 16, v198
	v_and_b32_e32 v205, 0xffff0000, v198
	v_lshlrev_b32_e32 v206, 16, v202
	v_and_b32_e32 v207, 0xffff0000, v202
	v_pk_fma_f32 v[0:1], v[0:1], v[204:205], v[206:207]
	v_lshlrev_b32_e32 v204, 16, v199
	v_and_b32_e32 v205, 0xffff0000, v199
	v_lshlrev_b32_e32 v206, 16, v203
	v_and_b32_e32 v207, 0xffff0000, v203
	v_pk_fma_f32 v[2:3], v[2:3], v[204:205], v[206:207]
	v_cvt_pk_bf16_f32 v4, v4, v5
	v_cvt_pk_bf16_f32 v5, v6, v7
	v_cvt_pk_bf16_f32 v6, v0, v1
	v_cvt_pk_bf16_f32 v7, v2, v3
	global_store_dwordx4 v215, v[4:7], s[12:13] offset:256
	s_mov_b32 s47, s14
	s_mov_b64 s[22:23], s[18:19]
	s_mov_b64 s[20:21], s[16:17]
	s_and_b64 vcc, exec, s[2:3]
	s_mov_b32 s1, s46
	s_cbranch_vccz .LBB0_1016
	s_waitcnt vmcnt(0)
	s_cmpk_gt_u32 s29, 0xff
	s_cbranch_scc1 .LBB0_1029
	s_barrier

; #define PG8_STAGE(bufoff, gbase, voff) do { _Pragma("unroll") for (int _i = 0; _i < 2; ++_i) \
;     __builtin_amdgcn_global_load_lds((const unsigned*)((const char*)(gbase) + (voff)[_i]), (LAS unsigned*)(lds + (bufoff) + ldsw + _i * 8192), 16, 0, 0); } while (0)
; #define PG8_LDA(dst, b, h) do { _Pragma("unroll") for (int m = 0; m < 4; ++m) _Pragma("unroll") for (int k = 0; k < 2; ++k) dst[m][k] = *(const LAS bf16x8*)(lds + PG8_SA(b, h) + aoff + m * 2048 + k * 1024); } while (0)
; #define PG8_LDB(dst, b, h) do { _Pragma("unroll") for (int n = 0; n < 2; ++n) _Pragma("unroll") for (int k = 0; k < 2; ++k) dst[n][k] = *(const LAS bf16x8*)(lds + PG8_SB(b, h) + boff + n * 2048 + k * 1024); } while (0)
; #define PG8_MMA(ai, bj, At, Bt) do { __builtin_amdgcn_s_setprio(1); _Pragma("unroll") for (int m = 0; m < 4; ++m) _Pragma("unroll") for (int n = 0; n < 2; ++n) _Pragma("unroll") for (int k = 0; k < 2; ++k) \
;     acc[ai][bj][m][n] = __builtin_amdgcn_mfma_f32_16x16x32_bf16(Bt[n][k], At[m][k], acc[ai][bj][m][n], 0, 0, 0); __builtin_amdgcn_s_setprio(0); } while (0)
; #define PG8_WAIT_L(n) asm volatile("s_waitcnt lgkmcnt(" #n ")" ::: "memory")
; template <class Epi>
; __device__ __forceinline__ void gemm_phase(LAS unsigned char* lds, const Gemm g, const StaticOrder& S, const Epi& E, int wv0) {
;     ...
;   for (;;) {
;     const bool has_next = S.next(ui + 1, nxt);
;     const char* nA = has_next ? (const char*)g.A + (size_t)nxt.pm * tstepA : cA; const char* nB = has_next ? (const char*)g.Bt + (size_t)nxt.pn * tstepB : cB;
;     for (int t = 0; t < nt; t += 2) {
;       const bool last = (t == nt - 2);
;       const char* a1 = cA + (size_t)(t + 1) * kstep;
;       const char* a2 = last ? nA : cA + (size_t)(t + 2) * kstep; const char* b2 = last ? nB : cB + (size_t)(t + 2) * kstep;
;       const char* a3 = a2 + kstep; const char* b3 = b2 + kstep;
;       PG8_LDB(B0, 0, 0); PG8_SCHED; PG8_LDA(At, 0, 0); PG8_STAGE(PG8_SA(1, 1), a1 + hstepA, voffA);
;       PG8_WAIT_L(8); PG8_BAR; PG8_WAIT_L(0); PG8_MMA(0, 0, At, B0); PG8_BAR; PG8_SCHED;
;     ...
; #pragma unroll
;     for (int a = 0; a < 2; ++a)
; #pragma unroll
;       for (int b = 0; b < 2; ++b)
; #pragma unroll
;         for (int m = 0; m < 4; ++m)
; #pragma unroll
;           for (int n = 0; n < 2; ++n) acc[a][b][m][n] = (f32x4){0.f, 0.f, 0.f, 0.f};
;     cur = nxt; cA = nA; cB = nB; ++ui;
.LBB0_1099:
	s_ashr_i32 s13, s12, 31
	v_cmp_lt_i64_e32 vcc, s[14:15], v[244:245]
	s_lshl_b64 s[14:15], s[12:13], 20
	s_add_u32 s14, s34, s14
	s_addc_u32 s15, s35, s15
	s_and_b64 s[16:17], vcc, exec
	s_cselect_b32 s13, s15, s21
	s_cselect_b32 s45, s14, s20
	s_ashr_i32 s11, s10, 31
	s_lshl_b64 s[16:17], s[10:11], 20
	s_add_u32 s16, s36, s16
	s_addc_u32 s17, s37, s17
	s_and_b64 s[24:25], vcc, exec
	s_cselect_b32 s11, s17, s23
	s_cselect_b32 s46, s16, s22
	s_add_u32 s20, s20, 0x80080
	s_addc_u32 s21, s21, 0
	s_add_u32 s47, s22, 0x100
	v_mov_b32_e32 v0, 0
	s_addc_u32 s48, s23, 0
	s_mov_b32 s49, -2
	v_mov_b32_e32 v1, v0
	v_mov_b32_e32 v2, v0
	v_mov_b32_e32 v3, v0
	v_mov_b32_e32 v4, v0
	v_mov_b32_e32 v5, v0
	v_mov_b32_e32 v6, v0
	v_mov_b32_e32 v7, v0
	v_mov_b32_e32 v12, v0
	v_mov_b32_e32 v13, v0
	v_mov_b32_e32 v14, v0
	v_mov_b32_e32 v15, v0
	v_mov_b32_e32 v16, v0
	v_mov_b32_e32 v17, v0
	v_mov_b32_e32 v18, v0
	v_mov_b32_e32 v19, v0
	v_mov_b32_e32 v32, v0
	v_mov_b32_e32 v33, v0
	v_mov_b32_e32 v34, v0
	v_mov_b32_e32 v35, v0
	v_mov_b32_e32 v36, v0
	v_mov_b32_e32 v37, v0
	v_mov_b32_e32 v38, v0
	v_mov_b32_e32 v39, v0
	v_mov_b32_e32 v48, v0
	v_mov_b32_e32 v49, v0
	v_mov_b32_e32 v50, v0
	v_mov_b32_e32 v51, v0
	v_mov_b32_e32 v52, v0
	v_mov_b32_e32 v53, v0
	v_mov_b32_e32 v54, v0
	v_mov_b32_e32 v55, v0
	v_mov_b32_e32 v8, v0
	v_mov_b32_e32 v9, v0
	v_mov_b32_e32 v10, v0
	v_mov_b32_e32 v11, v0
	v_mov_b32_e32 v20, v0
	v_mov_b32_e32 v21, v0
	v_mov_b32_e32 v22, v0
	v_mov_b32_e32 v23, v0
	v_mov_b32_e32 v24, v0
	v_mov_b32_e32 v25, v0
	v_mov_b32_e32 v26, v0
	v_mov_b32_e32 v27, v0
	v_mov_b32_e32 v28, v0
	v_mov_b32_e32 v29, v0
	v_mov_b32_e32 v30, v0
	v_mov_b32_e32 v31, v0
	v_mov_b32_e32 v40, v0
	v_mov_b32_e32 v41, v0
	v_mov_b32_e32 v42, v0
	v_mov_b32_e32 v43, v0
	v_mov_b32_e32 v44, v0
	v_mov_b32_e32 v45, v0
	v_mov_b32_e32 v46, v0
	v_mov_b32_e32 v47, v0
	v_mov_b32_e32 v56, v0
	v_mov_b32_e32 v57, v0
	v_mov_b32_e32 v58, v0
	v_mov_b32_e32 v59, v0
	v_mov_b32_e32 v60, v0
	v_mov_b32_e32 v61, v0
	v_mov_b32_e32 v62, v0
	v_mov_b32_e32 v63, v0
	v_mov_b32_e32 v64, v0
	v_mov_b32_e32 v65, v0
	v_mov_b32_e32 v66, v0
	v_mov_b32_e32 v67, v0
	v_mov_b32_e32 v68, v0
	v_mov_b32_e32 v69, v0
	v_mov_b32_e32 v70, v0
	v_mov_b32_e32 v71, v0
	v_mov_b32_e32 v72, v0
	v_mov_b32_e32 v73, v0
	v_mov_b32_e32 v74, v0
	v_mov_b32_e32 v75, v0
	v_mov_b32_e32 v80, v0
	v_mov_b32_e32 v81, v0
	v_mov_b32_e32 v82, v0
	v_mov_b32_e32 v83, v0
	v_mov_b32_e32 v98, v0
	v_mov_b32_e32 v99, v0
	v_mov_b32_e32 v100, v0
	v_mov_b32_e32 v101, v0
	v_mov_b32_e32 v102, v0
	v_mov_b32_e32 v103, v0
	v_mov_b32_e32 v104, v0
	v_mov_b32_e32 v105, v0
	v_mov_b32_e32 v106, v0
	v_mov_b32_e32 v107, v0
	v_mov_b32_e32 v108, v0
	v_mov_b32_e32 v109, v0
	v_mov_b32_e32 v110, v0
	v_mov_b32_e32 v111, v0
	v_mov_b32_e32 v112, v0
	v_mov_b32_e32 v113, v0
	v_mov_b32_e32 v76, v0
	v_mov_b32_e32 v77, v0
	v_mov_b32_e32 v78, v0
	v_mov_b32_e32 v79, v0
	v_mov_b32_e32 v84, v0
	v_mov_b32_e32 v85, v0
	v_mov_b32_e32 v86, v0
	v_mov_b32_e32 v87, v0
	v_mov_b32_e32 v88, v0
	v_mov_b32_e32 v89, v0
	v_mov_b32_e32 v90, v0
	v_mov_b32_e32 v91, v0
	v_mov_b32_e32 v92, v0
	v_mov_b32_e32 v93, v0
	v_mov_b32_e32 v94, v0
	v_mov_b32_e32 v95, v0
	v_mov_b32_e32 v114, v0
	v_mov_b32_e32 v115, v0
	v_mov_b32_e32 v116, v0
	v_mov_b32_e32 v117, v0
	v_mov_b32_e32 v118, v0
	v_mov_b32_e32 v119, v0
	v_mov_b32_e32 v120, v0
	v_mov_b32_e32 v121, v0
	v_mov_b32_e32 v122, v0
	v_mov_b32_e32 v123, v0
	v_mov_b32_e32 v124, v0
	v_mov_b32_e32 v125, v0
	v_mov_b32_e32 v126, v0
	v_mov_b32_e32 v127, v0
	v_mov_b32_e32 v128, v0
	v_mov_b32_e32 v129, v0
	s_cmp_lt_u32 s53, 4
	s_cbranch_scc1 .Lgprio7
	s_setprio 1
.Lgprio7:
.LBB0_1100:
	s_add_u32 s0, s20, 0xfff80080
	s_addc_u32 s22, s21, -1
	s_add_i32 s50, 0, 0x10000
	v_add_u32_e32 v142, s50, v185
	ds_read_b128 v[130:133], v142
	ds_read_b128 v[134:137], v142 offset:1024
	ds_read_b128 v[138:141], v142 offset:2048
	ds_read_b128 v[142:145], v142 offset:3072
	s_cmp_eq_u32 s49, 28
	s_cselect_b32 s25, s13, s22
	s_cselect_b32 s24, s45, s0
	s_cselect_b32 s23, s11, s48
	s_cselect_b32 s22, s46, s47
	v_lshl_add_u64 v[192:193], s[20:21], 0, v[168:169]
	s_add_i32 m0, s19, 0xc000
	ds_read_b128 v[146:149], v187
	ds_read_b128 v[150:153], v187 offset:1024
	ds_read_b128 v[154:157], v187 offset:2048
	ds_read_b128 v[158:161], v187 offset:3072
	ds_read_b128 v[172:175], v187 offset:4096
	ds_read_b128 v[176:179], v187 offset:5120
	ds_read_b128 v[180:183], v187 offset:6144
	ds_read_b128 v[188:191], v187 offset:7168
	global_load_lds_dwordx4 v[192:193], off
	v_lshl_add_u64 v[192:193], s[20:21], 0, v[170:171]
	s_add_i32 m0, s19, 0xe000
	s_nop 0
	global_load_lds_dwordx4 v[192:193], off
	s_waitcnt lgkmcnt(8)
	s_barrier
	s_waitcnt lgkmcnt(0)
	s_waitcnt lgkmcnt(0)
	v_mfma_f32_16x16x32_bf16 v[126:129], v[130:133], v[146:149], v[126:129]
	v_mfma_f32_16x16x32_bf16 v[122:125], v[138:141], v[146:149], v[122:125]
	v_mfma_f32_16x16x32_bf16 v[118:121], v[130:133], v[154:157], v[118:121]
	v_mfma_f32_16x16x32_bf16 v[114:117], v[138:141], v[154:157], v[114:117]
	v_mfma_f32_16x16x32_bf16 v[92:95], v[130:133], v[172:175], v[92:95]
	v_mfma_f32_16x16x32_bf16 v[88:91], v[138:141], v[172:175], v[88:91]
	v_mfma_f32_16x16x32_bf16 v[84:87], v[130:133], v[180:183], v[84:87]
	v_mfma_f32_16x16x32_bf16 v[76:79], v[138:141], v[180:183], v[76:79]
	v_mfma_f32_16x16x32_bf16 v[126:129], v[134:137], v[150:153], v[126:129]
	v_mfma_f32_16x16x32_bf16 v[122:125], v[142:145], v[150:153], v[122:125]
	v_mfma_f32_16x16x32_bf16 v[118:121], v[134:137], v[158:161], v[118:121]
	v_mfma_f32_16x16x32_bf16 v[114:117], v[142:145], v[158:161], v[114:117]
	v_mfma_f32_16x16x32_bf16 v[92:95], v[134:137], v[176:179], v[92:95]
	v_mfma_f32_16x16x32_bf16 v[88:91], v[142:145], v[176:179], v[88:91]
	v_mfma_f32_16x16x32_bf16 v[84:87], v[134:137], v[188:191], v[84:87]
	v_mfma_f32_16x16x32_bf16 v[76:79], v[142:145], v[188:191], v[76:79]
	s_barrier
; #define PG8_STAGE(bufoff, gbase, voff) do { _Pragma("unroll") for (int _i = 0; _i < 2; ++_i) \
;     __builtin_amdgcn_global_load_lds((const unsigned*)((const char*)(gbase) + (voff)[_i]), (LAS unsigned*)(lds + (bufoff) + ldsw + _i * 8192), 16, 0, 0); } while (0)
; #define PG8_LDA(dst, b, h) do { _Pragma("unroll") for (int m = 0; m < 4; ++m) _Pragma("unroll") for (int k = 0; k < 2; ++k) dst[m][k] = *(const LAS bf16x8*)(lds + PG8_SA(b, h) + aoff + m * 2048 + k * 1024); } while (0)
; #define PG8_LDB(dst, b, h) do { _Pragma("unroll") for (int n = 0; n < 2; ++n) _Pragma("unroll") for (int k = 0; k < 2; ++k) dst[n][k] = *(const LAS bf16x8*)(lds + PG8_SB(b, h) + boff + n * 2048 + k * 1024); } while (0)
; #define PG8_MMA(ai, bj, At, Bt) do { __builtin_amdgcn_s_setprio(1); _Pragma("unroll") for (int m = 0; m < 4; ++m) _Pragma("unroll") for (int n = 0; n < 2; ++n) _Pragma("unroll") for (int k = 0; k < 2; ++k) \
;     acc[ai][bj][m][n] = __builtin_amdgcn_mfma_f32_16x16x32_bf16(Bt[n][k], At[m][k], acc[ai][bj][m][n], 0, 0, 0); __builtin_amdgcn_s_setprio(0); } while (0)
; #define PG8_WAIT_V(n) asm volatile("s_waitcnt vmcnt(" #n ")" ::: "memory")
; #define PG8_WAIT_L(n) asm volatile("s_waitcnt lgkmcnt(" #n ")" ::: "memory")
; #define PG8_BAR __builtin_amdgcn_s_barrier()
; template <class Epi>
; __device__ __forceinline__ void gemm_phase(LAS unsigned char* lds, const Gemm g, const StaticOrder& S, const Epi& E, int wv0) {
;     ...
;       PG8_LDB(B1, 0, 1); PG8_STAGE(PG8_SB(0, 0), b2, voffB);
;       PG8_BAR; PG8_WAIT_L(0); PG8_MMA(0, 1, At, B1); PG8_BAR;
;       PG8_LDA(At, 0, 1); PG8_STAGE(PG8_SA(0, 0), a2, voffA);
;       PG8_BAR; PG8_WAIT_L(0); PG8_MMA(1, 0, At, B0); PG8_BAR; PG8_SCHED;
;       PG8_STAGE(PG8_SB(0, 1), b2 + hstepB, voffB);
;       PG8_WAIT_V(6); PG8_BAR; PG8_MMA(1, 1, At, B1); PG8_BAR;
;       PG8_LDB(B0, 1, 0); PG8_SCHED; PG8_LDA(At, 1, 0); PG8_STAGE(PG8_SA(0, 1), a2 + hstepA, voffA);
;       PG8_WAIT_L(8); PG8_BAR; PG8_WAIT_L(0); PG8_MMA(0, 0, At, B0); PG8_BAR; PG8_SCHED;
;       PG8_LDB(B1, 1, 1); PG8_STAGE(PG8_SB(1, 0), b3, voffB);
;       PG8_BAR; PG8_WAIT_L(0); PG8_MMA(0, 1, At, B1); PG8_BAR;
;       PG8_LDA(At, 1, 1); PG8_STAGE(PG8_SA(1, 0), a3, voffA);
;       PG8_BAR; PG8_WAIT_L(0); PG8_MMA(1, 0, At, B0); PG8_BAR; PG8_SCHED;
;       PG8_STAGE(PG8_SB(1, 1), b3 + hstepB, voffB);
;       PG8_WAIT_V(6); PG8_BAR; PG8_MMA(1, 1, At, B1); PG8_BAR;
	s_add_i32 s0, 0, 0x14000
	s_add_i32 s50, s50, s31
	v_add_u32_e32 v204, s0, v185
	v_lshl_add_u64 v[208:209], s[22:23], 0, v[96:97]
	s_mov_b32 m0, s50
	ds_read_b128 v[192:195], v204
	ds_read_b128 v[196:199], v204 offset:1024
	ds_read_b128 v[200:203], v204 offset:2048
	ds_read_b128 v[204:207], v204 offset:3072
	global_load_lds_dwordx4 v[208:209], off
	v_lshl_add_u64 v[210:211], s[22:23], 0, v[166:167]
	s_add_i32 m0, s50, 0x2000
	s_nop 0
	global_load_lds_dwordx4 v[210:211], off
	s_barrier
	s_waitcnt lgkmcnt(0)
	s_waitcnt lgkmcnt(0)
	v_mfma_f32_16x16x32_bf16 v[110:113], v[192:195], v[146:149], v[110:113]
	v_mfma_f32_16x16x32_bf16 v[106:109], v[200:203], v[146:149], v[106:109]
	v_mfma_f32_16x16x32_bf16 v[102:105], v[192:195], v[154:157], v[102:105]
	v_mfma_f32_16x16x32_bf16 v[98:101], v[200:203], v[154:157], v[98:101]
	v_mfma_f32_16x16x32_bf16 v[80:83], v[192:195], v[172:175], v[80:83]
	v_mfma_f32_16x16x32_bf16 v[72:75], v[200:203], v[172:175], v[72:75]
	v_mfma_f32_16x16x32_bf16 v[68:71], v[192:195], v[180:183], v[68:71]
	v_mfma_f32_16x16x32_bf16 v[64:67], v[200:203], v[180:183], v[64:67]
	v_mfma_f32_16x16x32_bf16 v[110:113], v[196:199], v[150:153], v[110:113]
	v_mfma_f32_16x16x32_bf16 v[106:109], v[204:207], v[150:153], v[106:109]
	v_mfma_f32_16x16x32_bf16 v[102:105], v[196:199], v[158:161], v[102:105]
	v_mfma_f32_16x16x32_bf16 v[98:101], v[204:207], v[158:161], v[98:101]
	v_mfma_f32_16x16x32_bf16 v[80:83], v[196:199], v[176:179], v[80:83]
	v_mfma_f32_16x16x32_bf16 v[72:75], v[204:207], v[176:179], v[72:75]
	v_mfma_f32_16x16x32_bf16 v[68:71], v[196:199], v[188:191], v[68:71]
	v_mfma_f32_16x16x32_bf16 v[64:67], v[204:207], v[188:191], v[64:67]
	s_mov_b32 m0, s19
	v_lshl_add_u64 v[212:213], s[24:25], 0, v[162:163]
	s_barrier
	ds_read_b128 v[146:149], v187 offset:16384
	ds_read_b128 v[150:153], v187 offset:17408
	ds_read_b128 v[154:157], v187 offset:18432
	ds_read_b128 v[158:161], v187 offset:19456
	ds_read_b128 v[172:175], v187 offset:20480
	ds_read_b128 v[176:179], v187 offset:21504
	ds_read_b128 v[180:183], v187 offset:22528
	ds_read_b128 v[188:191], v187 offset:23552
	global_load_lds_dwordx4 v[212:213], off
	v_lshl_add_u64 v[214:215], s[24:25], 0, v[164:165]
	s_mov_b32 m0, s38
	s_nop 0
	global_load_lds_dwordx4 v[214:215], off
	s_barrier
	s_waitcnt lgkmcnt(0)
	s_waitcnt lgkmcnt(0)
	v_mfma_f32_16x16x32_bf16 v[60:63], v[130:133], v[146:149], v[60:63]
	v_mfma_f32_16x16x32_bf16 v[56:59], v[138:141], v[146:149], v[56:59]
	v_mfma_f32_16x16x32_bf16 v[44:47], v[130:133], v[154:157], v[44:47]
	v_mfma_f32_16x16x32_bf16 v[40:43], v[138:141], v[154:157], v[40:43]
	v_mfma_f32_16x16x32_bf16 v[28:31], v[130:133], v[172:175], v[28:31]
	v_mfma_f32_16x16x32_bf16 v[24:27], v[138:141], v[172:175], v[24:27]
	v_mfma_f32_16x16x32_bf16 v[20:23], v[130:133], v[180:183], v[20:23]
	v_mfma_f32_16x16x32_bf16 v[8:11], v[138:141], v[180:183], v[8:11]
	v_mfma_f32_16x16x32_bf16 v[60:63], v[134:137], v[150:153], v[60:63]
	v_mfma_f32_16x16x32_bf16 v[56:59], v[142:145], v[150:153], v[56:59]
	v_mfma_f32_16x16x32_bf16 v[44:47], v[134:137], v[158:161], v[44:47]
	v_mfma_f32_16x16x32_bf16 v[40:43], v[142:145], v[158:161], v[40:43]
	v_mfma_f32_16x16x32_bf16 v[28:31], v[134:137], v[176:179], v[28:31]
	v_mfma_f32_16x16x32_bf16 v[24:27], v[142:145], v[176:179], v[24:27]
	v_mfma_f32_16x16x32_bf16 v[20:23], v[134:137], v[188:191], v[20:23]
	v_mfma_f32_16x16x32_bf16 v[8:11], v[142:145], v[188:191], v[8:11]
	s_barrier
	s_add_u32 s50, s22, 0x80000
	s_addc_u32 s51, s23, 0
	s_add_i32 s0, s0, s31
	v_lshl_add_u64 v[130:131], s[50:51], 0, v[96:97]
	s_mov_b32 m0, s0
	s_nop 0
	global_load_lds_dwordx4 v[130:131], off
	v_lshl_add_u64 v[130:131], s[50:51], 0, v[166:167]
	s_add_i32 m0, s0, 0x2000
	s_nop 0
	global_load_lds_dwordx4 v[130:131], off
	s_waitcnt vmcnt(6)
	s_barrier
	v_mfma_f32_16x16x32_bf16 v[52:55], v[192:195], v[146:149], v[52:55]
	v_mfma_f32_16x16x32_bf16 v[48:51], v[200:203], v[146:149], v[48:51]
	v_mfma_f32_16x16x32_bf16 v[36:39], v[192:195], v[154:157], v[36:39]
	v_mfma_f32_16x16x32_bf16 v[32:35], v[200:203], v[154:157], v[32:35]
	v_mfma_f32_16x16x32_bf16 v[16:19], v[192:195], v[172:175], v[16:19]
	v_mfma_f32_16x16x32_bf16 v[12:15], v[200:203], v[172:175], v[12:15]
	v_mfma_f32_16x16x32_bf16 v[4:7], v[192:195], v[180:183], v[4:7]
	v_mfma_f32_16x16x32_bf16 v[0:3], v[200:203], v[180:183], v[0:3]
	v_mfma_f32_16x16x32_bf16 v[52:55], v[196:199], v[150:153], v[52:55]
	v_mfma_f32_16x16x32_bf16 v[48:51], v[204:207], v[150:153], v[48:51]
	v_mfma_f32_16x16x32_bf16 v[36:39], v[196:199], v[158:161], v[36:39]
	v_mfma_f32_16x16x32_bf16 v[32:35], v[204:207], v[158:161], v[32:35]
	v_mfma_f32_16x16x32_bf16 v[16:19], v[196:199], v[176:179], v[16:19]
	v_mfma_f32_16x16x32_bf16 v[12:15], v[204:207], v[176:179], v[12:15]
	v_mfma_f32_16x16x32_bf16 v[4:7], v[196:199], v[188:191], v[4:7]
	v_mfma_f32_16x16x32_bf16 v[0:3], v[204:207], v[188:191], v[0:3]
	s_add_i32 s0, 0, 0x18000
	v_add_u32_e32 v142, s0, v185
	s_barrier
	ds_read_b128 v[130:133], v142
	ds_read_b128 v[134:137], v142 offset:1024
	ds_read_b128 v[138:141], v142 offset:2048
	ds_read_b128 v[142:145], v142 offset:3072
	s_add_u32 s24, s24, 0x80000
	s_addc_u32 s25, s25, 0
	s_mov_b32 m0, s39
	v_lshl_add_u64 v[192:193], s[24:25], 0, v[162:163]
	ds_read_b128 v[146:149], v187 offset:32768
	ds_read_b128 v[150:153], v187 offset:33792
	ds_read_b128 v[154:157], v187 offset:34816
	ds_read_b128 v[158:161], v187 offset:35840
	ds_read_b128 v[172:175], v187 offset:36864
	ds_read_b128 v[176:179], v187 offset:37888
	ds_read_b128 v[180:183], v187 offset:38912
	ds_read_b128 v[188:191], v187 offset:39936
	global_load_lds_dwordx4 v[192:193], off
	v_lshl_add_u64 v[192:193], s[24:25], 0, v[164:165]
	s_mov_b32 m0, s40
	s_nop 0
	global_load_lds_dwordx4 v[192:193], off
	s_waitcnt lgkmcnt(8)
	s_barrier
; #define PG8_STAGE(bufoff, gbase, voff) do { _Pragma("unroll") for (int _i = 0; _i < 2; ++_i) \
;     __builtin_amdgcn_global_load_lds((const unsigned*)((const char*)(gbase) + (voff)[_i]), (LAS unsigned*)(lds + (bufoff) + ldsw + _i * 8192), 16, 0, 0); } while (0)
; #define PG8_LDA(dst, b, h) do { _Pragma("unroll") for (int m = 0; m < 4; ++m) _Pragma("unroll") for (int k = 0; k < 2; ++k) dst[m][k] = *(const LAS bf16x8*)(lds + PG8_SA(b, h) + aoff + m * 2048 + k * 1024); } while (0)
; #define PG8_LDB(dst, b, h) do { _Pragma("unroll") for (int n = 0; n < 2; ++n) _Pragma("unroll") for (int k = 0; k < 2; ++k) dst[n][k] = *(const LAS bf16x8*)(lds + PG8_SB(b, h) + boff + n * 2048 + k * 1024); } while (0)
; #define PG8_MMA(ai, bj, At, Bt) do { __builtin_amdgcn_s_setprio(1); _Pragma("unroll") for (int m = 0; m < 4; ++m) _Pragma("unroll") for (int n = 0; n < 2; ++n) _Pragma("unroll") for (int k = 0; k < 2; ++k) \
;     acc[ai][bj][m][n] = __builtin_amdgcn_mfma_f32_16x16x32_bf16(Bt[n][k], At[m][k], acc[ai][bj][m][n], 0, 0, 0); __builtin_amdgcn_s_setprio(0); } while (0)
; #define PG8_WAIT_V(n) asm volatile("s_waitcnt vmcnt(" #n ")" ::: "memory")
; #define PG8_WAIT_L(n) asm volatile("s_waitcnt lgkmcnt(" #n ")" ::: "memory")
; #define PG8_BAR __builtin_amdgcn_s_barrier()
; #define PG8_SCHED __builtin_amdgcn_sched_barrier(0)
; template <class Epi>
; __device__ __forceinline__ void gemm_phase(LAS unsigned char* lds, const Gemm g, const StaticOrder& S, const Epi& E, int wv0) {
;     ...
;       PG8_LDB(B0, 1, 0); PG8_SCHED; PG8_LDA(At, 1, 0); PG8_STAGE(PG8_SA(0, 1), a2 + hstepA, voffA);
;       PG8_WAIT_L(8); PG8_BAR; PG8_WAIT_L(0); PG8_MMA(0, 0, At, B0); PG8_BAR; PG8_SCHED;
;       PG8_LDB(B1, 1, 1); PG8_STAGE(PG8_SB(1, 0), b3, voffB);
;       PG8_BAR; PG8_WAIT_L(0); PG8_MMA(0, 1, At, B1); PG8_BAR;
;       PG8_LDA(At, 1, 1); PG8_STAGE(PG8_SA(1, 0), a3, voffA);
;       PG8_BAR; PG8_WAIT_L(0); PG8_MMA(1, 0, At, B0); PG8_BAR; PG8_SCHED;
;       PG8_STAGE(PG8_SB(1, 1), b3 + hstepB, voffB);
;       PG8_WAIT_V(6); PG8_BAR; PG8_MMA(1, 1, At, B1); PG8_BAR;
	s_waitcnt lgkmcnt(0)
	s_waitcnt lgkmcnt(0)
	v_mfma_f32_16x16x32_bf16 v[126:129], v[130:133], v[146:149], v[126:129]
	v_mfma_f32_16x16x32_bf16 v[122:125], v[138:141], v[146:149], v[122:125]
	v_mfma_f32_16x16x32_bf16 v[118:121], v[130:133], v[154:157], v[118:121]
	v_mfma_f32_16x16x32_bf16 v[114:117], v[138:141], v[154:157], v[114:117]
	v_mfma_f32_16x16x32_bf16 v[92:95], v[130:133], v[172:175], v[92:95]
	v_mfma_f32_16x16x32_bf16 v[88:91], v[138:141], v[172:175], v[88:91]
	v_mfma_f32_16x16x32_bf16 v[84:87], v[130:133], v[180:183], v[84:87]
	v_mfma_f32_16x16x32_bf16 v[76:79], v[138:141], v[180:183], v[76:79]
	v_mfma_f32_16x16x32_bf16 v[126:129], v[134:137], v[150:153], v[126:129]
	v_mfma_f32_16x16x32_bf16 v[122:125], v[142:145], v[150:153], v[122:125]
	v_mfma_f32_16x16x32_bf16 v[118:121], v[134:137], v[158:161], v[118:121]
	v_mfma_f32_16x16x32_bf16 v[114:117], v[142:145], v[158:161], v[114:117]
	v_mfma_f32_16x16x32_bf16 v[92:95], v[134:137], v[176:179], v[92:95]
	v_mfma_f32_16x16x32_bf16 v[88:91], v[142:145], v[176:179], v[88:91]
	v_mfma_f32_16x16x32_bf16 v[84:87], v[134:137], v[188:191], v[84:87]
	v_mfma_f32_16x16x32_bf16 v[76:79], v[142:145], v[188:191], v[76:79]
	s_barrier
	s_add_i32 s24, 0, 0x1c000
	s_add_i32 s0, s0, s31
	v_add_u32_e32 v204, s24, v185
	v_lshl_add_u64 v[208:209], v[208:209], 0, s[72:73]
	s_mov_b32 m0, s0
	ds_read_b128 v[192:195], v204
	ds_read_b128 v[196:199], v204 offset:1024
	ds_read_b128 v[200:203], v204 offset:2048
	ds_read_b128 v[204:207], v204 offset:3072
	global_load_lds_dwordx4 v[208:209], off
	v_lshl_add_u64 v[208:209], v[210:211], 0, s[72:73]
	s_add_i32 m0, s0, 0x2000
	s_nop 0
	global_load_lds_dwordx4 v[208:209], off
	s_barrier
	s_waitcnt lgkmcnt(0)
	s_waitcnt lgkmcnt(0)
	v_mfma_f32_16x16x32_bf16 v[110:113], v[192:195], v[146:149], v[110:113]
	v_mfma_f32_16x16x32_bf16 v[106:109], v[200:203], v[146:149], v[106:109]
	v_mfma_f32_16x16x32_bf16 v[102:105], v[192:195], v[154:157], v[102:105]
	v_mfma_f32_16x16x32_bf16 v[98:101], v[200:203], v[154:157], v[98:101]
	v_mfma_f32_16x16x32_bf16 v[80:83], v[192:195], v[172:175], v[80:83]
	v_mfma_f32_16x16x32_bf16 v[72:75], v[200:203], v[172:175], v[72:75]
	v_mfma_f32_16x16x32_bf16 v[68:71], v[192:195], v[180:183], v[68:71]
	v_mfma_f32_16x16x32_bf16 v[64:67], v[200:203], v[180:183], v[64:67]
	v_mfma_f32_16x16x32_bf16 v[110:113], v[196:199], v[150:153], v[110:113]
	v_mfma_f32_16x16x32_bf16 v[106:109], v[204:207], v[150:153], v[106:109]
	v_mfma_f32_16x16x32_bf16 v[102:105], v[196:199], v[158:161], v[102:105]
	v_mfma_f32_16x16x32_bf16 v[98:101], v[204:207], v[158:161], v[98:101]
	v_mfma_f32_16x16x32_bf16 v[80:83], v[196:199], v[176:179], v[80:83]
	v_mfma_f32_16x16x32_bf16 v[72:75], v[204:207], v[176:179], v[72:75]
	v_mfma_f32_16x16x32_bf16 v[68:71], v[196:199], v[188:191], v[68:71]
	v_mfma_f32_16x16x32_bf16 v[64:67], v[204:207], v[188:191], v[64:67]
	s_mov_b32 m0, s41
	v_lshl_add_u64 v[208:209], v[212:213], 0, s[72:73]
	s_barrier
	ds_read_b128 v[146:149], v187 offset:49152
	ds_read_b128 v[150:153], v187 offset:50176
	ds_read_b128 v[154:157], v187 offset:51200
	ds_read_b128 v[158:161], v187 offset:52224
	ds_read_b128 v[172:175], v187 offset:53248
	ds_read_b128 v[176:179], v187 offset:54272
	ds_read_b128 v[180:183], v187 offset:55296
	ds_read_b128 v[188:191], v187 offset:56320
	global_load_lds_dwordx4 v[208:209], off
	v_lshl_add_u64 v[208:209], v[214:215], 0, s[72:73]
	s_mov_b32 m0, s42
	s_nop 0
	global_load_lds_dwordx4 v[208:209], off
	s_barrier
	s_waitcnt lgkmcnt(0)
	s_waitcnt lgkmcnt(0)
	v_mfma_f32_16x16x32_bf16 v[60:63], v[130:133], v[146:149], v[60:63]
	v_mfma_f32_16x16x32_bf16 v[56:59], v[138:141], v[146:149], v[56:59]
	v_mfma_f32_16x16x32_bf16 v[44:47], v[130:133], v[154:157], v[44:47]
	v_mfma_f32_16x16x32_bf16 v[40:43], v[138:141], v[154:157], v[40:43]
	v_mfma_f32_16x16x32_bf16 v[28:31], v[130:133], v[172:175], v[28:31]
	v_mfma_f32_16x16x32_bf16 v[24:27], v[138:141], v[172:175], v[24:27]
	v_mfma_f32_16x16x32_bf16 v[20:23], v[130:133], v[180:183], v[20:23]
	v_mfma_f32_16x16x32_bf16 v[8:11], v[138:141], v[180:183], v[8:11]
	v_mfma_f32_16x16x32_bf16 v[60:63], v[134:137], v[150:153], v[60:63]
	v_mfma_f32_16x16x32_bf16 v[56:59], v[142:145], v[150:153], v[56:59]
	v_mfma_f32_16x16x32_bf16 v[44:47], v[134:137], v[158:161], v[44:47]
	v_mfma_f32_16x16x32_bf16 v[40:43], v[142:145], v[158:161], v[40:43]
	v_mfma_f32_16x16x32_bf16 v[28:31], v[134:137], v[176:179], v[28:31]
	v_mfma_f32_16x16x32_bf16 v[24:27], v[142:145], v[176:179], v[24:27]
	v_mfma_f32_16x16x32_bf16 v[20:23], v[134:137], v[188:191], v[20:23]
	v_mfma_f32_16x16x32_bf16 v[8:11], v[142:145], v[188:191], v[8:11]
	s_barrier
	s_add_u32 s22, s22, 0x80080
	s_addc_u32 s23, s23, 0
	s_add_i32 s0, s24, s31
	v_lshl_add_u64 v[130:131], s[22:23], 0, v[96:97]
	s_mov_b32 m0, s0
	s_nop 0
	global_load_lds_dwordx4 v[130:131], off
	v_lshl_add_u64 v[130:131], s[22:23], 0, v[166:167]
	s_add_i32 m0, s0, 0x2000
	s_nop 0
	global_load_lds_dwordx4 v[130:131], off
	s_waitcnt vmcnt(6)
	s_barrier
	v_mfma_f32_16x16x32_bf16 v[52:55], v[192:195], v[146:149], v[52:55]
	v_mfma_f32_16x16x32_bf16 v[48:51], v[200:203], v[146:149], v[48:51]
	v_mfma_f32_16x16x32_bf16 v[36:39], v[192:195], v[154:157], v[36:39]
	v_mfma_f32_16x16x32_bf16 v[32:35], v[200:203], v[154:157], v[32:35]
	v_mfma_f32_16x16x32_bf16 v[16:19], v[192:195], v[172:175], v[16:19]
	v_mfma_f32_16x16x32_bf16 v[12:15], v[200:203], v[172:175], v[12:15]
	v_mfma_f32_16x16x32_bf16 v[4:7], v[192:195], v[180:183], v[4:7]
	v_mfma_f32_16x16x32_bf16 v[0:3], v[200:203], v[180:183], v[0:3]
	v_mfma_f32_16x16x32_bf16 v[52:55], v[196:199], v[150:153], v[52:55]
	v_mfma_f32_16x16x32_bf16 v[48:51], v[204:207], v[150:153], v[48:51]
	v_mfma_f32_16x16x32_bf16 v[36:39], v[196:199], v[158:161], v[36:39]
	v_mfma_f32_16x16x32_bf16 v[32:35], v[204:207], v[158:161], v[32:35]
	v_mfma_f32_16x16x32_bf16 v[16:19], v[196:199], v[176:179], v[16:19]
	v_mfma_f32_16x16x32_bf16 v[12:15], v[204:207], v[176:179], v[12:15]
	v_mfma_f32_16x16x32_bf16 v[4:7], v[196:199], v[188:191], v[4:7]
	v_mfma_f32_16x16x32_bf16 v[0:3], v[204:207], v[188:191], v[0:3]
	s_add_i32 s49, s49, 2
	s_add_u32 s20, s20, 0x100
	s_addc_u32 s21, s21, 0
	s_add_u32 s47, s47, 0x100
	s_addc_u32 s48, s48, 0
	s_cmp_gt_u32 s49, 29
	s_barrier
;   __device__ __forceinline__ void emit(const EpiPre& q0, int row, int col, f32x4 a, f32x4 b, const f32x4 (&hb)[2][2], const float (&hs)[2][4], int ai_, int m_, int bj_) const {
;     ...
;     } else if (MODE == E_RES) {
;       const f32x4 r0 = q.a0, r1 = q.a1;
;       float* o = (float*)e.out + (size_t)row * DM + col;
;       *(f32x4*)o = (f32x4){ALPHA * r0[0] + v[0], ALPHA * r0[1] + v[1], ALPHA * r0[2] + v[2], ALPHA * r0[3] + v[3]};
;       *(f32x4*)(o + 4) = (f32x4){ALPHA * r1[0] + v[4], ALPHA * r1[1] + v[5], ALPHA * r1[2] + v[6], ALPHA * r1[3] + v[7]};
; __device__ __forceinline__ void ln_phase(const float* in, float* outf, bf16_t* outb, const float* g, const float* b, int wv0) {
;     ...
;     for (int i = 0; i < 8; ++i) { v[i] -= mu; sq += v[i][0] * v[i][0] + v[i][1] * v[i][1] + v[i][2] * v[i][2] + v[i][3] * v[i][3]; }
;     sq = wave_sum(sq); const float rstd = __builtin_amdgcn_rsqf(sq * (1.0f / 2048.0f) + EPS);
; #pragma unroll
;     for (int i = 0; i < 8; ++i) {
;       const f32x4 y = v[i] * rstd * gg[i] + bb[i];
	s_cbranch_scc0 .LBB0_1100
	s_setprio 0
	s_cmp_eq_u32 s66, 0
	s_cbranch_scc1 .Lwo_plain
	s_load_dwordx4 s[48:51], s[54:55], 0xb8
	s_load_dwordx2 s[96:97], s[54:55], 0xc8
	v_lshl_add_u32 v243, s18, 8, v184
	v_lshl_or_b32 v247, s1, 8, v186
	v_lshlrev_b32_e32 v242, 13, v243
	v_lshlrev_b32_e32 v247, 2, v247
	v_lshlrev_b32_e32 v243, 3, v243
	v_add_u32_e32 v242, v242, v247
	s_waitcnt lgkmcnt(0)
	s_add_u32 s100, s96, 0x4000000
	s_addc_u32 s101, s97, 0
	s_add_u32 s20, s6, 0x0
	s_addc_u32 s21, s7, 0
	global_load_dwordx2 v[220:221], v243, s[100:101] offset:0
	global_load_dwordx4 v[130:133], v242, s[20:21]
	global_load_dwordx4 v[134:137], v242, s[20:21] offset:16
	global_load_dwordx4 v[138:141], v242, s[20:21] offset:512
	global_load_dwordx4 v[142:145], v242, s[20:21] offset:528
	s_add_u32 s22, s6, 0x20000
	s_addc_u32 s23, s7, 0
	global_load_dwordx2 v[238:239], v243, s[100:101] offset:128
	global_load_dwordx4 v[146:149], v242, s[22:23]
	global_load_dwordx4 v[150:153], v242, s[22:23] offset:16
	global_load_dwordx4 v[154:157], v242, s[22:23] offset:512
	global_load_dwordx4 v[158:161], v242, s[22:23] offset:528
	s_add_u32 s24, s6, 0x40000
	s_addc_u32 s25, s7, 0
	global_load_dwordx2 v[240:241], v243, s[100:101] offset:256
	global_load_dwordx4 v[172:175], v242, s[24:25]
	global_load_dwordx4 v[176:179], v242, s[24:25] offset:16
	global_load_dwordx4 v[180:183], v242, s[24:25] offset:512
	global_load_dwordx4 v[234:237], v242, s[24:25] offset:528
	global_load_dwordx4 v[188:191], v247, s[48:49]
	global_load_dwordx4 v[192:195], v247, s[48:49] offset:16
	global_load_dwordx4 v[196:199], v247, s[48:49] offset:512
	global_load_dwordx4 v[200:203], v247, s[48:49] offset:528
	global_load_dwordx4 v[204:207], v247, s[50:51]
	global_load_dwordx4 v[208:211], v247, s[50:51] offset:16
	global_load_dwordx4 v[212:215], v247, s[50:51] offset:512
	global_load_dwordx4 v[216:219], v247, s[50:51] offset:528
	s_waitcnt vmcnt(0)
	v_pk_add_f32 v[130:131], v[130:131], v[220:221] op_sel_hi:[1,0]
	v_pk_add_f32 v[132:133], v[132:133], v[220:221] op_sel_hi:[1,0]
	v_pk_add_f32 v[134:135], v[134:135], v[220:221] op_sel_hi:[1,0]
	v_pk_add_f32 v[136:137], v[136:137], v[220:221] op_sel_hi:[1,0]
	v_pk_add_f32 v[138:139], v[138:139], v[220:221] op_sel_hi:[1,0]
	v_pk_add_f32 v[140:141], v[140:141], v[220:221] op_sel_hi:[1,0]
	v_pk_add_f32 v[142:143], v[142:143], v[220:221] op_sel_hi:[1,0]
	v_pk_add_f32 v[144:145], v[144:145], v[220:221] op_sel_hi:[1,0]
	v_pk_mul_f32 v[130:131], v[130:131], v[220:221] op_sel:[0,1] op_sel_hi:[1,1]
	v_pk_mul_f32 v[132:133], v[132:133], v[220:221] op_sel:[0,1] op_sel_hi:[1,1]
	v_pk_mul_f32 v[134:135], v[134:135], v[220:221] op_sel:[0,1] op_sel_hi:[1,1]
	v_pk_mul_f32 v[136:137], v[136:137], v[220:221] op_sel:[0,1] op_sel_hi:[1,1]
	v_pk_mul_f32 v[138:139], v[138:139], v[220:221] op_sel:[0,1] op_sel_hi:[1,1]
	v_pk_mul_f32 v[140:141], v[140:141], v[220:221] op_sel:[0,1] op_sel_hi:[1,1]
	v_pk_mul_f32 v[142:143], v[142:143], v[220:221] op_sel:[0,1] op_sel_hi:[1,1]
	v_pk_mul_f32 v[144:145], v[144:145], v[220:221] op_sel:[0,1] op_sel_hi:[1,1]
	v_pk_fma_f32 v[130:131], v[188:189], v[130:131], v[204:205]
	v_pk_fma_f32 v[132:133], v[190:191], v[132:133], v[206:207]
	v_pk_fma_f32 v[134:135], v[192:193], v[134:135], v[208:209]
	v_pk_fma_f32 v[136:137], v[194:195], v[136:137], v[210:211]
	v_pk_fma_f32 v[138:139], v[196:197], v[138:139], v[212:213]
	v_pk_fma_f32 v[140:141], v[198:199], v[140:141], v[214:215]
	v_pk_fma_f32 v[142:143], v[200:201], v[142:143], v[216:217]
	v_pk_fma_f32 v[144:145], v[202:203], v[144:145], v[218:219]
	v_pk_fma_f32 v[126:127], v[130:131], s[90:91], v[126:127] op_sel_hi:[1,0,1]
	v_pk_fma_f32 v[128:129], v[132:133], s[90:91], v[128:129] op_sel_hi:[1,0,1]
	v_pk_fma_f32 v[122:123], v[134:135], s[90:91], v[122:123] op_sel_hi:[1,0,1]
	v_pk_fma_f32 v[124:125], v[136:137], s[90:91], v[124:125] op_sel_hi:[1,0,1]
	v_pk_fma_f32 v[110:111], v[138:139], s[90:91], v[110:111] op_sel_hi:[1,0,1]
	v_pk_fma_f32 v[112:113], v[140:141], s[90:91], v[112:113] op_sel_hi:[1,0,1]
	v_pk_fma_f32 v[106:107], v[142:143], s[90:91], v[106:107] op_sel_hi:[1,0,1]
	v_pk_fma_f32 v[108:109], v[144:145], s[90:91], v[108:109] op_sel_hi:[1,0,1]
	s_add_u32 s46, s6, 0x60000
	s_addc_u32 s47, s7, 0
	global_load_dwordx2 v[220:221], v243, s[100:101] offset:384
	global_load_dwordx4 v[130:133], v242, s[46:47]
	global_load_dwordx4 v[134:137], v242, s[46:47] offset:16
	global_load_dwordx4 v[138:141], v242, s[46:47] offset:512
	global_load_dwordx4 v[142:145], v242, s[46:47] offset:528
	s_waitcnt vmcnt(18)
;   __device__ __forceinline__ void emit(const EpiPre& q0, int row, int col, f32x4 a, f32x4 b, const f32x4 (&hb)[2][2], const float (&hs)[2][4], int ai_, int m_, int bj_) const {
;     ...
;     } else if (MODE == E_RES) {
;       const f32x4 r0 = q.a0, r1 = q.a1;
;       float* o = (float*)e.out + (size_t)row * DM + col;
;       *(f32x4*)o = (f32x4){ALPHA * r0[0] + v[0], ALPHA * r0[1] + v[1], ALPHA * r0[2] + v[2], ALPHA * r0[3] + v[3]};
;       *(f32x4*)(o + 4) = (f32x4){ALPHA * r1[0] + v[4], ALPHA * r1[1] + v[5], ALPHA * r1[2] + v[6], ALPHA * r1[3] + v[7]};
; __device__ __forceinline__ void ln_phase(const float* in, float* outf, bf16_t* outb, const float* g, const float* b, int wv0) {
;     ...
;     for (int i = 0; i < 8; ++i) { v[i] -= mu; sq += v[i][0] * v[i][0] + v[i][1] * v[i][1] + v[i][2] * v[i][2] + v[i][3] * v[i][3]; }
;     sq = wave_sum(sq); const float rstd = __builtin_amdgcn_rsqf(sq * (1.0f / 2048.0f) + EPS);
; #pragma unroll
;     for (int i = 0; i < 8; ++i) {
;       const f32x4 y = v[i] * rstd * gg[i] + bb[i];
	v_pk_add_f32 v[146:147], v[146:147], v[238:239] op_sel_hi:[1,0]
	v_pk_add_f32 v[148:149], v[148:149], v[238:239] op_sel_hi:[1,0]
	v_pk_add_f32 v[150:151], v[150:151], v[238:239] op_sel_hi:[1,0]
	v_pk_add_f32 v[152:153], v[152:153], v[238:239] op_sel_hi:[1,0]
	v_pk_add_f32 v[154:155], v[154:155], v[238:239] op_sel_hi:[1,0]
	v_pk_add_f32 v[156:157], v[156:157], v[238:239] op_sel_hi:[1,0]
	v_pk_add_f32 v[158:159], v[158:159], v[238:239] op_sel_hi:[1,0]
	v_pk_add_f32 v[160:161], v[160:161], v[238:239] op_sel_hi:[1,0]
	v_pk_mul_f32 v[146:147], v[146:147], v[238:239] op_sel:[0,1] op_sel_hi:[1,1]
	v_pk_mul_f32 v[148:149], v[148:149], v[238:239] op_sel:[0,1] op_sel_hi:[1,1]
	v_pk_mul_f32 v[150:151], v[150:151], v[238:239] op_sel:[0,1] op_sel_hi:[1,1]
	v_pk_mul_f32 v[152:153], v[152:153], v[238:239] op_sel:[0,1] op_sel_hi:[1,1]
	v_pk_mul_f32 v[154:155], v[154:155], v[238:239] op_sel:[0,1] op_sel_hi:[1,1]
	v_pk_mul_f32 v[156:157], v[156:157], v[238:239] op_sel:[0,1] op_sel_hi:[1,1]
	v_pk_mul_f32 v[158:159], v[158:159], v[238:239] op_sel:[0,1] op_sel_hi:[1,1]
	v_pk_mul_f32 v[160:161], v[160:161], v[238:239] op_sel:[0,1] op_sel_hi:[1,1]
	v_pk_fma_f32 v[146:147], v[188:189], v[146:147], v[204:205]
	v_pk_fma_f32 v[148:149], v[190:191], v[148:149], v[206:207]
	v_pk_fma_f32 v[150:151], v[192:193], v[150:151], v[208:209]
	v_pk_fma_f32 v[152:153], v[194:195], v[152:153], v[210:211]
	v_pk_fma_f32 v[154:155], v[196:197], v[154:155], v[212:213]
	v_pk_fma_f32 v[156:157], v[198:199], v[156:157], v[214:215]
	v_pk_fma_f32 v[158:159], v[200:201], v[158:159], v[216:217]
	v_pk_fma_f32 v[160:161], v[202:203], v[160:161], v[218:219]
	v_pk_fma_f32 v[118:119], v[146:147], s[90:91], v[118:119] op_sel_hi:[1,0,1]
	v_pk_fma_f32 v[120:121], v[148:149], s[90:91], v[120:121] op_sel_hi:[1,0,1]
	v_pk_fma_f32 v[114:115], v[150:151], s[90:91], v[114:115] op_sel_hi:[1,0,1]
	v_pk_fma_f32 v[116:117], v[152:153], s[90:91], v[116:117] op_sel_hi:[1,0,1]
	v_pk_fma_f32 v[102:103], v[154:155], s[90:91], v[102:103] op_sel_hi:[1,0,1]
	v_pk_fma_f32 v[104:105], v[156:157], s[90:91], v[104:105] op_sel_hi:[1,0,1]
	v_pk_fma_f32 v[98:99], v[158:159], s[90:91], v[98:99] op_sel_hi:[1,0,1]
	v_pk_fma_f32 v[100:101], v[160:161], s[90:91], v[100:101] op_sel_hi:[1,0,1]
	s_add_u32 s48, s6, 0x100000
	s_addc_u32 s49, s7, 0
	global_load_dwordx2 v[238:239], v243, s[100:101] offset:1024
	global_load_dwordx4 v[146:149], v242, s[48:49]
	global_load_dwordx4 v[150:153], v242, s[48:49] offset:16
	global_load_dwordx4 v[154:157], v242, s[48:49] offset:512
	global_load_dwordx4 v[158:161], v242, s[48:49] offset:528
	s_waitcnt vmcnt(18)
	v_pk_add_f32 v[172:173], v[172:173], v[240:241] op_sel_hi:[1,0]
	v_pk_add_f32 v[174:175], v[174:175], v[240:241] op_sel_hi:[1,0]
	v_pk_add_f32 v[176:177], v[176:177], v[240:241] op_sel_hi:[1,0]
	v_pk_add_f32 v[178:179], v[178:179], v[240:241] op_sel_hi:[1,0]
	v_pk_add_f32 v[180:181], v[180:181], v[240:241] op_sel_hi:[1,0]
	v_pk_add_f32 v[182:183], v[182:183], v[240:241] op_sel_hi:[1,0]
	v_pk_add_f32 v[234:235], v[234:235], v[240:241] op_sel_hi:[1,0]
	v_pk_add_f32 v[236:237], v[236:237], v[240:241] op_sel_hi:[1,0]
	v_pk_mul_f32 v[172:173], v[172:173], v[240:241] op_sel:[0,1] op_sel_hi:[1,1]
	v_pk_mul_f32 v[174:175], v[174:175], v[240:241] op_sel:[0,1] op_sel_hi:[1,1]
	v_pk_mul_f32 v[176:177], v[176:177], v[240:241] op_sel:[0,1] op_sel_hi:[1,1]
	v_pk_mul_f32 v[178:179], v[178:179], v[240:241] op_sel:[0,1] op_sel_hi:[1,1]
	v_pk_mul_f32 v[180:181], v[180:181], v[240:241] op_sel:[0,1] op_sel_hi:[1,1]
	v_pk_mul_f32 v[182:183], v[182:183], v[240:241] op_sel:[0,1] op_sel_hi:[1,1]
	v_pk_mul_f32 v[234:235], v[234:235], v[240:241] op_sel:[0,1] op_sel_hi:[1,1]
	v_pk_mul_f32 v[236:237], v[236:237], v[240:241] op_sel:[0,1] op_sel_hi:[1,1]
	v_pk_fma_f32 v[172:173], v[188:189], v[172:173], v[204:205]
	v_pk_fma_f32 v[174:175], v[190:191], v[174:175], v[206:207]
	v_pk_fma_f32 v[176:177], v[192:193], v[176:177], v[208:209]
	v_pk_fma_f32 v[178:179], v[194:195], v[178:179], v[210:211]
	v_pk_fma_f32 v[180:181], v[196:197], v[180:181], v[212:213]
	v_pk_fma_f32 v[182:183], v[198:199], v[182:183], v[214:215]
	v_pk_fma_f32 v[234:235], v[200:201], v[234:235], v[216:217]
	v_pk_fma_f32 v[236:237], v[202:203], v[236:237], v[218:219]
	v_pk_fma_f32 v[92:93], v[172:173], s[90:91], v[92:93] op_sel_hi:[1,0,1]
	v_pk_fma_f32 v[94:95], v[174:175], s[90:91], v[94:95] op_sel_hi:[1,0,1]
	v_pk_fma_f32 v[88:89], v[176:177], s[90:91], v[88:89] op_sel_hi:[1,0,1]
	v_pk_fma_f32 v[90:91], v[178:179], s[90:91], v[90:91] op_sel_hi:[1,0,1]
	v_pk_fma_f32 v[80:81], v[180:181], s[90:91], v[80:81] op_sel_hi:[1,0,1]
	v_pk_fma_f32 v[82:83], v[182:183], s[90:91], v[82:83] op_sel_hi:[1,0,1]
	v_pk_fma_f32 v[72:73], v[234:235], s[90:91], v[72:73] op_sel_hi:[1,0,1]
	v_pk_fma_f32 v[74:75], v[236:237], s[90:91], v[74:75] op_sel_hi:[1,0,1]
	s_add_u32 s50, s6, 0x120000
	s_addc_u32 s51, s7, 0
	global_load_dwordx2 v[240:241], v243, s[100:101] offset:1152
	global_load_dwordx4 v[172:175], v242, s[50:51]
	global_load_dwordx4 v[176:179], v242, s[50:51] offset:16
	global_load_dwordx4 v[180:183], v242, s[50:51] offset:512
	global_load_dwordx4 v[234:237], v242, s[50:51] offset:528
	global_store_dwordx4 v242, v[126:129], s[20:21]
	global_store_dwordx4 v242, v[122:125], s[20:21] offset:16
	global_store_dwordx4 v242, v[110:113], s[20:21] offset:512
	global_store_dwordx4 v242, v[106:109], s[20:21] offset:528
	global_store_dwordx4 v242, v[118:121], s[22:23]
	global_store_dwordx4 v242, v[114:117], s[22:23] offset:16
	global_store_dwordx4 v242, v[102:105], s[22:23] offset:512
	global_store_dwordx4 v242, v[98:101], s[22:23] offset:528
	global_store_dwordx4 v242, v[92:95], s[24:25]
	global_store_dwordx4 v242, v[88:91], s[24:25] offset:16
	global_store_dwordx4 v242, v[80:83], s[24:25] offset:512
	global_store_dwordx4 v242, v[72:75], s[24:25] offset:528
	s_add_u32 s20, s6, 0x140000
	s_addc_u32 s21, s7, 0
	global_load_dwordx2 v[92:93], v243, s[100:101] offset:1280
	global_load_dwordx4 v[126:129], v242, s[20:21]
	global_load_dwordx4 v[122:125], v242, s[20:21] offset:16
	global_load_dwordx4 v[110:113], v242, s[20:21] offset:512
	global_load_dwordx4 v[106:109], v242, s[20:21] offset:528
	s_add_u32 s22, s6, 0x160000
	s_addc_u32 s23, s7, 0
	global_load_dwordx2 v[88:89], v243, s[100:101] offset:1408
	global_load_dwordx4 v[118:121], v242, s[22:23]
	global_load_dwordx4 v[114:117], v242, s[22:23] offset:16
	global_load_dwordx4 v[102:105], v242, s[22:23] offset:512
	global_load_dwordx4 v[98:101], v242, s[22:23] offset:528
	s_waitcnt vmcnt(32)
;   __device__ __forceinline__ void emit(const EpiPre& q0, int row, int col, f32x4 a, f32x4 b, const f32x4 (&hb)[2][2], const float (&hs)[2][4], int ai_, int m_, int bj_) const {
;     ...
;     } else if (MODE == E_RES) {
;       const f32x4 r0 = q.a0, r1 = q.a1;
;       float* o = (float*)e.out + (size_t)row * DM + col;
;       *(f32x4*)o = (f32x4){ALPHA * r0[0] + v[0], ALPHA * r0[1] + v[1], ALPHA * r0[2] + v[2], ALPHA * r0[3] + v[3]};
;       *(f32x4*)(o + 4) = (f32x4){ALPHA * r1[0] + v[4], ALPHA * r1[1] + v[5], ALPHA * r1[2] + v[6], ALPHA * r1[3] + v[7]};
; __device__ __forceinline__ void ln_phase(const float* in, float* outf, bf16_t* outb, const float* g, const float* b, int wv0) {
;     ...
;     for (int i = 0; i < 8; ++i) { v[i] -= mu; sq += v[i][0] * v[i][0] + v[i][1] * v[i][1] + v[i][2] * v[i][2] + v[i][3] * v[i][3]; }
;     sq = wave_sum(sq); const float rstd = __builtin_amdgcn_rsqf(sq * (1.0f / 2048.0f) + EPS);
; #pragma unroll
;     for (int i = 0; i < 8; ++i) {
;       const f32x4 y = v[i] * rstd * gg[i] + bb[i];
	v_pk_add_f32 v[130:131], v[130:131], v[220:221] op_sel_hi:[1,0]
	v_pk_add_f32 v[132:133], v[132:133], v[220:221] op_sel_hi:[1,0]
	v_pk_add_f32 v[134:135], v[134:135], v[220:221] op_sel_hi:[1,0]
	v_pk_add_f32 v[136:137], v[136:137], v[220:221] op_sel_hi:[1,0]
	v_pk_add_f32 v[138:139], v[138:139], v[220:221] op_sel_hi:[1,0]
	v_pk_add_f32 v[140:141], v[140:141], v[220:221] op_sel_hi:[1,0]
	v_pk_add_f32 v[142:143], v[142:143], v[220:221] op_sel_hi:[1,0]
	v_pk_add_f32 v[144:145], v[144:145], v[220:221] op_sel_hi:[1,0]
	v_pk_mul_f32 v[130:131], v[130:131], v[220:221] op_sel:[0,1] op_sel_hi:[1,1]
	v_pk_mul_f32 v[132:133], v[132:133], v[220:221] op_sel:[0,1] op_sel_hi:[1,1]
	v_pk_mul_f32 v[134:135], v[134:135], v[220:221] op_sel:[0,1] op_sel_hi:[1,1]
	v_pk_mul_f32 v[136:137], v[136:137], v[220:221] op_sel:[0,1] op_sel_hi:[1,1]
	v_pk_mul_f32 v[138:139], v[138:139], v[220:221] op_sel:[0,1] op_sel_hi:[1,1]
	v_pk_mul_f32 v[140:141], v[140:141], v[220:221] op_sel:[0,1] op_sel_hi:[1,1]
	v_pk_mul_f32 v[142:143], v[142:143], v[220:221] op_sel:[0,1] op_sel_hi:[1,1]
	v_pk_mul_f32 v[144:145], v[144:145], v[220:221] op_sel:[0,1] op_sel_hi:[1,1]
	v_pk_fma_f32 v[130:131], v[188:189], v[130:131], v[204:205]
	v_pk_fma_f32 v[132:133], v[190:191], v[132:133], v[206:207]
	v_pk_fma_f32 v[134:135], v[192:193], v[134:135], v[208:209]
	v_pk_fma_f32 v[136:137], v[194:195], v[136:137], v[210:211]
	v_pk_fma_f32 v[138:139], v[196:197], v[138:139], v[212:213]
	v_pk_fma_f32 v[140:141], v[198:199], v[140:141], v[214:215]
	v_pk_fma_f32 v[142:143], v[200:201], v[142:143], v[216:217]
	v_pk_fma_f32 v[144:145], v[202:203], v[144:145], v[218:219]
	v_pk_fma_f32 v[84:85], v[130:131], s[90:91], v[84:85] op_sel_hi:[1,0,1]
	v_pk_fma_f32 v[86:87], v[132:133], s[90:91], v[86:87] op_sel_hi:[1,0,1]
	v_pk_fma_f32 v[76:77], v[134:135], s[90:91], v[76:77] op_sel_hi:[1,0,1]
	v_pk_fma_f32 v[78:79], v[136:137], s[90:91], v[78:79] op_sel_hi:[1,0,1]
	v_pk_fma_f32 v[68:69], v[138:139], s[90:91], v[68:69] op_sel_hi:[1,0,1]
	v_pk_fma_f32 v[70:71], v[140:141], s[90:91], v[70:71] op_sel_hi:[1,0,1]
	v_pk_fma_f32 v[64:65], v[142:143], s[90:91], v[64:65] op_sel_hi:[1,0,1]
	v_pk_fma_f32 v[66:67], v[144:145], s[90:91], v[66:67] op_sel_hi:[1,0,1]
	global_store_dwordx4 v242, v[84:87], s[46:47]
	global_store_dwordx4 v242, v[76:79], s[46:47] offset:16
	global_store_dwordx4 v242, v[68:71], s[46:47] offset:512
	global_store_dwordx4 v242, v[64:67], s[46:47] offset:528
	s_waitcnt vmcnt(31)
	v_pk_add_f32 v[146:147], v[146:147], v[238:239] op_sel_hi:[1,0]
	v_pk_add_f32 v[148:149], v[148:149], v[238:239] op_sel_hi:[1,0]
	v_pk_add_f32 v[150:151], v[150:151], v[238:239] op_sel_hi:[1,0]
	v_pk_add_f32 v[152:153], v[152:153], v[238:239] op_sel_hi:[1,0]
	v_pk_add_f32 v[154:155], v[154:155], v[238:239] op_sel_hi:[1,0]
	v_pk_add_f32 v[156:157], v[156:157], v[238:239] op_sel_hi:[1,0]
	v_pk_add_f32 v[158:159], v[158:159], v[238:239] op_sel_hi:[1,0]
	v_pk_add_f32 v[160:161], v[160:161], v[238:239] op_sel_hi:[1,0]
	v_pk_mul_f32 v[146:147], v[146:147], v[238:239] op_sel:[0,1] op_sel_hi:[1,1]
	v_pk_mul_f32 v[148:149], v[148:149], v[238:239] op_sel:[0,1] op_sel_hi:[1,1]
	v_pk_mul_f32 v[150:151], v[150:151], v[238:239] op_sel:[0,1] op_sel_hi:[1,1]
	v_pk_mul_f32 v[152:153], v[152:153], v[238:239] op_sel:[0,1] op_sel_hi:[1,1]
	v_pk_mul_f32 v[154:155], v[154:155], v[238:239] op_sel:[0,1] op_sel_hi:[1,1]
	v_pk_mul_f32 v[156:157], v[156:157], v[238:239] op_sel:[0,1] op_sel_hi:[1,1]
	v_pk_mul_f32 v[158:159], v[158:159], v[238:239] op_sel:[0,1] op_sel_hi:[1,1]
	v_pk_mul_f32 v[160:161], v[160:161], v[238:239] op_sel:[0,1] op_sel_hi:[1,1]
	v_pk_fma_f32 v[146:147], v[188:189], v[146:147], v[204:205]
	v_pk_fma_f32 v[148:149], v[190:191], v[148:149], v[206:207]
	v_pk_fma_f32 v[150:151], v[192:193], v[150:151], v[208:209]
	v_pk_fma_f32 v[152:153], v[194:195], v[152:153], v[210:211]
	v_pk_fma_f32 v[154:155], v[196:197], v[154:155], v[212:213]
	v_pk_fma_f32 v[156:157], v[198:199], v[156:157], v[214:215]
	v_pk_fma_f32 v[158:159], v[200:201], v[158:159], v[216:217]
	v_pk_fma_f32 v[160:161], v[202:203], v[160:161], v[218:219]
	v_pk_fma_f32 v[60:61], v[146:147], s[90:91], v[60:61] op_sel_hi:[1,0,1]
	v_pk_fma_f32 v[62:63], v[148:149], s[90:91], v[62:63] op_sel_hi:[1,0,1]
	v_pk_fma_f32 v[56:57], v[150:151], s[90:91], v[56:57] op_sel_hi:[1,0,1]
	v_pk_fma_f32 v[58:59], v[152:153], s[90:91], v[58:59] op_sel_hi:[1,0,1]
	v_pk_fma_f32 v[52:53], v[154:155], s[90:91], v[52:53] op_sel_hi:[1,0,1]
	v_pk_fma_f32 v[54:55], v[156:157], s[90:91], v[54:55] op_sel_hi:[1,0,1]
	v_pk_fma_f32 v[48:49], v[158:159], s[90:91], v[48:49] op_sel_hi:[1,0,1]
	v_pk_fma_f32 v[50:51], v[160:161], s[90:91], v[50:51] op_sel_hi:[1,0,1]
	global_store_dwordx4 v242, v[60:63], s[48:49]
	global_store_dwordx4 v242, v[56:59], s[48:49] offset:16
	global_store_dwordx4 v242, v[52:55], s[48:49] offset:512
	global_store_dwordx4 v242, v[48:51], s[48:49] offset:528
	s_waitcnt vmcnt(30)
;   __device__ __forceinline__ void emit(const EpiPre& q0, int row, int col, f32x4 a, f32x4 b, const f32x4 (&hb)[2][2], const float (&hs)[2][4], int ai_, int m_, int bj_) const {
;     ...
;     } else if (MODE == E_RES) {
;       const f32x4 r0 = q.a0, r1 = q.a1;
;       float* o = (float*)e.out + (size_t)row * DM + col;
;       *(f32x4*)o = (f32x4){ALPHA * r0[0] + v[0], ALPHA * r0[1] + v[1], ALPHA * r0[2] + v[2], ALPHA * r0[3] + v[3]};
;       *(f32x4*)(o + 4) = (f32x4){ALPHA * r1[0] + v[4], ALPHA * r1[1] + v[5], ALPHA * r1[2] + v[6], ALPHA * r1[3] + v[7]};
; __device__ __forceinline__ void ln_phase(const float* in, float* outf, bf16_t* outb, const float* g, const float* b, int wv0) {
;     ...
;     for (int i = 0; i < 8; ++i) { v[i] -= mu; sq += v[i][0] * v[i][0] + v[i][1] * v[i][1] + v[i][2] * v[i][2] + v[i][3] * v[i][3]; }
;     sq = wave_sum(sq); const float rstd = __builtin_amdgcn_rsqf(sq * (1.0f / 2048.0f) + EPS);
; #pragma unroll
;     for (int i = 0; i < 8; ++i) {
;       const f32x4 y = v[i] * rstd * gg[i] + bb[i];
	v_pk_add_f32 v[172:173], v[172:173], v[240:241] op_sel_hi:[1,0]
	v_pk_add_f32 v[174:175], v[174:175], v[240:241] op_sel_hi:[1,0]
	v_pk_add_f32 v[176:177], v[176:177], v[240:241] op_sel_hi:[1,0]
	v_pk_add_f32 v[178:179], v[178:179], v[240:241] op_sel_hi:[1,0]
	v_pk_add_f32 v[180:181], v[180:181], v[240:241] op_sel_hi:[1,0]
	v_pk_add_f32 v[182:183], v[182:183], v[240:241] op_sel_hi:[1,0]
	v_pk_add_f32 v[234:235], v[234:235], v[240:241] op_sel_hi:[1,0]
	v_pk_add_f32 v[236:237], v[236:237], v[240:241] op_sel_hi:[1,0]
	v_pk_mul_f32 v[172:173], v[172:173], v[240:241] op_sel:[0,1] op_sel_hi:[1,1]
	v_pk_mul_f32 v[174:175], v[174:175], v[240:241] op_sel:[0,1] op_sel_hi:[1,1]
	v_pk_mul_f32 v[176:177], v[176:177], v[240:241] op_sel:[0,1] op_sel_hi:[1,1]
	v_pk_mul_f32 v[178:179], v[178:179], v[240:241] op_sel:[0,1] op_sel_hi:[1,1]
	v_pk_mul_f32 v[180:181], v[180:181], v[240:241] op_sel:[0,1] op_sel_hi:[1,1]
	v_pk_mul_f32 v[182:183], v[182:183], v[240:241] op_sel:[0,1] op_sel_hi:[1,1]
	v_pk_mul_f32 v[234:235], v[234:235], v[240:241] op_sel:[0,1] op_sel_hi:[1,1]
	v_pk_mul_f32 v[236:237], v[236:237], v[240:241] op_sel:[0,1] op_sel_hi:[1,1]
	v_pk_fma_f32 v[172:173], v[188:189], v[172:173], v[204:205]
	v_pk_fma_f32 v[174:175], v[190:191], v[174:175], v[206:207]
	v_pk_fma_f32 v[176:177], v[192:193], v[176:177], v[208:209]
	v_pk_fma_f32 v[178:179], v[194:195], v[178:179], v[210:211]
	v_pk_fma_f32 v[180:181], v[196:197], v[180:181], v[212:213]
	v_pk_fma_f32 v[182:183], v[198:199], v[182:183], v[214:215]
	v_pk_fma_f32 v[234:235], v[200:201], v[234:235], v[216:217]
	v_pk_fma_f32 v[236:237], v[202:203], v[236:237], v[218:219]
	v_pk_fma_f32 v[44:45], v[172:173], s[90:91], v[44:45] op_sel_hi:[1,0,1]
	v_pk_fma_f32 v[46:47], v[174:175], s[90:91], v[46:47] op_sel_hi:[1,0,1]
	v_pk_fma_f32 v[40:41], v[176:177], s[90:91], v[40:41] op_sel_hi:[1,0,1]
	v_pk_fma_f32 v[42:43], v[178:179], s[90:91], v[42:43] op_sel_hi:[1,0,1]
	v_pk_fma_f32 v[36:37], v[180:181], s[90:91], v[36:37] op_sel_hi:[1,0,1]
	v_pk_fma_f32 v[38:39], v[182:183], s[90:91], v[38:39] op_sel_hi:[1,0,1]
	v_pk_fma_f32 v[32:33], v[234:235], s[90:91], v[32:33] op_sel_hi:[1,0,1]
	v_pk_fma_f32 v[34:35], v[236:237], s[90:91], v[34:35] op_sel_hi:[1,0,1]
	global_store_dwordx4 v242, v[44:47], s[50:51]
	global_store_dwordx4 v242, v[40:43], s[50:51] offset:16
	global_store_dwordx4 v242, v[36:39], s[50:51] offset:512
	global_store_dwordx4 v242, v[32:35], s[50:51] offset:528
	s_waitcnt vmcnt(17)
	v_pk_add_f32 v[126:127], v[126:127], v[92:93] op_sel_hi:[1,0]
	v_pk_add_f32 v[128:129], v[128:129], v[92:93] op_sel_hi:[1,0]
	v_pk_add_f32 v[122:123], v[122:123], v[92:93] op_sel_hi:[1,0]
	v_pk_add_f32 v[124:125], v[124:125], v[92:93] op_sel_hi:[1,0]
	v_pk_add_f32 v[110:111], v[110:111], v[92:93] op_sel_hi:[1,0]
	v_pk_add_f32 v[112:113], v[112:113], v[92:93] op_sel_hi:[1,0]
	v_pk_add_f32 v[106:107], v[106:107], v[92:93] op_sel_hi:[1,0]
	v_pk_add_f32 v[108:109], v[108:109], v[92:93] op_sel_hi:[1,0]
	v_pk_mul_f32 v[126:127], v[126:127], v[92:93] op_sel:[0,1] op_sel_hi:[1,1]
	v_pk_mul_f32 v[128:129], v[128:129], v[92:93] op_sel:[0,1] op_sel_hi:[1,1]
	v_pk_mul_f32 v[122:123], v[122:123], v[92:93] op_sel:[0,1] op_sel_hi:[1,1]
	v_pk_mul_f32 v[124:125], v[124:125], v[92:93] op_sel:[0,1] op_sel_hi:[1,1]
	v_pk_mul_f32 v[110:111], v[110:111], v[92:93] op_sel:[0,1] op_sel_hi:[1,1]
	v_pk_mul_f32 v[112:113], v[112:113], v[92:93] op_sel:[0,1] op_sel_hi:[1,1]
	v_pk_mul_f32 v[106:107], v[106:107], v[92:93] op_sel:[0,1] op_sel_hi:[1,1]
	v_pk_mul_f32 v[108:109], v[108:109], v[92:93] op_sel:[0,1] op_sel_hi:[1,1]
	v_pk_fma_f32 v[126:127], v[188:189], v[126:127], v[204:205]
	v_pk_fma_f32 v[128:129], v[190:191], v[128:129], v[206:207]
	v_pk_fma_f32 v[122:123], v[192:193], v[122:123], v[208:209]
	v_pk_fma_f32 v[124:125], v[194:195], v[124:125], v[210:211]
	v_pk_fma_f32 v[110:111], v[196:197], v[110:111], v[212:213]
	v_pk_fma_f32 v[112:113], v[198:199], v[112:113], v[214:215]
	v_pk_fma_f32 v[106:107], v[200:201], v[106:107], v[216:217]
	v_pk_fma_f32 v[108:109], v[202:203], v[108:109], v[218:219]
	v_pk_fma_f32 v[28:29], v[126:127], s[90:91], v[28:29] op_sel_hi:[1,0,1]
	v_pk_fma_f32 v[30:31], v[128:129], s[90:91], v[30:31] op_sel_hi:[1,0,1]
	v_pk_fma_f32 v[24:25], v[122:123], s[90:91], v[24:25] op_sel_hi:[1,0,1]
	v_pk_fma_f32 v[26:27], v[124:125], s[90:91], v[26:27] op_sel_hi:[1,0,1]
	v_pk_fma_f32 v[16:17], v[110:111], s[90:91], v[16:17] op_sel_hi:[1,0,1]
	v_pk_fma_f32 v[18:19], v[112:113], s[90:91], v[18:19] op_sel_hi:[1,0,1]
	v_pk_fma_f32 v[12:13], v[106:107], s[90:91], v[12:13] op_sel_hi:[1,0,1]
	v_pk_fma_f32 v[14:15], v[108:109], s[90:91], v[14:15] op_sel_hi:[1,0,1]
	global_store_dwordx4 v242, v[28:31], s[20:21]
	global_store_dwordx4 v242, v[24:27], s[20:21] offset:16
	global_store_dwordx4 v242, v[16:19], s[20:21] offset:512
	global_store_dwordx4 v242, v[12:15], s[20:21] offset:528
	s_waitcnt vmcnt(16)
;   __device__ __forceinline__ void emit(const EpiPre& q0, int row, int col, f32x4 a, f32x4 b, const f32x4 (&hb)[2][2], const float (&hs)[2][4], int ai_, int m_, int bj_) const {
;     ...
;     } else if (MODE == E_RES) {
;       const f32x4 r0 = q.a0, r1 = q.a1;
;       float* o = (float*)e.out + (size_t)row * DM + col;
;       *(f32x4*)o = (f32x4){ALPHA * r0[0] + v[0], ALPHA * r0[1] + v[1], ALPHA * r0[2] + v[2], ALPHA * r0[3] + v[3]};
;       *(f32x4*)(o + 4) = (f32x4){ALPHA * r1[0] + v[4], ALPHA * r1[1] + v[5], ALPHA * r1[2] + v[6], ALPHA * r1[3] + v[7]};
	v_pk_add_f32 v[118:119], v[118:119], v[88:89] op_sel_hi:[1,0]
	v_pk_add_f32 v[120:121], v[120:121], v[88:89] op_sel_hi:[1,0]
	v_pk_add_f32 v[114:115], v[114:115], v[88:89] op_sel_hi:[1,0]
	v_pk_add_f32 v[116:117], v[116:117], v[88:89] op_sel_hi:[1,0]
	v_pk_add_f32 v[102:103], v[102:103], v[88:89] op_sel_hi:[1,0]
	v_pk_add_f32 v[104:105], v[104:105], v[88:89] op_sel_hi:[1,0]
	v_pk_add_f32 v[98:99], v[98:99], v[88:89] op_sel_hi:[1,0]
	v_pk_add_f32 v[100:101], v[100:101], v[88:89] op_sel_hi:[1,0]
	v_pk_mul_f32 v[118:119], v[118:119], v[88:89] op_sel:[0,1] op_sel_hi:[1,1]
	v_pk_mul_f32 v[120:121], v[120:121], v[88:89] op_sel:[0,1] op_sel_hi:[1,1]
	v_pk_mul_f32 v[114:115], v[114:115], v[88:89] op_sel:[0,1] op_sel_hi:[1,1]
	v_pk_mul_f32 v[116:117], v[116:117], v[88:89] op_sel:[0,1] op_sel_hi:[1,1]
	v_pk_mul_f32 v[102:103], v[102:103], v[88:89] op_sel:[0,1] op_sel_hi:[1,1]
	v_pk_mul_f32 v[104:105], v[104:105], v[88:89] op_sel:[0,1] op_sel_hi:[1,1]
	v_pk_mul_f32 v[98:99], v[98:99], v[88:89] op_sel:[0,1] op_sel_hi:[1,1]
	v_pk_mul_f32 v[100:101], v[100:101], v[88:89] op_sel:[0,1] op_sel_hi:[1,1]
	v_pk_fma_f32 v[118:119], v[188:189], v[118:119], v[204:205]
	v_pk_fma_f32 v[120:121], v[190:191], v[120:121], v[206:207]
	v_pk_fma_f32 v[114:115], v[192:193], v[114:115], v[208:209]
	v_pk_fma_f32 v[116:117], v[194:195], v[116:117], v[210:211]
	v_pk_fma_f32 v[102:103], v[196:197], v[102:103], v[212:213]
	v_pk_fma_f32 v[104:105], v[198:199], v[104:105], v[214:215]
	v_pk_fma_f32 v[98:99], v[200:201], v[98:99], v[216:217]
	v_pk_fma_f32 v[100:101], v[202:203], v[100:101], v[218:219]
	v_pk_fma_f32 v[20:21], v[118:119], s[90:91], v[20:21] op_sel_hi:[1,0,1]
	v_pk_fma_f32 v[22:23], v[120:121], s[90:91], v[22:23] op_sel_hi:[1,0,1]
	v_pk_fma_f32 v[8:9], v[114:115], s[90:91], v[8:9] op_sel_hi:[1,0,1]
	v_pk_fma_f32 v[10:11], v[116:117], s[90:91], v[10:11] op_sel_hi:[1,0,1]
	v_pk_fma_f32 v[4:5], v[102:103], s[90:91], v[4:5] op_sel_hi:[1,0,1]
	v_pk_fma_f32 v[6:7], v[104:105], s[90:91], v[6:7] op_sel_hi:[1,0,1]
	v_pk_fma_f32 v[0:1], v[98:99], s[90:91], v[0:1] op_sel_hi:[1,0,1]
	v_pk_fma_f32 v[2:3], v[100:101], s[90:91], v[2:3] op_sel_hi:[1,0,1]
	global_store_dwordx4 v242, v[20:23], s[22:23]
	global_store_dwordx4 v242, v[8:11], s[22:23] offset:16
	global_store_dwordx4 v242, v[4:7], s[22:23] offset:512
	global_store_dwordx4 v242, v[0:3], s[22:23] offset:528
	s_mov_b32 s18, s12
	s_mov_b64 s[22:23], s[16:17]
	s_mov_b64 s[20:21], s[14:15]
	s_and_b64 vcc, exec, s[2:3]
	s_mov_b32 s1, s10
	s_branch .Lwo_join

; #define PG8_STAGE(bufoff, gbase, voff) do { _Pragma("unroll") for (int _i = 0; _i < 2; ++_i) \
;     __builtin_amdgcn_global_load_lds((const unsigned*)((const char*)(gbase) + (voff)[_i]), (LAS unsigned*)(lds + (bufoff) + ldsw + _i * 8192), 16, 0, 0); } while (0)
; #define PG8_LDA(dst, b, h) do { _Pragma("unroll") for (int m = 0; m < 4; ++m) _Pragma("unroll") for (int k = 0; k < 2; ++k) dst[m][k] = *(const LAS bf16x8*)(lds + PG8_SA(b, h) + aoff + m * 2048 + k * 1024); } while (0)
; #define PG8_LDB(dst, b, h) do { _Pragma("unroll") for (int n = 0; n < 2; ++n) _Pragma("unroll") for (int k = 0; k < 2; ++k) dst[n][k] = *(const LAS bf16x8*)(lds + PG8_SB(b, h) + boff + n * 2048 + k * 1024); } while (0)
; #define PG8_MMA(ai, bj, At, Bt) do { __builtin_amdgcn_s_setprio(1); _Pragma("unroll") for (int m = 0; m < 4; ++m) _Pragma("unroll") for (int n = 0; n < 2; ++n) _Pragma("unroll") for (int k = 0; k < 2; ++k) \
;     acc[ai][bj][m][n] = __builtin_amdgcn_mfma_f32_16x16x32_bf16(Bt[n][k], At[m][k], acc[ai][bj][m][n], 0, 0, 0); __builtin_amdgcn_s_setprio(0); } while (0)
; #define PG8_WAIT_L(n) asm volatile("s_waitcnt lgkmcnt(" #n ")" ::: "memory")
; template <class Epi>
; __device__ __forceinline__ void gemm_phase(LAS unsigned char* lds, const Gemm g, const StaticOrder& S, const Epi& E, int wv0) {
;     ...
;   for (;;) {
;     const bool has_next = S.next(ui + 1, nxt);
;     const char* nA = has_next ? (const char*)g.A + (size_t)nxt.pm * tstepA : cA; const char* nB = has_next ? (const char*)g.Bt + (size_t)nxt.pn * tstepB : cB;
;     for (int t = 0; t < nt; t += 2) {
;       const bool last = (t == nt - 2);
;       const char* a1 = cA + (size_t)(t + 1) * kstep;
;       const char* a2 = last ? nA : cA + (size_t)(t + 2) * kstep; const char* b2 = last ? nB : cB + (size_t)(t + 2) * kstep;
;       const char* a3 = a2 + kstep; const char* b3 = b2 + kstep;
;       PG8_LDB(B0, 0, 0); PG8_SCHED; PG8_LDA(At, 0, 0); PG8_STAGE(PG8_SA(1, 1), a1 + hstepA, voffA);
;       PG8_WAIT_L(8); PG8_BAR; PG8_WAIT_L(0); PG8_MMA(0, 0, At, B0); PG8_BAR; PG8_SCHED;
;     ...
; #pragma unroll
;     for (int a = 0; a < 2; ++a)
; #pragma unroll
;       for (int b = 0; b < 2; ++b)
; #pragma unroll
;         for (int m = 0; m < 4; ++m)
; #pragma unroll
;           for (int n = 0; n < 2; ++n) acc[a][b][m][n] = (f32x4){0.f, 0.f, 0.f, 0.f};
;     cur = nxt; cA = nA; cB = nB; ++ui;
.LBB0_1269:
	s_ashr_i32 s51, s50, 31
	v_mov_b64_e32 v[0:1], 0xb00
	s_lshl_b64 s[0:1], s[50:51], 20
	v_cmp_lt_i64_e32 vcc, s[52:53], v[0:1]
	s_add_u32 s52, s70, s0
	s_addc_u32 s53, s71, s1
	s_and_b64 s[0:1], vcc, exec
	s_cselect_b32 s1, s53, s61
	s_cselect_b32 s51, s52, s60
	s_ashr_i32 s49, s48, 31
	s_lshl_b64 s[54:55], s[48:49], 20
	s_add_u32 s54, s10, s54
	s_addc_u32 s55, s11, s55
	s_and_b64 s[64:65], vcc, exec
	s_cselect_b32 s49, s55, s63
	s_cselect_b32 s57, s54, s62
	s_add_u32 s60, s60, 0x80080
	s_addc_u32 s61, s61, 0
	s_add_u32 s59, s62, 0x100
	v_mov_b32_e32 v0, 0
	s_addc_u32 s75, s63, 0
	s_mov_b32 s78, -2
	v_mov_b32_e32 v1, v0
	v_mov_b32_e32 v2, v0
	v_mov_b32_e32 v3, v0
	v_mov_b32_e32 v64, v0
	v_mov_b32_e32 v65, v0
	v_mov_b32_e32 v66, v0
	v_mov_b32_e32 v67, v0
	v_mov_b32_e32 v4, v0
	v_mov_b32_e32 v5, v0
	v_mov_b32_e32 v6, v0
	v_mov_b32_e32 v7, v0
	v_mov_b32_e32 v68, v0
	v_mov_b32_e32 v69, v0
	v_mov_b32_e32 v70, v0
	v_mov_b32_e32 v71, v0
	v_mov_b32_e32 v16, v0
	v_mov_b32_e32 v17, v0
	v_mov_b32_e32 v18, v0
	v_mov_b32_e32 v19, v0
	v_mov_b32_e32 v80, v0
	v_mov_b32_e32 v81, v0
	v_mov_b32_e32 v82, v0
	v_mov_b32_e32 v83, v0
	v_mov_b32_e32 v24, v0
	v_mov_b32_e32 v25, v0
	v_mov_b32_e32 v26, v0
	v_mov_b32_e32 v27, v0
	v_mov_b32_e32 v88, v0
	v_mov_b32_e32 v89, v0
	v_mov_b32_e32 v90, v0
	v_mov_b32_e32 v91, v0
	v_mov_b32_e32 v8, v0
	v_mov_b32_e32 v9, v0
	v_mov_b32_e32 v10, v0
	v_mov_b32_e32 v11, v0
	v_mov_b32_e32 v72, v0
	v_mov_b32_e32 v73, v0
	v_mov_b32_e32 v74, v0
	v_mov_b32_e32 v75, v0
	v_mov_b32_e32 v12, v0
	v_mov_b32_e32 v13, v0
	v_mov_b32_e32 v14, v0
	v_mov_b32_e32 v15, v0
	v_mov_b32_e32 v76, v0
	v_mov_b32_e32 v77, v0
	v_mov_b32_e32 v78, v0
	v_mov_b32_e32 v79, v0
	v_mov_b32_e32 v20, v0
	v_mov_b32_e32 v21, v0
	v_mov_b32_e32 v22, v0
	v_mov_b32_e32 v23, v0
	v_mov_b32_e32 v84, v0
	v_mov_b32_e32 v85, v0
	v_mov_b32_e32 v86, v0
	v_mov_b32_e32 v87, v0
	v_mov_b32_e32 v28, v0
	v_mov_b32_e32 v29, v0
	v_mov_b32_e32 v30, v0
	v_mov_b32_e32 v31, v0
	v_mov_b32_e32 v92, v0
	v_mov_b32_e32 v93, v0
	v_mov_b32_e32 v94, v0
	v_mov_b32_e32 v95, v0
	v_mov_b32_e32 v32, v0
	v_mov_b32_e32 v33, v0
	v_mov_b32_e32 v34, v0
	v_mov_b32_e32 v35, v0
	v_mov_b32_e32 v98, v0
	v_mov_b32_e32 v99, v0
	v_mov_b32_e32 v100, v0
	v_mov_b32_e32 v101, v0
	v_mov_b32_e32 v36, v0
	v_mov_b32_e32 v37, v0
	v_mov_b32_e32 v38, v0
	v_mov_b32_e32 v39, v0
	v_mov_b32_e32 v102, v0
	v_mov_b32_e32 v103, v0
	v_mov_b32_e32 v104, v0
	v_mov_b32_e32 v105, v0
	v_mov_b32_e32 v48, v0
	v_mov_b32_e32 v49, v0
	v_mov_b32_e32 v50, v0
	v_mov_b32_e32 v51, v0
	v_mov_b32_e32 v114, v0
	v_mov_b32_e32 v115, v0
	v_mov_b32_e32 v116, v0
	v_mov_b32_e32 v117, v0
	v_mov_b32_e32 v56, v0
	v_mov_b32_e32 v57, v0
	v_mov_b32_e32 v58, v0
	v_mov_b32_e32 v59, v0
	v_mov_b32_e32 v154, v0
	v_mov_b32_e32 v155, v0
	v_mov_b32_e32 v156, v0
	v_mov_b32_e32 v157, v0
	v_mov_b32_e32 v40, v0
	v_mov_b32_e32 v41, v0
	v_mov_b32_e32 v42, v0
	v_mov_b32_e32 v43, v0
	v_mov_b32_e32 v106, v0
	v_mov_b32_e32 v107, v0
	v_mov_b32_e32 v108, v0
	v_mov_b32_e32 v109, v0
	v_mov_b32_e32 v44, v0
	v_mov_b32_e32 v45, v0
	v_mov_b32_e32 v46, v0
	v_mov_b32_e32 v47, v0
	v_mov_b32_e32 v110, v0
	v_mov_b32_e32 v111, v0
	v_mov_b32_e32 v112, v0
	v_mov_b32_e32 v113, v0
	v_mov_b32_e32 v52, v0
	v_mov_b32_e32 v53, v0
	v_mov_b32_e32 v54, v0
	v_mov_b32_e32 v55, v0
	v_mov_b32_e32 v118, v0
	v_mov_b32_e32 v119, v0
	v_mov_b32_e32 v120, v0
	v_mov_b32_e32 v121, v0
	v_mov_b32_e32 v60, v0
	v_mov_b32_e32 v61, v0
	v_mov_b32_e32 v62, v0
	v_mov_b32_e32 v63, v0
	v_mov_b32_e32 v158, v0
	v_mov_b32_e32 v159, v0
	v_mov_b32_e32 v160, v0
	v_mov_b32_e32 v161, v0
	s_cmp_lt_u32 s53, 4
	s_cbranch_scc1 .Lgprio8
	s_setprio 1
.Lgprio8:
.LBB0_1270:
	s_add_u32 s0, s60, 0xfff80080
	s_addc_u32 s62, s61, -1
	s_add_i32 s80, 0, 0x10000
	v_add_u32_e32 v134, s80, v213
	ds_read_b128 v[122:125], v134
	ds_read_b128 v[126:129], v134 offset:1024
	ds_read_b128 v[130:133], v134 offset:2048
	ds_read_b128 v[134:137], v134 offset:3072
	s_cmp_eq_u32 s78, 28
	s_cselect_b32 s65, s1, s62
	s_cselect_b32 s64, s51, s0
	s_cselect_b32 s63, s49, s75
	s_cselect_b32 s62, s57, s59
	v_lshl_add_u64 v[192:193], s[60:61], 0, v[172:173]
	s_add_i32 m0, s77, 0xc000
	ds_read_b128 v[138:141], v225
	ds_read_b128 v[142:145], v225 offset:1024
	ds_read_b128 v[146:149], v225 offset:2048
	ds_read_b128 v[150:153], v225 offset:3072
	ds_read_b128 v[176:179], v225 offset:4096
	ds_read_b128 v[180:183], v225 offset:5120
	ds_read_b128 v[184:187], v225 offset:6144
	ds_read_b128 v[188:191], v225 offset:7168
	global_load_lds_dwordx4 v[192:193], off
	v_lshl_add_u64 v[192:193], s[60:61], 0, v[174:175]
	s_add_i32 m0, s77, 0xe000
	s_nop 0
	global_load_lds_dwordx4 v[192:193], off
	s_waitcnt lgkmcnt(8)
	s_barrier
	s_waitcnt lgkmcnt(0)
	s_waitcnt lgkmcnt(0)
	v_mfma_f32_16x16x32_bf16 v[158:161], v[122:125], v[138:141], v[158:161]
	v_mfma_f32_16x16x32_bf16 v[60:63], v[130:133], v[138:141], v[60:63]
	v_mfma_f32_16x16x32_bf16 v[118:121], v[122:125], v[146:149], v[118:121]
	v_mfma_f32_16x16x32_bf16 v[52:55], v[130:133], v[146:149], v[52:55]
	v_mfma_f32_16x16x32_bf16 v[110:113], v[122:125], v[176:179], v[110:113]
	v_mfma_f32_16x16x32_bf16 v[44:47], v[130:133], v[176:179], v[44:47]
	v_mfma_f32_16x16x32_bf16 v[106:109], v[122:125], v[184:187], v[106:109]
	v_mfma_f32_16x16x32_bf16 v[40:43], v[130:133], v[184:187], v[40:43]
	v_mfma_f32_16x16x32_bf16 v[158:161], v[126:129], v[142:145], v[158:161]
	v_mfma_f32_16x16x32_bf16 v[60:63], v[134:137], v[142:145], v[60:63]
	v_mfma_f32_16x16x32_bf16 v[118:121], v[126:129], v[150:153], v[118:121]
	v_mfma_f32_16x16x32_bf16 v[52:55], v[134:137], v[150:153], v[52:55]
	v_mfma_f32_16x16x32_bf16 v[110:113], v[126:129], v[180:183], v[110:113]
	v_mfma_f32_16x16x32_bf16 v[44:47], v[134:137], v[180:183], v[44:47]
	v_mfma_f32_16x16x32_bf16 v[106:109], v[126:129], v[188:191], v[106:109]
	v_mfma_f32_16x16x32_bf16 v[40:43], v[134:137], v[188:191], v[40:43]
	s_barrier
; #define PG8_STAGE(bufoff, gbase, voff) do { _Pragma("unroll") for (int _i = 0; _i < 2; ++_i) \
;     __builtin_amdgcn_global_load_lds((const unsigned*)((const char*)(gbase) + (voff)[_i]), (LAS unsigned*)(lds + (bufoff) + ldsw + _i * 8192), 16, 0, 0); } while (0)
; #define PG8_LDA(dst, b, h) do { _Pragma("unroll") for (int m = 0; m < 4; ++m) _Pragma("unroll") for (int k = 0; k < 2; ++k) dst[m][k] = *(const LAS bf16x8*)(lds + PG8_SA(b, h) + aoff + m * 2048 + k * 1024); } while (0)
; #define PG8_LDB(dst, b, h) do { _Pragma("unroll") for (int n = 0; n < 2; ++n) _Pragma("unroll") for (int k = 0; k < 2; ++k) dst[n][k] = *(const LAS bf16x8*)(lds + PG8_SB(b, h) + boff + n * 2048 + k * 1024); } while (0)
; #define PG8_MMA(ai, bj, At, Bt) do { __builtin_amdgcn_s_setprio(1); _Pragma("unroll") for (int m = 0; m < 4; ++m) _Pragma("unroll") for (int n = 0; n < 2; ++n) _Pragma("unroll") for (int k = 0; k < 2; ++k) \
;     acc[ai][bj][m][n] = __builtin_amdgcn_mfma_f32_16x16x32_bf16(Bt[n][k], At[m][k], acc[ai][bj][m][n], 0, 0, 0); __builtin_amdgcn_s_setprio(0); } while (0)
; #define PG8_WAIT_V(n) asm volatile("s_waitcnt vmcnt(" #n ")" ::: "memory")
; #define PG8_WAIT_L(n) asm volatile("s_waitcnt lgkmcnt(" #n ")" ::: "memory")
; #define PG8_BAR __builtin_amdgcn_s_barrier()
; template <class Epi>
; __device__ __forceinline__ void gemm_phase(LAS unsigned char* lds, const Gemm g, const StaticOrder& S, const Epi& E, int wv0) {
;     ...
;       PG8_LDB(B1, 0, 1); PG8_STAGE(PG8_SB(0, 0), b2, voffB);
;       PG8_BAR; PG8_WAIT_L(0); PG8_MMA(0, 1, At, B1); PG8_BAR;
;       PG8_LDA(At, 0, 1); PG8_STAGE(PG8_SA(0, 0), a2, voffA);
;       PG8_BAR; PG8_WAIT_L(0); PG8_MMA(1, 0, At, B0); PG8_BAR; PG8_SCHED;
;       PG8_STAGE(PG8_SB(0, 1), b2 + hstepB, voffB);
;       PG8_WAIT_V(6); PG8_BAR; PG8_MMA(1, 1, At, B1); PG8_BAR;
;       PG8_LDB(B0, 1, 0); PG8_SCHED; PG8_LDA(At, 1, 0); PG8_STAGE(PG8_SA(0, 1), a2 + hstepA, voffA);
;       PG8_WAIT_L(8); PG8_BAR; PG8_WAIT_L(0); PG8_MMA(0, 0, At, B0); PG8_BAR; PG8_SCHED;
;       PG8_LDB(B1, 1, 1); PG8_STAGE(PG8_SB(1, 0), b3, voffB);
;       PG8_BAR; PG8_WAIT_L(0); PG8_MMA(0, 1, At, B1); PG8_BAR;
;       PG8_LDA(At, 1, 1); PG8_STAGE(PG8_SA(1, 0), a3, voffA);
;       PG8_BAR; PG8_WAIT_L(0); PG8_MMA(1, 0, At, B0); PG8_BAR; PG8_SCHED;
;       PG8_STAGE(PG8_SB(1, 1), b3 + hstepB, voffB);
;       PG8_WAIT_V(6); PG8_BAR; PG8_MMA(1, 1, At, B1); PG8_BAR;
	s_add_i32 s0, 0, 0x14000
	s_add_i32 s80, s80, s76
	v_add_u32_e32 v204, s0, v213
	v_lshl_add_u64 v[208:209], s[62:63], 0, v[96:97]
	s_mov_b32 m0, s80
	ds_read_b128 v[192:195], v204
	ds_read_b128 v[196:199], v204 offset:1024
	ds_read_b128 v[200:203], v204 offset:2048
	ds_read_b128 v[204:207], v204 offset:3072
	global_load_lds_dwordx4 v[208:209], off
	v_lshl_add_u64 v[210:211], s[62:63], 0, v[166:167]
	s_add_i32 m0, s80, 0x2000
	s_nop 0
	global_load_lds_dwordx4 v[210:211], off
	s_barrier
	s_waitcnt lgkmcnt(0)
	s_waitcnt lgkmcnt(0)
	v_mfma_f32_16x16x32_bf16 v[154:157], v[192:195], v[138:141], v[154:157]
	v_mfma_f32_16x16x32_bf16 v[56:59], v[200:203], v[138:141], v[56:59]
	v_mfma_f32_16x16x32_bf16 v[114:117], v[192:195], v[146:149], v[114:117]
	v_mfma_f32_16x16x32_bf16 v[48:51], v[200:203], v[146:149], v[48:51]
	v_mfma_f32_16x16x32_bf16 v[102:105], v[192:195], v[176:179], v[102:105]
	v_mfma_f32_16x16x32_bf16 v[36:39], v[200:203], v[176:179], v[36:39]
	v_mfma_f32_16x16x32_bf16 v[98:101], v[192:195], v[184:187], v[98:101]
	v_mfma_f32_16x16x32_bf16 v[32:35], v[200:203], v[184:187], v[32:35]
	v_mfma_f32_16x16x32_bf16 v[154:157], v[196:199], v[142:145], v[154:157]
	v_mfma_f32_16x16x32_bf16 v[56:59], v[204:207], v[142:145], v[56:59]
	v_mfma_f32_16x16x32_bf16 v[114:117], v[196:199], v[150:153], v[114:117]
	v_mfma_f32_16x16x32_bf16 v[48:51], v[204:207], v[150:153], v[48:51]
	v_mfma_f32_16x16x32_bf16 v[102:105], v[196:199], v[180:183], v[102:105]
	v_mfma_f32_16x16x32_bf16 v[36:39], v[204:207], v[180:183], v[36:39]
	v_mfma_f32_16x16x32_bf16 v[98:101], v[196:199], v[188:191], v[98:101]
	v_mfma_f32_16x16x32_bf16 v[32:35], v[204:207], v[188:191], v[32:35]
	s_mov_b32 m0, s77
	v_lshl_add_u64 v[220:221], s[64:65], 0, v[162:163]
	s_barrier
	ds_read_b128 v[138:141], v225 offset:16384
	ds_read_b128 v[142:145], v225 offset:17408
	ds_read_b128 v[146:149], v225 offset:18432
	ds_read_b128 v[150:153], v225 offset:19456
	ds_read_b128 v[176:179], v225 offset:20480
	ds_read_b128 v[180:183], v225 offset:21504
	ds_read_b128 v[184:187], v225 offset:22528
	ds_read_b128 v[188:191], v225 offset:23552
	global_load_lds_dwordx4 v[220:221], off
	v_lshl_add_u64 v[222:223], s[64:65], 0, v[164:165]
	s_mov_b32 m0, s86
	s_nop 0
	global_load_lds_dwordx4 v[222:223], off
	s_barrier
	s_waitcnt lgkmcnt(0)
	s_waitcnt lgkmcnt(0)
	v_mfma_f32_16x16x32_bf16 v[92:95], v[122:125], v[138:141], v[92:95]
	v_mfma_f32_16x16x32_bf16 v[28:31], v[130:133], v[138:141], v[28:31]
	v_mfma_f32_16x16x32_bf16 v[84:87], v[122:125], v[146:149], v[84:87]
	v_mfma_f32_16x16x32_bf16 v[20:23], v[130:133], v[146:149], v[20:23]
	v_mfma_f32_16x16x32_bf16 v[76:79], v[122:125], v[176:179], v[76:79]
	v_mfma_f32_16x16x32_bf16 v[12:15], v[130:133], v[176:179], v[12:15]
	v_mfma_f32_16x16x32_bf16 v[72:75], v[122:125], v[184:187], v[72:75]
	v_mfma_f32_16x16x32_bf16 v[8:11], v[130:133], v[184:187], v[8:11]
	v_mfma_f32_16x16x32_bf16 v[92:95], v[126:129], v[142:145], v[92:95]
	v_mfma_f32_16x16x32_bf16 v[28:31], v[134:137], v[142:145], v[28:31]
	v_mfma_f32_16x16x32_bf16 v[84:87], v[126:129], v[150:153], v[84:87]
	v_mfma_f32_16x16x32_bf16 v[20:23], v[134:137], v[150:153], v[20:23]
	v_mfma_f32_16x16x32_bf16 v[76:79], v[126:129], v[180:183], v[76:79]
	v_mfma_f32_16x16x32_bf16 v[12:15], v[134:137], v[180:183], v[12:15]
	v_mfma_f32_16x16x32_bf16 v[72:75], v[126:129], v[188:191], v[72:75]
	v_mfma_f32_16x16x32_bf16 v[8:11], v[134:137], v[188:191], v[8:11]
	s_barrier
	s_add_u32 vcc_lo, s62, 0x80000
	s_addc_u32 vcc_hi, s63, 0
	s_add_i32 s0, s0, s76
	v_lshl_add_u64 v[122:123], vcc, 0, v[96:97]
	s_mov_b32 m0, s0
	s_nop 0
	global_load_lds_dwordx4 v[122:123], off
	v_lshl_add_u64 v[122:123], vcc, 0, v[166:167]
	s_add_i32 m0, s0, 0x2000
	s_nop 0
	global_load_lds_dwordx4 v[122:123], off
	s_waitcnt vmcnt(6)
	s_barrier
	v_mfma_f32_16x16x32_bf16 v[88:91], v[192:195], v[138:141], v[88:91]
	v_mfma_f32_16x16x32_bf16 v[24:27], v[200:203], v[138:141], v[24:27]
	v_mfma_f32_16x16x32_bf16 v[80:83], v[192:195], v[146:149], v[80:83]
	v_mfma_f32_16x16x32_bf16 v[16:19], v[200:203], v[146:149], v[16:19]
	v_mfma_f32_16x16x32_bf16 v[68:71], v[192:195], v[176:179], v[68:71]
	v_mfma_f32_16x16x32_bf16 v[4:7], v[200:203], v[176:179], v[4:7]
	v_mfma_f32_16x16x32_bf16 v[64:67], v[192:195], v[184:187], v[64:67]
	v_mfma_f32_16x16x32_bf16 v[0:3], v[200:203], v[184:187], v[0:3]
	v_mfma_f32_16x16x32_bf16 v[88:91], v[196:199], v[142:145], v[88:91]
	v_mfma_f32_16x16x32_bf16 v[24:27], v[204:207], v[142:145], v[24:27]
	v_mfma_f32_16x16x32_bf16 v[80:83], v[196:199], v[150:153], v[80:83]
	v_mfma_f32_16x16x32_bf16 v[16:19], v[204:207], v[150:153], v[16:19]
	v_mfma_f32_16x16x32_bf16 v[68:71], v[196:199], v[180:183], v[68:71]
	v_mfma_f32_16x16x32_bf16 v[4:7], v[204:207], v[180:183], v[4:7]
	v_mfma_f32_16x16x32_bf16 v[64:67], v[196:199], v[188:191], v[64:67]
	v_mfma_f32_16x16x32_bf16 v[0:3], v[204:207], v[188:191], v[0:3]
	s_add_i32 s0, 0, 0x18000
	v_add_u32_e32 v134, s0, v213
	s_barrier
	ds_read_b128 v[122:125], v134
	ds_read_b128 v[126:129], v134 offset:1024
	ds_read_b128 v[130:133], v134 offset:2048
	ds_read_b128 v[134:137], v134 offset:3072
	s_add_u32 s64, s64, 0x80000
	s_addc_u32 s65, s65, 0
	s_mov_b32 m0, s87
	v_lshl_add_u64 v[192:193], s[64:65], 0, v[162:163]
	ds_read_b128 v[138:141], v225 offset:32768
	ds_read_b128 v[142:145], v225 offset:33792
	ds_read_b128 v[146:149], v225 offset:34816
	ds_read_b128 v[150:153], v225 offset:35840
	ds_read_b128 v[176:179], v225 offset:36864
	ds_read_b128 v[180:183], v225 offset:37888
	ds_read_b128 v[184:187], v225 offset:38912
	ds_read_b128 v[188:191], v225 offset:39936
	global_load_lds_dwordx4 v[192:193], off
	v_lshl_add_u64 v[192:193], s[64:65], 0, v[164:165]
	s_mov_b32 m0, s88
	s_nop 0
	global_load_lds_dwordx4 v[192:193], off
	s_waitcnt lgkmcnt(8)
	s_barrier
; #define PG8_STAGE(bufoff, gbase, voff) do { _Pragma("unroll") for (int _i = 0; _i < 2; ++_i) \
;     __builtin_amdgcn_global_load_lds((const unsigned*)((const char*)(gbase) + (voff)[_i]), (LAS unsigned*)(lds + (bufoff) + ldsw + _i * 8192), 16, 0, 0); } while (0)
; #define PG8_LDA(dst, b, h) do { _Pragma("unroll") for (int m = 0; m < 4; ++m) _Pragma("unroll") for (int k = 0; k < 2; ++k) dst[m][k] = *(const LAS bf16x8*)(lds + PG8_SA(b, h) + aoff + m * 2048 + k * 1024); } while (0)
; #define PG8_LDB(dst, b, h) do { _Pragma("unroll") for (int n = 0; n < 2; ++n) _Pragma("unroll") for (int k = 0; k < 2; ++k) dst[n][k] = *(const LAS bf16x8*)(lds + PG8_SB(b, h) + boff + n * 2048 + k * 1024); } while (0)
; #define PG8_MMA(ai, bj, At, Bt) do { __builtin_amdgcn_s_setprio(1); _Pragma("unroll") for (int m = 0; m < 4; ++m) _Pragma("unroll") for (int n = 0; n < 2; ++n) _Pragma("unroll") for (int k = 0; k < 2; ++k) \
;     acc[ai][bj][m][n] = __builtin_amdgcn_mfma_f32_16x16x32_bf16(Bt[n][k], At[m][k], acc[ai][bj][m][n], 0, 0, 0); __builtin_amdgcn_s_setprio(0); } while (0)
; #define PG8_WAIT_L(n) asm volatile("s_waitcnt lgkmcnt(" #n ")" ::: "memory")
; #define PG8_BAR __builtin_amdgcn_s_barrier()
; #define PG8_SCHED __builtin_amdgcn_sched_barrier(0)
; template <class Epi>
; __device__ __forceinline__ void gemm_phase(LAS unsigned char* lds, const Gemm g, const StaticOrder& S, const Epi& E, int wv0) {
;     ...
;       PG8_LDB(B0, 1, 0); PG8_SCHED; PG8_LDA(At, 1, 0); PG8_STAGE(PG8_SA(0, 1), a2 + hstepA, voffA);
;       PG8_WAIT_L(8); PG8_BAR; PG8_WAIT_L(0); PG8_MMA(0, 0, At, B0); PG8_BAR; PG8_SCHED;
;       PG8_LDB(B1, 1, 1); PG8_STAGE(PG8_SB(1, 0), b3, voffB);
;       PG8_BAR; PG8_WAIT_L(0); PG8_MMA(0, 1, At, B1); PG8_BAR;
;       PG8_LDA(At, 1, 1); PG8_STAGE(PG8_SA(1, 0), a3, voffA);
;       PG8_BAR; PG8_WAIT_L(0); PG8_MMA(1, 0, At, B0); PG8_BAR; PG8_SCHED;
	s_waitcnt lgkmcnt(0)
	s_waitcnt lgkmcnt(0)
	v_mfma_f32_16x16x32_bf16 v[158:161], v[122:125], v[138:141], v[158:161]
	v_mfma_f32_16x16x32_bf16 v[60:63], v[130:133], v[138:141], v[60:63]
	v_mfma_f32_16x16x32_bf16 v[118:121], v[122:125], v[146:149], v[118:121]
	v_mfma_f32_16x16x32_bf16 v[52:55], v[130:133], v[146:149], v[52:55]
	v_mfma_f32_16x16x32_bf16 v[110:113], v[122:125], v[176:179], v[110:113]
	v_mfma_f32_16x16x32_bf16 v[44:47], v[130:133], v[176:179], v[44:47]
	v_mfma_f32_16x16x32_bf16 v[106:109], v[122:125], v[184:187], v[106:109]
	v_mfma_f32_16x16x32_bf16 v[40:43], v[130:133], v[184:187], v[40:43]
	v_mfma_f32_16x16x32_bf16 v[158:161], v[126:129], v[142:145], v[158:161]
	v_mfma_f32_16x16x32_bf16 v[60:63], v[134:137], v[142:145], v[60:63]
	v_mfma_f32_16x16x32_bf16 v[118:121], v[126:129], v[150:153], v[118:121]
	v_mfma_f32_16x16x32_bf16 v[52:55], v[134:137], v[150:153], v[52:55]
	v_mfma_f32_16x16x32_bf16 v[110:113], v[126:129], v[180:183], v[110:113]
	v_mfma_f32_16x16x32_bf16 v[44:47], v[134:137], v[180:183], v[44:47]
	v_mfma_f32_16x16x32_bf16 v[106:109], v[126:129], v[188:191], v[106:109]
	v_mfma_f32_16x16x32_bf16 v[40:43], v[134:137], v[188:191], v[40:43]
	s_barrier
	s_add_i32 s64, 0, 0x1c000
	s_add_i32 s0, s0, s76
	v_add_u32_e32 v204, s64, v213
	v_lshl_add_u64 v[208:209], v[208:209], 0, s[72:73]
	s_mov_b32 m0, s0
	ds_read_b128 v[192:195], v204
	ds_read_b128 v[196:199], v204 offset:1024
	ds_read_b128 v[200:203], v204 offset:2048
	ds_read_b128 v[204:207], v204 offset:3072
	global_load_lds_dwordx4 v[208:209], off
	v_lshl_add_u64 v[208:209], v[210:211], 0, s[72:73]
	s_add_i32 m0, s0, 0x2000
	s_nop 0
	global_load_lds_dwordx4 v[208:209], off
	s_barrier
	s_waitcnt lgkmcnt(0)
	s_waitcnt lgkmcnt(0)
	v_mfma_f32_16x16x32_bf16 v[154:157], v[192:195], v[138:141], v[154:157]
	v_mfma_f32_16x16x32_bf16 v[56:59], v[200:203], v[138:141], v[56:59]
	v_mfma_f32_16x16x32_bf16 v[114:117], v[192:195], v[146:149], v[114:117]
	v_mfma_f32_16x16x32_bf16 v[48:51], v[200:203], v[146:149], v[48:51]
	v_mfma_f32_16x16x32_bf16 v[102:105], v[192:195], v[176:179], v[102:105]
	v_mfma_f32_16x16x32_bf16 v[36:39], v[200:203], v[176:179], v[36:39]
	v_mfma_f32_16x16x32_bf16 v[98:101], v[192:195], v[184:187], v[98:101]
	v_mfma_f32_16x16x32_bf16 v[32:35], v[200:203], v[184:187], v[32:35]
	v_mfma_f32_16x16x32_bf16 v[154:157], v[196:199], v[142:145], v[154:157]
	v_mfma_f32_16x16x32_bf16 v[56:59], v[204:207], v[142:145], v[56:59]
	v_mfma_f32_16x16x32_bf16 v[114:117], v[196:199], v[150:153], v[114:117]
	v_mfma_f32_16x16x32_bf16 v[48:51], v[204:207], v[150:153], v[48:51]
	v_mfma_f32_16x16x32_bf16 v[102:105], v[196:199], v[180:183], v[102:105]
	v_mfma_f32_16x16x32_bf16 v[36:39], v[204:207], v[180:183], v[36:39]
	v_mfma_f32_16x16x32_bf16 v[98:101], v[196:199], v[188:191], v[98:101]
	v_mfma_f32_16x16x32_bf16 v[32:35], v[204:207], v[188:191], v[32:35]
	s_mov_b32 m0, s89
	v_lshl_add_u64 v[208:209], v[220:221], 0, s[72:73]
	s_barrier
	ds_read_b128 v[138:141], v225 offset:49152
	ds_read_b128 v[142:145], v225 offset:50176
	ds_read_b128 v[146:149], v225 offset:51200
	ds_read_b128 v[150:153], v225 offset:52224
	ds_read_b128 v[176:179], v225 offset:53248
	ds_read_b128 v[180:183], v225 offset:54272
	ds_read_b128 v[184:187], v225 offset:55296
	ds_read_b128 v[188:191], v225 offset:56320
	global_load_lds_dwordx4 v[208:209], off
	v_lshl_add_u64 v[208:209], v[222:223], 0, s[72:73]
	s_mov_b32 m0, s92
	s_nop 0
	global_load_lds_dwordx4 v[208:209], off
	s_barrier
; #define LAS __attribute__((address_space(3)))
; #define PG8_STAGE(bufoff, gbase, voff) do { _Pragma("unroll") for (int _i = 0; _i < 2; ++_i) \
;     __builtin_amdgcn_global_load_lds((const unsigned*)((const char*)(gbase) + (voff)[_i]), (LAS unsigned*)(lds + (bufoff) + ldsw + _i * 8192), 16, 0, 0); } while (0)
; #define PG8_MMA(ai, bj, At, Bt) do { __builtin_amdgcn_s_setprio(1); _Pragma("unroll") for (int m = 0; m < 4; ++m) _Pragma("unroll") for (int n = 0; n < 2; ++n) _Pragma("unroll") for (int k = 0; k < 2; ++k) \
;     acc[ai][bj][m][n] = __builtin_amdgcn_mfma_f32_16x16x32_bf16(Bt[n][k], At[m][k], acc[ai][bj][m][n], 0, 0, 0); __builtin_amdgcn_s_setprio(0); } while (0)
; #define PG8_WAIT_V(n) asm volatile("s_waitcnt vmcnt(" #n ")" ::: "memory")
; #define PG8_BAR __builtin_amdgcn_s_barrier()
; template <class Epi>
; __device__ __forceinline__ void gemm_phase(LAS unsigned char* lds, const Gemm g, const StaticOrder& S, const Epi& E, int wv0) {
;     ...
;       PG8_STAGE(PG8_SB(1, 1), b3 + hstepB, voffB);
;       PG8_WAIT_V(6); PG8_BAR; PG8_MMA(1, 1, At, B1); PG8_BAR;
; __device__ __forceinline__ void epi_upc(const EpiP& e, const f32x4 (&acc)[2][2][4][2], const pg8::Unit& u, int wr, int wc, int fr, int fq) {
;     ...
;         u32x4 w; w.x = pk2(acc[ai][bj][m][0][0], acc[ai][bj][m][0][1]); w.y = pk2(acc[ai][bj][m][0][2], acc[ai][bj][m][0][3]);
;         w.z = pk2(acc[ai][bj][m][1][0], acc[ai][bj][m][1][1]); w.w = pk2(acc[ai][bj][m][1][2], acc[ai][bj][m][1][3]);
;         if (m == 3 && fr >= 14) *(LAS u32x4*)(ex + ((g * 2 + (fr - 14)) * 256 + bj * 128 + lc0) * 2) = w;
;         const int ucol = bj * DFF + 128 * u.pn + lc0;
;         if (g == 15 && fr >= 14) *(u32x4*)(side + ((size_t)u.pm * 4 + 2 + (fr - 14)) * NUP + ucol) = w;
;         if (g == 0 && fr < 2) *(u32x4*)(side + ((size_t)u.pm * 4 + fr) * NUP + ucol) = w;
	s_waitcnt lgkmcnt(0)
	s_waitcnt lgkmcnt(0)
	v_mfma_f32_16x16x32_bf16 v[92:95], v[122:125], v[138:141], v[92:95]
	v_mfma_f32_16x16x32_bf16 v[28:31], v[130:133], v[138:141], v[28:31]
	v_mfma_f32_16x16x32_bf16 v[84:87], v[122:125], v[146:149], v[84:87]
	v_mfma_f32_16x16x32_bf16 v[20:23], v[130:133], v[146:149], v[20:23]
	v_mfma_f32_16x16x32_bf16 v[76:79], v[122:125], v[176:179], v[76:79]
	v_mfma_f32_16x16x32_bf16 v[12:15], v[130:133], v[176:179], v[12:15]
	v_mfma_f32_16x16x32_bf16 v[72:75], v[122:125], v[184:187], v[72:75]
	v_mfma_f32_16x16x32_bf16 v[8:11], v[130:133], v[184:187], v[8:11]
	v_mfma_f32_16x16x32_bf16 v[92:95], v[126:129], v[142:145], v[92:95]
	v_mfma_f32_16x16x32_bf16 v[28:31], v[134:137], v[142:145], v[28:31]
	v_mfma_f32_16x16x32_bf16 v[84:87], v[126:129], v[150:153], v[84:87]
	v_mfma_f32_16x16x32_bf16 v[20:23], v[134:137], v[150:153], v[20:23]
	v_mfma_f32_16x16x32_bf16 v[76:79], v[126:129], v[180:183], v[76:79]
	v_mfma_f32_16x16x32_bf16 v[12:15], v[134:137], v[180:183], v[12:15]
	v_mfma_f32_16x16x32_bf16 v[72:75], v[126:129], v[188:191], v[72:75]
	v_mfma_f32_16x16x32_bf16 v[8:11], v[134:137], v[188:191], v[8:11]
	s_barrier
	s_add_u32 s62, s62, 0x80080
	s_addc_u32 s63, s63, 0
	s_add_i32 s0, s64, s76
	v_lshl_add_u64 v[122:123], s[62:63], 0, v[96:97]
	s_mov_b32 m0, s0
	s_nop 0
	global_load_lds_dwordx4 v[122:123], off
	v_lshl_add_u64 v[122:123], s[62:63], 0, v[166:167]
	s_add_i32 m0, s0, 0x2000
	s_nop 0
	global_load_lds_dwordx4 v[122:123], off
	s_waitcnt vmcnt(6)
	s_barrier
	v_mfma_f32_16x16x32_bf16 v[88:91], v[192:195], v[138:141], v[88:91]
	v_mfma_f32_16x16x32_bf16 v[24:27], v[200:203], v[138:141], v[24:27]
	v_mfma_f32_16x16x32_bf16 v[80:83], v[192:195], v[146:149], v[80:83]
	v_mfma_f32_16x16x32_bf16 v[16:19], v[200:203], v[146:149], v[16:19]
	v_mfma_f32_16x16x32_bf16 v[68:71], v[192:195], v[176:179], v[68:71]
	v_mfma_f32_16x16x32_bf16 v[4:7], v[200:203], v[176:179], v[4:7]
	v_mfma_f32_16x16x32_bf16 v[64:67], v[192:195], v[184:187], v[64:67]
	v_mfma_f32_16x16x32_bf16 v[0:3], v[200:203], v[184:187], v[0:3]
	v_mfma_f32_16x16x32_bf16 v[88:91], v[196:199], v[142:145], v[88:91]
	v_mfma_f32_16x16x32_bf16 v[24:27], v[204:207], v[142:145], v[24:27]
	v_mfma_f32_16x16x32_bf16 v[80:83], v[196:199], v[150:153], v[80:83]
	v_mfma_f32_16x16x32_bf16 v[16:19], v[204:207], v[150:153], v[16:19]
	v_mfma_f32_16x16x32_bf16 v[68:71], v[196:199], v[180:183], v[68:71]
	v_mfma_f32_16x16x32_bf16 v[4:7], v[204:207], v[180:183], v[4:7]
	v_mfma_f32_16x16x32_bf16 v[64:67], v[196:199], v[188:191], v[64:67]
	v_mfma_f32_16x16x32_bf16 v[0:3], v[204:207], v[188:191], v[0:3]
	s_add_i32 s78, s78, 2
	s_add_u32 s60, s60, 0x100
	s_addc_u32 s61, s61, 0
	s_add_u32 s59, s59, 0x100
	s_addc_u32 s75, s75, 0
	s_cmp_gt_u32 s78, 29
	s_barrier
	s_cbranch_scc0 .LBB0_1270
	s_setprio 0
	s_and_saveexec_b64 s[60:61], s[36:37]
	s_movk_i32 s78, 0x5800
	s_cbranch_execz .LBB0_1273
	s_ashr_i32 s57, s56, 31
	s_lshl_b64 s[0:1], s[56:57], 2
	s_lshl_b32 s49, s58, 7
	v_or_b32_e32 v127, s0, v168
	v_mov_b64_e32 v[128:129], s[14:15]
	v_or_b32_e32 v126, s49, v214
	v_mad_u64_u32 v[128:129], s[62:63], v127, s78, v[128:129]
	v_mov_b32_e32 v127, 0x5800
	v_mad_i32_i24 v129, s1, v127, v129
	v_ashrrev_i32_e32 v127, 31, v126
	v_cvt_pk_bf16_f32 v122, v158, v159
	v_cvt_pk_bf16_f32 v123, v160, v161
	v_cvt_pk_bf16_f32 v124, v60, v61
	v_cvt_pk_bf16_f32 v125, v62, v63
	v_lshl_add_u64 v[126:127], v[126:127], 1, v[128:129]
	global_store_dwordx4 v[126:127], v[122:125], off
	v_add_u32_e32 v126, s49, v169
	v_ashrrev_i32_e32 v127, 31, v126
	v_cvt_pk_bf16_f32 v122, v154, v155
	v_cvt_pk_bf16_f32 v123, v156, v157
	v_cvt_pk_bf16_f32 v124, v56, v57
	v_cvt_pk_bf16_f32 v125, v58, v59
	v_lshl_add_u64 v[126:127], v[126:127], 1, v[128:129]
	global_store_dwordx4 v[126:127], v[122:125], off

; #define PG8_STAGE(bufoff, gbase, voff) do { _Pragma("unroll") for (int _i = 0; _i < 2; ++_i) \
;     __builtin_amdgcn_global_load_lds((const unsigned*)((const char*)(gbase) + (voff)[_i]), (LAS unsigned*)(lds + (bufoff) + ldsw + _i * 8192), 16, 0, 0); } while (0)
; #define PG8_LDA(dst, b, h) do { _Pragma("unroll") for (int m = 0; m < 4; ++m) _Pragma("unroll") for (int k = 0; k < 2; ++k) dst[m][k] = *(const LAS bf16x8*)(lds + PG8_SA(b, h) + aoff + m * 2048 + k * 1024); } while (0)
; #define PG8_LDB(dst, b, h) do { _Pragma("unroll") for (int n = 0; n < 2; ++n) _Pragma("unroll") for (int k = 0; k < 2; ++k) dst[n][k] = *(const LAS bf16x8*)(lds + PG8_SB(b, h) + boff + n * 2048 + k * 1024); } while (0)
; #define PG8_MMA(ai, bj, At, Bt) do { __builtin_amdgcn_s_setprio(1); _Pragma("unroll") for (int m = 0; m < 4; ++m) _Pragma("unroll") for (int n = 0; n < 2; ++n) _Pragma("unroll") for (int k = 0; k < 2; ++k) \
;     acc[ai][bj][m][n] = __builtin_amdgcn_mfma_f32_16x16x32_bf16(Bt[n][k], At[m][k], acc[ai][bj][m][n], 0, 0, 0); __builtin_amdgcn_s_setprio(0); } while (0)
; #define PG8_WAIT_L(n) asm volatile("s_waitcnt lgkmcnt(" #n ")" ::: "memory")
; #define PG8_BAR __builtin_amdgcn_s_barrier()
; #define PG8_SCHED __builtin_amdgcn_sched_barrier(0)
; template <class Epi>
; __device__ __forceinline__ void gemm_phase(LAS unsigned char* lds, const Gemm g, const StaticOrder& S, const Epi& E, int wv0) {
;     ...
;     for (int t = 0; t < nt; t += 2) {
;       const bool last = (t == nt - 2);
;       const char* a1 = cA + (size_t)(t + 1) * kstep;
;       const char* a2 = last ? nA : cA + (size_t)(t + 2) * kstep; const char* b2 = last ? nB : cB + (size_t)(t + 2) * kstep;
;       const char* a3 = a2 + kstep; const char* b3 = b2 + kstep;
;       PG8_LDB(B0, 0, 0); PG8_SCHED; PG8_LDA(At, 0, 0); PG8_STAGE(PG8_SA(1, 1), a1 + hstepA, voffA);
;       PG8_WAIT_L(8); PG8_BAR; PG8_WAIT_L(0); PG8_MMA(0, 0, At, B0); PG8_BAR; PG8_SCHED;
;       PG8_LDB(B1, 0, 1); PG8_STAGE(PG8_SB(0, 0), b2, voffB);
;       PG8_BAR; PG8_WAIT_L(0); PG8_MMA(0, 1, At, B1); PG8_BAR;
;     ...
; #pragma unroll
;     for (int a = 0; a < 2; ++a)
; #pragma unroll
;       for (int b = 0; b < 2; ++b)
; #pragma unroll
;         for (int m = 0; m < 4; ++m)
; #pragma unroll
;           for (int n = 0; n < 2; ++n) acc[a][b][m][n] = (f32x4){0.f, 0.f, 0.f, 0.f};
.LBB0_1428:
	s_add_u32 s43, s14, 0x100
	v_mov_b32_e32 v0, 0
	s_addc_u32 s44, s15, 0
	s_mov_b32 s45, -2
	v_mov_b32_e32 v1, v0
	v_mov_b32_e32 v2, v0
	v_mov_b32_e32 v3, v0
	v_mov_b32_e32 v4, v0
	v_mov_b32_e32 v5, v0
	v_mov_b32_e32 v6, v0
	v_mov_b32_e32 v7, v0
	v_mov_b32_e32 v12, v0
	v_mov_b32_e32 v13, v0
	v_mov_b32_e32 v14, v0
	v_mov_b32_e32 v15, v0
	v_mov_b32_e32 v20, v0
	v_mov_b32_e32 v21, v0
	v_mov_b32_e32 v22, v0
	v_mov_b32_e32 v23, v0
	v_mov_b32_e32 v32, v0
	v_mov_b32_e32 v33, v0
	v_mov_b32_e32 v34, v0
	v_mov_b32_e32 v35, v0
	v_mov_b32_e32 v36, v0
	v_mov_b32_e32 v37, v0
	v_mov_b32_e32 v38, v0
	v_mov_b32_e32 v39, v0
	v_mov_b32_e32 v44, v0
	v_mov_b32_e32 v45, v0
	v_mov_b32_e32 v46, v0
	v_mov_b32_e32 v47, v0
	v_mov_b32_e32 v52, v0
	v_mov_b32_e32 v53, v0
	v_mov_b32_e32 v54, v0
	v_mov_b32_e32 v55, v0
	v_mov_b32_e32 v8, v0
	v_mov_b32_e32 v9, v0
	v_mov_b32_e32 v10, v0
	v_mov_b32_e32 v11, v0
	v_mov_b32_e32 v16, v0
	v_mov_b32_e32 v17, v0
	v_mov_b32_e32 v18, v0
	v_mov_b32_e32 v19, v0
	v_mov_b32_e32 v24, v0
	v_mov_b32_e32 v25, v0
	v_mov_b32_e32 v26, v0
	v_mov_b32_e32 v27, v0
	v_mov_b32_e32 v28, v0
	v_mov_b32_e32 v29, v0
	v_mov_b32_e32 v30, v0
	v_mov_b32_e32 v31, v0
	v_mov_b32_e32 v40, v0
	v_mov_b32_e32 v41, v0
	v_mov_b32_e32 v42, v0
	v_mov_b32_e32 v43, v0
	v_mov_b32_e32 v48, v0
	v_mov_b32_e32 v49, v0
	v_mov_b32_e32 v50, v0
	v_mov_b32_e32 v51, v0
	v_mov_b32_e32 v56, v0
	v_mov_b32_e32 v57, v0
	v_mov_b32_e32 v58, v0
	v_mov_b32_e32 v59, v0
	v_mov_b32_e32 v60, v0
	v_mov_b32_e32 v61, v0
	v_mov_b32_e32 v62, v0
	v_mov_b32_e32 v63, v0
	v_mov_b32_e32 v64, v0
	v_mov_b32_e32 v65, v0
	v_mov_b32_e32 v66, v0
	v_mov_b32_e32 v67, v0
	v_mov_b32_e32 v68, v0
	v_mov_b32_e32 v69, v0
	v_mov_b32_e32 v70, v0
	v_mov_b32_e32 v71, v0
	v_mov_b32_e32 v72, v0
	v_mov_b32_e32 v73, v0
	v_mov_b32_e32 v74, v0
	v_mov_b32_e32 v75, v0
	v_mov_b32_e32 v80, v0
	v_mov_b32_e32 v81, v0
	v_mov_b32_e32 v82, v0
	v_mov_b32_e32 v83, v0
	v_mov_b32_e32 v98, v0
	v_mov_b32_e32 v99, v0
	v_mov_b32_e32 v100, v0
	v_mov_b32_e32 v101, v0
	v_mov_b32_e32 v102, v0
	v_mov_b32_e32 v103, v0
	v_mov_b32_e32 v104, v0
	v_mov_b32_e32 v105, v0
	v_mov_b32_e32 v106, v0
	v_mov_b32_e32 v107, v0
	v_mov_b32_e32 v108, v0
	v_mov_b32_e32 v109, v0
	v_mov_b32_e32 v110, v0
	v_mov_b32_e32 v111, v0
	v_mov_b32_e32 v112, v0
	v_mov_b32_e32 v113, v0
	v_mov_b32_e32 v76, v0
	v_mov_b32_e32 v77, v0
	v_mov_b32_e32 v78, v0
	v_mov_b32_e32 v79, v0
	v_mov_b32_e32 v84, v0
	v_mov_b32_e32 v85, v0
	v_mov_b32_e32 v86, v0
	v_mov_b32_e32 v87, v0
	v_mov_b32_e32 v88, v0
	v_mov_b32_e32 v89, v0
	v_mov_b32_e32 v90, v0
	v_mov_b32_e32 v91, v0
	v_mov_b32_e32 v92, v0
	v_mov_b32_e32 v93, v0
	v_mov_b32_e32 v94, v0
	v_mov_b32_e32 v95, v0
	v_mov_b32_e32 v114, v0
	v_mov_b32_e32 v115, v0
	v_mov_b32_e32 v116, v0
	v_mov_b32_e32 v117, v0
	v_mov_b32_e32 v118, v0
	v_mov_b32_e32 v119, v0
	v_mov_b32_e32 v120, v0
	v_mov_b32_e32 v121, v0
	v_mov_b32_e32 v122, v0
	v_mov_b32_e32 v123, v0
	v_mov_b32_e32 v124, v0
	v_mov_b32_e32 v125, v0
	v_mov_b32_e32 v126, v0
	v_mov_b32_e32 v127, v0
	v_mov_b32_e32 v128, v0
	v_mov_b32_e32 v129, v0
	s_cmp_lt_u32 s53, 4
	s_cbranch_scc1 .Lgprio9
	s_setprio 1
.Lgprio9:
.LBB0_1429:
	s_add_u32 s14, s12, 0x100
	s_addc_u32 s15, s13, 0
	s_add_i32 s0, 0, 0x10000
	v_add_u32_e32 v142, s0, v187
	ds_read_b128 v[130:133], v142
	ds_read_b128 v[134:137], v142 offset:1024
	ds_read_b128 v[138:141], v142 offset:2048
	ds_read_b128 v[142:145], v142 offset:3072
	s_cmpk_eq_i32 s45, 0x54
	s_cselect_b32 s19, s5, s15
	s_cselect_b32 s18, s4, s14
	s_cselect_b32 s17, s7, s44
	s_cselect_b32 s16, s6, s43
	v_lshl_add_u64 v[184:185], s[12:13], 0, v[168:169]
	s_add_i32 m0, s30, 0xc000
	ds_read_b128 v[146:149], v189
	ds_read_b128 v[150:153], v189 offset:1024
	ds_read_b128 v[154:157], v189 offset:2048
	ds_read_b128 v[158:161], v189 offset:3072
	ds_read_b128 v[172:175], v189 offset:4096
	ds_read_b128 v[176:179], v189 offset:5120
	ds_read_b128 v[180:183], v189 offset:6144
	ds_read_b128 v[190:193], v189 offset:7168
	global_load_lds_dwordx4 v[184:185], off
	v_lshl_add_u64 v[184:185], s[12:13], 0, v[170:171]
	s_add_i32 m0, s30, 0xe000
	s_nop 0
	global_load_lds_dwordx4 v[184:185], off
	s_waitcnt lgkmcnt(8)
	s_barrier
	s_waitcnt lgkmcnt(0)
	s_waitcnt lgkmcnt(0)
	v_mfma_f32_16x16x32_bf16 v[126:129], v[130:133], v[146:149], v[126:129]
	v_mfma_f32_16x16x32_bf16 v[122:125], v[138:141], v[146:149], v[122:125]
	v_mfma_f32_16x16x32_bf16 v[118:121], v[130:133], v[154:157], v[118:121]
	v_mfma_f32_16x16x32_bf16 v[114:117], v[138:141], v[154:157], v[114:117]
	v_mfma_f32_16x16x32_bf16 v[92:95], v[130:133], v[172:175], v[92:95]
	v_mfma_f32_16x16x32_bf16 v[88:91], v[138:141], v[172:175], v[88:91]
	v_mfma_f32_16x16x32_bf16 v[84:87], v[130:133], v[180:183], v[84:87]
	v_mfma_f32_16x16x32_bf16 v[76:79], v[138:141], v[180:183], v[76:79]
	v_mfma_f32_16x16x32_bf16 v[126:129], v[134:137], v[150:153], v[126:129]
	v_mfma_f32_16x16x32_bf16 v[122:125], v[142:145], v[150:153], v[122:125]
	v_mfma_f32_16x16x32_bf16 v[118:121], v[134:137], v[158:161], v[118:121]
	v_mfma_f32_16x16x32_bf16 v[114:117], v[142:145], v[158:161], v[114:117]
	v_mfma_f32_16x16x32_bf16 v[92:95], v[134:137], v[176:179], v[92:95]
	v_mfma_f32_16x16x32_bf16 v[88:91], v[142:145], v[176:179], v[88:91]
	v_mfma_f32_16x16x32_bf16 v[84:87], v[134:137], v[190:193], v[84:87]
	v_mfma_f32_16x16x32_bf16 v[76:79], v[142:145], v[190:193], v[76:79]
	s_barrier
	s_add_i32 s46, 0, 0x14000
	v_add_u32_e32 v184, s46, v187
	s_add_i32 s0, s0, s29
	ds_read_b128 v[194:197], v184
	ds_read_b128 v[198:201], v184 offset:1024
	ds_read_b128 v[202:205], v184 offset:2048
	ds_read_b128 v[206:209], v184 offset:3072
	v_lshl_add_u64 v[184:185], s[16:17], 0, v[96:97]
	s_mov_b32 m0, s0
	v_lshl_add_u64 v[210:211], s[16:17], 0, v[166:167]
	global_load_lds_dwordx4 v[184:185], off
	s_add_i32 m0, s0, 0x2000
	s_nop 0
	global_load_lds_dwordx4 v[210:211], off
	s_barrier
; #define PG8_STAGE(bufoff, gbase, voff) do { _Pragma("unroll") for (int _i = 0; _i < 2; ++_i) \
;     __builtin_amdgcn_global_load_lds((const unsigned*)((const char*)(gbase) + (voff)[_i]), (LAS unsigned*)(lds + (bufoff) + ldsw + _i * 8192), 16, 0, 0); } while (0)
; #define PG8_LDA(dst, b, h) do { _Pragma("unroll") for (int m = 0; m < 4; ++m) _Pragma("unroll") for (int k = 0; k < 2; ++k) dst[m][k] = *(const LAS bf16x8*)(lds + PG8_SA(b, h) + aoff + m * 2048 + k * 1024); } while (0)
; #define PG8_LDB(dst, b, h) do { _Pragma("unroll") for (int n = 0; n < 2; ++n) _Pragma("unroll") for (int k = 0; k < 2; ++k) dst[n][k] = *(const LAS bf16x8*)(lds + PG8_SB(b, h) + boff + n * 2048 + k * 1024); } while (0)
; #define PG8_MMA(ai, bj, At, Bt) do { __builtin_amdgcn_s_setprio(1); _Pragma("unroll") for (int m = 0; m < 4; ++m) _Pragma("unroll") for (int n = 0; n < 2; ++n) _Pragma("unroll") for (int k = 0; k < 2; ++k) \
;     acc[ai][bj][m][n] = __builtin_amdgcn_mfma_f32_16x16x32_bf16(Bt[n][k], At[m][k], acc[ai][bj][m][n], 0, 0, 0); __builtin_amdgcn_s_setprio(0); } while (0)
; #define PG8_WAIT_V(n) asm volatile("s_waitcnt vmcnt(" #n ")" ::: "memory")
; #define PG8_WAIT_L(n) asm volatile("s_waitcnt lgkmcnt(" #n ")" ::: "memory")
; #define PG8_BAR __builtin_amdgcn_s_barrier()
; #define PG8_SCHED __builtin_amdgcn_sched_barrier(0)
; template <class Epi>
; __device__ __forceinline__ void gemm_phase(LAS unsigned char* lds, const Gemm g, const StaticOrder& S, const Epi& E, int wv0) {
;     ...
;       PG8_BAR; PG8_WAIT_L(0); PG8_MMA(0, 1, At, B1); PG8_BAR;
;       PG8_LDA(At, 0, 1); PG8_STAGE(PG8_SA(0, 0), a2, voffA);
;       PG8_BAR; PG8_WAIT_L(0); PG8_MMA(1, 0, At, B0); PG8_BAR; PG8_SCHED;
;       PG8_STAGE(PG8_SB(0, 1), b2 + hstepB, voffB);
;       PG8_WAIT_V(6); PG8_BAR; PG8_MMA(1, 1, At, B1); PG8_BAR;
;       PG8_LDB(B0, 1, 0); PG8_SCHED; PG8_LDA(At, 1, 0); PG8_STAGE(PG8_SA(0, 1), a2 + hstepA, voffA);
;       PG8_WAIT_L(8); PG8_BAR; PG8_WAIT_L(0); PG8_MMA(0, 0, At, B0); PG8_BAR; PG8_SCHED;
	s_waitcnt lgkmcnt(0)
	s_waitcnt lgkmcnt(0)
	v_mfma_f32_16x16x32_bf16 v[110:113], v[194:197], v[146:149], v[110:113]
	v_mfma_f32_16x16x32_bf16 v[106:109], v[202:205], v[146:149], v[106:109]
	v_mfma_f32_16x16x32_bf16 v[102:105], v[194:197], v[154:157], v[102:105]
	v_mfma_f32_16x16x32_bf16 v[98:101], v[202:205], v[154:157], v[98:101]
	v_mfma_f32_16x16x32_bf16 v[80:83], v[194:197], v[172:175], v[80:83]
	v_mfma_f32_16x16x32_bf16 v[72:75], v[202:205], v[172:175], v[72:75]
	v_mfma_f32_16x16x32_bf16 v[68:71], v[194:197], v[180:183], v[68:71]
	v_mfma_f32_16x16x32_bf16 v[64:67], v[202:205], v[180:183], v[64:67]
	v_mfma_f32_16x16x32_bf16 v[110:113], v[198:201], v[150:153], v[110:113]
	v_mfma_f32_16x16x32_bf16 v[106:109], v[206:209], v[150:153], v[106:109]
	v_mfma_f32_16x16x32_bf16 v[102:105], v[198:201], v[158:161], v[102:105]
	v_mfma_f32_16x16x32_bf16 v[98:101], v[206:209], v[158:161], v[98:101]
	v_mfma_f32_16x16x32_bf16 v[80:83], v[198:201], v[176:179], v[80:83]
	v_mfma_f32_16x16x32_bf16 v[72:75], v[206:209], v[176:179], v[72:75]
	v_mfma_f32_16x16x32_bf16 v[68:71], v[198:201], v[190:193], v[68:71]
	v_mfma_f32_16x16x32_bf16 v[64:67], v[206:209], v[190:193], v[64:67]
	s_mov_b32 m0, s30
	v_lshl_add_u64 v[212:213], s[18:19], 0, v[162:163]
	s_barrier
	ds_read_b128 v[146:149], v189 offset:16384
	ds_read_b128 v[150:153], v189 offset:17408
	ds_read_b128 v[154:157], v189 offset:18432
	ds_read_b128 v[158:161], v189 offset:19456
	ds_read_b128 v[172:175], v189 offset:20480
	ds_read_b128 v[176:179], v189 offset:21504
	ds_read_b128 v[180:183], v189 offset:22528
	ds_read_b128 v[190:193], v189 offset:23552
	global_load_lds_dwordx4 v[212:213], off
	v_lshl_add_u64 v[214:215], s[18:19], 0, v[164:165]
	s_mov_b32 m0, s31
	s_nop 0
	global_load_lds_dwordx4 v[214:215], off
	s_barrier
	s_waitcnt lgkmcnt(0)
	s_waitcnt lgkmcnt(0)
	v_mfma_f32_16x16x32_bf16 v[60:63], v[130:133], v[146:149], v[60:63]
	v_mfma_f32_16x16x32_bf16 v[56:59], v[138:141], v[146:149], v[56:59]
	v_mfma_f32_16x16x32_bf16 v[48:51], v[130:133], v[154:157], v[48:51]
	v_mfma_f32_16x16x32_bf16 v[40:43], v[138:141], v[154:157], v[40:43]
	v_mfma_f32_16x16x32_bf16 v[28:31], v[130:133], v[172:175], v[28:31]
	v_mfma_f32_16x16x32_bf16 v[24:27], v[138:141], v[172:175], v[24:27]
	v_mfma_f32_16x16x32_bf16 v[16:19], v[130:133], v[180:183], v[16:19]
	v_mfma_f32_16x16x32_bf16 v[8:11], v[138:141], v[180:183], v[8:11]
	v_mfma_f32_16x16x32_bf16 v[60:63], v[134:137], v[150:153], v[60:63]
	v_mfma_f32_16x16x32_bf16 v[56:59], v[142:145], v[150:153], v[56:59]
	v_mfma_f32_16x16x32_bf16 v[48:51], v[134:137], v[158:161], v[48:51]
	v_mfma_f32_16x16x32_bf16 v[40:43], v[142:145], v[158:161], v[40:43]
	v_mfma_f32_16x16x32_bf16 v[28:31], v[134:137], v[176:179], v[28:31]
	v_mfma_f32_16x16x32_bf16 v[24:27], v[142:145], v[176:179], v[24:27]
	v_mfma_f32_16x16x32_bf16 v[16:19], v[134:137], v[190:193], v[16:19]
	v_mfma_f32_16x16x32_bf16 v[8:11], v[142:145], v[190:193], v[8:11]
	s_barrier
	s_add_u32 s12, s16, 0x160000
	s_addc_u32 s13, s17, 0
	s_add_i32 s0, s46, s29
	v_lshl_add_u64 v[130:131], s[12:13], 0, v[96:97]
	s_mov_b32 m0, s0
	s_nop 0
	global_load_lds_dwordx4 v[130:131], off
	v_lshl_add_u64 v[130:131], s[12:13], 0, v[166:167]
	s_add_i32 m0, s0, 0x2000
	s_nop 0
	global_load_lds_dwordx4 v[130:131], off
	s_waitcnt vmcnt(6)
	s_barrier
	v_mfma_f32_16x16x32_bf16 v[52:55], v[194:197], v[146:149], v[52:55]
	v_mfma_f32_16x16x32_bf16 v[44:47], v[202:205], v[146:149], v[44:47]
	v_mfma_f32_16x16x32_bf16 v[36:39], v[194:197], v[154:157], v[36:39]
	v_mfma_f32_16x16x32_bf16 v[32:35], v[202:205], v[154:157], v[32:35]
	v_mfma_f32_16x16x32_bf16 v[20:23], v[194:197], v[172:175], v[20:23]
	v_mfma_f32_16x16x32_bf16 v[12:15], v[202:205], v[172:175], v[12:15]
	v_mfma_f32_16x16x32_bf16 v[4:7], v[194:197], v[180:183], v[4:7]
	v_mfma_f32_16x16x32_bf16 v[0:3], v[202:205], v[180:183], v[0:3]
	v_mfma_f32_16x16x32_bf16 v[52:55], v[198:201], v[150:153], v[52:55]
	v_mfma_f32_16x16x32_bf16 v[44:47], v[206:209], v[150:153], v[44:47]
	v_mfma_f32_16x16x32_bf16 v[36:39], v[198:201], v[158:161], v[36:39]
	v_mfma_f32_16x16x32_bf16 v[32:35], v[206:209], v[158:161], v[32:35]
	v_mfma_f32_16x16x32_bf16 v[20:23], v[198:201], v[176:179], v[20:23]
	v_mfma_f32_16x16x32_bf16 v[12:15], v[206:209], v[176:179], v[12:15]
	v_mfma_f32_16x16x32_bf16 v[4:7], v[198:201], v[190:193], v[4:7]
	v_mfma_f32_16x16x32_bf16 v[0:3], v[206:209], v[190:193], v[0:3]
	s_add_i32 s0, 0, 0x18000
	v_add_u32_e32 v142, s0, v187
	s_barrier
	ds_read_b128 v[130:133], v142
	ds_read_b128 v[134:137], v142 offset:1024
	ds_read_b128 v[138:141], v142 offset:2048
	ds_read_b128 v[142:145], v142 offset:3072
	s_add_u32 s12, s18, 0x160000
	s_addc_u32 s13, s19, 0
	s_mov_b32 m0, s34
	v_lshl_add_u64 v[194:195], s[12:13], 0, v[162:163]
	ds_read_b128 v[146:149], v189 offset:32768
	ds_read_b128 v[150:153], v189 offset:33792
	ds_read_b128 v[154:157], v189 offset:34816
	ds_read_b128 v[158:161], v189 offset:35840
	ds_read_b128 v[172:175], v189 offset:36864
	ds_read_b128 v[176:179], v189 offset:37888
	ds_read_b128 v[180:183], v189 offset:38912
	ds_read_b128 v[190:193], v189 offset:39936
	global_load_lds_dwordx4 v[194:195], off
	v_lshl_add_u64 v[194:195], s[12:13], 0, v[164:165]
	s_mov_b32 m0, s35
	s_nop 0
	global_load_lds_dwordx4 v[194:195], off
	s_waitcnt lgkmcnt(8)
	s_barrier
; #define PG8_STAGE(bufoff, gbase, voff) do { _Pragma("unroll") for (int _i = 0; _i < 2; ++_i) \
;     __builtin_amdgcn_global_load_lds((const unsigned*)((const char*)(gbase) + (voff)[_i]), (LAS unsigned*)(lds + (bufoff) + ldsw + _i * 8192), 16, 0, 0); } while (0)
; #define PG8_LDA(dst, b, h) do { _Pragma("unroll") for (int m = 0; m < 4; ++m) _Pragma("unroll") for (int k = 0; k < 2; ++k) dst[m][k] = *(const LAS bf16x8*)(lds + PG8_SA(b, h) + aoff + m * 2048 + k * 1024); } while (0)
; #define PG8_LDB(dst, b, h) do { _Pragma("unroll") for (int n = 0; n < 2; ++n) _Pragma("unroll") for (int k = 0; k < 2; ++k) dst[n][k] = *(const LAS bf16x8*)(lds + PG8_SB(b, h) + boff + n * 2048 + k * 1024); } while (0)
; #define PG8_MMA(ai, bj, At, Bt) do { __builtin_amdgcn_s_setprio(1); _Pragma("unroll") for (int m = 0; m < 4; ++m) _Pragma("unroll") for (int n = 0; n < 2; ++n) _Pragma("unroll") for (int k = 0; k < 2; ++k) \
;     acc[ai][bj][m][n] = __builtin_amdgcn_mfma_f32_16x16x32_bf16(Bt[n][k], At[m][k], acc[ai][bj][m][n], 0, 0, 0); __builtin_amdgcn_s_setprio(0); } while (0)
; #define PG8_WAIT_V(n) asm volatile("s_waitcnt vmcnt(" #n ")" ::: "memory")
; #define PG8_WAIT_L(n) asm volatile("s_waitcnt lgkmcnt(" #n ")" ::: "memory")
; #define PG8_BAR __builtin_amdgcn_s_barrier()
; #define PG8_SCHED __builtin_amdgcn_sched_barrier(0)
; template <class Epi>
; __device__ __forceinline__ void gemm_phase(LAS unsigned char* lds, const Gemm g, const StaticOrder& S, const Epi& E, int wv0) {
;     ...
;       PG8_WAIT_L(8); PG8_BAR; PG8_WAIT_L(0); PG8_MMA(0, 0, At, B0); PG8_BAR; PG8_SCHED;
;       PG8_LDB(B1, 1, 1); PG8_STAGE(PG8_SB(1, 0), b3, voffB);
;       PG8_BAR; PG8_WAIT_L(0); PG8_MMA(0, 1, At, B1); PG8_BAR;
;       PG8_LDA(At, 1, 1); PG8_STAGE(PG8_SA(1, 0), a3, voffA);
;       PG8_BAR; PG8_WAIT_L(0); PG8_MMA(1, 0, At, B0); PG8_BAR; PG8_SCHED;
;       PG8_STAGE(PG8_SB(1, 1), b3 + hstepB, voffB);
;       PG8_WAIT_V(6); PG8_BAR; PG8_MMA(1, 1, At, B1); PG8_BAR;
	s_waitcnt lgkmcnt(0)
	s_waitcnt lgkmcnt(0)
	v_mfma_f32_16x16x32_bf16 v[126:129], v[130:133], v[146:149], v[126:129]
	v_mfma_f32_16x16x32_bf16 v[122:125], v[138:141], v[146:149], v[122:125]
	v_mfma_f32_16x16x32_bf16 v[118:121], v[130:133], v[154:157], v[118:121]
	v_mfma_f32_16x16x32_bf16 v[114:117], v[138:141], v[154:157], v[114:117]
	v_mfma_f32_16x16x32_bf16 v[92:95], v[130:133], v[172:175], v[92:95]
	v_mfma_f32_16x16x32_bf16 v[88:91], v[138:141], v[172:175], v[88:91]
	v_mfma_f32_16x16x32_bf16 v[84:87], v[130:133], v[180:183], v[84:87]
	v_mfma_f32_16x16x32_bf16 v[76:79], v[138:141], v[180:183], v[76:79]
	v_mfma_f32_16x16x32_bf16 v[126:129], v[134:137], v[150:153], v[126:129]
	v_mfma_f32_16x16x32_bf16 v[122:125], v[142:145], v[150:153], v[122:125]
	v_mfma_f32_16x16x32_bf16 v[118:121], v[134:137], v[158:161], v[118:121]
	v_mfma_f32_16x16x32_bf16 v[114:117], v[142:145], v[158:161], v[114:117]
	v_mfma_f32_16x16x32_bf16 v[92:95], v[134:137], v[176:179], v[92:95]
	v_mfma_f32_16x16x32_bf16 v[88:91], v[142:145], v[176:179], v[88:91]
	v_mfma_f32_16x16x32_bf16 v[84:87], v[134:137], v[190:193], v[84:87]
	v_mfma_f32_16x16x32_bf16 v[76:79], v[142:145], v[190:193], v[76:79]
	s_barrier
	s_add_i32 s18, 0, 0x1c000
	s_add_i32 s0, s0, s29
	v_add_u32_e32 v206, s18, v187
	v_lshl_add_u64 v[184:185], v[184:185], 0, s[72:73]
	s_mov_b32 m0, s0
	ds_read_b128 v[194:197], v206
	ds_read_b128 v[198:201], v206 offset:1024
	ds_read_b128 v[202:205], v206 offset:2048
	ds_read_b128 v[206:209], v206 offset:3072
	global_load_lds_dwordx4 v[184:185], off
	v_lshl_add_u64 v[184:185], v[210:211], 0, s[72:73]
	s_add_i32 m0, s0, 0x2000
	s_nop 0
	global_load_lds_dwordx4 v[184:185], off
	s_barrier
	s_waitcnt lgkmcnt(0)
	s_waitcnt lgkmcnt(0)
	v_mfma_f32_16x16x32_bf16 v[110:113], v[194:197], v[146:149], v[110:113]
	v_mfma_f32_16x16x32_bf16 v[106:109], v[202:205], v[146:149], v[106:109]
	v_mfma_f32_16x16x32_bf16 v[102:105], v[194:197], v[154:157], v[102:105]
	v_mfma_f32_16x16x32_bf16 v[98:101], v[202:205], v[154:157], v[98:101]
	v_mfma_f32_16x16x32_bf16 v[80:83], v[194:197], v[172:175], v[80:83]
	v_mfma_f32_16x16x32_bf16 v[72:75], v[202:205], v[172:175], v[72:75]
	v_mfma_f32_16x16x32_bf16 v[68:71], v[194:197], v[180:183], v[68:71]
	v_mfma_f32_16x16x32_bf16 v[64:67], v[202:205], v[180:183], v[64:67]
	v_mfma_f32_16x16x32_bf16 v[110:113], v[198:201], v[150:153], v[110:113]
	v_mfma_f32_16x16x32_bf16 v[106:109], v[206:209], v[150:153], v[106:109]
	v_mfma_f32_16x16x32_bf16 v[102:105], v[198:201], v[158:161], v[102:105]
	v_mfma_f32_16x16x32_bf16 v[98:101], v[206:209], v[158:161], v[98:101]
	v_mfma_f32_16x16x32_bf16 v[80:83], v[198:201], v[176:179], v[80:83]
	v_mfma_f32_16x16x32_bf16 v[72:75], v[206:209], v[176:179], v[72:75]
	v_mfma_f32_16x16x32_bf16 v[68:71], v[198:201], v[190:193], v[68:71]
	v_mfma_f32_16x16x32_bf16 v[64:67], v[206:209], v[190:193], v[64:67]
	s_mov_b32 m0, s36
	v_lshl_add_u64 v[184:185], v[212:213], 0, s[72:73]
	s_barrier
	ds_read_b128 v[146:149], v189 offset:49152
	ds_read_b128 v[150:153], v189 offset:50176
	ds_read_b128 v[154:157], v189 offset:51200
	ds_read_b128 v[158:161], v189 offset:52224
	ds_read_b128 v[172:175], v189 offset:53248
	ds_read_b128 v[176:179], v189 offset:54272
	ds_read_b128 v[180:183], v189 offset:55296
	ds_read_b128 v[190:193], v189 offset:56320
	global_load_lds_dwordx4 v[184:185], off
	v_lshl_add_u64 v[184:185], v[214:215], 0, s[72:73]
	s_mov_b32 m0, s37
	s_nop 0
	global_load_lds_dwordx4 v[184:185], off
	s_barrier
	s_waitcnt lgkmcnt(0)
	s_waitcnt lgkmcnt(0)
	v_mfma_f32_16x16x32_bf16 v[60:63], v[130:133], v[146:149], v[60:63]
	v_mfma_f32_16x16x32_bf16 v[56:59], v[138:141], v[146:149], v[56:59]
	v_mfma_f32_16x16x32_bf16 v[48:51], v[130:133], v[154:157], v[48:51]
	v_mfma_f32_16x16x32_bf16 v[40:43], v[138:141], v[154:157], v[40:43]
	v_mfma_f32_16x16x32_bf16 v[28:31], v[130:133], v[172:175], v[28:31]
	v_mfma_f32_16x16x32_bf16 v[24:27], v[138:141], v[172:175], v[24:27]
	v_mfma_f32_16x16x32_bf16 v[16:19], v[130:133], v[180:183], v[16:19]
	v_mfma_f32_16x16x32_bf16 v[8:11], v[138:141], v[180:183], v[8:11]
	v_mfma_f32_16x16x32_bf16 v[60:63], v[134:137], v[150:153], v[60:63]
	v_mfma_f32_16x16x32_bf16 v[56:59], v[142:145], v[150:153], v[56:59]
	v_mfma_f32_16x16x32_bf16 v[48:51], v[134:137], v[158:161], v[48:51]
	v_mfma_f32_16x16x32_bf16 v[40:43], v[142:145], v[158:161], v[40:43]
	v_mfma_f32_16x16x32_bf16 v[28:31], v[134:137], v[176:179], v[28:31]
	v_mfma_f32_16x16x32_bf16 v[24:27], v[142:145], v[176:179], v[24:27]
	v_mfma_f32_16x16x32_bf16 v[16:19], v[134:137], v[190:193], v[16:19]
	v_mfma_f32_16x16x32_bf16 v[8:11], v[142:145], v[190:193], v[8:11]
	s_barrier
	s_add_u32 s12, s16, 0x160080
	s_addc_u32 s13, s17, 0
	s_add_i32 s0, s18, s29
	v_lshl_add_u64 v[130:131], s[12:13], 0, v[96:97]
	s_mov_b32 m0, s0
	s_nop 0
	global_load_lds_dwordx4 v[130:131], off
	v_lshl_add_u64 v[130:131], s[12:13], 0, v[166:167]
	s_add_i32 m0, s0, 0x2000
	s_nop 0
	global_load_lds_dwordx4 v[130:131], off
	s_waitcnt vmcnt(6)
	s_barrier
	v_mfma_f32_16x16x32_bf16 v[52:55], v[194:197], v[146:149], v[52:55]
	v_mfma_f32_16x16x32_bf16 v[44:47], v[202:205], v[146:149], v[44:47]
	v_mfma_f32_16x16x32_bf16 v[36:39], v[194:197], v[154:157], v[36:39]
	v_mfma_f32_16x16x32_bf16 v[32:35], v[202:205], v[154:157], v[32:35]
	v_mfma_f32_16x16x32_bf16 v[20:23], v[194:197], v[172:175], v[20:23]
	v_mfma_f32_16x16x32_bf16 v[12:15], v[202:205], v[172:175], v[12:15]
	v_mfma_f32_16x16x32_bf16 v[4:7], v[194:197], v[180:183], v[4:7]
	v_mfma_f32_16x16x32_bf16 v[0:3], v[202:205], v[180:183], v[0:3]
	v_mfma_f32_16x16x32_bf16 v[52:55], v[198:201], v[150:153], v[52:55]
	v_mfma_f32_16x16x32_bf16 v[44:47], v[206:209], v[150:153], v[44:47]
	v_mfma_f32_16x16x32_bf16 v[36:39], v[198:201], v[158:161], v[36:39]
	v_mfma_f32_16x16x32_bf16 v[32:35], v[206:209], v[158:161], v[32:35]
	v_mfma_f32_16x16x32_bf16 v[20:23], v[198:201], v[176:179], v[20:23]
	v_mfma_f32_16x16x32_bf16 v[12:15], v[206:209], v[176:179], v[12:15]
	v_mfma_f32_16x16x32_bf16 v[4:7], v[198:201], v[190:193], v[4:7]
	v_mfma_f32_16x16x32_bf16 v[0:3], v[206:209], v[190:193], v[0:3]
	s_add_i32 s45, s45, 2
	s_add_u32 s43, s43, 0x100
	s_addc_u32 s44, s44, 0
	s_cmpk_gt_u32 s45, 0x55
	s_mov_b64 s[12:13], s[14:15]
	s_barrier
;   __device__ __forceinline__ void preload(EpiPre& q, int row, int col) const {
;     ...
;     } else if (MODE == E_RES) {
;       const float* rs = e.f0 + (size_t)row * DM + col; q.a0 = *(const f32x4*)rs; q.a1 = *(const f32x4*)(rs + 4);
;   __device__ __forceinline__ void emit(const EpiPre& q0, int row, int col, f32x4 a, f32x4 b, const f32x4 (&hb)[2][2], const float (&hs)[2][4], int ai_, int m_, int bj_) const {
;     ...
;     } else if (MODE == E_RES) {
;       const f32x4 r0 = q.a0, r1 = q.a1;
;       float* o = (float*)e.out + (size_t)row * DM + col;
;       *(f32x4*)o = (f32x4){ALPHA * r0[0] + v[0], ALPHA * r0[1] + v[1], ALPHA * r0[2] + v[2], ALPHA * r0[3] + v[3]};
;       *(f32x4*)(o + 4) = (f32x4){ALPHA * r1[0] + v[4], ALPHA * r1[1] + v[5], ALPHA * r1[2] + v[6], ALPHA * r1[3] + v[7]};
	s_cbranch_scc0 .LBB0_1429
	s_setprio 0
	s_load_dwordx4 s[16:19], s[54:55], 0x88
	v_lshl_add_u32 v252, s1, 8, v186
	v_lshl_or_b32 v218, s42, 8, v188
	v_lshlrev_b32_e32 v247, 13, v252
	v_lshlrev_b32_e32 v218, 2, v218
	v_lshlrev_b32_e32 v252, 3, v252
	v_add_u32_e32 v247, v247, v218
	s_add_u32 s12, s8, 0x27700000
	s_addc_u32 s13, s9, 0
	s_add_u32 s14, s10, 0x0
	s_addc_u32 s15, s11, 0
	global_load_dwordx2 v[184:185], v252, s[12:13] offset:0
	global_load_dwordx4 v[130:133], v247, s[14:15]
	global_load_dwordx4 v[134:137], v247, s[14:15] offset:16
	global_load_dwordx4 v[138:141], v247, s[14:15] offset:512
	global_load_dwordx4 v[142:145], v247, s[14:15] offset:528
	s_add_u32 s44, s10, 0x20000
	s_addc_u32 s45, s11, 0
	global_load_dwordx2 v[242:243], v252, s[12:13] offset:128
	global_load_dwordx4 v[146:149], v247, s[44:45]
	global_load_dwordx4 v[150:153], v247, s[44:45] offset:16
	global_load_dwordx4 v[154:157], v247, s[44:45] offset:512
	global_load_dwordx4 v[158:161], v247, s[44:45] offset:528
	s_add_u32 s46, s10, 0x40000
	s_addc_u32 s47, s11, 0
	global_load_dwordx2 v[248:249], v252, s[12:13] offset:256
	global_load_dwordx4 v[172:175], v247, s[46:47]
	global_load_dwordx4 v[176:179], v247, s[46:47] offset:16
	global_load_dwordx4 v[180:183], v247, s[46:47] offset:512
	global_load_dwordx4 v[238:241], v247, s[46:47] offset:528
	s_lshl_b32 s0, s66, 13
	s_waitcnt lgkmcnt(0)
	s_add_u32 s16, s16, s0
	s_addc_u32 s17, s17, 0
	s_add_u32 s18, s18, s0
	s_addc_u32 s19, s19, 0
	global_load_dwordx4 v[190:193], v218, s[16:17]
	global_load_dwordx4 v[194:197], v218, s[16:17] offset:16
	global_load_dwordx4 v[198:201], v218, s[16:17] offset:512
	global_load_dwordx4 v[202:205], v218, s[16:17] offset:528
	global_load_dwordx4 v[206:209], v218, s[18:19]
	global_load_dwordx4 v[210:213], v218, s[18:19] offset:16
	global_load_dwordx4 v[214:217], v218, s[18:19] offset:512
	global_load_dwordx4 v[234:237], v218, s[18:19] offset:528
	s_waitcnt vmcnt(0)
	v_pk_add_f32 v[130:131], v[130:131], v[184:185] op_sel_hi:[1,0]
	v_pk_add_f32 v[132:133], v[132:133], v[184:185] op_sel_hi:[1,0]
	v_pk_add_f32 v[134:135], v[134:135], v[184:185] op_sel_hi:[1,0]
	v_pk_add_f32 v[136:137], v[136:137], v[184:185] op_sel_hi:[1,0]
	v_pk_add_f32 v[138:139], v[138:139], v[184:185] op_sel_hi:[1,0]
	v_pk_add_f32 v[140:141], v[140:141], v[184:185] op_sel_hi:[1,0]
	v_pk_add_f32 v[142:143], v[142:143], v[184:185] op_sel_hi:[1,0]
	v_pk_add_f32 v[144:145], v[144:145], v[184:185] op_sel_hi:[1,0]
	v_pk_mul_f32 v[130:131], v[130:131], v[184:185] op_sel:[0,1] op_sel_hi:[1,1]
	v_pk_mul_f32 v[132:133], v[132:133], v[184:185] op_sel:[0,1] op_sel_hi:[1,1]
	v_pk_mul_f32 v[134:135], v[134:135], v[184:185] op_sel:[0,1] op_sel_hi:[1,1]
	v_pk_mul_f32 v[136:137], v[136:137], v[184:185] op_sel:[0,1] op_sel_hi:[1,1]
	v_pk_mul_f32 v[138:139], v[138:139], v[184:185] op_sel:[0,1] op_sel_hi:[1,1]
	v_pk_mul_f32 v[140:141], v[140:141], v[184:185] op_sel:[0,1] op_sel_hi:[1,1]
	v_pk_mul_f32 v[142:143], v[142:143], v[184:185] op_sel:[0,1] op_sel_hi:[1,1]
	v_pk_mul_f32 v[144:145], v[144:145], v[184:185] op_sel:[0,1] op_sel_hi:[1,1]
	v_pk_fma_f32 v[130:131], v[190:191], v[130:131], v[206:207]
	v_pk_fma_f32 v[132:133], v[192:193], v[132:133], v[208:209]
	v_pk_fma_f32 v[134:135], v[194:195], v[134:135], v[210:211]
	v_pk_fma_f32 v[136:137], v[196:197], v[136:137], v[212:213]
	v_pk_fma_f32 v[138:139], v[198:199], v[138:139], v[214:215]
	v_pk_fma_f32 v[140:141], v[200:201], v[140:141], v[216:217]
	v_pk_fma_f32 v[142:143], v[202:203], v[142:143], v[234:235]
	v_pk_fma_f32 v[144:145], v[204:205], v[144:145], v[236:237]
	v_pk_fma_f32 v[126:127], v[130:131], s[90:91], v[126:127] op_sel_hi:[1,0,1]
	v_pk_fma_f32 v[128:129], v[132:133], s[90:91], v[128:129] op_sel_hi:[1,0,1]
	v_pk_fma_f32 v[122:123], v[134:135], s[90:91], v[122:123] op_sel_hi:[1,0,1]
	v_pk_fma_f32 v[124:125], v[136:137], s[90:91], v[124:125] op_sel_hi:[1,0,1]
	v_pk_fma_f32 v[110:111], v[138:139], s[90:91], v[110:111] op_sel_hi:[1,0,1]
	v_pk_fma_f32 v[112:113], v[140:141], s[90:91], v[112:113] op_sel_hi:[1,0,1]
	v_pk_fma_f32 v[106:107], v[142:143], s[90:91], v[106:107] op_sel_hi:[1,0,1]
	v_pk_fma_f32 v[108:109], v[144:145], s[90:91], v[108:109] op_sel_hi:[1,0,1]
	s_add_u32 s48, s10, 0x60000
	s_addc_u32 s49, s11, 0
	global_load_dwordx2 v[184:185], v252, s[12:13] offset:384
	global_load_dwordx4 v[130:133], v247, s[48:49]
	global_load_dwordx4 v[134:137], v247, s[48:49] offset:16
	global_load_dwordx4 v[138:141], v247, s[48:49] offset:512
	global_load_dwordx4 v[142:145], v247, s[48:49] offset:528
	s_waitcnt vmcnt(18)
;   __device__ __forceinline__ void preload(EpiPre& q, int row, int col) const {
;     ...
;     } else if (MODE == E_RES) {
;       const float* rs = e.f0 + (size_t)row * DM + col; q.a0 = *(const f32x4*)rs; q.a1 = *(const f32x4*)(rs + 4);
;   __device__ __forceinline__ void emit(const EpiPre& q0, int row, int col, f32x4 a, f32x4 b, const f32x4 (&hb)[2][2], const float (&hs)[2][4], int ai_, int m_, int bj_) const {
;     ...
;     } else if (MODE == E_RES) {
;       const f32x4 r0 = q.a0, r1 = q.a1;
;       float* o = (float*)e.out + (size_t)row * DM + col;
;       *(f32x4*)o = (f32x4){ALPHA * r0[0] + v[0], ALPHA * r0[1] + v[1], ALPHA * r0[2] + v[2], ALPHA * r0[3] + v[3]};
;       *(f32x4*)(o + 4) = (f32x4){ALPHA * r1[0] + v[4], ALPHA * r1[1] + v[5], ALPHA * r1[2] + v[6], ALPHA * r1[3] + v[7]};
	v_pk_add_f32 v[146:147], v[146:147], v[242:243] op_sel_hi:[1,0]
	v_pk_add_f32 v[148:149], v[148:149], v[242:243] op_sel_hi:[1,0]
	v_pk_add_f32 v[150:151], v[150:151], v[242:243] op_sel_hi:[1,0]
	v_pk_add_f32 v[152:153], v[152:153], v[242:243] op_sel_hi:[1,0]
	v_pk_add_f32 v[154:155], v[154:155], v[242:243] op_sel_hi:[1,0]
	v_pk_add_f32 v[156:157], v[156:157], v[242:243] op_sel_hi:[1,0]
	v_pk_add_f32 v[158:159], v[158:159], v[242:243] op_sel_hi:[1,0]
	v_pk_add_f32 v[160:161], v[160:161], v[242:243] op_sel_hi:[1,0]
	v_pk_mul_f32 v[146:147], v[146:147], v[242:243] op_sel:[0,1] op_sel_hi:[1,1]
	v_pk_mul_f32 v[148:149], v[148:149], v[242:243] op_sel:[0,1] op_sel_hi:[1,1]
	v_pk_mul_f32 v[150:151], v[150:151], v[242:243] op_sel:[0,1] op_sel_hi:[1,1]
	v_pk_mul_f32 v[152:153], v[152:153], v[242:243] op_sel:[0,1] op_sel_hi:[1,1]
	v_pk_mul_f32 v[154:155], v[154:155], v[242:243] op_sel:[0,1] op_sel_hi:[1,1]
	v_pk_mul_f32 v[156:157], v[156:157], v[242:243] op_sel:[0,1] op_sel_hi:[1,1]
	v_pk_mul_f32 v[158:159], v[158:159], v[242:243] op_sel:[0,1] op_sel_hi:[1,1]
	v_pk_mul_f32 v[160:161], v[160:161], v[242:243] op_sel:[0,1] op_sel_hi:[1,1]
	v_pk_fma_f32 v[146:147], v[190:191], v[146:147], v[206:207]
	v_pk_fma_f32 v[148:149], v[192:193], v[148:149], v[208:209]
	v_pk_fma_f32 v[150:151], v[194:195], v[150:151], v[210:211]
	v_pk_fma_f32 v[152:153], v[196:197], v[152:153], v[212:213]
	v_pk_fma_f32 v[154:155], v[198:199], v[154:155], v[214:215]
	v_pk_fma_f32 v[156:157], v[200:201], v[156:157], v[216:217]
	v_pk_fma_f32 v[158:159], v[202:203], v[158:159], v[234:235]
	v_pk_fma_f32 v[160:161], v[204:205], v[160:161], v[236:237]
	v_pk_fma_f32 v[118:119], v[146:147], s[90:91], v[118:119] op_sel_hi:[1,0,1]
	v_pk_fma_f32 v[120:121], v[148:149], s[90:91], v[120:121] op_sel_hi:[1,0,1]
	v_pk_fma_f32 v[114:115], v[150:151], s[90:91], v[114:115] op_sel_hi:[1,0,1]
	v_pk_fma_f32 v[116:117], v[152:153], s[90:91], v[116:117] op_sel_hi:[1,0,1]
	v_pk_fma_f32 v[102:103], v[154:155], s[90:91], v[102:103] op_sel_hi:[1,0,1]
	v_pk_fma_f32 v[104:105], v[156:157], s[90:91], v[104:105] op_sel_hi:[1,0,1]
	v_pk_fma_f32 v[98:99], v[158:159], s[90:91], v[98:99] op_sel_hi:[1,0,1]
	v_pk_fma_f32 v[100:101], v[160:161], s[90:91], v[100:101] op_sel_hi:[1,0,1]
	s_add_u32 s16, s10, 0x100000
	s_addc_u32 s17, s11, 0
	global_load_dwordx2 v[242:243], v252, s[12:13] offset:1024
	global_load_dwordx4 v[146:149], v247, s[16:17]
	global_load_dwordx4 v[150:153], v247, s[16:17] offset:16
	global_load_dwordx4 v[154:157], v247, s[16:17] offset:512
	global_load_dwordx4 v[158:161], v247, s[16:17] offset:528
	s_waitcnt vmcnt(18)
	v_pk_add_f32 v[172:173], v[172:173], v[248:249] op_sel_hi:[1,0]
	v_pk_add_f32 v[174:175], v[174:175], v[248:249] op_sel_hi:[1,0]
	v_pk_add_f32 v[176:177], v[176:177], v[248:249] op_sel_hi:[1,0]
	v_pk_add_f32 v[178:179], v[178:179], v[248:249] op_sel_hi:[1,0]
	v_pk_add_f32 v[180:181], v[180:181], v[248:249] op_sel_hi:[1,0]
	v_pk_add_f32 v[182:183], v[182:183], v[248:249] op_sel_hi:[1,0]
	v_pk_add_f32 v[238:239], v[238:239], v[248:249] op_sel_hi:[1,0]
	v_pk_add_f32 v[240:241], v[240:241], v[248:249] op_sel_hi:[1,0]
	v_pk_mul_f32 v[172:173], v[172:173], v[248:249] op_sel:[0,1] op_sel_hi:[1,1]
	v_pk_mul_f32 v[174:175], v[174:175], v[248:249] op_sel:[0,1] op_sel_hi:[1,1]
	v_pk_mul_f32 v[176:177], v[176:177], v[248:249] op_sel:[0,1] op_sel_hi:[1,1]
	v_pk_mul_f32 v[178:179], v[178:179], v[248:249] op_sel:[0,1] op_sel_hi:[1,1]
	v_pk_mul_f32 v[180:181], v[180:181], v[248:249] op_sel:[0,1] op_sel_hi:[1,1]
	v_pk_mul_f32 v[182:183], v[182:183], v[248:249] op_sel:[0,1] op_sel_hi:[1,1]
	v_pk_mul_f32 v[238:239], v[238:239], v[248:249] op_sel:[0,1] op_sel_hi:[1,1]
	v_pk_mul_f32 v[240:241], v[240:241], v[248:249] op_sel:[0,1] op_sel_hi:[1,1]
	v_pk_fma_f32 v[172:173], v[190:191], v[172:173], v[206:207]
	v_pk_fma_f32 v[174:175], v[192:193], v[174:175], v[208:209]
	v_pk_fma_f32 v[176:177], v[194:195], v[176:177], v[210:211]
	v_pk_fma_f32 v[178:179], v[196:197], v[178:179], v[212:213]
	v_pk_fma_f32 v[180:181], v[198:199], v[180:181], v[214:215]
	v_pk_fma_f32 v[182:183], v[200:201], v[182:183], v[216:217]
	v_pk_fma_f32 v[238:239], v[202:203], v[238:239], v[234:235]
	v_pk_fma_f32 v[240:241], v[204:205], v[240:241], v[236:237]
	v_pk_fma_f32 v[92:93], v[172:173], s[90:91], v[92:93] op_sel_hi:[1,0,1]
	v_pk_fma_f32 v[94:95], v[174:175], s[90:91], v[94:95] op_sel_hi:[1,0,1]
	v_pk_fma_f32 v[88:89], v[176:177], s[90:91], v[88:89] op_sel_hi:[1,0,1]
	v_pk_fma_f32 v[90:91], v[178:179], s[90:91], v[90:91] op_sel_hi:[1,0,1]
	v_pk_fma_f32 v[80:81], v[180:181], s[90:91], v[80:81] op_sel_hi:[1,0,1]
	v_pk_fma_f32 v[82:83], v[182:183], s[90:91], v[82:83] op_sel_hi:[1,0,1]
	v_pk_fma_f32 v[72:73], v[238:239], s[90:91], v[72:73] op_sel_hi:[1,0,1]
	v_pk_fma_f32 v[74:75], v[240:241], s[90:91], v[74:75] op_sel_hi:[1,0,1]
	s_add_u32 s18, s10, 0x120000
	s_addc_u32 s19, s11, 0
	global_load_dwordx2 v[248:249], v252, s[12:13] offset:1152
	global_load_dwordx4 v[172:175], v247, s[18:19]
	global_load_dwordx4 v[176:179], v247, s[18:19] offset:16
	global_load_dwordx4 v[180:183], v247, s[18:19] offset:512
	global_load_dwordx4 v[238:241], v247, s[18:19] offset:528
	global_store_dwordx4 v247, v[126:129], s[14:15]
	global_store_dwordx4 v247, v[122:125], s[14:15] offset:16
	global_store_dwordx4 v247, v[110:113], s[14:15] offset:512
	global_store_dwordx4 v247, v[106:109], s[14:15] offset:528
	global_store_dwordx4 v247, v[118:121], s[44:45]
	global_store_dwordx4 v247, v[114:117], s[44:45] offset:16
	global_store_dwordx4 v247, v[102:105], s[44:45] offset:512
	global_store_dwordx4 v247, v[98:101], s[44:45] offset:528
	global_store_dwordx4 v247, v[92:95], s[46:47]
	global_store_dwordx4 v247, v[88:91], s[46:47] offset:16
	global_store_dwordx4 v247, v[80:83], s[46:47] offset:512
	global_store_dwordx4 v247, v[72:75], s[46:47] offset:528
	s_add_u32 s14, s10, 0x140000
	s_addc_u32 s15, s11, 0
	global_load_dwordx2 v[92:93], v252, s[12:13] offset:1280
	global_load_dwordx4 v[126:129], v247, s[14:15]
	global_load_dwordx4 v[122:125], v247, s[14:15] offset:16
	global_load_dwordx4 v[110:113], v247, s[14:15] offset:512
	global_load_dwordx4 v[106:109], v247, s[14:15] offset:528
	s_add_u32 s44, s10, 0x160000
	s_addc_u32 s45, s11, 0
	global_load_dwordx2 v[88:89], v252, s[12:13] offset:1408
	global_load_dwordx4 v[118:121], v247, s[44:45]
	global_load_dwordx4 v[114:117], v247, s[44:45] offset:16
	global_load_dwordx4 v[102:105], v247, s[44:45] offset:512
	global_load_dwordx4 v[98:101], v247, s[44:45] offset:528
	s_waitcnt vmcnt(32)
;   __device__ __forceinline__ void emit(const EpiPre& q0, int row, int col, f32x4 a, f32x4 b, const f32x4 (&hb)[2][2], const float (&hs)[2][4], int ai_, int m_, int bj_) const {
;     ...
;     } else if (MODE == E_RES) {
;       const f32x4 r0 = q.a0, r1 = q.a1;
;       float* o = (float*)e.out + (size_t)row * DM + col;
;       *(f32x4*)o = (f32x4){ALPHA * r0[0] + v[0], ALPHA * r0[1] + v[1], ALPHA * r0[2] + v[2], ALPHA * r0[3] + v[3]};
;       *(f32x4*)(o + 4) = (f32x4){ALPHA * r1[0] + v[4], ALPHA * r1[1] + v[5], ALPHA * r1[2] + v[6], ALPHA * r1[3] + v[7]};
	v_pk_add_f32 v[130:131], v[130:131], v[184:185] op_sel_hi:[1,0]
	v_pk_add_f32 v[132:133], v[132:133], v[184:185] op_sel_hi:[1,0]
	v_pk_add_f32 v[134:135], v[134:135], v[184:185] op_sel_hi:[1,0]
	v_pk_add_f32 v[136:137], v[136:137], v[184:185] op_sel_hi:[1,0]
	v_pk_add_f32 v[138:139], v[138:139], v[184:185] op_sel_hi:[1,0]
	v_pk_add_f32 v[140:141], v[140:141], v[184:185] op_sel_hi:[1,0]
	v_pk_add_f32 v[142:143], v[142:143], v[184:185] op_sel_hi:[1,0]
	v_pk_add_f32 v[144:145], v[144:145], v[184:185] op_sel_hi:[1,0]
	v_pk_mul_f32 v[130:131], v[130:131], v[184:185] op_sel:[0,1] op_sel_hi:[1,1]
	v_pk_mul_f32 v[132:133], v[132:133], v[184:185] op_sel:[0,1] op_sel_hi:[1,1]
	v_pk_mul_f32 v[134:135], v[134:135], v[184:185] op_sel:[0,1] op_sel_hi:[1,1]
	v_pk_mul_f32 v[136:137], v[136:137], v[184:185] op_sel:[0,1] op_sel_hi:[1,1]
	v_pk_mul_f32 v[138:139], v[138:139], v[184:185] op_sel:[0,1] op_sel_hi:[1,1]
	v_pk_mul_f32 v[140:141], v[140:141], v[184:185] op_sel:[0,1] op_sel_hi:[1,1]
	v_pk_mul_f32 v[142:143], v[142:143], v[184:185] op_sel:[0,1] op_sel_hi:[1,1]
	v_pk_mul_f32 v[144:145], v[144:145], v[184:185] op_sel:[0,1] op_sel_hi:[1,1]
	v_pk_fma_f32 v[130:131], v[190:191], v[130:131], v[206:207]
	v_pk_fma_f32 v[132:133], v[192:193], v[132:133], v[208:209]
	v_pk_fma_f32 v[134:135], v[194:195], v[134:135], v[210:211]
	v_pk_fma_f32 v[136:137], v[196:197], v[136:137], v[212:213]
	v_pk_fma_f32 v[138:139], v[198:199], v[138:139], v[214:215]
	v_pk_fma_f32 v[140:141], v[200:201], v[140:141], v[216:217]
	v_pk_fma_f32 v[142:143], v[202:203], v[142:143], v[234:235]
	v_pk_fma_f32 v[144:145], v[204:205], v[144:145], v[236:237]
	v_pk_fma_f32 v[84:85], v[130:131], s[90:91], v[84:85] op_sel_hi:[1,0,1]
	v_pk_fma_f32 v[86:87], v[132:133], s[90:91], v[86:87] op_sel_hi:[1,0,1]
	v_pk_fma_f32 v[76:77], v[134:135], s[90:91], v[76:77] op_sel_hi:[1,0,1]
	v_pk_fma_f32 v[78:79], v[136:137], s[90:91], v[78:79] op_sel_hi:[1,0,1]
	v_pk_fma_f32 v[68:69], v[138:139], s[90:91], v[68:69] op_sel_hi:[1,0,1]
	v_pk_fma_f32 v[70:71], v[140:141], s[90:91], v[70:71] op_sel_hi:[1,0,1]
	v_pk_fma_f32 v[64:65], v[142:143], s[90:91], v[64:65] op_sel_hi:[1,0,1]
	v_pk_fma_f32 v[66:67], v[144:145], s[90:91], v[66:67] op_sel_hi:[1,0,1]
	global_store_dwordx4 v247, v[84:87], s[48:49]
	global_store_dwordx4 v247, v[76:79], s[48:49] offset:16
	global_store_dwordx4 v247, v[68:71], s[48:49] offset:512
	global_store_dwordx4 v247, v[64:67], s[48:49] offset:528
	s_waitcnt vmcnt(31)
	v_pk_add_f32 v[146:147], v[146:147], v[242:243] op_sel_hi:[1,0]
	v_pk_add_f32 v[148:149], v[148:149], v[242:243] op_sel_hi:[1,0]
	v_pk_add_f32 v[150:151], v[150:151], v[242:243] op_sel_hi:[1,0]
	v_pk_add_f32 v[152:153], v[152:153], v[242:243] op_sel_hi:[1,0]
	v_pk_add_f32 v[154:155], v[154:155], v[242:243] op_sel_hi:[1,0]
	v_pk_add_f32 v[156:157], v[156:157], v[242:243] op_sel_hi:[1,0]
	v_pk_add_f32 v[158:159], v[158:159], v[242:243] op_sel_hi:[1,0]
	v_pk_add_f32 v[160:161], v[160:161], v[242:243] op_sel_hi:[1,0]
	v_pk_mul_f32 v[146:147], v[146:147], v[242:243] op_sel:[0,1] op_sel_hi:[1,1]
	v_pk_mul_f32 v[148:149], v[148:149], v[242:243] op_sel:[0,1] op_sel_hi:[1,1]
	v_pk_mul_f32 v[150:151], v[150:151], v[242:243] op_sel:[0,1] op_sel_hi:[1,1]
	v_pk_mul_f32 v[152:153], v[152:153], v[242:243] op_sel:[0,1] op_sel_hi:[1,1]
	v_pk_mul_f32 v[154:155], v[154:155], v[242:243] op_sel:[0,1] op_sel_hi:[1,1]
	v_pk_mul_f32 v[156:157], v[156:157], v[242:243] op_sel:[0,1] op_sel_hi:[1,1]
	v_pk_mul_f32 v[158:159], v[158:159], v[242:243] op_sel:[0,1] op_sel_hi:[1,1]
	v_pk_mul_f32 v[160:161], v[160:161], v[242:243] op_sel:[0,1] op_sel_hi:[1,1]
	v_pk_fma_f32 v[146:147], v[190:191], v[146:147], v[206:207]
	v_pk_fma_f32 v[148:149], v[192:193], v[148:149], v[208:209]
	v_pk_fma_f32 v[150:151], v[194:195], v[150:151], v[210:211]
	v_pk_fma_f32 v[152:153], v[196:197], v[152:153], v[212:213]
	v_pk_fma_f32 v[154:155], v[198:199], v[154:155], v[214:215]
	v_pk_fma_f32 v[156:157], v[200:201], v[156:157], v[216:217]
	v_pk_fma_f32 v[158:159], v[202:203], v[158:159], v[234:235]
	v_pk_fma_f32 v[160:161], v[204:205], v[160:161], v[236:237]
	v_pk_fma_f32 v[60:61], v[146:147], s[90:91], v[60:61] op_sel_hi:[1,0,1]
	v_pk_fma_f32 v[62:63], v[148:149], s[90:91], v[62:63] op_sel_hi:[1,0,1]
	v_pk_fma_f32 v[56:57], v[150:151], s[90:91], v[56:57] op_sel_hi:[1,0,1]
	v_pk_fma_f32 v[58:59], v[152:153], s[90:91], v[58:59] op_sel_hi:[1,0,1]
	v_pk_fma_f32 v[52:53], v[154:155], s[90:91], v[52:53] op_sel_hi:[1,0,1]
	v_pk_fma_f32 v[54:55], v[156:157], s[90:91], v[54:55] op_sel_hi:[1,0,1]
	v_pk_fma_f32 v[44:45], v[158:159], s[90:91], v[44:45] op_sel_hi:[1,0,1]
	v_pk_fma_f32 v[46:47], v[160:161], s[90:91], v[46:47] op_sel_hi:[1,0,1]
	global_store_dwordx4 v247, v[60:63], s[16:17]
	global_store_dwordx4 v247, v[56:59], s[16:17] offset:16
	global_store_dwordx4 v247, v[52:55], s[16:17] offset:512
	global_store_dwordx4 v247, v[44:47], s[16:17] offset:528
	s_waitcnt vmcnt(30)
;   __device__ __forceinline__ void emit(const EpiPre& q0, int row, int col, f32x4 a, f32x4 b, const f32x4 (&hb)[2][2], const float (&hs)[2][4], int ai_, int m_, int bj_) const {
;     ...
;     } else if (MODE == E_RES) {
;       const f32x4 r0 = q.a0, r1 = q.a1;
;       float* o = (float*)e.out + (size_t)row * DM + col;
;       *(f32x4*)o = (f32x4){ALPHA * r0[0] + v[0], ALPHA * r0[1] + v[1], ALPHA * r0[2] + v[2], ALPHA * r0[3] + v[3]};
;       *(f32x4*)(o + 4) = (f32x4){ALPHA * r1[0] + v[4], ALPHA * r1[1] + v[5], ALPHA * r1[2] + v[6], ALPHA * r1[3] + v[7]};
	v_pk_add_f32 v[172:173], v[172:173], v[248:249] op_sel_hi:[1,0]
	v_pk_add_f32 v[174:175], v[174:175], v[248:249] op_sel_hi:[1,0]
	v_pk_add_f32 v[176:177], v[176:177], v[248:249] op_sel_hi:[1,0]
	v_pk_add_f32 v[178:179], v[178:179], v[248:249] op_sel_hi:[1,0]
	v_pk_add_f32 v[180:181], v[180:181], v[248:249] op_sel_hi:[1,0]
	v_pk_add_f32 v[182:183], v[182:183], v[248:249] op_sel_hi:[1,0]
	v_pk_add_f32 v[238:239], v[238:239], v[248:249] op_sel_hi:[1,0]
	v_pk_add_f32 v[240:241], v[240:241], v[248:249] op_sel_hi:[1,0]
	v_pk_mul_f32 v[172:173], v[172:173], v[248:249] op_sel:[0,1] op_sel_hi:[1,1]
	v_pk_mul_f32 v[174:175], v[174:175], v[248:249] op_sel:[0,1] op_sel_hi:[1,1]
	v_pk_mul_f32 v[176:177], v[176:177], v[248:249] op_sel:[0,1] op_sel_hi:[1,1]
	v_pk_mul_f32 v[178:179], v[178:179], v[248:249] op_sel:[0,1] op_sel_hi:[1,1]
	v_pk_mul_f32 v[180:181], v[180:181], v[248:249] op_sel:[0,1] op_sel_hi:[1,1]
	v_pk_mul_f32 v[182:183], v[182:183], v[248:249] op_sel:[0,1] op_sel_hi:[1,1]
	v_pk_mul_f32 v[238:239], v[238:239], v[248:249] op_sel:[0,1] op_sel_hi:[1,1]
	v_pk_mul_f32 v[240:241], v[240:241], v[248:249] op_sel:[0,1] op_sel_hi:[1,1]
	v_pk_fma_f32 v[172:173], v[190:191], v[172:173], v[206:207]
	v_pk_fma_f32 v[174:175], v[192:193], v[174:175], v[208:209]
	v_pk_fma_f32 v[176:177], v[194:195], v[176:177], v[210:211]
	v_pk_fma_f32 v[178:179], v[196:197], v[178:179], v[212:213]
	v_pk_fma_f32 v[180:181], v[198:199], v[180:181], v[214:215]
	v_pk_fma_f32 v[182:183], v[200:201], v[182:183], v[216:217]
	v_pk_fma_f32 v[238:239], v[202:203], v[238:239], v[234:235]
	v_pk_fma_f32 v[240:241], v[204:205], v[240:241], v[236:237]
	v_pk_fma_f32 v[48:49], v[172:173], s[90:91], v[48:49] op_sel_hi:[1,0,1]
	v_pk_fma_f32 v[50:51], v[174:175], s[90:91], v[50:51] op_sel_hi:[1,0,1]
	v_pk_fma_f32 v[40:41], v[176:177], s[90:91], v[40:41] op_sel_hi:[1,0,1]
	v_pk_fma_f32 v[42:43], v[178:179], s[90:91], v[42:43] op_sel_hi:[1,0,1]
	v_pk_fma_f32 v[36:37], v[180:181], s[90:91], v[36:37] op_sel_hi:[1,0,1]
	v_pk_fma_f32 v[38:39], v[182:183], s[90:91], v[38:39] op_sel_hi:[1,0,1]
	v_pk_fma_f32 v[32:33], v[238:239], s[90:91], v[32:33] op_sel_hi:[1,0,1]
	v_pk_fma_f32 v[34:35], v[240:241], s[90:91], v[34:35] op_sel_hi:[1,0,1]
	global_store_dwordx4 v247, v[48:51], s[18:19]
	global_store_dwordx4 v247, v[40:43], s[18:19] offset:16
	global_store_dwordx4 v247, v[36:39], s[18:19] offset:512
	global_store_dwordx4 v247, v[32:35], s[18:19] offset:528
	s_waitcnt vmcnt(17)
	v_pk_add_f32 v[126:127], v[126:127], v[92:93] op_sel_hi:[1,0]
	v_pk_add_f32 v[128:129], v[128:129], v[92:93] op_sel_hi:[1,0]
	v_pk_add_f32 v[122:123], v[122:123], v[92:93] op_sel_hi:[1,0]
	v_pk_add_f32 v[124:125], v[124:125], v[92:93] op_sel_hi:[1,0]
	v_pk_add_f32 v[110:111], v[110:111], v[92:93] op_sel_hi:[1,0]
	v_pk_add_f32 v[112:113], v[112:113], v[92:93] op_sel_hi:[1,0]
	v_pk_add_f32 v[106:107], v[106:107], v[92:93] op_sel_hi:[1,0]
	v_pk_add_f32 v[108:109], v[108:109], v[92:93] op_sel_hi:[1,0]
	v_pk_mul_f32 v[126:127], v[126:127], v[92:93] op_sel:[0,1] op_sel_hi:[1,1]
	v_pk_mul_f32 v[128:129], v[128:129], v[92:93] op_sel:[0,1] op_sel_hi:[1,1]
	v_pk_mul_f32 v[122:123], v[122:123], v[92:93] op_sel:[0,1] op_sel_hi:[1,1]
	v_pk_mul_f32 v[124:125], v[124:125], v[92:93] op_sel:[0,1] op_sel_hi:[1,1]
	v_pk_mul_f32 v[110:111], v[110:111], v[92:93] op_sel:[0,1] op_sel_hi:[1,1]
	v_pk_mul_f32 v[112:113], v[112:113], v[92:93] op_sel:[0,1] op_sel_hi:[1,1]
	v_pk_mul_f32 v[106:107], v[106:107], v[92:93] op_sel:[0,1] op_sel_hi:[1,1]
	v_pk_mul_f32 v[108:109], v[108:109], v[92:93] op_sel:[0,1] op_sel_hi:[1,1]
	v_pk_fma_f32 v[126:127], v[190:191], v[126:127], v[206:207]
	v_pk_fma_f32 v[128:129], v[192:193], v[128:129], v[208:209]
	v_pk_fma_f32 v[122:123], v[194:195], v[122:123], v[210:211]
	v_pk_fma_f32 v[124:125], v[196:197], v[124:125], v[212:213]
	v_pk_fma_f32 v[110:111], v[198:199], v[110:111], v[214:215]
	v_pk_fma_f32 v[112:113], v[200:201], v[112:113], v[216:217]
	v_pk_fma_f32 v[106:107], v[202:203], v[106:107], v[234:235]
	v_pk_fma_f32 v[108:109], v[204:205], v[108:109], v[236:237]
	v_pk_fma_f32 v[28:29], v[126:127], s[90:91], v[28:29] op_sel_hi:[1,0,1]
	v_pk_fma_f32 v[30:31], v[128:129], s[90:91], v[30:31] op_sel_hi:[1,0,1]
	v_pk_fma_f32 v[24:25], v[122:123], s[90:91], v[24:25] op_sel_hi:[1,0,1]
	v_pk_fma_f32 v[26:27], v[124:125], s[90:91], v[26:27] op_sel_hi:[1,0,1]
	v_pk_fma_f32 v[20:21], v[110:111], s[90:91], v[20:21] op_sel_hi:[1,0,1]
	v_pk_fma_f32 v[22:23], v[112:113], s[90:91], v[22:23] op_sel_hi:[1,0,1]
	v_pk_fma_f32 v[12:13], v[106:107], s[90:91], v[12:13] op_sel_hi:[1,0,1]
	v_pk_fma_f32 v[14:15], v[108:109], s[90:91], v[14:15] op_sel_hi:[1,0,1]
	global_store_dwordx4 v247, v[28:31], s[14:15]
	global_store_dwordx4 v247, v[24:27], s[14:15] offset:16
	global_store_dwordx4 v247, v[20:23], s[14:15] offset:512
	global_store_dwordx4 v247, v[12:15], s[14:15] offset:528
	s_waitcnt vmcnt(16)
; #define PG8_WAIT_V(n) asm volatile("s_waitcnt vmcnt(" #n ")" ::: "memory")
; #define PG8_BAR __builtin_amdgcn_s_barrier()
; template <class Epi>
; __device__ __forceinline__ void gemm_phase(LAS unsigned char* lds, const Gemm g, const StaticOrder& S, const Epi& E, int wv0) {
;     ...
;     if (!has_next) break;
; #pragma unroll
;     for (int a = 0; a < 2; ++a)
; #pragma unroll
;       for (int b = 0; b < 2; ++b)
; #pragma unroll
;         for (int m = 0; m < 4; ++m)
; #pragma unroll
;           for (int n = 0; n < 2; ++n) acc[a][b][m][n] = (f32x4){0.f, 0.f, 0.f, 0.f};
;     cur = nxt; cA = nA; cB = nB; ++ui;
;   }
;   PG8_WAIT_V(0);
;   if (wr == 0) PG8_BAR;
;   PG8_BAR;
;   __device__ __forceinline__ void emit(const EpiPre& q0, int row, int col, f32x4 a, f32x4 b, const f32x4 (&hb)[2][2], const float (&hs)[2][4], int ai_, int m_, int bj_) const {
;     ...
;     } else if (MODE == E_RES) {
;       const f32x4 r0 = q.a0, r1 = q.a1;
;       float* o = (float*)e.out + (size_t)row * DM + col;
;       *(f32x4*)o = (f32x4){ALPHA * r0[0] + v[0], ALPHA * r0[1] + v[1], ALPHA * r0[2] + v[2], ALPHA * r0[3] + v[3]};
;       *(f32x4*)(o + 4) = (f32x4){ALPHA * r1[0] + v[4], ALPHA * r1[1] + v[5], ALPHA * r1[2] + v[6], ALPHA * r1[3] + v[7]};
	v_pk_add_f32 v[118:119], v[118:119], v[88:89] op_sel_hi:[1,0]
	v_pk_add_f32 v[120:121], v[120:121], v[88:89] op_sel_hi:[1,0]
	v_pk_add_f32 v[114:115], v[114:115], v[88:89] op_sel_hi:[1,0]
	v_pk_add_f32 v[116:117], v[116:117], v[88:89] op_sel_hi:[1,0]
	v_pk_add_f32 v[102:103], v[102:103], v[88:89] op_sel_hi:[1,0]
	v_pk_add_f32 v[104:105], v[104:105], v[88:89] op_sel_hi:[1,0]
	v_pk_add_f32 v[98:99], v[98:99], v[88:89] op_sel_hi:[1,0]
	v_pk_add_f32 v[100:101], v[100:101], v[88:89] op_sel_hi:[1,0]
	v_pk_mul_f32 v[118:119], v[118:119], v[88:89] op_sel:[0,1] op_sel_hi:[1,1]
	v_pk_mul_f32 v[120:121], v[120:121], v[88:89] op_sel:[0,1] op_sel_hi:[1,1]
	v_pk_mul_f32 v[114:115], v[114:115], v[88:89] op_sel:[0,1] op_sel_hi:[1,1]
	v_pk_mul_f32 v[116:117], v[116:117], v[88:89] op_sel:[0,1] op_sel_hi:[1,1]
	v_pk_mul_f32 v[102:103], v[102:103], v[88:89] op_sel:[0,1] op_sel_hi:[1,1]
	v_pk_mul_f32 v[104:105], v[104:105], v[88:89] op_sel:[0,1] op_sel_hi:[1,1]
	v_pk_mul_f32 v[98:99], v[98:99], v[88:89] op_sel:[0,1] op_sel_hi:[1,1]
	v_pk_mul_f32 v[100:101], v[100:101], v[88:89] op_sel:[0,1] op_sel_hi:[1,1]
	v_pk_fma_f32 v[118:119], v[190:191], v[118:119], v[206:207]
	v_pk_fma_f32 v[120:121], v[192:193], v[120:121], v[208:209]
	v_pk_fma_f32 v[114:115], v[194:195], v[114:115], v[210:211]
	v_pk_fma_f32 v[116:117], v[196:197], v[116:117], v[212:213]
	v_pk_fma_f32 v[102:103], v[198:199], v[102:103], v[214:215]
	v_pk_fma_f32 v[104:105], v[200:201], v[104:105], v[216:217]
	v_pk_fma_f32 v[98:99], v[202:203], v[98:99], v[234:235]
	v_pk_fma_f32 v[100:101], v[204:205], v[100:101], v[236:237]
	v_pk_fma_f32 v[16:17], v[118:119], s[90:91], v[16:17] op_sel_hi:[1,0,1]
	v_pk_fma_f32 v[18:19], v[120:121], s[90:91], v[18:19] op_sel_hi:[1,0,1]
	v_pk_fma_f32 v[8:9], v[114:115], s[90:91], v[8:9] op_sel_hi:[1,0,1]
	v_pk_fma_f32 v[10:11], v[116:117], s[90:91], v[10:11] op_sel_hi:[1,0,1]
	v_pk_fma_f32 v[4:5], v[102:103], s[90:91], v[4:5] op_sel_hi:[1,0,1]
	v_pk_fma_f32 v[6:7], v[104:105], s[90:91], v[6:7] op_sel_hi:[1,0,1]
	v_pk_fma_f32 v[0:1], v[98:99], s[90:91], v[0:1] op_sel_hi:[1,0,1]
	v_pk_fma_f32 v[2:3], v[100:101], s[90:91], v[2:3] op_sel_hi:[1,0,1]
	global_store_dwordx4 v247, v[16:19], s[44:45]
	global_store_dwordx4 v247, v[8:11], s[44:45] offset:16
	global_store_dwordx4 v247, v[4:7], s[44:45] offset:512
	global_store_dwordx4 v247, v[0:3], s[44:45] offset:528
	s_mov_b64 s[0:1], 0x100000
	s_mov_b32 s42, s40
	s_mov_b64 s[14:15], s[6:7]
	s_mov_b64 s[12:13], s[4:5]
	s_and_b64 vcc, exec, s[2:3]
	s_mov_b32 s1, s41
	s_cbranch_vccz .LBB0_1418
	s_waitcnt vmcnt(0)
	s_cmpk_gt_u32 s23, 0xff
	s_cbranch_scc1 .LBB0_1433
	s_barrier
